# E+A deferred-store version plus 2 wait states between each deferred store and the update of its address register (hazard safety)
# baseline (speedup 1.0000x reference)
; #define PG8_STAGE(bufoff, gbase, voff) do { _Pragma("unroll") for (int _i = 0; _i < 2; ++_i) \
;         __builtin_amdgcn_global_load_lds((const unsigned*)((const char*)(gbase) + (voff)[_i]), (LAS unsigned*)(lds + (bufoff) + ldsw + _i * 8192), 16, 0, 0); } while (0)
; #define PG8_LDA(dst, b, h) do { _Pragma("unroll") for (int m = 0; m < 4; ++m) _Pragma("unroll") for (int k = 0; k < 2; ++k) dst[m][k] = *(const LAS bf16x8*)(lds + PG8_SA(b, h) + aoff + m * 2048 + k * 1024); } while (0)
; #define PG8_LDB(dst, b, h) do { _Pragma("unroll") for (int n = 0; n < 2; ++n) _Pragma("unroll") for (int k = 0; k < 2; ++k) dst[n][k] = *(const LAS bf16x8*)(lds + PG8_SB(b, h) + boff + n * 2048 + k * 1024); } while (0)
; #define PG8_WAIT_V(n) asm volatile("s_waitcnt vmcnt(" #n ")" ::: "memory")
; #define PG8_WAIT_L(n) asm volatile("s_waitcnt lgkmcnt(" #n ")" ::: "memory")
; #define PG8_BAR __builtin_amdgcn_s_barrier()
; #define PG8_SCHED __builtin_amdgcn_sched_barrier(0)
; template <class Epi>
; __device__ __forceinline__ void gemm_phase(LAS unsigned char* lds, const Gemm g, const StaticOrder& S, const Epi& E) {
;     ...
;             PG8_LDB(B0, 0, 0); PG8_SCHED; PG8_LDA(At, 0, 0); PG8_STAGE(PG8_SA(1, 1), a1 + hstep, voffA);
;             PG8_WAIT_L(8); PG8_BAR; PG8_WAIT_L(0); PG8_MMA(0, 0, At, B0); PG8_BAR; PG8_SCHED;
;             PG8_LDB(B1, 0, 1); PG8_STAGE(PG8_SB(0, 0), b2, voffB);
;             PG8_BAR; PG8_WAIT_L(0); PG8_MMA(0, 1, At, B1); PG8_BAR;
;             PG8_LDA(At, 0, 1); PG8_STAGE(PG8_SA(0, 0), a2, voffA);
;             PG8_BAR; PG8_WAIT_L(0); PG8_MMA(1, 0, At, B0); PG8_BAR; PG8_SCHED;
;             PG8_STAGE(PG8_SB(0, 1), b2 + hstep, voffB);
;             PG8_WAIT_V(6); PG8_BAR; PG8_MMA(1, 1, At, B1); PG8_BAR;
;             PG8_LDB(B0, 1, 0); PG8_SCHED; PG8_LDA(At, 1, 0); PG8_STAGE(PG8_SA(0, 1), a2 + hstep, voffA);
;             PG8_WAIT_L(8); PG8_BAR; PG8_WAIT_L(0); PG8_MMA(0, 0, At, B0); PG8_BAR; PG8_SCHED;
;             PG8_LDB(B1, 1, 1); PG8_STAGE(PG8_SB(1, 0), b3, voffB);
;             PG8_BAR; PG8_WAIT_L(0); PG8_MMA(0, 1, At, B1); PG8_BAR;
;             PG8_LDA(At, 1, 1); PG8_STAGE(PG8_SA(1, 0), a3, voffA);
;             PG8_BAR; PG8_WAIT_L(0); PG8_MMA(1, 0, At, B0); PG8_BAR; PG8_SCHED;
;             PG8_STAGE(PG8_SB(1, 1), b3 + hstep, voffB);
;             PG8_WAIT_V(6); PG8_BAR; PG8_MMA(1, 1, At, B1); PG8_BAR;
.LdsE_skip_0:
	v_mfma_f32_16x16x32_bf16 v[38:41], v[230:233], v[184:187], 0
	v_mfma_f32_16x16x32_bf16 v[34:37], v[238:241], v[184:187], 0
	v_mfma_f32_16x16x32_bf16 v[22:25], v[230:233], v[208:211], 0
	v_mfma_f32_16x16x32_bf16 v[18:21], v[238:241], v[208:211], 0
	v_mfma_f32_16x16x32_bf16 v[6:9], v[230:233], v[216:219], 0
	v_mfma_f32_16x16x32_bf16 v[2:5], v[238:241], v[216:219], 0
	v_mfma_f32_16x16x32_bf16 v[54:57], v[234:237], v[180:183], v[54:57]
	v_mfma_f32_16x16x32_bf16 v[50:53], v[242:245], v[180:183], v[50:53]
	v_mfma_f32_16x16x32_bf16 v[38:41], v[234:237], v[204:207], v[38:41]
	v_mfma_f32_16x16x32_bf16 v[34:37], v[242:245], v[204:207], v[34:37]
	v_mfma_f32_16x16x32_bf16 v[22:25], v[234:237], v[212:215], v[22:25]
	v_mfma_f32_16x16x32_bf16 v[18:21], v[242:245], v[212:215], v[18:21]
	v_mfma_f32_16x16x32_bf16 v[6:9], v[234:237], v[226:229], v[6:9]
	v_mfma_f32_16x16x32_bf16 v[2:5], v[242:245], v[226:229], v[2:5]
	s_setprio 0
	s_add_i32 s58, 0, 0x18000
	v_add_u32_e32 v151, s58, v147
	s_barrier
	ds_read_b128 v[140:143], v151
	ds_read_b128 v[152:155], v151 offset:1024
	ds_read_b128 v[168:171], v151 offset:2048
	ds_read_b128 v[172:175], v151 offset:3072
	s_add_u32 s42, s42, 0x40000
	s_addc_u32 s43, s43, 0
	s_mov_b32 m0, s55
	ds_read_b128 v[176:179], v150 offset:32768
	ds_read_b128 v[180:183], v150 offset:33792
	ds_read_b128 v[184:187], v150 offset:34816
	ds_read_b128 v[204:207], v150 offset:35840
	ds_read_b128 v[208:211], v150 offset:36864
	ds_read_b128 v[212:215], v150 offset:37888
	ds_read_b128 v[216:219], v150 offset:38912
	ds_read_b128 v[226:229], v150 offset:39936
	global_load_lds_dwordx4 v134, s[42:43]
	s_mov_b32 m0, s83
	s_nop 0
	global_load_lds_dwordx4 v132, s[42:43]
	s_waitcnt lgkmcnt(8)
	s_barrier
	s_waitcnt lgkmcnt(0)
	s_setprio 1
	s_waitcnt lgkmcnt(0)
	v_mfma_f32_16x16x32_bf16 v[126:129], v[140:143], v[176:179], v[126:129]
	v_mfma_f32_16x16x32_bf16 v[122:125], v[168:171], v[176:179], v[122:125]
	v_mfma_f32_16x16x32_bf16 v[110:113], v[140:143], v[184:187], v[110:113]
	v_mfma_f32_16x16x32_bf16 v[106:109], v[168:171], v[184:187], v[106:109]
	v_mfma_f32_16x16x32_bf16 v[94:97], v[140:143], v[208:211], v[94:97]
	v_mfma_f32_16x16x32_bf16 v[90:93], v[168:171], v[208:211], v[90:93]
	v_mfma_f32_16x16x32_bf16 v[78:81], v[140:143], v[216:219], v[78:81]
	v_mfma_f32_16x16x32_bf16 v[74:77], v[168:171], v[216:219], v[74:77]
	v_mfma_f32_16x16x32_bf16 v[126:129], v[152:155], v[180:183], v[126:129]
	v_mfma_f32_16x16x32_bf16 v[122:125], v[172:175], v[180:183], v[122:125]
	v_mfma_f32_16x16x32_bf16 v[110:113], v[152:155], v[204:207], v[110:113]
	v_mfma_f32_16x16x32_bf16 v[106:109], v[172:175], v[204:207], v[106:109]
	v_mfma_f32_16x16x32_bf16 v[94:97], v[152:155], v[212:215], v[94:97]
	v_mfma_f32_16x16x32_bf16 v[90:93], v[172:175], v[212:215], v[90:93]
	v_mfma_f32_16x16x32_bf16 v[78:81], v[152:155], v[226:229], v[78:81]
	v_mfma_f32_16x16x32_bf16 v[74:77], v[172:175], v[226:229], v[74:77]
	s_setprio 0
	s_barrier
	s_add_i32 s42, 0, 0x1c000
	s_add_i32 s43, s58, s48
	v_add_u32_e32 v151, s42, v147
	s_add_u32 s60, s6, 0x80
	s_addc_u32 s61, s7, 0
	s_mov_b32 m0, s43
	ds_read_b128 v[230:233], v151
	ds_read_b128 v[234:237], v151 offset:1024
	ds_read_b128 v[238:241], v151 offset:2048
	ds_read_b128 v[242:245], v151 offset:3072
	global_load_lds_dwordx4 v0, s[60:61]
	s_add_i32 m0, s43, 0x2000
	s_nop 0
	global_load_lds_dwordx4 v130, s[60:61]
	s_barrier
	s_waitcnt lgkmcnt(0)
	s_setprio 1
	s_waitcnt lgkmcnt(0)
	v_mfma_f32_16x16x32_bf16 v[118:121], v[230:233], v[176:179], v[118:121]
	v_mfma_f32_16x16x32_bf16 v[114:117], v[238:241], v[176:179], v[114:117]
	v_mfma_f32_16x16x32_bf16 v[102:105], v[230:233], v[184:187], v[102:105]
	v_mfma_f32_16x16x32_bf16 v[98:101], v[238:241], v[184:187], v[98:101]
	v_mfma_f32_16x16x32_bf16 v[86:89], v[230:233], v[208:211], v[86:89]
	v_mfma_f32_16x16x32_bf16 v[82:85], v[238:241], v[208:211], v[82:85]
	v_mfma_f32_16x16x32_bf16 v[70:73], v[230:233], v[216:219], v[70:73]
	v_mfma_f32_16x16x32_bf16 v[66:69], v[238:241], v[216:219], v[66:69]
	v_mfma_f32_16x16x32_bf16 v[118:121], v[234:237], v[180:183], v[118:121]
	v_mfma_f32_16x16x32_bf16 v[114:117], v[242:245], v[180:183], v[114:117]
	v_mfma_f32_16x16x32_bf16 v[102:105], v[234:237], v[204:207], v[102:105]
	v_mfma_f32_16x16x32_bf16 v[98:101], v[242:245], v[204:207], v[98:101]
	v_mfma_f32_16x16x32_bf16 v[86:89], v[234:237], v[212:215], v[86:89]
	v_mfma_f32_16x16x32_bf16 v[82:85], v[242:245], v[212:215], v[82:85]
	v_mfma_f32_16x16x32_bf16 v[70:73], v[234:237], v[226:229], v[70:73]
	v_mfma_f32_16x16x32_bf16 v[66:69], v[242:245], v[226:229], v[66:69]
	s_setprio 0
	s_mov_b32 m0, s84
	s_barrier
	ds_read_b128 v[176:179], v150 offset:49152
	ds_read_b128 v[180:183], v150 offset:50176
	ds_read_b128 v[184:187], v150 offset:51200
	ds_read_b128 v[204:207], v150 offset:52224
	ds_read_b128 v[208:211], v150 offset:53248
	ds_read_b128 v[212:215], v150 offset:54272
	ds_read_b128 v[216:219], v150 offset:55296
	ds_read_b128 v[226:229], v150 offset:56320
	global_load_lds_dwordx4 v134, vcc
	s_mov_b32 m0, s85
	s_nop 0
	global_load_lds_dwordx4 v132, vcc
	s_barrier
; #define PG8_STAGE(bufoff, gbase, voff) do { _Pragma("unroll") for (int _i = 0; _i < 2; ++_i) \
;         __builtin_amdgcn_global_load_lds((const unsigned*)((const char*)(gbase) + (voff)[_i]), (LAS unsigned*)(lds + (bufoff) + ldsw + _i * 8192), 16, 0, 0); } while (0)
; #define PG8_LDA(dst, b, h) do { _Pragma("unroll") for (int m = 0; m < 4; ++m) _Pragma("unroll") for (int k = 0; k < 2; ++k) dst[m][k] = *(const LAS bf16x8*)(lds + PG8_SA(b, h) + aoff + m * 2048 + k * 1024); } while (0)
; #define PG8_LDB(dst, b, h) do { _Pragma("unroll") for (int n = 0; n < 2; ++n) _Pragma("unroll") for (int k = 0; k < 2; ++k) dst[n][k] = *(const LAS bf16x8*)(lds + PG8_SB(b, h) + boff + n * 2048 + k * 1024); } while (0)
; #define PG8_WAIT_V(n) asm volatile("s_waitcnt vmcnt(" #n ")" ::: "memory")
; #define PG8_WAIT_L(n) asm volatile("s_waitcnt lgkmcnt(" #n ")" ::: "memory")
; #define PG8_BAR __builtin_amdgcn_s_barrier()
; #define PG8_SCHED __builtin_amdgcn_sched_barrier(0)
; template <class Epi>
; __device__ __forceinline__ void gemm_phase(LAS unsigned char* lds, const Gemm g, const StaticOrder& S, const Epi& E) {
;     ...
;             PG8_LDB(B0, 0, 0); PG8_SCHED; PG8_LDA(At, 0, 0); PG8_STAGE(PG8_SA(1, 1), a1 + hstep, voffA);
;             PG8_WAIT_L(8); PG8_BAR; PG8_WAIT_L(0); PG8_MMA(0, 0, At, B0); PG8_BAR; PG8_SCHED;
;             PG8_LDB(B1, 0, 1); PG8_STAGE(PG8_SB(0, 0), b2, voffB);
;             PG8_BAR; PG8_WAIT_L(0); PG8_MMA(0, 1, At, B1); PG8_BAR;
;             PG8_LDA(At, 0, 1); PG8_STAGE(PG8_SA(0, 0), a2, voffA);
;             PG8_BAR; PG8_WAIT_L(0); PG8_MMA(1, 0, At, B0); PG8_BAR; PG8_SCHED;
;             PG8_STAGE(PG8_SB(0, 1), b2 + hstep, voffB);
;             PG8_WAIT_V(6); PG8_BAR; PG8_MMA(1, 1, At, B1); PG8_BAR;
;             PG8_LDB(B0, 1, 0); PG8_SCHED; PG8_LDA(At, 1, 0); PG8_STAGE(PG8_SA(0, 1), a2 + hstep, voffA);
;             PG8_WAIT_L(8); PG8_BAR; PG8_WAIT_L(0); PG8_MMA(0, 0, At, B0); PG8_BAR; PG8_SCHED;
;             PG8_LDB(B1, 1, 1); PG8_STAGE(PG8_SB(1, 0), b3, voffB);
;             PG8_BAR; PG8_WAIT_L(0); PG8_MMA(0, 1, At, B1); PG8_BAR;
;             PG8_LDA(At, 1, 1); PG8_STAGE(PG8_SA(1, 0), a3, voffA);
;             PG8_BAR; PG8_WAIT_L(0); PG8_MMA(1, 0, At, B0); PG8_BAR; PG8_SCHED;
;             PG8_STAGE(PG8_SB(1, 1), b3 + hstep, voffB);
;             PG8_WAIT_V(6); PG8_BAR; PG8_MMA(1, 1, At, B1); PG8_BAR;
	s_waitcnt lgkmcnt(0)
	s_setprio 1
	s_waitcnt lgkmcnt(0)
	v_mfma_f32_16x16x32_bf16 v[62:65], v[140:143], v[176:179], v[62:65]
	v_mfma_f32_16x16x32_bf16 v[58:61], v[168:171], v[176:179], v[58:61]
	v_mfma_f32_16x16x32_bf16 v[46:49], v[140:143], v[184:187], v[46:49]
	v_mfma_f32_16x16x32_bf16 v[42:45], v[168:171], v[184:187], v[42:45]
	v_mfma_f32_16x16x32_bf16 v[30:33], v[140:143], v[208:211], v[30:33]
	v_mfma_f32_16x16x32_bf16 v[26:29], v[168:171], v[208:211], v[26:29]
	v_mfma_f32_16x16x32_bf16 v[14:17], v[140:143], v[216:219], v[14:17]
	v_mfma_f32_16x16x32_bf16 v[10:13], v[168:171], v[216:219], v[10:13]
	v_mfma_f32_16x16x32_bf16 v[62:65], v[152:155], v[180:183], v[62:65]
	v_mfma_f32_16x16x32_bf16 v[58:61], v[172:175], v[180:183], v[58:61]
	v_mfma_f32_16x16x32_bf16 v[46:49], v[152:155], v[204:207], v[46:49]
	v_mfma_f32_16x16x32_bf16 v[42:45], v[172:175], v[204:207], v[42:45]
	v_mfma_f32_16x16x32_bf16 v[30:33], v[152:155], v[212:215], v[30:33]
	v_mfma_f32_16x16x32_bf16 v[26:29], v[172:175], v[212:215], v[26:29]
	v_mfma_f32_16x16x32_bf16 v[14:17], v[152:155], v[226:229], v[14:17]
	v_mfma_f32_16x16x32_bf16 v[10:13], v[172:175], v[226:229], v[10:13]
	s_setprio 0
	s_barrier
	s_add_u32 s6, s6, 0x40080
	s_addc_u32 s7, s7, 0
	s_add_i32 s42, s42, s48
	s_mov_b32 m0, s42
	s_nop 0
	global_load_lds_dwordx4 v0, s[6:7]
	s_add_i32 m0, s42, 0x2000
	s_nop 0
	global_load_lds_dwordx4 v130, s[6:7]
	s_waitcnt vmcnt(6)
	s_barrier
	s_setprio 1
	v_mfma_f32_16x16x32_bf16 v[54:57], v[230:233], v[176:179], v[54:57]
	v_mfma_f32_16x16x32_bf16 v[50:53], v[238:241], v[176:179], v[50:53]
	v_mfma_f32_16x16x32_bf16 v[38:41], v[230:233], v[184:187], v[38:41]
	v_mfma_f32_16x16x32_bf16 v[34:37], v[238:241], v[184:187], v[34:37]
	v_mfma_f32_16x16x32_bf16 v[22:25], v[230:233], v[208:211], v[22:25]
	v_mfma_f32_16x16x32_bf16 v[18:21], v[238:241], v[208:211], v[18:21]
	v_mfma_f32_16x16x32_bf16 v[6:9], v[230:233], v[216:219], v[6:9]
	v_mfma_f32_16x16x32_bf16 v[2:5], v[238:241], v[216:219], v[2:5]
	v_mfma_f32_16x16x32_bf16 v[54:57], v[234:237], v[180:183], v[54:57]
	v_mfma_f32_16x16x32_bf16 v[50:53], v[242:245], v[180:183], v[50:53]
	v_mfma_f32_16x16x32_bf16 v[38:41], v[234:237], v[204:207], v[38:41]
	v_mfma_f32_16x16x32_bf16 v[34:37], v[242:245], v[204:207], v[34:37]
	v_mfma_f32_16x16x32_bf16 v[22:25], v[234:237], v[212:215], v[22:25]
	v_mfma_f32_16x16x32_bf16 v[18:21], v[242:245], v[212:215], v[18:21]
	v_mfma_f32_16x16x32_bf16 v[6:9], v[234:237], v[226:229], v[6:9]
	v_mfma_f32_16x16x32_bf16 v[2:5], v[242:245], v[226:229], v[2:5]
	s_setprio 0
	s_add_i32 s93, s93, 2
	s_add_u32 s36, s36, 0x100
	s_addc_u32 s37, s37, 0
	s_add_u32 s91, s91, 0x100
	s_addc_u32 s92, s92, 0
	s_cmp_gt_u32 s93, 13
	s_barrier
	s_add_u32 s6, s36, 0xfffc0080
	s_addc_u32 s7, s37, -1
	s_add_i32 s58, 0, 0x10000
	v_add_u32_e32 v144, s58, v147
	ds_read_b128 v[140:143], v144
	ds_read_b128 v[152:155], v144 offset:1024
	ds_read_b128 v[168:171], v144 offset:2048
	ds_read_b128 v[172:175], v144 offset:3072
	s_cmp_eq_u32 s93, 12
	s_cselect_b32 s43, s11, s7
	s_cselect_b32 s42, s71, s6
	s_cselect_b32 s7, s9, s92
	s_cselect_b32 s6, s90, s91
	s_add_i32 m0, s49, 0xc000
	ds_read_b128 v[176:179], v150
	ds_read_b128 v[180:183], v150 offset:1024
	ds_read_b128 v[184:187], v150 offset:2048
	ds_read_b128 v[204:207], v150 offset:3072
	ds_read_b128 v[208:211], v150 offset:4096
	ds_read_b128 v[212:215], v150 offset:5120
	ds_read_b128 v[216:219], v150 offset:6144
	ds_read_b128 v[226:229], v150 offset:7168
	global_load_lds_dwordx4 v136, s[36:37]
	s_add_i32 m0, s49, 0xe000
	s_nop 0
	global_load_lds_dwordx4 v138, s[36:37]
	s_waitcnt lgkmcnt(8)
	s_barrier
	s_waitcnt lgkmcnt(0)
	s_setprio 1
	s_waitcnt lgkmcnt(0)
	v_mfma_f32_16x16x32_bf16 v[126:129], v[140:143], v[176:179], v[126:129]
	v_mfma_f32_16x16x32_bf16 v[122:125], v[168:171], v[176:179], v[122:125]
	v_mfma_f32_16x16x32_bf16 v[110:113], v[140:143], v[184:187], v[110:113]
	v_mfma_f32_16x16x32_bf16 v[106:109], v[168:171], v[184:187], v[106:109]
	v_mfma_f32_16x16x32_bf16 v[94:97], v[140:143], v[208:211], v[94:97]
	v_mfma_f32_16x16x32_bf16 v[90:93], v[168:171], v[208:211], v[90:93]
	v_mfma_f32_16x16x32_bf16 v[78:81], v[140:143], v[216:219], v[78:81]
	v_mfma_f32_16x16x32_bf16 v[74:77], v[168:171], v[216:219], v[74:77]
	v_mfma_f32_16x16x32_bf16 v[126:129], v[152:155], v[180:183], v[126:129]
	v_mfma_f32_16x16x32_bf16 v[122:125], v[172:175], v[180:183], v[122:125]
	v_mfma_f32_16x16x32_bf16 v[110:113], v[152:155], v[204:207], v[110:113]
	v_mfma_f32_16x16x32_bf16 v[106:109], v[172:175], v[204:207], v[106:109]
	v_mfma_f32_16x16x32_bf16 v[94:97], v[152:155], v[212:215], v[94:97]
	v_mfma_f32_16x16x32_bf16 v[90:93], v[172:175], v[212:215], v[90:93]
	v_mfma_f32_16x16x32_bf16 v[78:81], v[152:155], v[226:229], v[78:81]
	v_mfma_f32_16x16x32_bf16 v[74:77], v[172:175], v[226:229], v[74:77]
	s_setprio 0
	s_barrier
; __device__ __forceinline__ unsigned pk2(float lo, float hi) { unsigned r; asm("v_cvt_pk_bf16_f32 %0, %1, %2" : "=v"(r) : "v"(lo), "v"(hi)); return r; }
; #define PG8_STAGE(bufoff, gbase, voff) do { _Pragma("unroll") for (int _i = 0; _i < 2; ++_i) \
;         __builtin_amdgcn_global_load_lds((const unsigned*)((const char*)(gbase) + (voff)[_i]), (LAS unsigned*)(lds + (bufoff) + ldsw + _i * 8192), 16, 0, 0); } while (0)
; #define PG8_LDA(dst, b, h) do { _Pragma("unroll") for (int m = 0; m < 4; ++m) _Pragma("unroll") for (int k = 0; k < 2; ++k) dst[m][k] = *(const LAS bf16x8*)(lds + PG8_SA(b, h) + aoff + m * 2048 + k * 1024); } while (0)
;     __device__ __forceinline__ void operator()(const f32x4 (&acc)[2][2][4][2], const Unit& u, int ui, int wr, int wc, int fr, int fq) const {
;     ...
;                     u32x4 w; w.x = pk2(v0[0], v0[1]); w.y = pk2(v0[2], v0[3]); w.z = pk2(v1[0], v1[1]); w.w = pk2(v1[2], v1[3]);
;                     *(u32x4*)(rowp + bj * HALF) = w;
; template <class Epi>
; __device__ __forceinline__ void gemm_phase(LAS unsigned char* lds, const Gemm g, const StaticOrder& S, const Epi& E) {
;     ...
;             PG8_LDB(B0, 0, 0); PG8_SCHED; PG8_LDA(At, 0, 0); PG8_STAGE(PG8_SA(1, 1), a1 + hstep, voffA);
;             PG8_WAIT_L(8); PG8_BAR; PG8_WAIT_L(0); PG8_MMA(0, 0, At, B0); PG8_BAR; PG8_SCHED;
;             PG8_LDB(B1, 0, 1); PG8_STAGE(PG8_SB(0, 0), b2, voffB);
;             PG8_BAR; PG8_WAIT_L(0); PG8_MMA(0, 1, At, B1); PG8_BAR;
;             PG8_LDA(At, 0, 1); PG8_STAGE(PG8_SA(0, 0), a2, voffA);
;             PG8_BAR; PG8_WAIT_L(0); PG8_MMA(1, 0, At, B0); PG8_BAR; PG8_SCHED;
;             PG8_STAGE(PG8_SB(0, 1), b2 + hstep, voffB);
;             PG8_WAIT_V(6); PG8_BAR; PG8_MMA(1, 1, At, B1); PG8_BAR;
;             PG8_LDB(B0, 1, 0); PG8_SCHED; PG8_LDA(At, 1, 0); PG8_STAGE(PG8_SA(0, 1), a2 + hstep, voffA);
;             PG8_WAIT_L(8); PG8_BAR; PG8_WAIT_L(0); PG8_MMA(0, 0, At, B0); PG8_BAR; PG8_SCHED;
;             PG8_LDB(B1, 1, 1); PG8_STAGE(PG8_SB(1, 0), b3, voffB);
;             PG8_BAR; PG8_WAIT_L(0); PG8_MMA(0, 1, At, B1); PG8_BAR;
;             PG8_LDA(At, 1, 1); PG8_STAGE(PG8_SA(1, 0), a3, voffA);
;             PG8_BAR; PG8_WAIT_L(0); PG8_MMA(1, 0, At, B0); PG8_BAR; PG8_SCHED;
;             PG8_STAGE(PG8_SB(1, 1), b3 + hstep, voffB);
;             PG8_WAIT_V(6); PG8_BAR; PG8_MMA(1, 1, At, B1); PG8_BAR;
	s_add_i32 s70, 0, 0x14000
	v_add_u32_e32 v144, s70, v147
	s_add_i32 s58, s58, s48
	ds_read_b128 v[230:233], v144
	ds_read_b128 v[234:237], v144 offset:1024
	ds_read_b128 v[238:241], v144 offset:2048
	ds_read_b128 v[242:245], v144 offset:3072
	s_mov_b32 m0, s58
	s_nop 0
	global_load_lds_dwordx4 v0, s[6:7]
	s_add_i32 m0, s58, 0x2000
	s_nop 0
	global_load_lds_dwordx4 v130, s[6:7]
	s_barrier
	s_waitcnt lgkmcnt(0)
	s_setprio 1
	s_waitcnt lgkmcnt(0)
	v_mfma_f32_16x16x32_bf16 v[118:121], v[230:233], v[176:179], v[118:121]
	v_mfma_f32_16x16x32_bf16 v[114:117], v[238:241], v[176:179], v[114:117]
	v_mfma_f32_16x16x32_bf16 v[102:105], v[230:233], v[184:187], v[102:105]
	v_mfma_f32_16x16x32_bf16 v[98:101], v[238:241], v[184:187], v[98:101]
	v_mfma_f32_16x16x32_bf16 v[86:89], v[230:233], v[208:211], v[86:89]
	v_mfma_f32_16x16x32_bf16 v[82:85], v[238:241], v[208:211], v[82:85]
	v_mfma_f32_16x16x32_bf16 v[70:73], v[230:233], v[216:219], v[70:73]
	v_mfma_f32_16x16x32_bf16 v[66:69], v[238:241], v[216:219], v[66:69]
	v_mfma_f32_16x16x32_bf16 v[118:121], v[234:237], v[180:183], v[118:121]
	v_mfma_f32_16x16x32_bf16 v[114:117], v[242:245], v[180:183], v[114:117]
	v_mfma_f32_16x16x32_bf16 v[102:105], v[234:237], v[204:207], v[102:105]
	v_mfma_f32_16x16x32_bf16 v[98:101], v[242:245], v[204:207], v[98:101]
	v_mfma_f32_16x16x32_bf16 v[86:89], v[234:237], v[212:215], v[86:89]
	v_mfma_f32_16x16x32_bf16 v[82:85], v[242:245], v[212:215], v[82:85]
	v_mfma_f32_16x16x32_bf16 v[70:73], v[234:237], v[226:229], v[70:73]
	v_mfma_f32_16x16x32_bf16 v[66:69], v[242:245], v[226:229], v[66:69]
	s_setprio 0
	s_mov_b32 m0, s49
	s_add_u32 vcc_lo, s42, 0x80
	s_addc_u32 vcc_hi, s43, 0
	s_barrier
	ds_read_b128 v[176:179], v150 offset:16384
	ds_read_b128 v[180:183], v150 offset:17408
	ds_read_b128 v[184:187], v150 offset:18432
	ds_read_b128 v[204:207], v150 offset:19456
	ds_read_b128 v[208:211], v150 offset:20480
	ds_read_b128 v[212:215], v150 offset:21504
	ds_read_b128 v[216:219], v150 offset:22528
	ds_read_b128 v[226:229], v150 offset:23552
	global_load_lds_dwordx4 v134, s[42:43]
	s_mov_b32 m0, s54
	s_nop 0
	global_load_lds_dwordx4 v132, s[42:43]
	s_barrier
	s_waitcnt lgkmcnt(0)
	s_setprio 1
	s_waitcnt lgkmcnt(0)
	v_mfma_f32_16x16x32_bf16 v[62:65], v[140:143], v[176:179], v[62:65]
	v_mfma_f32_16x16x32_bf16 v[58:61], v[168:171], v[176:179], v[58:61]
	v_mfma_f32_16x16x32_bf16 v[46:49], v[140:143], v[184:187], v[46:49]
	v_mfma_f32_16x16x32_bf16 v[42:45], v[168:171], v[184:187], v[42:45]
	v_mfma_f32_16x16x32_bf16 v[30:33], v[140:143], v[208:211], v[30:33]
	v_mfma_f32_16x16x32_bf16 v[26:29], v[168:171], v[208:211], v[26:29]
	v_mfma_f32_16x16x32_bf16 v[14:17], v[140:143], v[216:219], v[14:17]
	v_mfma_f32_16x16x32_bf16 v[10:13], v[168:171], v[216:219], v[10:13]
	v_mfma_f32_16x16x32_bf16 v[62:65], v[152:155], v[180:183], v[62:65]
	v_mfma_f32_16x16x32_bf16 v[58:61], v[172:175], v[180:183], v[58:61]
	v_mfma_f32_16x16x32_bf16 v[46:49], v[152:155], v[204:207], v[46:49]
	v_mfma_f32_16x16x32_bf16 v[42:45], v[172:175], v[204:207], v[42:45]
	v_mfma_f32_16x16x32_bf16 v[30:33], v[152:155], v[212:215], v[30:33]
	v_mfma_f32_16x16x32_bf16 v[26:29], v[172:175], v[212:215], v[26:29]
	v_mfma_f32_16x16x32_bf16 v[14:17], v[152:155], v[226:229], v[14:17]
	v_mfma_f32_16x16x32_bf16 v[10:13], v[172:175], v[226:229], v[10:13]
	s_setprio 0
	s_barrier
	s_add_u32 s60, s6, 0x40000
	s_addc_u32 s61, s7, 0
	s_add_i32 s58, s70, s48
	s_mov_b32 m0, s58
	s_nop 0
	global_load_lds_dwordx4 v0, s[60:61]
	s_add_i32 m0, s58, 0x2000
	s_nop 0
	global_load_lds_dwordx4 v130, s[60:61]
	s_waitcnt vmcnt(6)
	s_barrier
	s_setprio 1
	v_mfma_f32_16x16x32_bf16 v[54:57], v[230:233], v[176:179], v[54:57]
	v_mfma_f32_16x16x32_bf16 v[50:53], v[238:241], v[176:179], v[50:53]
	s_cmp_eq_u32 s89, 0
	s_cbranch_scc1 .LdsE_skip_1
	global_store_dwordx4 v250, v[164:167], s[4:5] offset:256
	s_nop 1
	v_add_u32_e32 v250, 0x20000, v250

; #define PG8_STAGE(bufoff, gbase, voff) do { _Pragma("unroll") for (int _i = 0; _i < 2; ++_i) \
;         __builtin_amdgcn_global_load_lds((const unsigned*)((const char*)(gbase) + (voff)[_i]), (LAS unsigned*)(lds + (bufoff) + ldsw + _i * 8192), 16, 0, 0); } while (0)
; #define PG8_LDA(dst, b, h) do { _Pragma("unroll") for (int m = 0; m < 4; ++m) _Pragma("unroll") for (int k = 0; k < 2; ++k) dst[m][k] = *(const LAS bf16x8*)(lds + PG8_SA(b, h) + aoff + m * 2048 + k * 1024); } while (0)
; #define PG8_LDB(dst, b, h) do { _Pragma("unroll") for (int n = 0; n < 2; ++n) _Pragma("unroll") for (int k = 0; k < 2; ++k) dst[n][k] = *(const LAS bf16x8*)(lds + PG8_SB(b, h) + boff + n * 2048 + k * 1024); } while (0)
; #define PG8_WAIT_V(n) asm volatile("s_waitcnt vmcnt(" #n ")" ::: "memory")
; #define PG8_WAIT_L(n) asm volatile("s_waitcnt lgkmcnt(" #n ")" ::: "memory")
; #define PG8_BAR __builtin_amdgcn_s_barrier()
; #define PG8_SCHED __builtin_amdgcn_sched_barrier(0)
; template <class Epi>
; __device__ __forceinline__ void gemm_phase(LAS unsigned char* lds, const Gemm g, const StaticOrder& S, const Epi& E) {
;     ...
;             PG8_LDB(B0, 0, 0); PG8_SCHED; PG8_LDA(At, 0, 0); PG8_STAGE(PG8_SA(1, 1), a1 + hstep, voffA);
;             PG8_WAIT_L(8); PG8_BAR; PG8_WAIT_L(0); PG8_MMA(0, 0, At, B0); PG8_BAR; PG8_SCHED;
;             PG8_LDB(B1, 0, 1); PG8_STAGE(PG8_SB(0, 0), b2, voffB);
;             PG8_BAR; PG8_WAIT_L(0); PG8_MMA(0, 1, At, B1); PG8_BAR;
;             PG8_LDA(At, 0, 1); PG8_STAGE(PG8_SA(0, 0), a2, voffA);
;             PG8_BAR; PG8_WAIT_L(0); PG8_MMA(1, 0, At, B0); PG8_BAR; PG8_SCHED;
;             PG8_STAGE(PG8_SB(0, 1), b2 + hstep, voffB);
;             PG8_WAIT_V(6); PG8_BAR; PG8_MMA(1, 1, At, B1); PG8_BAR;
;             PG8_LDB(B0, 1, 0); PG8_SCHED; PG8_LDA(At, 1, 0); PG8_STAGE(PG8_SA(0, 1), a2 + hstep, voffA);
;             PG8_WAIT_L(8); PG8_BAR; PG8_WAIT_L(0); PG8_MMA(0, 0, At, B0); PG8_BAR; PG8_SCHED;
;             PG8_LDB(B1, 1, 1); PG8_STAGE(PG8_SB(1, 0), b3, voffB);
;             PG8_BAR; PG8_WAIT_L(0); PG8_MMA(0, 1, At, B1); PG8_BAR;
;             PG8_LDA(At, 1, 1); PG8_STAGE(PG8_SA(1, 0), a3, voffA);
;             PG8_BAR; PG8_WAIT_L(0); PG8_MMA(1, 0, At, B0); PG8_BAR; PG8_SCHED;
;             PG8_STAGE(PG8_SB(1, 1), b3 + hstep, voffB);
;             PG8_WAIT_V(6); PG8_BAR; PG8_MMA(1, 1, At, B1); PG8_BAR;
.LdsE_skip_2:
	v_mfma_f32_16x16x32_bf16 v[38:41], v[230:233], v[184:187], v[38:41]
	v_mfma_f32_16x16x32_bf16 v[34:37], v[238:241], v[184:187], v[34:37]
	v_mfma_f32_16x16x32_bf16 v[22:25], v[230:233], v[208:211], v[22:25]
	v_mfma_f32_16x16x32_bf16 v[18:21], v[238:241], v[208:211], v[18:21]
	v_mfma_f32_16x16x32_bf16 v[6:9], v[230:233], v[216:219], v[6:9]
	v_mfma_f32_16x16x32_bf16 v[2:5], v[238:241], v[216:219], v[2:5]
	v_mfma_f32_16x16x32_bf16 v[54:57], v[234:237], v[180:183], v[54:57]
	v_mfma_f32_16x16x32_bf16 v[50:53], v[242:245], v[180:183], v[50:53]
	v_mfma_f32_16x16x32_bf16 v[38:41], v[234:237], v[204:207], v[38:41]
	v_mfma_f32_16x16x32_bf16 v[34:37], v[242:245], v[204:207], v[34:37]
	v_mfma_f32_16x16x32_bf16 v[22:25], v[234:237], v[212:215], v[22:25]
	v_mfma_f32_16x16x32_bf16 v[18:21], v[242:245], v[212:215], v[18:21]
	v_mfma_f32_16x16x32_bf16 v[6:9], v[234:237], v[226:229], v[6:9]
	v_mfma_f32_16x16x32_bf16 v[2:5], v[242:245], v[226:229], v[2:5]
	s_setprio 0
	s_add_i32 s58, 0, 0x18000
	v_add_u32_e32 v151, s58, v147
	s_barrier
	ds_read_b128 v[140:143], v151
	ds_read_b128 v[152:155], v151 offset:1024
	ds_read_b128 v[168:171], v151 offset:2048
	ds_read_b128 v[172:175], v151 offset:3072
	s_add_u32 s42, s42, 0x40000
	s_addc_u32 s43, s43, 0
	s_mov_b32 m0, s55
	ds_read_b128 v[176:179], v150 offset:32768
	ds_read_b128 v[180:183], v150 offset:33792
	ds_read_b128 v[184:187], v150 offset:34816
	ds_read_b128 v[204:207], v150 offset:35840
	ds_read_b128 v[208:211], v150 offset:36864
	ds_read_b128 v[212:215], v150 offset:37888
	ds_read_b128 v[216:219], v150 offset:38912
	ds_read_b128 v[226:229], v150 offset:39936
	global_load_lds_dwordx4 v134, s[42:43]
	s_mov_b32 m0, s83
	s_nop 0
	global_load_lds_dwordx4 v132, s[42:43]
	s_waitcnt lgkmcnt(8)
	s_barrier
	s_waitcnt lgkmcnt(0)
	s_setprio 1
	s_waitcnt lgkmcnt(0)
	v_mfma_f32_16x16x32_bf16 v[126:129], v[140:143], v[176:179], v[126:129]
	v_mfma_f32_16x16x32_bf16 v[122:125], v[168:171], v[176:179], v[122:125]
	v_mfma_f32_16x16x32_bf16 v[110:113], v[140:143], v[184:187], v[110:113]
	v_mfma_f32_16x16x32_bf16 v[106:109], v[168:171], v[184:187], v[106:109]
	v_mfma_f32_16x16x32_bf16 v[94:97], v[140:143], v[208:211], v[94:97]
	v_mfma_f32_16x16x32_bf16 v[90:93], v[168:171], v[208:211], v[90:93]
	v_mfma_f32_16x16x32_bf16 v[78:81], v[140:143], v[216:219], v[78:81]
	v_mfma_f32_16x16x32_bf16 v[74:77], v[168:171], v[216:219], v[74:77]
	v_mfma_f32_16x16x32_bf16 v[126:129], v[152:155], v[180:183], v[126:129]
	v_mfma_f32_16x16x32_bf16 v[122:125], v[172:175], v[180:183], v[122:125]
	v_mfma_f32_16x16x32_bf16 v[110:113], v[152:155], v[204:207], v[110:113]
	v_mfma_f32_16x16x32_bf16 v[106:109], v[172:175], v[204:207], v[106:109]
	v_mfma_f32_16x16x32_bf16 v[94:97], v[152:155], v[212:215], v[94:97]
	v_mfma_f32_16x16x32_bf16 v[90:93], v[172:175], v[212:215], v[90:93]
	v_mfma_f32_16x16x32_bf16 v[78:81], v[152:155], v[226:229], v[78:81]
	v_mfma_f32_16x16x32_bf16 v[74:77], v[172:175], v[226:229], v[74:77]
	s_setprio 0
	s_barrier
	s_add_i32 s42, 0, 0x1c000
	s_add_i32 s43, s58, s48
	v_add_u32_e32 v151, s42, v147
	s_add_u32 s60, s6, 0x80
	s_addc_u32 s61, s7, 0
	s_mov_b32 m0, s43
	ds_read_b128 v[230:233], v151
	ds_read_b128 v[234:237], v151 offset:1024
	ds_read_b128 v[238:241], v151 offset:2048
	ds_read_b128 v[242:245], v151 offset:3072
	global_load_lds_dwordx4 v0, s[60:61]
	s_add_i32 m0, s43, 0x2000
	s_nop 0
	global_load_lds_dwordx4 v130, s[60:61]
	s_barrier
	s_waitcnt lgkmcnt(0)
	s_setprio 1
	s_waitcnt lgkmcnt(0)
	v_mfma_f32_16x16x32_bf16 v[118:121], v[230:233], v[176:179], v[118:121]
	v_mfma_f32_16x16x32_bf16 v[114:117], v[238:241], v[176:179], v[114:117]
	v_mfma_f32_16x16x32_bf16 v[102:105], v[230:233], v[184:187], v[102:105]
	v_mfma_f32_16x16x32_bf16 v[98:101], v[238:241], v[184:187], v[98:101]
	v_mfma_f32_16x16x32_bf16 v[86:89], v[230:233], v[208:211], v[86:89]
	v_mfma_f32_16x16x32_bf16 v[82:85], v[238:241], v[208:211], v[82:85]
	v_mfma_f32_16x16x32_bf16 v[70:73], v[230:233], v[216:219], v[70:73]
	v_mfma_f32_16x16x32_bf16 v[66:69], v[238:241], v[216:219], v[66:69]
	v_mfma_f32_16x16x32_bf16 v[118:121], v[234:237], v[180:183], v[118:121]
	v_mfma_f32_16x16x32_bf16 v[114:117], v[242:245], v[180:183], v[114:117]
	v_mfma_f32_16x16x32_bf16 v[102:105], v[234:237], v[204:207], v[102:105]
	v_mfma_f32_16x16x32_bf16 v[98:101], v[242:245], v[204:207], v[98:101]
	v_mfma_f32_16x16x32_bf16 v[86:89], v[234:237], v[212:215], v[86:89]
	v_mfma_f32_16x16x32_bf16 v[82:85], v[242:245], v[212:215], v[82:85]
	v_mfma_f32_16x16x32_bf16 v[70:73], v[234:237], v[226:229], v[70:73]
	v_mfma_f32_16x16x32_bf16 v[66:69], v[242:245], v[226:229], v[66:69]
	s_setprio 0
	s_mov_b32 m0, s84
	s_barrier
	ds_read_b128 v[176:179], v150 offset:49152
	ds_read_b128 v[180:183], v150 offset:50176
	ds_read_b128 v[184:187], v150 offset:51200
	ds_read_b128 v[204:207], v150 offset:52224
	ds_read_b128 v[208:211], v150 offset:53248
	ds_read_b128 v[212:215], v150 offset:54272
	ds_read_b128 v[216:219], v150 offset:55296
	ds_read_b128 v[226:229], v150 offset:56320
	global_load_lds_dwordx4 v134, vcc
	s_mov_b32 m0, s85
	s_nop 0
	global_load_lds_dwordx4 v132, vcc
	s_barrier
; #define PG8_STAGE(bufoff, gbase, voff) do { _Pragma("unroll") for (int _i = 0; _i < 2; ++_i) \
;         __builtin_amdgcn_global_load_lds((const unsigned*)((const char*)(gbase) + (voff)[_i]), (LAS unsigned*)(lds + (bufoff) + ldsw + _i * 8192), 16, 0, 0); } while (0)
; #define PG8_LDA(dst, b, h) do { _Pragma("unroll") for (int m = 0; m < 4; ++m) _Pragma("unroll") for (int k = 0; k < 2; ++k) dst[m][k] = *(const LAS bf16x8*)(lds + PG8_SA(b, h) + aoff + m * 2048 + k * 1024); } while (0)
; #define PG8_LDB(dst, b, h) do { _Pragma("unroll") for (int n = 0; n < 2; ++n) _Pragma("unroll") for (int k = 0; k < 2; ++k) dst[n][k] = *(const LAS bf16x8*)(lds + PG8_SB(b, h) + boff + n * 2048 + k * 1024); } while (0)
; #define PG8_WAIT_V(n) asm volatile("s_waitcnt vmcnt(" #n ")" ::: "memory")
; #define PG8_WAIT_L(n) asm volatile("s_waitcnt lgkmcnt(" #n ")" ::: "memory")
; #define PG8_BAR __builtin_amdgcn_s_barrier()
; #define PG8_SCHED __builtin_amdgcn_sched_barrier(0)
; template <class Epi>
; __device__ __forceinline__ void gemm_phase(LAS unsigned char* lds, const Gemm g, const StaticOrder& S, const Epi& E) {
;     ...
;             PG8_LDB(B0, 0, 0); PG8_SCHED; PG8_LDA(At, 0, 0); PG8_STAGE(PG8_SA(1, 1), a1 + hstep, voffA);
;             PG8_WAIT_L(8); PG8_BAR; PG8_WAIT_L(0); PG8_MMA(0, 0, At, B0); PG8_BAR; PG8_SCHED;
;             PG8_LDB(B1, 0, 1); PG8_STAGE(PG8_SB(0, 0), b2, voffB);
;             PG8_BAR; PG8_WAIT_L(0); PG8_MMA(0, 1, At, B1); PG8_BAR;
;             PG8_LDA(At, 0, 1); PG8_STAGE(PG8_SA(0, 0), a2, voffA);
;             PG8_BAR; PG8_WAIT_L(0); PG8_MMA(1, 0, At, B0); PG8_BAR; PG8_SCHED;
;             PG8_STAGE(PG8_SB(0, 1), b2 + hstep, voffB);
;             PG8_WAIT_V(6); PG8_BAR; PG8_MMA(1, 1, At, B1); PG8_BAR;
;             PG8_LDB(B0, 1, 0); PG8_SCHED; PG8_LDA(At, 1, 0); PG8_STAGE(PG8_SA(0, 1), a2 + hstep, voffA);
;             PG8_WAIT_L(8); PG8_BAR; PG8_WAIT_L(0); PG8_MMA(0, 0, At, B0); PG8_BAR; PG8_SCHED;
;             PG8_LDB(B1, 1, 1); PG8_STAGE(PG8_SB(1, 0), b3, voffB);
;             PG8_BAR; PG8_WAIT_L(0); PG8_MMA(0, 1, At, B1); PG8_BAR;
;             PG8_LDA(At, 1, 1); PG8_STAGE(PG8_SA(1, 0), a3, voffA);
;             PG8_BAR; PG8_WAIT_L(0); PG8_MMA(1, 0, At, B0); PG8_BAR; PG8_SCHED;
;             PG8_STAGE(PG8_SB(1, 1), b3 + hstep, voffB);
;             PG8_WAIT_V(6); PG8_BAR; PG8_MMA(1, 1, At, B1); PG8_BAR;
	s_waitcnt lgkmcnt(0)
	s_setprio 1
	s_waitcnt lgkmcnt(0)
	v_mfma_f32_16x16x32_bf16 v[62:65], v[140:143], v[176:179], v[62:65]
	v_mfma_f32_16x16x32_bf16 v[58:61], v[168:171], v[176:179], v[58:61]
	v_mfma_f32_16x16x32_bf16 v[46:49], v[140:143], v[184:187], v[46:49]
	v_mfma_f32_16x16x32_bf16 v[42:45], v[168:171], v[184:187], v[42:45]
	v_mfma_f32_16x16x32_bf16 v[30:33], v[140:143], v[208:211], v[30:33]
	v_mfma_f32_16x16x32_bf16 v[26:29], v[168:171], v[208:211], v[26:29]
	v_mfma_f32_16x16x32_bf16 v[14:17], v[140:143], v[216:219], v[14:17]
	v_mfma_f32_16x16x32_bf16 v[10:13], v[168:171], v[216:219], v[10:13]
	v_mfma_f32_16x16x32_bf16 v[62:65], v[152:155], v[180:183], v[62:65]
	v_mfma_f32_16x16x32_bf16 v[58:61], v[172:175], v[180:183], v[58:61]
	v_mfma_f32_16x16x32_bf16 v[46:49], v[152:155], v[204:207], v[46:49]
	v_mfma_f32_16x16x32_bf16 v[42:45], v[172:175], v[204:207], v[42:45]
	v_mfma_f32_16x16x32_bf16 v[30:33], v[152:155], v[212:215], v[30:33]
	v_mfma_f32_16x16x32_bf16 v[26:29], v[172:175], v[212:215], v[26:29]
	v_mfma_f32_16x16x32_bf16 v[14:17], v[152:155], v[226:229], v[14:17]
	v_mfma_f32_16x16x32_bf16 v[10:13], v[172:175], v[226:229], v[10:13]
	s_setprio 0
	s_barrier
	s_add_u32 s6, s6, 0x40080
	s_addc_u32 s7, s7, 0
	s_add_i32 s42, s42, s48
	s_mov_b32 m0, s42
	s_nop 0
	global_load_lds_dwordx4 v0, s[6:7]
	s_add_i32 m0, s42, 0x2000
	s_nop 0
	global_load_lds_dwordx4 v130, s[6:7]
	s_waitcnt vmcnt(6)
	s_barrier
	s_setprio 1
	v_mfma_f32_16x16x32_bf16 v[54:57], v[230:233], v[176:179], v[54:57]
	v_mfma_f32_16x16x32_bf16 v[50:53], v[238:241], v[176:179], v[50:53]
	v_mfma_f32_16x16x32_bf16 v[38:41], v[230:233], v[184:187], v[38:41]
	v_mfma_f32_16x16x32_bf16 v[34:37], v[238:241], v[184:187], v[34:37]
	v_mfma_f32_16x16x32_bf16 v[22:25], v[230:233], v[208:211], v[22:25]
	v_mfma_f32_16x16x32_bf16 v[18:21], v[238:241], v[208:211], v[18:21]
	v_mfma_f32_16x16x32_bf16 v[6:9], v[230:233], v[216:219], v[6:9]
	v_mfma_f32_16x16x32_bf16 v[2:5], v[238:241], v[216:219], v[2:5]
	v_mfma_f32_16x16x32_bf16 v[54:57], v[234:237], v[180:183], v[54:57]
	v_mfma_f32_16x16x32_bf16 v[50:53], v[242:245], v[180:183], v[50:53]
	v_mfma_f32_16x16x32_bf16 v[38:41], v[234:237], v[204:207], v[38:41]
	v_mfma_f32_16x16x32_bf16 v[34:37], v[242:245], v[204:207], v[34:37]
	v_mfma_f32_16x16x32_bf16 v[22:25], v[234:237], v[212:215], v[22:25]
	v_mfma_f32_16x16x32_bf16 v[18:21], v[242:245], v[212:215], v[18:21]
	v_mfma_f32_16x16x32_bf16 v[6:9], v[234:237], v[226:229], v[6:9]
	v_mfma_f32_16x16x32_bf16 v[2:5], v[242:245], v[226:229], v[2:5]
	s_setprio 0
	s_add_i32 s93, s93, 2
	s_add_u32 s36, s36, 0x100
	s_addc_u32 s37, s37, 0
	s_add_u32 s91, s91, 0x100
	s_addc_u32 s92, s92, 0
	s_cmp_gt_u32 s93, 13
	s_barrier
	s_add_u32 s6, s36, 0xfffc0080
	s_addc_u32 s7, s37, -1
	s_add_i32 s58, 0, 0x10000
	v_add_u32_e32 v144, s58, v147
	ds_read_b128 v[140:143], v144
	ds_read_b128 v[152:155], v144 offset:1024
	ds_read_b128 v[168:171], v144 offset:2048
	ds_read_b128 v[172:175], v144 offset:3072
	s_cmp_eq_u32 s93, 12
	s_cselect_b32 s43, s11, s7
	s_cselect_b32 s42, s71, s6
	s_cselect_b32 s7, s9, s92
	s_cselect_b32 s6, s90, s91
	s_add_i32 m0, s49, 0xc000
	ds_read_b128 v[176:179], v150
	ds_read_b128 v[180:183], v150 offset:1024
	ds_read_b128 v[184:187], v150 offset:2048
	ds_read_b128 v[204:207], v150 offset:3072
	ds_read_b128 v[208:211], v150 offset:4096
	ds_read_b128 v[212:215], v150 offset:5120
	ds_read_b128 v[216:219], v150 offset:6144
	ds_read_b128 v[226:229], v150 offset:7168
	global_load_lds_dwordx4 v136, s[36:37]
	s_add_i32 m0, s49, 0xe000
	s_nop 0
	global_load_lds_dwordx4 v138, s[36:37]
	s_waitcnt lgkmcnt(8)
	s_barrier
	s_waitcnt lgkmcnt(0)
	s_setprio 1
	s_waitcnt lgkmcnt(0)
	v_mfma_f32_16x16x32_bf16 v[126:129], v[140:143], v[176:179], v[126:129]
	v_mfma_f32_16x16x32_bf16 v[122:125], v[168:171], v[176:179], v[122:125]
	v_mfma_f32_16x16x32_bf16 v[110:113], v[140:143], v[184:187], v[110:113]
	v_mfma_f32_16x16x32_bf16 v[106:109], v[168:171], v[184:187], v[106:109]
	v_mfma_f32_16x16x32_bf16 v[94:97], v[140:143], v[208:211], v[94:97]
	v_mfma_f32_16x16x32_bf16 v[90:93], v[168:171], v[208:211], v[90:93]
	v_mfma_f32_16x16x32_bf16 v[78:81], v[140:143], v[216:219], v[78:81]
	v_mfma_f32_16x16x32_bf16 v[74:77], v[168:171], v[216:219], v[74:77]
	v_mfma_f32_16x16x32_bf16 v[126:129], v[152:155], v[180:183], v[126:129]
	v_mfma_f32_16x16x32_bf16 v[122:125], v[172:175], v[180:183], v[122:125]
	v_mfma_f32_16x16x32_bf16 v[110:113], v[152:155], v[204:207], v[110:113]
	v_mfma_f32_16x16x32_bf16 v[106:109], v[172:175], v[204:207], v[106:109]
	v_mfma_f32_16x16x32_bf16 v[94:97], v[152:155], v[212:215], v[94:97]
	v_mfma_f32_16x16x32_bf16 v[90:93], v[172:175], v[212:215], v[90:93]
	v_mfma_f32_16x16x32_bf16 v[78:81], v[152:155], v[226:229], v[78:81]
	v_mfma_f32_16x16x32_bf16 v[74:77], v[172:175], v[226:229], v[74:77]
	s_setprio 0
	s_barrier
; __device__ __forceinline__ unsigned pk2(float lo, float hi) { unsigned r; asm("v_cvt_pk_bf16_f32 %0, %1, %2" : "=v"(r) : "v"(lo), "v"(hi)); return r; }
; #define PG8_STAGE(bufoff, gbase, voff) do { _Pragma("unroll") for (int _i = 0; _i < 2; ++_i) \
;         __builtin_amdgcn_global_load_lds((const unsigned*)((const char*)(gbase) + (voff)[_i]), (LAS unsigned*)(lds + (bufoff) + ldsw + _i * 8192), 16, 0, 0); } while (0)
; #define PG8_LDA(dst, b, h) do { _Pragma("unroll") for (int m = 0; m < 4; ++m) _Pragma("unroll") for (int k = 0; k < 2; ++k) dst[m][k] = *(const LAS bf16x8*)(lds + PG8_SA(b, h) + aoff + m * 2048 + k * 1024); } while (0)
;     __device__ __forceinline__ void operator()(const f32x4 (&acc)[2][2][4][2], const Unit& u, int ui, int wr, int wc, int fr, int fq) const {
;     ...
;                     u32x4 w; w.x = pk2(v0[0], v0[1]); w.y = pk2(v0[2], v0[3]); w.z = pk2(v1[0], v1[1]); w.w = pk2(v1[2], v1[3]);
;                     *(u32x4*)(rowp + bj * HALF) = w;
; template <class Epi>
; __device__ __forceinline__ void gemm_phase(LAS unsigned char* lds, const Gemm g, const StaticOrder& S, const Epi& E) {
;     ...
;             PG8_LDB(B0, 0, 0); PG8_SCHED; PG8_LDA(At, 0, 0); PG8_STAGE(PG8_SA(1, 1), a1 + hstep, voffA);
;             PG8_WAIT_L(8); PG8_BAR; PG8_WAIT_L(0); PG8_MMA(0, 0, At, B0); PG8_BAR; PG8_SCHED;
;             PG8_LDB(B1, 0, 1); PG8_STAGE(PG8_SB(0, 0), b2, voffB);
;             PG8_BAR; PG8_WAIT_L(0); PG8_MMA(0, 1, At, B1); PG8_BAR;
;             PG8_LDA(At, 0, 1); PG8_STAGE(PG8_SA(0, 0), a2, voffA);
;             PG8_BAR; PG8_WAIT_L(0); PG8_MMA(1, 0, At, B0); PG8_BAR; PG8_SCHED;
;             PG8_STAGE(PG8_SB(0, 1), b2 + hstep, voffB);
;             PG8_WAIT_V(6); PG8_BAR; PG8_MMA(1, 1, At, B1); PG8_BAR;
;             PG8_LDB(B0, 1, 0); PG8_SCHED; PG8_LDA(At, 1, 0); PG8_STAGE(PG8_SA(0, 1), a2 + hstep, voffA);
;             PG8_WAIT_L(8); PG8_BAR; PG8_WAIT_L(0); PG8_MMA(0, 0, At, B0); PG8_BAR; PG8_SCHED;
;             PG8_LDB(B1, 1, 1); PG8_STAGE(PG8_SB(1, 0), b3, voffB);
;             PG8_BAR; PG8_WAIT_L(0); PG8_MMA(0, 1, At, B1); PG8_BAR;
;             PG8_LDA(At, 1, 1); PG8_STAGE(PG8_SA(1, 0), a3, voffA);
;             PG8_BAR; PG8_WAIT_L(0); PG8_MMA(1, 0, At, B0); PG8_BAR; PG8_SCHED;
;             PG8_STAGE(PG8_SB(1, 1), b3 + hstep, voffB);
;             PG8_WAIT_V(6); PG8_BAR; PG8_MMA(1, 1, At, B1); PG8_BAR;
	s_add_i32 s70, 0, 0x14000
	v_add_u32_e32 v144, s70, v147
	s_add_i32 s58, s58, s48
	ds_read_b128 v[230:233], v144
	ds_read_b128 v[234:237], v144 offset:1024
	ds_read_b128 v[238:241], v144 offset:2048
	ds_read_b128 v[242:245], v144 offset:3072
	s_mov_b32 m0, s58
	s_nop 0
	global_load_lds_dwordx4 v0, s[6:7]
	s_add_i32 m0, s58, 0x2000
	s_nop 0
	global_load_lds_dwordx4 v130, s[6:7]
	s_barrier
	s_waitcnt lgkmcnt(0)
	s_setprio 1
	s_waitcnt lgkmcnt(0)
	v_mfma_f32_16x16x32_bf16 v[118:121], v[230:233], v[176:179], v[118:121]
	v_mfma_f32_16x16x32_bf16 v[114:117], v[238:241], v[176:179], v[114:117]
	v_mfma_f32_16x16x32_bf16 v[102:105], v[230:233], v[184:187], v[102:105]
	v_mfma_f32_16x16x32_bf16 v[98:101], v[238:241], v[184:187], v[98:101]
	v_mfma_f32_16x16x32_bf16 v[86:89], v[230:233], v[208:211], v[86:89]
	v_mfma_f32_16x16x32_bf16 v[82:85], v[238:241], v[208:211], v[82:85]
	v_mfma_f32_16x16x32_bf16 v[70:73], v[230:233], v[216:219], v[70:73]
	v_mfma_f32_16x16x32_bf16 v[66:69], v[238:241], v[216:219], v[66:69]
	v_mfma_f32_16x16x32_bf16 v[118:121], v[234:237], v[180:183], v[118:121]
	v_mfma_f32_16x16x32_bf16 v[114:117], v[242:245], v[180:183], v[114:117]
	v_mfma_f32_16x16x32_bf16 v[102:105], v[234:237], v[204:207], v[102:105]
	v_mfma_f32_16x16x32_bf16 v[98:101], v[242:245], v[204:207], v[98:101]
	v_mfma_f32_16x16x32_bf16 v[86:89], v[234:237], v[212:215], v[86:89]
	v_mfma_f32_16x16x32_bf16 v[82:85], v[242:245], v[212:215], v[82:85]
	v_mfma_f32_16x16x32_bf16 v[70:73], v[234:237], v[226:229], v[70:73]
	v_mfma_f32_16x16x32_bf16 v[66:69], v[242:245], v[226:229], v[66:69]
	s_setprio 0
	s_mov_b32 m0, s49
	s_add_u32 vcc_lo, s42, 0x80
	s_addc_u32 vcc_hi, s43, 0
	s_barrier
	ds_read_b128 v[176:179], v150 offset:16384
	ds_read_b128 v[180:183], v150 offset:17408
	ds_read_b128 v[184:187], v150 offset:18432
	ds_read_b128 v[204:207], v150 offset:19456
	ds_read_b128 v[208:211], v150 offset:20480
	ds_read_b128 v[212:215], v150 offset:21504
	ds_read_b128 v[216:219], v150 offset:22528
	ds_read_b128 v[226:229], v150 offset:23552
	global_load_lds_dwordx4 v134, s[42:43]
	s_mov_b32 m0, s54
	s_nop 0
	global_load_lds_dwordx4 v132, s[42:43]
	s_barrier
	s_waitcnt lgkmcnt(0)
	s_setprio 1
	s_waitcnt lgkmcnt(0)
	v_mfma_f32_16x16x32_bf16 v[62:65], v[140:143], v[176:179], v[62:65]
	v_mfma_f32_16x16x32_bf16 v[58:61], v[168:171], v[176:179], v[58:61]
	v_mfma_f32_16x16x32_bf16 v[46:49], v[140:143], v[184:187], v[46:49]
	v_mfma_f32_16x16x32_bf16 v[42:45], v[168:171], v[184:187], v[42:45]
	v_mfma_f32_16x16x32_bf16 v[30:33], v[140:143], v[208:211], v[30:33]
	v_mfma_f32_16x16x32_bf16 v[26:29], v[168:171], v[208:211], v[26:29]
	v_mfma_f32_16x16x32_bf16 v[14:17], v[140:143], v[216:219], v[14:17]
	v_mfma_f32_16x16x32_bf16 v[10:13], v[168:171], v[216:219], v[10:13]
	v_mfma_f32_16x16x32_bf16 v[62:65], v[152:155], v[180:183], v[62:65]
	v_mfma_f32_16x16x32_bf16 v[58:61], v[172:175], v[180:183], v[58:61]
	v_mfma_f32_16x16x32_bf16 v[46:49], v[152:155], v[204:207], v[46:49]
	v_mfma_f32_16x16x32_bf16 v[42:45], v[172:175], v[204:207], v[42:45]
	v_mfma_f32_16x16x32_bf16 v[30:33], v[152:155], v[212:215], v[30:33]
	v_mfma_f32_16x16x32_bf16 v[26:29], v[172:175], v[212:215], v[26:29]
	v_mfma_f32_16x16x32_bf16 v[14:17], v[152:155], v[226:229], v[14:17]
	v_mfma_f32_16x16x32_bf16 v[10:13], v[172:175], v[226:229], v[10:13]
	s_setprio 0
	s_barrier
	s_add_u32 s60, s6, 0x40000
	s_addc_u32 s61, s7, 0
	s_add_i32 s58, s70, s48
	s_mov_b32 m0, s58
	s_nop 0
	global_load_lds_dwordx4 v0, s[60:61]
	s_add_i32 m0, s58, 0x2000
	s_nop 0
	global_load_lds_dwordx4 v130, s[60:61]
	s_waitcnt vmcnt(6)
	s_barrier
	s_setprio 1
	v_mfma_f32_16x16x32_bf16 v[54:57], v[230:233], v[176:179], v[54:57]
	v_mfma_f32_16x16x32_bf16 v[50:53], v[238:241], v[176:179], v[50:53]
	s_cmp_eq_u32 s89, 0
	s_cbranch_scc1 .LdsE_skip_3
	global_store_dwordx4 v250, v[192:195], s[4:5] offset:256
	s_nop 1
	v_add_u32_e32 v250, 0x20000, v250

; #define PG8_STAGE(bufoff, gbase, voff) do { _Pragma("unroll") for (int _i = 0; _i < 2; ++_i) \
;         __builtin_amdgcn_global_load_lds((const unsigned*)((const char*)(gbase) + (voff)[_i]), (LAS unsigned*)(lds + (bufoff) + ldsw + _i * 8192), 16, 0, 0); } while (0)
; #define PG8_LDA(dst, b, h) do { _Pragma("unroll") for (int m = 0; m < 4; ++m) _Pragma("unroll") for (int k = 0; k < 2; ++k) dst[m][k] = *(const LAS bf16x8*)(lds + PG8_SA(b, h) + aoff + m * 2048 + k * 1024); } while (0)
; #define PG8_LDB(dst, b, h) do { _Pragma("unroll") for (int n = 0; n < 2; ++n) _Pragma("unroll") for (int k = 0; k < 2; ++k) dst[n][k] = *(const LAS bf16x8*)(lds + PG8_SB(b, h) + boff + n * 2048 + k * 1024); } while (0)
; #define PG8_WAIT_V(n) asm volatile("s_waitcnt vmcnt(" #n ")" ::: "memory")
; #define PG8_WAIT_L(n) asm volatile("s_waitcnt lgkmcnt(" #n ")" ::: "memory")
; #define PG8_BAR __builtin_amdgcn_s_barrier()
; #define PG8_SCHED __builtin_amdgcn_sched_barrier(0)
; template <class Epi>
; __device__ __forceinline__ void gemm_phase(LAS unsigned char* lds, const Gemm g, const StaticOrder& S, const Epi& E) {
;     ...
;             PG8_LDB(B0, 0, 0); PG8_SCHED; PG8_LDA(At, 0, 0); PG8_STAGE(PG8_SA(1, 1), a1 + hstep, voffA);
;             PG8_WAIT_L(8); PG8_BAR; PG8_WAIT_L(0); PG8_MMA(0, 0, At, B0); PG8_BAR; PG8_SCHED;
;             PG8_LDB(B1, 0, 1); PG8_STAGE(PG8_SB(0, 0), b2, voffB);
;             PG8_BAR; PG8_WAIT_L(0); PG8_MMA(0, 1, At, B1); PG8_BAR;
;             PG8_LDA(At, 0, 1); PG8_STAGE(PG8_SA(0, 0), a2, voffA);
;             PG8_BAR; PG8_WAIT_L(0); PG8_MMA(1, 0, At, B0); PG8_BAR; PG8_SCHED;
;             PG8_STAGE(PG8_SB(0, 1), b2 + hstep, voffB);
;             PG8_WAIT_V(6); PG8_BAR; PG8_MMA(1, 1, At, B1); PG8_BAR;
;             PG8_LDB(B0, 1, 0); PG8_SCHED; PG8_LDA(At, 1, 0); PG8_STAGE(PG8_SA(0, 1), a2 + hstep, voffA);
;             PG8_WAIT_L(8); PG8_BAR; PG8_WAIT_L(0); PG8_MMA(0, 0, At, B0); PG8_BAR; PG8_SCHED;
;             PG8_LDB(B1, 1, 1); PG8_STAGE(PG8_SB(1, 0), b3, voffB);
;             PG8_BAR; PG8_WAIT_L(0); PG8_MMA(0, 1, At, B1); PG8_BAR;
;             PG8_LDA(At, 1, 1); PG8_STAGE(PG8_SA(1, 0), a3, voffA);
;             PG8_BAR; PG8_WAIT_L(0); PG8_MMA(1, 0, At, B0); PG8_BAR; PG8_SCHED;
;             PG8_STAGE(PG8_SB(1, 1), b3 + hstep, voffB);
;             PG8_WAIT_V(6); PG8_BAR; PG8_MMA(1, 1, At, B1); PG8_BAR;
.LdsE_skip_4:
	v_mfma_f32_16x16x32_bf16 v[38:41], v[230:233], v[184:187], v[38:41]
	v_mfma_f32_16x16x32_bf16 v[34:37], v[238:241], v[184:187], v[34:37]
	v_mfma_f32_16x16x32_bf16 v[22:25], v[230:233], v[208:211], v[22:25]
	v_mfma_f32_16x16x32_bf16 v[18:21], v[238:241], v[208:211], v[18:21]
	v_mfma_f32_16x16x32_bf16 v[6:9], v[230:233], v[216:219], v[6:9]
	v_mfma_f32_16x16x32_bf16 v[2:5], v[238:241], v[216:219], v[2:5]
	v_mfma_f32_16x16x32_bf16 v[54:57], v[234:237], v[180:183], v[54:57]
	v_mfma_f32_16x16x32_bf16 v[50:53], v[242:245], v[180:183], v[50:53]
	v_mfma_f32_16x16x32_bf16 v[38:41], v[234:237], v[204:207], v[38:41]
	v_mfma_f32_16x16x32_bf16 v[34:37], v[242:245], v[204:207], v[34:37]
	v_mfma_f32_16x16x32_bf16 v[22:25], v[234:237], v[212:215], v[22:25]
	v_mfma_f32_16x16x32_bf16 v[18:21], v[242:245], v[212:215], v[18:21]
	v_mfma_f32_16x16x32_bf16 v[6:9], v[234:237], v[226:229], v[6:9]
	v_mfma_f32_16x16x32_bf16 v[2:5], v[242:245], v[226:229], v[2:5]
	s_setprio 0
	s_add_i32 s58, 0, 0x18000
	v_add_u32_e32 v151, s58, v147
	s_barrier
	ds_read_b128 v[140:143], v151
	ds_read_b128 v[152:155], v151 offset:1024
	ds_read_b128 v[168:171], v151 offset:2048
	ds_read_b128 v[172:175], v151 offset:3072
	s_add_u32 s42, s42, 0x40000
	s_addc_u32 s43, s43, 0
	s_mov_b32 m0, s55
	ds_read_b128 v[176:179], v150 offset:32768
	ds_read_b128 v[180:183], v150 offset:33792
	ds_read_b128 v[184:187], v150 offset:34816
	ds_read_b128 v[204:207], v150 offset:35840
	ds_read_b128 v[208:211], v150 offset:36864
	ds_read_b128 v[212:215], v150 offset:37888
	ds_read_b128 v[216:219], v150 offset:38912
	ds_read_b128 v[226:229], v150 offset:39936
	global_load_lds_dwordx4 v134, s[42:43]
	s_mov_b32 m0, s83
	s_nop 0
	global_load_lds_dwordx4 v132, s[42:43]
	s_waitcnt lgkmcnt(8)
	s_barrier
	s_waitcnt lgkmcnt(0)
	s_setprio 1
	s_waitcnt lgkmcnt(0)
	v_mfma_f32_16x16x32_bf16 v[126:129], v[140:143], v[176:179], v[126:129]
	v_mfma_f32_16x16x32_bf16 v[122:125], v[168:171], v[176:179], v[122:125]
	v_mfma_f32_16x16x32_bf16 v[110:113], v[140:143], v[184:187], v[110:113]
	v_mfma_f32_16x16x32_bf16 v[106:109], v[168:171], v[184:187], v[106:109]
	v_mfma_f32_16x16x32_bf16 v[94:97], v[140:143], v[208:211], v[94:97]
	v_mfma_f32_16x16x32_bf16 v[90:93], v[168:171], v[208:211], v[90:93]
	v_mfma_f32_16x16x32_bf16 v[78:81], v[140:143], v[216:219], v[78:81]
	v_mfma_f32_16x16x32_bf16 v[74:77], v[168:171], v[216:219], v[74:77]
	v_mfma_f32_16x16x32_bf16 v[126:129], v[152:155], v[180:183], v[126:129]
	v_mfma_f32_16x16x32_bf16 v[122:125], v[172:175], v[180:183], v[122:125]
	v_mfma_f32_16x16x32_bf16 v[110:113], v[152:155], v[204:207], v[110:113]
	v_mfma_f32_16x16x32_bf16 v[106:109], v[172:175], v[204:207], v[106:109]
	v_mfma_f32_16x16x32_bf16 v[94:97], v[152:155], v[212:215], v[94:97]
	v_mfma_f32_16x16x32_bf16 v[90:93], v[172:175], v[212:215], v[90:93]
	v_mfma_f32_16x16x32_bf16 v[78:81], v[152:155], v[226:229], v[78:81]
	v_mfma_f32_16x16x32_bf16 v[74:77], v[172:175], v[226:229], v[74:77]
	s_setprio 0
	s_barrier
	s_add_i32 s42, 0, 0x1c000
	s_add_i32 s43, s58, s48
	v_add_u32_e32 v151, s42, v147
	s_add_u32 s60, s6, 0x80
	s_addc_u32 s61, s7, 0
	s_mov_b32 m0, s43
	ds_read_b128 v[230:233], v151
	ds_read_b128 v[234:237], v151 offset:1024
	ds_read_b128 v[238:241], v151 offset:2048
	ds_read_b128 v[242:245], v151 offset:3072
	global_load_lds_dwordx4 v0, s[60:61]
	s_add_i32 m0, s43, 0x2000
	s_nop 0
	global_load_lds_dwordx4 v130, s[60:61]
	s_barrier
	s_waitcnt lgkmcnt(0)
	s_setprio 1
	s_waitcnt lgkmcnt(0)
	v_mfma_f32_16x16x32_bf16 v[118:121], v[230:233], v[176:179], v[118:121]
	v_mfma_f32_16x16x32_bf16 v[114:117], v[238:241], v[176:179], v[114:117]
	v_mfma_f32_16x16x32_bf16 v[102:105], v[230:233], v[184:187], v[102:105]
	v_mfma_f32_16x16x32_bf16 v[98:101], v[238:241], v[184:187], v[98:101]
	v_mfma_f32_16x16x32_bf16 v[86:89], v[230:233], v[208:211], v[86:89]
	v_mfma_f32_16x16x32_bf16 v[82:85], v[238:241], v[208:211], v[82:85]
	v_mfma_f32_16x16x32_bf16 v[70:73], v[230:233], v[216:219], v[70:73]
	v_mfma_f32_16x16x32_bf16 v[66:69], v[238:241], v[216:219], v[66:69]
	v_mfma_f32_16x16x32_bf16 v[118:121], v[234:237], v[180:183], v[118:121]
	v_mfma_f32_16x16x32_bf16 v[114:117], v[242:245], v[180:183], v[114:117]
	v_mfma_f32_16x16x32_bf16 v[102:105], v[234:237], v[204:207], v[102:105]
	v_mfma_f32_16x16x32_bf16 v[98:101], v[242:245], v[204:207], v[98:101]
	v_mfma_f32_16x16x32_bf16 v[86:89], v[234:237], v[212:215], v[86:89]
	v_mfma_f32_16x16x32_bf16 v[82:85], v[242:245], v[212:215], v[82:85]
	v_mfma_f32_16x16x32_bf16 v[70:73], v[234:237], v[226:229], v[70:73]
	v_mfma_f32_16x16x32_bf16 v[66:69], v[242:245], v[226:229], v[66:69]
	s_setprio 0
	s_mov_b32 m0, s84
	s_barrier
	ds_read_b128 v[176:179], v150 offset:49152
	ds_read_b128 v[180:183], v150 offset:50176
	ds_read_b128 v[184:187], v150 offset:51200
	ds_read_b128 v[204:207], v150 offset:52224
	ds_read_b128 v[208:211], v150 offset:53248
	ds_read_b128 v[212:215], v150 offset:54272
	ds_read_b128 v[216:219], v150 offset:55296
	ds_read_b128 v[226:229], v150 offset:56320
	global_load_lds_dwordx4 v134, vcc
	s_mov_b32 m0, s85
	s_nop 0
	global_load_lds_dwordx4 v132, vcc
	s_barrier
; #define PG8_STAGE(bufoff, gbase, voff) do { _Pragma("unroll") for (int _i = 0; _i < 2; ++_i) \
;         __builtin_amdgcn_global_load_lds((const unsigned*)((const char*)(gbase) + (voff)[_i]), (LAS unsigned*)(lds + (bufoff) + ldsw + _i * 8192), 16, 0, 0); } while (0)
; #define PG8_LDA(dst, b, h) do { _Pragma("unroll") for (int m = 0; m < 4; ++m) _Pragma("unroll") for (int k = 0; k < 2; ++k) dst[m][k] = *(const LAS bf16x8*)(lds + PG8_SA(b, h) + aoff + m * 2048 + k * 1024); } while (0)
; #define PG8_LDB(dst, b, h) do { _Pragma("unroll") for (int n = 0; n < 2; ++n) _Pragma("unroll") for (int k = 0; k < 2; ++k) dst[n][k] = *(const LAS bf16x8*)(lds + PG8_SB(b, h) + boff + n * 2048 + k * 1024); } while (0)
; #define PG8_WAIT_V(n) asm volatile("s_waitcnt vmcnt(" #n ")" ::: "memory")
; #define PG8_WAIT_L(n) asm volatile("s_waitcnt lgkmcnt(" #n ")" ::: "memory")
; #define PG8_BAR __builtin_amdgcn_s_barrier()
; #define PG8_SCHED __builtin_amdgcn_sched_barrier(0)
; template <class Epi>
; __device__ __forceinline__ void gemm_phase(LAS unsigned char* lds, const Gemm g, const StaticOrder& S, const Epi& E) {
;     ...
;             PG8_LDB(B0, 0, 0); PG8_SCHED; PG8_LDA(At, 0, 0); PG8_STAGE(PG8_SA(1, 1), a1 + hstep, voffA);
;             PG8_WAIT_L(8); PG8_BAR; PG8_WAIT_L(0); PG8_MMA(0, 0, At, B0); PG8_BAR; PG8_SCHED;
;             PG8_LDB(B1, 0, 1); PG8_STAGE(PG8_SB(0, 0), b2, voffB);
;             PG8_BAR; PG8_WAIT_L(0); PG8_MMA(0, 1, At, B1); PG8_BAR;
;             PG8_LDA(At, 0, 1); PG8_STAGE(PG8_SA(0, 0), a2, voffA);
;             PG8_BAR; PG8_WAIT_L(0); PG8_MMA(1, 0, At, B0); PG8_BAR; PG8_SCHED;
;             PG8_STAGE(PG8_SB(0, 1), b2 + hstep, voffB);
;             PG8_WAIT_V(6); PG8_BAR; PG8_MMA(1, 1, At, B1); PG8_BAR;
;             PG8_LDB(B0, 1, 0); PG8_SCHED; PG8_LDA(At, 1, 0); PG8_STAGE(PG8_SA(0, 1), a2 + hstep, voffA);
;             PG8_WAIT_L(8); PG8_BAR; PG8_WAIT_L(0); PG8_MMA(0, 0, At, B0); PG8_BAR; PG8_SCHED;
;             PG8_LDB(B1, 1, 1); PG8_STAGE(PG8_SB(1, 0), b3, voffB);
;             PG8_BAR; PG8_WAIT_L(0); PG8_MMA(0, 1, At, B1); PG8_BAR;
;             PG8_LDA(At, 1, 1); PG8_STAGE(PG8_SA(1, 0), a3, voffA);
;             PG8_BAR; PG8_WAIT_L(0); PG8_MMA(1, 0, At, B0); PG8_BAR; PG8_SCHED;
;             PG8_STAGE(PG8_SB(1, 1), b3 + hstep, voffB);
;             PG8_WAIT_V(6); PG8_BAR; PG8_MMA(1, 1, At, B1); PG8_BAR;
	s_waitcnt lgkmcnt(0)
	s_setprio 1
	s_waitcnt lgkmcnt(0)
	v_mfma_f32_16x16x32_bf16 v[62:65], v[140:143], v[176:179], v[62:65]
	v_mfma_f32_16x16x32_bf16 v[58:61], v[168:171], v[176:179], v[58:61]
	v_mfma_f32_16x16x32_bf16 v[46:49], v[140:143], v[184:187], v[46:49]
	v_mfma_f32_16x16x32_bf16 v[42:45], v[168:171], v[184:187], v[42:45]
	v_mfma_f32_16x16x32_bf16 v[30:33], v[140:143], v[208:211], v[30:33]
	v_mfma_f32_16x16x32_bf16 v[26:29], v[168:171], v[208:211], v[26:29]
	v_mfma_f32_16x16x32_bf16 v[14:17], v[140:143], v[216:219], v[14:17]
	v_mfma_f32_16x16x32_bf16 v[10:13], v[168:171], v[216:219], v[10:13]
	v_mfma_f32_16x16x32_bf16 v[62:65], v[152:155], v[180:183], v[62:65]
	v_mfma_f32_16x16x32_bf16 v[58:61], v[172:175], v[180:183], v[58:61]
	v_mfma_f32_16x16x32_bf16 v[46:49], v[152:155], v[204:207], v[46:49]
	v_mfma_f32_16x16x32_bf16 v[42:45], v[172:175], v[204:207], v[42:45]
	v_mfma_f32_16x16x32_bf16 v[30:33], v[152:155], v[212:215], v[30:33]
	v_mfma_f32_16x16x32_bf16 v[26:29], v[172:175], v[212:215], v[26:29]
	v_mfma_f32_16x16x32_bf16 v[14:17], v[152:155], v[226:229], v[14:17]
	v_mfma_f32_16x16x32_bf16 v[10:13], v[172:175], v[226:229], v[10:13]
	s_setprio 0
	s_barrier
	s_add_u32 s6, s6, 0x40080
	s_addc_u32 s7, s7, 0
	s_add_i32 s42, s42, s48
	s_mov_b32 m0, s42
	s_nop 0
	global_load_lds_dwordx4 v0, s[6:7]
	s_add_i32 m0, s42, 0x2000
	s_nop 0
	global_load_lds_dwordx4 v130, s[6:7]
	s_waitcnt vmcnt(6)
	s_barrier
	s_setprio 1
	v_mfma_f32_16x16x32_bf16 v[54:57], v[230:233], v[176:179], v[54:57]
	v_mfma_f32_16x16x32_bf16 v[50:53], v[238:241], v[176:179], v[50:53]
	v_mfma_f32_16x16x32_bf16 v[38:41], v[230:233], v[184:187], v[38:41]
	v_mfma_f32_16x16x32_bf16 v[34:37], v[238:241], v[184:187], v[34:37]
	v_mfma_f32_16x16x32_bf16 v[22:25], v[230:233], v[208:211], v[22:25]
	v_mfma_f32_16x16x32_bf16 v[18:21], v[238:241], v[208:211], v[18:21]
	v_mfma_f32_16x16x32_bf16 v[6:9], v[230:233], v[216:219], v[6:9]
	v_mfma_f32_16x16x32_bf16 v[2:5], v[238:241], v[216:219], v[2:5]
	v_mfma_f32_16x16x32_bf16 v[54:57], v[234:237], v[180:183], v[54:57]
	v_mfma_f32_16x16x32_bf16 v[50:53], v[242:245], v[180:183], v[50:53]
	v_mfma_f32_16x16x32_bf16 v[38:41], v[234:237], v[204:207], v[38:41]
	v_mfma_f32_16x16x32_bf16 v[34:37], v[242:245], v[204:207], v[34:37]
	v_mfma_f32_16x16x32_bf16 v[22:25], v[234:237], v[212:215], v[22:25]
	v_mfma_f32_16x16x32_bf16 v[18:21], v[242:245], v[212:215], v[18:21]
	v_mfma_f32_16x16x32_bf16 v[6:9], v[234:237], v[226:229], v[6:9]
	v_mfma_f32_16x16x32_bf16 v[2:5], v[242:245], v[226:229], v[2:5]
	s_setprio 0
	s_add_i32 s93, s93, 2
	s_add_u32 s36, s36, 0x100
	s_addc_u32 s37, s37, 0
	s_add_u32 s91, s91, 0x100
	s_addc_u32 s92, s92, 0
	s_cmp_gt_u32 s93, 13
	s_barrier
	s_add_u32 s6, s36, 0xfffc0080
	s_addc_u32 s7, s37, -1
	s_add_i32 s58, 0, 0x10000
	v_add_u32_e32 v144, s58, v147
	ds_read_b128 v[140:143], v144
	ds_read_b128 v[152:155], v144 offset:1024
	ds_read_b128 v[168:171], v144 offset:2048
	ds_read_b128 v[172:175], v144 offset:3072
	s_cmp_eq_u32 s93, 12
	s_cselect_b32 s43, s11, s7
	s_cselect_b32 s42, s71, s6
	s_cselect_b32 s7, s9, s92
	s_cselect_b32 s6, s90, s91
	s_add_i32 m0, s49, 0xc000
	ds_read_b128 v[176:179], v150
	ds_read_b128 v[180:183], v150 offset:1024
	ds_read_b128 v[184:187], v150 offset:2048
	ds_read_b128 v[204:207], v150 offset:3072
	ds_read_b128 v[208:211], v150 offset:4096
	ds_read_b128 v[212:215], v150 offset:5120
	ds_read_b128 v[216:219], v150 offset:6144
	ds_read_b128 v[226:229], v150 offset:7168
	global_load_lds_dwordx4 v136, s[36:37]
	s_add_i32 m0, s49, 0xe000
	s_nop 0
	global_load_lds_dwordx4 v138, s[36:37]
	s_waitcnt lgkmcnt(8)
	s_barrier
	s_waitcnt lgkmcnt(0)
	s_setprio 1
	s_waitcnt lgkmcnt(0)
	v_mfma_f32_16x16x32_bf16 v[126:129], v[140:143], v[176:179], v[126:129]
	v_mfma_f32_16x16x32_bf16 v[122:125], v[168:171], v[176:179], v[122:125]
	v_mfma_f32_16x16x32_bf16 v[110:113], v[140:143], v[184:187], v[110:113]
	v_mfma_f32_16x16x32_bf16 v[106:109], v[168:171], v[184:187], v[106:109]
	v_mfma_f32_16x16x32_bf16 v[94:97], v[140:143], v[208:211], v[94:97]
	v_mfma_f32_16x16x32_bf16 v[90:93], v[168:171], v[208:211], v[90:93]
	v_mfma_f32_16x16x32_bf16 v[78:81], v[140:143], v[216:219], v[78:81]
	v_mfma_f32_16x16x32_bf16 v[74:77], v[168:171], v[216:219], v[74:77]
	v_mfma_f32_16x16x32_bf16 v[126:129], v[152:155], v[180:183], v[126:129]
	v_mfma_f32_16x16x32_bf16 v[122:125], v[172:175], v[180:183], v[122:125]
	v_mfma_f32_16x16x32_bf16 v[110:113], v[152:155], v[204:207], v[110:113]
	v_mfma_f32_16x16x32_bf16 v[106:109], v[172:175], v[204:207], v[106:109]
	v_mfma_f32_16x16x32_bf16 v[94:97], v[152:155], v[212:215], v[94:97]
	v_mfma_f32_16x16x32_bf16 v[90:93], v[172:175], v[212:215], v[90:93]
	v_mfma_f32_16x16x32_bf16 v[78:81], v[152:155], v[226:229], v[78:81]
	v_mfma_f32_16x16x32_bf16 v[74:77], v[172:175], v[226:229], v[74:77]
	s_setprio 0
	s_barrier
; __device__ __forceinline__ unsigned pk2(float lo, float hi) { unsigned r; asm("v_cvt_pk_bf16_f32 %0, %1, %2" : "=v"(r) : "v"(lo), "v"(hi)); return r; }
; #define PG8_STAGE(bufoff, gbase, voff) do { _Pragma("unroll") for (int _i = 0; _i < 2; ++_i) \
;         __builtin_amdgcn_global_load_lds((const unsigned*)((const char*)(gbase) + (voff)[_i]), (LAS unsigned*)(lds + (bufoff) + ldsw + _i * 8192), 16, 0, 0); } while (0)
; #define PG8_LDA(dst, b, h) do { _Pragma("unroll") for (int m = 0; m < 4; ++m) _Pragma("unroll") for (int k = 0; k < 2; ++k) dst[m][k] = *(const LAS bf16x8*)(lds + PG8_SA(b, h) + aoff + m * 2048 + k * 1024); } while (0)
;     __device__ __forceinline__ void operator()(const f32x4 (&acc)[2][2][4][2], const Unit& u, int ui, int wr, int wc, int fr, int fq) const {
;     ...
;                     u32x4 w; w.x = pk2(v0[0], v0[1]); w.y = pk2(v0[2], v0[3]); w.z = pk2(v1[0], v1[1]); w.w = pk2(v1[2], v1[3]);
;                     *(u32x4*)(rowp + bj * HALF) = w;
; template <class Epi>
; __device__ __forceinline__ void gemm_phase(LAS unsigned char* lds, const Gemm g, const StaticOrder& S, const Epi& E) {
;     ...
;             PG8_LDB(B0, 0, 0); PG8_SCHED; PG8_LDA(At, 0, 0); PG8_STAGE(PG8_SA(1, 1), a1 + hstep, voffA);
;             PG8_WAIT_L(8); PG8_BAR; PG8_WAIT_L(0); PG8_MMA(0, 0, At, B0); PG8_BAR; PG8_SCHED;
;             PG8_LDB(B1, 0, 1); PG8_STAGE(PG8_SB(0, 0), b2, voffB);
;             PG8_BAR; PG8_WAIT_L(0); PG8_MMA(0, 1, At, B1); PG8_BAR;
;             PG8_LDA(At, 0, 1); PG8_STAGE(PG8_SA(0, 0), a2, voffA);
;             PG8_BAR; PG8_WAIT_L(0); PG8_MMA(1, 0, At, B0); PG8_BAR; PG8_SCHED;
;             PG8_STAGE(PG8_SB(0, 1), b2 + hstep, voffB);
;             PG8_WAIT_V(6); PG8_BAR; PG8_MMA(1, 1, At, B1); PG8_BAR;
;             PG8_LDB(B0, 1, 0); PG8_SCHED; PG8_LDA(At, 1, 0); PG8_STAGE(PG8_SA(0, 1), a2 + hstep, voffA);
;             PG8_WAIT_L(8); PG8_BAR; PG8_WAIT_L(0); PG8_MMA(0, 0, At, B0); PG8_BAR; PG8_SCHED;
;             PG8_LDB(B1, 1, 1); PG8_STAGE(PG8_SB(1, 0), b3, voffB);
;             PG8_BAR; PG8_WAIT_L(0); PG8_MMA(0, 1, At, B1); PG8_BAR;
;             PG8_LDA(At, 1, 1); PG8_STAGE(PG8_SA(1, 0), a3, voffA);
;             PG8_BAR; PG8_WAIT_L(0); PG8_MMA(1, 0, At, B0); PG8_BAR; PG8_SCHED;
;             PG8_STAGE(PG8_SB(1, 1), b3 + hstep, voffB);
;             PG8_WAIT_V(6); PG8_BAR; PG8_MMA(1, 1, At, B1); PG8_BAR;
	s_add_i32 s70, 0, 0x14000
	v_add_u32_e32 v144, s70, v147
	s_add_i32 s58, s58, s48
	ds_read_b128 v[230:233], v144
	ds_read_b128 v[234:237], v144 offset:1024
	ds_read_b128 v[238:241], v144 offset:2048
	ds_read_b128 v[242:245], v144 offset:3072
	s_mov_b32 m0, s58
	s_nop 0
	global_load_lds_dwordx4 v0, s[6:7]
	s_add_i32 m0, s58, 0x2000
	s_nop 0
	global_load_lds_dwordx4 v130, s[6:7]
	s_barrier
	s_waitcnt lgkmcnt(0)
	s_setprio 1
	s_waitcnt lgkmcnt(0)
	v_mfma_f32_16x16x32_bf16 v[118:121], v[230:233], v[176:179], v[118:121]
	v_mfma_f32_16x16x32_bf16 v[114:117], v[238:241], v[176:179], v[114:117]
	v_mfma_f32_16x16x32_bf16 v[102:105], v[230:233], v[184:187], v[102:105]
	v_mfma_f32_16x16x32_bf16 v[98:101], v[238:241], v[184:187], v[98:101]
	v_mfma_f32_16x16x32_bf16 v[86:89], v[230:233], v[208:211], v[86:89]
	v_mfma_f32_16x16x32_bf16 v[82:85], v[238:241], v[208:211], v[82:85]
	v_mfma_f32_16x16x32_bf16 v[70:73], v[230:233], v[216:219], v[70:73]
	v_mfma_f32_16x16x32_bf16 v[66:69], v[238:241], v[216:219], v[66:69]
	v_mfma_f32_16x16x32_bf16 v[118:121], v[234:237], v[180:183], v[118:121]
	v_mfma_f32_16x16x32_bf16 v[114:117], v[242:245], v[180:183], v[114:117]
	v_mfma_f32_16x16x32_bf16 v[102:105], v[234:237], v[204:207], v[102:105]
	v_mfma_f32_16x16x32_bf16 v[98:101], v[242:245], v[204:207], v[98:101]
	v_mfma_f32_16x16x32_bf16 v[86:89], v[234:237], v[212:215], v[86:89]
	v_mfma_f32_16x16x32_bf16 v[82:85], v[242:245], v[212:215], v[82:85]
	v_mfma_f32_16x16x32_bf16 v[70:73], v[234:237], v[226:229], v[70:73]
	v_mfma_f32_16x16x32_bf16 v[66:69], v[242:245], v[226:229], v[66:69]
	s_setprio 0
	s_mov_b32 m0, s49
	s_add_u32 vcc_lo, s42, 0x80
	s_addc_u32 vcc_hi, s43, 0
	s_barrier
	ds_read_b128 v[176:179], v150 offset:16384
	ds_read_b128 v[180:183], v150 offset:17408
	ds_read_b128 v[184:187], v150 offset:18432
	ds_read_b128 v[204:207], v150 offset:19456
	ds_read_b128 v[208:211], v150 offset:20480
	ds_read_b128 v[212:215], v150 offset:21504
	ds_read_b128 v[216:219], v150 offset:22528
	ds_read_b128 v[226:229], v150 offset:23552
	global_load_lds_dwordx4 v134, s[42:43]
	s_mov_b32 m0, s54
	s_nop 0
	global_load_lds_dwordx4 v132, s[42:43]
	s_barrier
	s_waitcnt lgkmcnt(0)
	s_setprio 1
	s_waitcnt lgkmcnt(0)
	v_mfma_f32_16x16x32_bf16 v[62:65], v[140:143], v[176:179], v[62:65]
	v_mfma_f32_16x16x32_bf16 v[58:61], v[168:171], v[176:179], v[58:61]
	v_mfma_f32_16x16x32_bf16 v[46:49], v[140:143], v[184:187], v[46:49]
	v_mfma_f32_16x16x32_bf16 v[42:45], v[168:171], v[184:187], v[42:45]
	v_mfma_f32_16x16x32_bf16 v[30:33], v[140:143], v[208:211], v[30:33]
	v_mfma_f32_16x16x32_bf16 v[26:29], v[168:171], v[208:211], v[26:29]
	v_mfma_f32_16x16x32_bf16 v[14:17], v[140:143], v[216:219], v[14:17]
	v_mfma_f32_16x16x32_bf16 v[10:13], v[168:171], v[216:219], v[10:13]
	v_mfma_f32_16x16x32_bf16 v[62:65], v[152:155], v[180:183], v[62:65]
	v_mfma_f32_16x16x32_bf16 v[58:61], v[172:175], v[180:183], v[58:61]
	v_mfma_f32_16x16x32_bf16 v[46:49], v[152:155], v[204:207], v[46:49]
	v_mfma_f32_16x16x32_bf16 v[42:45], v[172:175], v[204:207], v[42:45]
	v_mfma_f32_16x16x32_bf16 v[30:33], v[152:155], v[212:215], v[30:33]
	v_mfma_f32_16x16x32_bf16 v[26:29], v[172:175], v[212:215], v[26:29]
	v_mfma_f32_16x16x32_bf16 v[14:17], v[152:155], v[226:229], v[14:17]
	v_mfma_f32_16x16x32_bf16 v[10:13], v[172:175], v[226:229], v[10:13]
	s_setprio 0
	s_barrier
	s_add_u32 s60, s6, 0x40000
	s_addc_u32 s61, s7, 0
	s_add_i32 s58, s70, s48
	s_mov_b32 m0, s58
	s_nop 0
	global_load_lds_dwordx4 v0, s[60:61]
	s_add_i32 m0, s58, 0x2000
	s_nop 0
	global_load_lds_dwordx4 v130, s[60:61]
	s_waitcnt vmcnt(6)
	s_barrier
	s_setprio 1
	v_mfma_f32_16x16x32_bf16 v[54:57], v[230:233], v[176:179], v[54:57]
	v_mfma_f32_16x16x32_bf16 v[50:53], v[238:241], v[176:179], v[50:53]
	s_cmp_eq_u32 s89, 0
	s_cbranch_scc1 .LdsE_skip_5
	global_store_dwordx4 v250, v[200:203], s[4:5] offset:256
	s_nop 1
	v_add_u32_e32 v250, 0x20000, v250

; #define PG8_STAGE(bufoff, gbase, voff) do { _Pragma("unroll") for (int _i = 0; _i < 2; ++_i) \
;         __builtin_amdgcn_global_load_lds((const unsigned*)((const char*)(gbase) + (voff)[_i]), (LAS unsigned*)(lds + (bufoff) + ldsw + _i * 8192), 16, 0, 0); } while (0)
; #define PG8_LDA(dst, b, h) do { _Pragma("unroll") for (int m = 0; m < 4; ++m) _Pragma("unroll") for (int k = 0; k < 2; ++k) dst[m][k] = *(const LAS bf16x8*)(lds + PG8_SA(b, h) + aoff + m * 2048 + k * 1024); } while (0)
; #define PG8_LDB(dst, b, h) do { _Pragma("unroll") for (int n = 0; n < 2; ++n) _Pragma("unroll") for (int k = 0; k < 2; ++k) dst[n][k] = *(const LAS bf16x8*)(lds + PG8_SB(b, h) + boff + n * 2048 + k * 1024); } while (0)
; #define PG8_WAIT_V(n) asm volatile("s_waitcnt vmcnt(" #n ")" ::: "memory")
; #define PG8_WAIT_L(n) asm volatile("s_waitcnt lgkmcnt(" #n ")" ::: "memory")
; #define PG8_BAR __builtin_amdgcn_s_barrier()
; #define PG8_SCHED __builtin_amdgcn_sched_barrier(0)
; template <class Epi>
; __device__ __forceinline__ void gemm_phase(LAS unsigned char* lds, const Gemm g, const StaticOrder& S, const Epi& E) {
;     ...
;             PG8_LDB(B0, 0, 0); PG8_SCHED; PG8_LDA(At, 0, 0); PG8_STAGE(PG8_SA(1, 1), a1 + hstep, voffA);
;             PG8_WAIT_L(8); PG8_BAR; PG8_WAIT_L(0); PG8_MMA(0, 0, At, B0); PG8_BAR; PG8_SCHED;
;             PG8_LDB(B1, 0, 1); PG8_STAGE(PG8_SB(0, 0), b2, voffB);
;             PG8_BAR; PG8_WAIT_L(0); PG8_MMA(0, 1, At, B1); PG8_BAR;
;             PG8_LDA(At, 0, 1); PG8_STAGE(PG8_SA(0, 0), a2, voffA);
;             PG8_BAR; PG8_WAIT_L(0); PG8_MMA(1, 0, At, B0); PG8_BAR; PG8_SCHED;
;             PG8_STAGE(PG8_SB(0, 1), b2 + hstep, voffB);
;             PG8_WAIT_V(6); PG8_BAR; PG8_MMA(1, 1, At, B1); PG8_BAR;
;             PG8_LDB(B0, 1, 0); PG8_SCHED; PG8_LDA(At, 1, 0); PG8_STAGE(PG8_SA(0, 1), a2 + hstep, voffA);
;             PG8_WAIT_L(8); PG8_BAR; PG8_WAIT_L(0); PG8_MMA(0, 0, At, B0); PG8_BAR; PG8_SCHED;
;             PG8_LDB(B1, 1, 1); PG8_STAGE(PG8_SB(1, 0), b3, voffB);
;             PG8_BAR; PG8_WAIT_L(0); PG8_MMA(0, 1, At, B1); PG8_BAR;
;             PG8_LDA(At, 1, 1); PG8_STAGE(PG8_SA(1, 0), a3, voffA);
;             PG8_BAR; PG8_WAIT_L(0); PG8_MMA(1, 0, At, B0); PG8_BAR; PG8_SCHED;
;             PG8_STAGE(PG8_SB(1, 1), b3 + hstep, voffB);
;             PG8_WAIT_V(6); PG8_BAR; PG8_MMA(1, 1, At, B1); PG8_BAR;
.LdsE_skip_7:
	v_mfma_f32_16x16x32_bf16 v[38:41], v[230:233], v[184:187], v[38:41]
	v_mfma_f32_16x16x32_bf16 v[34:37], v[238:241], v[184:187], v[34:37]
	v_mfma_f32_16x16x32_bf16 v[22:25], v[230:233], v[208:211], v[22:25]
	v_mfma_f32_16x16x32_bf16 v[18:21], v[238:241], v[208:211], v[18:21]
	v_mfma_f32_16x16x32_bf16 v[6:9], v[230:233], v[216:219], v[6:9]
	v_mfma_f32_16x16x32_bf16 v[2:5], v[238:241], v[216:219], v[2:5]
	v_mfma_f32_16x16x32_bf16 v[54:57], v[234:237], v[180:183], v[54:57]
	v_mfma_f32_16x16x32_bf16 v[50:53], v[242:245], v[180:183], v[50:53]
	v_mfma_f32_16x16x32_bf16 v[38:41], v[234:237], v[204:207], v[38:41]
	v_mfma_f32_16x16x32_bf16 v[34:37], v[242:245], v[204:207], v[34:37]
	v_mfma_f32_16x16x32_bf16 v[22:25], v[234:237], v[212:215], v[22:25]
	v_mfma_f32_16x16x32_bf16 v[18:21], v[242:245], v[212:215], v[18:21]
	v_mfma_f32_16x16x32_bf16 v[6:9], v[234:237], v[226:229], v[6:9]
	v_mfma_f32_16x16x32_bf16 v[2:5], v[242:245], v[226:229], v[2:5]
	s_setprio 0
	s_add_i32 s58, 0, 0x18000
	v_add_u32_e32 v151, s58, v147
	s_barrier
	ds_read_b128 v[140:143], v151
	ds_read_b128 v[152:155], v151 offset:1024
	ds_read_b128 v[168:171], v151 offset:2048
	ds_read_b128 v[172:175], v151 offset:3072
	s_add_u32 s42, s42, 0x40000
	s_addc_u32 s43, s43, 0
	s_mov_b32 m0, s55
	ds_read_b128 v[176:179], v150 offset:32768
	ds_read_b128 v[180:183], v150 offset:33792
	ds_read_b128 v[184:187], v150 offset:34816
	ds_read_b128 v[204:207], v150 offset:35840
	ds_read_b128 v[208:211], v150 offset:36864
	ds_read_b128 v[212:215], v150 offset:37888
	ds_read_b128 v[216:219], v150 offset:38912
	ds_read_b128 v[226:229], v150 offset:39936
	global_load_lds_dwordx4 v134, s[42:43]
	s_mov_b32 m0, s83
	s_nop 0
	global_load_lds_dwordx4 v132, s[42:43]
	s_waitcnt lgkmcnt(8)
	s_barrier
	s_waitcnt lgkmcnt(0)
	s_setprio 1
	s_waitcnt lgkmcnt(0)
	v_mfma_f32_16x16x32_bf16 v[126:129], v[140:143], v[176:179], v[126:129]
	v_mfma_f32_16x16x32_bf16 v[122:125], v[168:171], v[176:179], v[122:125]
	v_mfma_f32_16x16x32_bf16 v[110:113], v[140:143], v[184:187], v[110:113]
	v_mfma_f32_16x16x32_bf16 v[106:109], v[168:171], v[184:187], v[106:109]
	v_mfma_f32_16x16x32_bf16 v[94:97], v[140:143], v[208:211], v[94:97]
	v_mfma_f32_16x16x32_bf16 v[90:93], v[168:171], v[208:211], v[90:93]
	v_mfma_f32_16x16x32_bf16 v[78:81], v[140:143], v[216:219], v[78:81]
	v_mfma_f32_16x16x32_bf16 v[74:77], v[168:171], v[216:219], v[74:77]
	v_mfma_f32_16x16x32_bf16 v[126:129], v[152:155], v[180:183], v[126:129]
	v_mfma_f32_16x16x32_bf16 v[122:125], v[172:175], v[180:183], v[122:125]
	v_mfma_f32_16x16x32_bf16 v[110:113], v[152:155], v[204:207], v[110:113]
	v_mfma_f32_16x16x32_bf16 v[106:109], v[172:175], v[204:207], v[106:109]
	v_mfma_f32_16x16x32_bf16 v[94:97], v[152:155], v[212:215], v[94:97]
	v_mfma_f32_16x16x32_bf16 v[90:93], v[172:175], v[212:215], v[90:93]
	v_mfma_f32_16x16x32_bf16 v[78:81], v[152:155], v[226:229], v[78:81]
	v_mfma_f32_16x16x32_bf16 v[74:77], v[172:175], v[226:229], v[74:77]
	s_setprio 0
	s_barrier
	s_add_i32 s42, 0, 0x1c000
	s_add_i32 s43, s58, s48
	v_add_u32_e32 v151, s42, v147
	s_add_u32 s60, s6, 0x80
	s_addc_u32 s61, s7, 0
	s_mov_b32 m0, s43
	ds_read_b128 v[230:233], v151
	ds_read_b128 v[234:237], v151 offset:1024
	ds_read_b128 v[238:241], v151 offset:2048
	ds_read_b128 v[242:245], v151 offset:3072
	global_load_lds_dwordx4 v0, s[60:61]
	s_add_i32 m0, s43, 0x2000
	s_nop 0
	global_load_lds_dwordx4 v130, s[60:61]
	s_barrier
	s_waitcnt lgkmcnt(0)
	s_setprio 1
	s_waitcnt lgkmcnt(0)
	v_mfma_f32_16x16x32_bf16 v[118:121], v[230:233], v[176:179], v[118:121]
	v_mfma_f32_16x16x32_bf16 v[114:117], v[238:241], v[176:179], v[114:117]
	v_mfma_f32_16x16x32_bf16 v[102:105], v[230:233], v[184:187], v[102:105]
	v_mfma_f32_16x16x32_bf16 v[98:101], v[238:241], v[184:187], v[98:101]
	v_mfma_f32_16x16x32_bf16 v[86:89], v[230:233], v[208:211], v[86:89]
	v_mfma_f32_16x16x32_bf16 v[82:85], v[238:241], v[208:211], v[82:85]
	v_mfma_f32_16x16x32_bf16 v[70:73], v[230:233], v[216:219], v[70:73]
	v_mfma_f32_16x16x32_bf16 v[66:69], v[238:241], v[216:219], v[66:69]
	v_mfma_f32_16x16x32_bf16 v[118:121], v[234:237], v[180:183], v[118:121]
	v_mfma_f32_16x16x32_bf16 v[114:117], v[242:245], v[180:183], v[114:117]
	v_mfma_f32_16x16x32_bf16 v[102:105], v[234:237], v[204:207], v[102:105]
	v_mfma_f32_16x16x32_bf16 v[98:101], v[242:245], v[204:207], v[98:101]
	v_mfma_f32_16x16x32_bf16 v[86:89], v[234:237], v[212:215], v[86:89]
	v_mfma_f32_16x16x32_bf16 v[82:85], v[242:245], v[212:215], v[82:85]
	v_mfma_f32_16x16x32_bf16 v[70:73], v[234:237], v[226:229], v[70:73]
	v_mfma_f32_16x16x32_bf16 v[66:69], v[242:245], v[226:229], v[66:69]
	s_setprio 0
	s_mov_b32 m0, s84
	s_barrier
	ds_read_b128 v[176:179], v150 offset:49152
	ds_read_b128 v[180:183], v150 offset:50176
	ds_read_b128 v[184:187], v150 offset:51200
	ds_read_b128 v[204:207], v150 offset:52224
	ds_read_b128 v[208:211], v150 offset:53248
	ds_read_b128 v[212:215], v150 offset:54272
	ds_read_b128 v[216:219], v150 offset:55296
	ds_read_b128 v[226:229], v150 offset:56320
	global_load_lds_dwordx4 v134, vcc
	s_mov_b32 m0, s85
	s_nop 0
	global_load_lds_dwordx4 v132, vcc
	s_barrier
; __device__ __forceinline__ unsigned pk2(float lo, float hi) { unsigned r; asm("v_cvt_pk_bf16_f32 %0, %1, %2" : "=v"(r) : "v"(lo), "v"(hi)); return r; }
; #define PG8_STAGE(bufoff, gbase, voff) do { _Pragma("unroll") for (int _i = 0; _i < 2; ++_i) \
;         __builtin_amdgcn_global_load_lds((const unsigned*)((const char*)(gbase) + (voff)[_i]), (LAS unsigned*)(lds + (bufoff) + ldsw + _i * 8192), 16, 0, 0); } while (0)
; #define PG8_WAIT_V(n) asm volatile("s_waitcnt vmcnt(" #n ")" ::: "memory")
; #define PG8_WAIT_L(n) asm volatile("s_waitcnt lgkmcnt(" #n ")" ::: "memory")
;     __device__ __forceinline__ void operator()(const f32x4 (&acc)[2][2][4][2], const Unit& u, int ui, int wr, int wc, int fr, int fq) const {
;         const int lrow0 = wr * 64 + fr, row0 = u.pm * BM + lrow0, col0 = u.pn * BM + wc * 32 + 8 * fq;
;         float rsv[2][4];
; #pragma unroll
;         for (int ai = 0; ai < 2; ++ai)
; #pragma unroll
;             for (int m = 0; m < 4; ++m) rsv[ai][m] = rstab[ui * 256 + lrow0 + ai * HALF + m * 16];
; #pragma unroll
;         for (int ai = 0; ai < 2; ++ai)
; #pragma unroll
;             for (int m = 0; m < 4; ++m) {
;                 const int row = row0 + ai * HALF + m * 16; const float rs = rsv[ai][m];
;                 bf16_t* rowp = O + (size_t)row * ldc + col0;
; #pragma unroll
;                 for (int bj = 0; bj < 2; ++bj) {
;                     f32x4 v0 = acc[ai][bj][m][0] * rs, v1 = acc[ai][bj][m][1] * rs;
;                     if (ACT == 1) {
; #pragma unroll
;                         for (int j = 0; j < 4; ++j) { const float a = fmaxf(v0[j], 0.f), b = fmaxf(v1[j], 0.f); v0[j] = a * a; v1[j] = b * b; }
;                     }
;                     u32x4 w; w.x = pk2(v0[0], v0[1]); w.y = pk2(v0[2], v0[3]); w.z = pk2(v1[0], v1[1]); w.w = pk2(v1[2], v1[3]);
;                     *(u32x4*)(rowp + bj * HALF) = w;
; template <class Epi>
; __device__ __forceinline__ void gemm_phase(LAS unsigned char* lds, const Gemm g, const StaticOrder& S, const Epi& E) {
;     ...
;             PG8_BAR; PG8_WAIT_L(0); PG8_MMA(0, 1, At, B1); PG8_BAR;
;             PG8_LDA(At, 1, 1); PG8_STAGE(PG8_SA(1, 0), a3, voffA);
;             PG8_BAR; PG8_WAIT_L(0); PG8_MMA(1, 0, At, B0); PG8_BAR; PG8_SCHED;
;             PG8_STAGE(PG8_SB(1, 1), b3 + hstep, voffB);
;             PG8_WAIT_V(6); PG8_BAR; PG8_MMA(1, 1, At, B1); PG8_BAR;
	s_waitcnt lgkmcnt(0)
	s_setprio 1
	s_waitcnt lgkmcnt(0)
	v_mfma_f32_16x16x32_bf16 v[62:65], v[140:143], v[176:179], v[62:65]
	v_mfma_f32_16x16x32_bf16 v[58:61], v[168:171], v[176:179], v[58:61]
	v_mfma_f32_16x16x32_bf16 v[46:49], v[140:143], v[184:187], v[46:49]
	v_mfma_f32_16x16x32_bf16 v[42:45], v[168:171], v[184:187], v[42:45]
	v_mfma_f32_16x16x32_bf16 v[30:33], v[140:143], v[208:211], v[30:33]
	v_mfma_f32_16x16x32_bf16 v[26:29], v[168:171], v[208:211], v[26:29]
	v_mfma_f32_16x16x32_bf16 v[14:17], v[140:143], v[216:219], v[14:17]
	v_mfma_f32_16x16x32_bf16 v[10:13], v[168:171], v[216:219], v[10:13]
	v_mfma_f32_16x16x32_bf16 v[62:65], v[152:155], v[180:183], v[62:65]
	v_mfma_f32_16x16x32_bf16 v[58:61], v[172:175], v[180:183], v[58:61]
	v_mfma_f32_16x16x32_bf16 v[46:49], v[152:155], v[204:207], v[46:49]
	v_mfma_f32_16x16x32_bf16 v[42:45], v[172:175], v[204:207], v[42:45]
	v_mfma_f32_16x16x32_bf16 v[30:33], v[152:155], v[212:215], v[30:33]
	v_mfma_f32_16x16x32_bf16 v[26:29], v[172:175], v[212:215], v[26:29]
	v_mfma_f32_16x16x32_bf16 v[14:17], v[152:155], v[226:229], v[14:17]
	v_mfma_f32_16x16x32_bf16 v[10:13], v[172:175], v[226:229], v[10:13]
	s_setprio 0
	s_barrier
	s_add_u32 s6, s6, 0x40080
	s_addc_u32 s7, s7, 0
	s_add_i32 s42, s42, s48
	s_mov_b32 m0, s42
	s_nop 0
	global_load_lds_dwordx4 v0, s[6:7]
	s_add_i32 m0, s42, 0x2000
	s_nop 0
	global_load_lds_dwordx4 v130, s[6:7]
	s_waitcnt vmcnt(6)
	s_barrier
	s_setprio 1
	v_mfma_f32_16x16x32_bf16 v[54:57], v[230:233], v[176:179], v[54:57]
	v_mfma_f32_16x16x32_bf16 v[50:53], v[238:241], v[176:179], v[50:53]
	v_mfma_f32_16x16x32_bf16 v[38:41], v[230:233], v[184:187], v[38:41]
	v_mfma_f32_16x16x32_bf16 v[34:37], v[238:241], v[184:187], v[34:37]
	v_mfma_f32_16x16x32_bf16 v[22:25], v[230:233], v[208:211], v[22:25]
	v_mfma_f32_16x16x32_bf16 v[18:21], v[238:241], v[208:211], v[18:21]
	v_mfma_f32_16x16x32_bf16 v[6:9], v[230:233], v[216:219], v[6:9]
	v_mfma_f32_16x16x32_bf16 v[2:5], v[238:241], v[216:219], v[2:5]
	v_mfma_f32_16x16x32_bf16 v[54:57], v[234:237], v[180:183], v[54:57]
	v_mfma_f32_16x16x32_bf16 v[50:53], v[242:245], v[180:183], v[50:53]
	v_mfma_f32_16x16x32_bf16 v[38:41], v[234:237], v[204:207], v[38:41]
	v_mfma_f32_16x16x32_bf16 v[34:37], v[242:245], v[204:207], v[34:37]
	v_mfma_f32_16x16x32_bf16 v[22:25], v[234:237], v[212:215], v[22:25]
	v_mfma_f32_16x16x32_bf16 v[18:21], v[242:245], v[212:215], v[18:21]
	v_mfma_f32_16x16x32_bf16 v[6:9], v[234:237], v[226:229], v[6:9]
	v_mfma_f32_16x16x32_bf16 v[2:5], v[242:245], v[226:229], v[2:5]
	s_setprio 0
	s_add_i32 s93, s93, 2
	s_add_u32 s36, s36, 0x100
	s_addc_u32 s37, s37, 0
	s_add_u32 s91, s91, 0x100
	s_addc_u32 s92, s92, 0
	s_cmp_gt_u32 s93, 13
	s_barrier
	v_lshl_add_u32 v140, s89, 10, v148
	ds_read2_b32 v[154:155], v140 offset1:16
	ds_read2_b32 v[156:157], v140 offset0:32 offset1:48
	ds_read2_b32 v[144:145], v140 offset0:128 offset1:144
	ds_read2_b32 v[142:143], v140 offset0:160 offset1:176
	v_lshl_add_u32 v152, s88, 8, v146
	s_waitcnt lgkmcnt(0)
	v_pk_mul_f32 v[122:123], v[122:123], v[154:155] op_sel_hi:[1,0]
	v_lshl_or_b32 v140, s87, 8, v149
	v_lshlrev_b32_e32 v250, 13, v152
	v_lshl_add_u32 v250, v140, 1, v250
	v_add_u32_e32 v250, 0x100000, v250
	v_ashrrev_i32_e32 v153, 31, v152
	v_pk_mul_f32 v[126:127], v[126:127], v[154:155] op_sel_hi:[1,0]
	v_pk_mul_f32 v[124:125], v[124:125], v[154:155] op_sel_hi:[1,0]
	v_max_f32_e32 v122, 0, v122
	v_ashrrev_i32_e32 v141, 31, v140
	v_lshlrev_b64 v[162:163], 13, v[152:153]
	v_pk_mul_f32 v[128:129], v[128:129], v[154:155] op_sel_hi:[1,0]
	v_mul_f32_e32 v151, v122, v122
	v_max_f32_e32 v122, 0, v127
	v_max_f32_e32 v123, 0, v123
	v_max_f32_e32 v124, 0, v124
	v_lshl_add_u64 v[162:163], s[4:5], 0, v[162:163]
	v_lshlrev_b64 v[168:169], 1, v[140:141]
	v_max_f32_e32 v126, 0, v126
	v_mul_f32_e32 v122, v122, v122
	v_mul_f32_e32 v127, v123, v123
	v_max_f32_e32 v123, 0, v128
	v_mul_f32_e32 v128, v124, v124
	v_max_f32_e32 v124, 0, v129
	v_max_f32_e32 v125, 0, v125
	v_pk_mul_f32 v[116:117], v[116:117], v[154:155] op_sel_hi:[1,0]
	v_pk_mul_f32 v[114:115], v[114:115], v[154:155] op_sel_hi:[1,0]
	v_lshl_add_u64 v[140:141], v[162:163], 0, v[168:169]
	v_mul_f32_e32 v126, v126, v126
	v_mul_f32_e32 v123, v123, v123
	v_mul_f32_e32 v124, v124, v124
	v_mul_f32_e32 v125, v125, v125
	v_cvt_pk_bf16_f32 v122, v126, v122
	v_pk_mul_f32 v[120:121], v[120:121], v[154:155] op_sel_hi:[1,0]
	v_pk_mul_f32 v[118:119], v[118:119], v[154:155] op_sel_hi:[1,0]
	v_max_f32_e32 v114, 0, v114
	v_max_f32_e32 v115, 0, v115
	v_max_f32_e32 v116, 0, v116
	v_cvt_pk_bf16_f32 v123, v123, v124
	v_cvt_pk_bf16_f32 v124, v151, v127
	v_cvt_pk_bf16_f32 v125, v128, v125
	global_store_dwordx4 v[140:141], v[122:125], off
	v_max_f32_e32 v117, 0, v117
	v_max_f32_e32 v118, 0, v118
	v_mul_f32_e32 v122, v114, v114
	v_max_f32_e32 v114, 0, v119
	v_mul_f32_e32 v119, v115, v115
	v_max_f32_e32 v115, 0, v120
	v_mul_f32_e32 v120, v116, v116
	v_max_f32_e32 v116, 0, v121
	v_mul_f32_e32 v115, v115, v115
	v_mul_f32_e32 v116, v116, v116
	v_mul_f32_e32 v114, v114, v114
	v_mul_f32_e32 v117, v117, v117
	v_cvt_pk_bf16_f32 v115, v115, v116
	v_cvt_pk_bf16_f32 v116, v122, v119
	v_mul_f32_e32 v118, v118, v118
	v_cvt_pk_bf16_f32 v114, v118, v114
	v_cvt_pk_bf16_f32 v117, v120, v117
	global_store_dwordx4 v[140:141], v[114:117], off offset:256
	v_pk_mul_f32 v[90:91], v[90:91], v[156:157] op_sel_hi:[1,0]
	v_pk_mul_f32 v[94:95], v[94:95], v[156:157] op_sel_hi:[1,0]
	v_mov_b32_e32 v116, v155
	v_or_b32_e32 v114, 16, v152
	v_pk_mul_f32 v[106:107], v[106:107], v[116:117] op_sel_hi:[1,0]
	v_ashrrev_i32_e32 v115, 31, v114
	v_pk_mul_f32 v[110:111], v[110:111], v[116:117] op_sel_hi:[1,0]
; __device__ __forceinline__ unsigned pk2(float lo, float hi) { unsigned r; asm("v_cvt_pk_bf16_f32 %0, %1, %2" : "=v"(r) : "v"(lo), "v"(hi)); return r; }
;     __device__ __forceinline__ void operator()(const f32x4 (&acc)[2][2][4][2], const Unit& u, int ui, int wr, int wc, int fr, int fq) const {
;     ...
;         for (int ai = 0; ai < 2; ++ai)
; #pragma unroll
;             for (int m = 0; m < 4; ++m) {
;                 const int row = row0 + ai * HALF + m * 16; const float rs = rsv[ai][m];
;                 bf16_t* rowp = O + (size_t)row * ldc + col0;
; #pragma unroll
;                 for (int bj = 0; bj < 2; ++bj) {
;                     f32x4 v0 = acc[ai][bj][m][0] * rs, v1 = acc[ai][bj][m][1] * rs;
;                     if (ACT == 1) {
; #pragma unroll
;                         for (int j = 0; j < 4; ++j) { const float a = fmaxf(v0[j], 0.f), b = fmaxf(v1[j], 0.f); v0[j] = a * a; v1[j] = b * b; }
;                     }
;                     u32x4 w; w.x = pk2(v0[0], v0[1]); w.y = pk2(v0[2], v0[3]); w.z = pk2(v1[0], v1[1]); w.w = pk2(v1[2], v1[3]);
;                     *(u32x4*)(rowp + bj * HALF) = w;
;                 }
	v_pk_mul_f32 v[108:109], v[108:109], v[116:117] op_sel_hi:[1,0]
	v_max_f32_e32 v106, 0, v106
	v_lshlrev_b64 v[114:115], 13, v[114:115]
	v_pk_mul_f32 v[112:113], v[112:113], v[116:117] op_sel_hi:[1,0]
	v_mul_f32_e32 v117, v106, v106
	v_max_f32_e32 v106, 0, v111
	v_max_f32_e32 v107, 0, v107
	v_max_f32_e32 v108, 0, v108
	v_lshl_add_u64 v[114:115], s[4:5], 0, v[114:115]
	v_max_f32_e32 v110, 0, v110
	v_mul_f32_e32 v106, v106, v106
	v_mul_f32_e32 v111, v107, v107
	v_max_f32_e32 v107, 0, v112
	v_mul_f32_e32 v112, v108, v108
	v_max_f32_e32 v108, 0, v113
	v_max_f32_e32 v109, 0, v109
	v_pk_mul_f32 v[98:99], v[98:99], v[116:117] op_sel_hi:[1,0]
	v_lshl_add_u64 v[114:115], v[114:115], 0, v[168:169]
	v_mul_f32_e32 v110, v110, v110
	v_mul_f32_e32 v107, v107, v107
	v_mul_f32_e32 v108, v108, v108
	v_mul_f32_e32 v109, v109, v109
	v_cvt_pk_bf16_f32 v106, v110, v106
	v_pk_mul_f32 v[102:103], v[102:103], v[116:117] op_sel_hi:[1,0]
	v_pk_mul_f32 v[100:101], v[100:101], v[116:117] op_sel_hi:[1,0]
	v_max_f32_e32 v98, 0, v98
	v_cvt_pk_bf16_f32 v107, v107, v108
	v_cvt_pk_bf16_f32 v108, v117, v111
	v_cvt_pk_bf16_f32 v109, v112, v109
	global_store_dwordx4 v[114:115], v[106:109], off
	v_pk_mul_f32 v[104:105], v[104:105], v[116:117] op_sel_hi:[1,0]
	v_max_f32_e32 v99, 0, v99
	v_mul_f32_e32 v106, v98, v98
	v_max_f32_e32 v98, 0, v103
	v_max_f32_e32 v100, 0, v100
	v_max_f32_e32 v102, 0, v102
	v_mul_f32_e32 v98, v98, v98
	v_mul_f32_e32 v103, v99, v99
	v_max_f32_e32 v99, 0, v104
	v_mul_f32_e32 v104, v100, v100
	v_max_f32_e32 v100, 0, v105
	v_max_f32_e32 v101, 0, v101
	v_mul_f32_e32 v102, v102, v102
	v_mul_f32_e32 v99, v99, v99
	v_mul_f32_e32 v100, v100, v100
	v_mul_f32_e32 v101, v101, v101
	v_cvt_pk_bf16_f32 v98, v102, v98
	v_cvt_pk_bf16_f32 v99, v99, v100
	v_cvt_pk_bf16_f32 v100, v106, v103
	v_cvt_pk_bf16_f32 v101, v104, v101
	global_store_dwordx4 v[114:115], v[98:101], off offset:256
	v_pk_mul_f32 v[92:93], v[92:93], v[156:157] op_sel_hi:[1,0]
	v_max_f32_e32 v90, 0, v90
	v_or_b32_e32 v98, 32, v152
	v_ashrrev_i32_e32 v99, 31, v98
	v_lshlrev_b64 v[98:99], 13, v[98:99]
	v_pk_mul_f32 v[96:97], v[96:97], v[156:157] op_sel_hi:[1,0]
	v_mul_f32_e32 v100, v90, v90
	v_max_f32_e32 v90, 0, v95
	v_max_f32_e32 v91, 0, v91
	v_max_f32_e32 v92, 0, v92
	v_lshl_add_u64 v[98:99], s[4:5], 0, v[98:99]
	v_max_f32_e32 v94, 0, v94
	v_mul_f32_e32 v90, v90, v90
	v_mul_f32_e32 v95, v91, v91
	v_max_f32_e32 v91, 0, v96
	v_mul_f32_e32 v96, v92, v92
	v_max_f32_e32 v92, 0, v97
	v_max_f32_e32 v93, 0, v93
	v_pk_mul_f32 v[84:85], v[84:85], v[156:157] op_sel_hi:[1,0]
	v_pk_mul_f32 v[82:83], v[82:83], v[156:157] op_sel_hi:[1,0]
	v_lshl_add_u64 v[98:99], v[98:99], 0, v[168:169]
	v_mul_f32_e32 v94, v94, v94
	v_mul_f32_e32 v91, v91, v91
	v_mul_f32_e32 v92, v92, v92
	v_mul_f32_e32 v93, v93, v93
	v_cvt_pk_bf16_f32 v90, v94, v90
	v_pk_mul_f32 v[88:89], v[88:89], v[156:157] op_sel_hi:[1,0]
	v_pk_mul_f32 v[86:87], v[86:87], v[156:157] op_sel_hi:[1,0]
	v_max_f32_e32 v82, 0, v82
	v_max_f32_e32 v83, 0, v83
	v_max_f32_e32 v84, 0, v84
	v_cvt_pk_bf16_f32 v91, v91, v92
	v_cvt_pk_bf16_f32 v92, v100, v95
	v_cvt_pk_bf16_f32 v93, v96, v93
	global_store_dwordx4 v[98:99], v[90:93], off
	v_max_f32_e32 v85, 0, v85
	v_max_f32_e32 v86, 0, v86
	v_mul_f32_e32 v90, v82, v82
	v_max_f32_e32 v82, 0, v87
	v_mul_f32_e32 v87, v83, v83
	v_max_f32_e32 v83, 0, v88
	v_mul_f32_e32 v88, v84, v84
	v_max_f32_e32 v84, 0, v89
	v_mul_f32_e32 v83, v83, v83
	v_mul_f32_e32 v84, v84, v84
	v_mul_f32_e32 v82, v82, v82
	v_mul_f32_e32 v85, v85, v85
	v_cvt_pk_bf16_f32 v83, v83, v84
	v_cvt_pk_bf16_f32 v84, v90, v87
	v_mul_f32_e32 v86, v86, v86
	v_cvt_pk_bf16_f32 v82, v86, v82
	v_cvt_pk_bf16_f32 v85, v88, v85
	global_store_dwordx4 v[98:99], v[82:85], off offset:256
	v_pk_mul_f32 v[58:59], v[58:59], v[144:145] op_sel_hi:[1,0]
	v_pk_mul_f32 v[62:63], v[62:63], v[144:145] op_sel_hi:[1,0]
	v_mov_b32_e32 v84, v157
	v_or_b32_e32 v82, 48, v152
	v_pk_mul_f32 v[74:75], v[74:75], v[84:85] op_sel_hi:[1,0]
	v_ashrrev_i32_e32 v83, 31, v82
	v_pk_mul_f32 v[78:79], v[78:79], v[84:85] op_sel_hi:[1,0]
	v_pk_mul_f32 v[76:77], v[76:77], v[84:85] op_sel_hi:[1,0]
	v_max_f32_e32 v74, 0, v74
	v_lshlrev_b64 v[82:83], 13, v[82:83]
	v_pk_mul_f32 v[80:81], v[80:81], v[84:85] op_sel_hi:[1,0]
	v_mul_f32_e32 v85, v74, v74
	v_max_f32_e32 v74, 0, v79
	v_max_f32_e32 v75, 0, v75
	v_max_f32_e32 v76, 0, v76
	v_lshl_add_u64 v[82:83], s[4:5], 0, v[82:83]
	v_max_f32_e32 v78, 0, v78
	v_mul_f32_e32 v74, v74, v74
	v_mul_f32_e32 v79, v75, v75
	v_max_f32_e32 v75, 0, v80
	v_mul_f32_e32 v80, v76, v76
	v_max_f32_e32 v76, 0, v81
	v_max_f32_e32 v77, 0, v77
	v_pk_mul_f32 v[68:69], v[68:69], v[84:85] op_sel_hi:[1,0]
	v_pk_mul_f32 v[66:67], v[66:67], v[84:85] op_sel_hi:[1,0]
	v_lshl_add_u64 v[82:83], v[82:83], 0, v[168:169]
	v_mul_f32_e32 v78, v78, v78
	v_mul_f32_e32 v75, v75, v75
	v_mul_f32_e32 v76, v76, v76
	v_mul_f32_e32 v77, v77, v77
	v_cvt_pk_bf16_f32 v74, v78, v74
	v_pk_mul_f32 v[72:73], v[72:73], v[84:85] op_sel_hi:[1,0]
	v_pk_mul_f32 v[70:71], v[70:71], v[84:85] op_sel_hi:[1,0]
	v_max_f32_e32 v66, 0, v66
	v_max_f32_e32 v67, 0, v67
	v_max_f32_e32 v68, 0, v68
	v_cvt_pk_bf16_f32 v75, v75, v76
	v_cvt_pk_bf16_f32 v76, v85, v79
	v_cvt_pk_bf16_f32 v77, v80, v77
	global_store_dwordx4 v[82:83], v[74:77], off
	v_max_f32_e32 v69, 0, v69
	v_max_f32_e32 v70, 0, v70
	v_mul_f32_e32 v74, v66, v66
	v_max_f32_e32 v66, 0, v71
	v_mul_f32_e32 v71, v67, v67
	v_max_f32_e32 v67, 0, v72
	v_mul_f32_e32 v72, v68, v68
	v_max_f32_e32 v68, 0, v73
	v_mul_f32_e32 v67, v67, v67
	v_mul_f32_e32 v68, v68, v68
	v_mul_f32_e32 v66, v66, v66
	v_mul_f32_e32 v69, v69, v69
	v_cvt_pk_bf16_f32 v67, v67, v68
	v_cvt_pk_bf16_f32 v68, v74, v71
; __device__ __forceinline__ unsigned pk2(float lo, float hi) { unsigned r; asm("v_cvt_pk_bf16_f32 %0, %1, %2" : "=v"(r) : "v"(lo), "v"(hi)); return r; }
;     __device__ __forceinline__ void operator()(const f32x4 (&acc)[2][2][4][2], const Unit& u, int ui, int wr, int wc, int fr, int fq) const {
;     ...
;         for (int ai = 0; ai < 2; ++ai)
; #pragma unroll
;             for (int m = 0; m < 4; ++m) {
;                 const int row = row0 + ai * HALF + m * 16; const float rs = rsv[ai][m];
;                 bf16_t* rowp = O + (size_t)row * ldc + col0;
; #pragma unroll
;                 for (int bj = 0; bj < 2; ++bj) {
;                     f32x4 v0 = acc[ai][bj][m][0] * rs, v1 = acc[ai][bj][m][1] * rs;
;                     if (ACT == 1) {
; #pragma unroll
;                         for (int j = 0; j < 4; ++j) { const float a = fmaxf(v0[j], 0.f), b = fmaxf(v1[j], 0.f); v0[j] = a * a; v1[j] = b * b; }
;                     }
;                     u32x4 w; w.x = pk2(v0[0], v0[1]); w.y = pk2(v0[2], v0[3]); w.z = pk2(v1[0], v1[1]); w.w = pk2(v1[2], v1[3]);
;                     *(u32x4*)(rowp + bj * HALF) = w;
;                 }
	v_pk_mul_f32 v[60:61], v[60:61], v[144:145] op_sel_hi:[1,0]
	v_max_f32_e32 v58, 0, v58
	v_mul_f32_e32 v70, v70, v70
	v_cvt_pk_bf16_f32 v66, v70, v66
	v_cvt_pk_bf16_f32 v69, v72, v69
	global_store_dwordx4 v[82:83], v[66:69], off offset:256
	s_mov_b64 s[6:7], 0x100000
	v_pk_mul_f32 v[64:65], v[64:65], v[144:145] op_sel_hi:[1,0]
	v_max_f32_e32 v62, 0, v62
	v_mul_f32_e32 v68, v58, v58
	v_max_f32_e32 v58, 0, v63
	v_max_f32_e32 v59, 0, v59
	v_max_f32_e32 v60, 0, v60
	v_lshl_add_u64 v[66:67], v[140:141], 0, s[6:7]
	v_mul_f32_e32 v62, v62, v62
	v_mul_f32_e32 v58, v58, v58
	v_mul_f32_e32 v63, v59, v59
	v_max_f32_e32 v59, 0, v64
	v_mul_f32_e32 v64, v60, v60
	v_max_f32_e32 v60, 0, v65
	s_mov_b32 s6, 0x100000
	v_mul_f32_e32 v59, v59, v59
	v_max_f32_e32 v61, 0, v61
	v_mul_f32_e32 v60, v60, v60
	v_cvt_pk_bf16_f32 v58, v62, v58
	v_add_co_u32_e32 v62, vcc, s6, v140
	v_pk_mul_f32 v[52:53], v[52:53], v[144:145] op_sel_hi:[1,0]
	v_pk_mul_f32 v[50:51], v[50:51], v[144:145] op_sel_hi:[1,0]
	v_mul_f32_e32 v61, v61, v61
	v_cvt_pk_bf16_f32 v59, v59, v60
	v_cvt_pk_bf16_f32 v60, v68, v63
	v_addc_co_u32_e32 v63, vcc, 0, v141, vcc
	v_pk_mul_f32 v[56:57], v[56:57], v[144:145] op_sel_hi:[1,0]
	v_pk_mul_f32 v[54:55], v[54:55], v[144:145] op_sel_hi:[1,0]
	v_max_f32_e32 v50, 0, v50
	v_max_f32_e32 v51, 0, v51
	v_max_f32_e32 v52, 0, v52
	v_cvt_pk_bf16_f32 v61, v64, v61
	v_mov_b32_e32 v158, v58
	v_mov_b32_e32 v159, v59
	v_mov_b32_e32 v160, v60
	v_mov_b32_e32 v161, v61
	v_max_f32_e32 v53, 0, v53
	v_max_f32_e32 v54, 0, v54
	v_mul_f32_e32 v58, v50, v50
	v_max_f32_e32 v50, 0, v55
	v_mul_f32_e32 v55, v51, v51
	v_max_f32_e32 v51, 0, v56
	v_mul_f32_e32 v56, v52, v52
	v_max_f32_e32 v52, 0, v57
	v_mul_f32_e32 v51, v51, v51
	v_mul_f32_e32 v52, v52, v52
	v_mul_f32_e32 v50, v50, v50
	v_mul_f32_e32 v53, v53, v53
	v_cvt_pk_bf16_f32 v51, v51, v52
	v_cvt_pk_bf16_f32 v52, v58, v55
	v_mul_f32_e32 v54, v54, v54
	v_cvt_pk_bf16_f32 v50, v54, v50
	v_cvt_pk_bf16_f32 v53, v56, v53
	v_mov_b32_e32 v164, v50
	v_mov_b32_e32 v165, v51
	v_mov_b32_e32 v166, v52
	v_mov_b32_e32 v167, v53
	s_mov_b64 s[6:7], 0x120000
	v_pk_mul_f32 v[26:27], v[26:27], v[142:143] op_sel_hi:[1,0]
	v_mov_b32_e32 v52, v145
	v_pk_mul_f32 v[42:43], v[42:43], v[52:53] op_sel_hi:[1,0]
	v_pk_mul_f32 v[46:47], v[46:47], v[52:53] op_sel_hi:[1,0]
	v_pk_mul_f32 v[44:45], v[44:45], v[52:53] op_sel_hi:[1,0]
	v_max_f32_e32 v42, 0, v42
	v_pk_mul_f32 v[48:49], v[48:49], v[52:53] op_sel_hi:[1,0]
	v_max_f32_e32 v46, 0, v46
	v_mul_f32_e32 v53, v42, v42
	v_max_f32_e32 v42, 0, v47
	v_max_f32_e32 v43, 0, v43
	v_max_f32_e32 v44, 0, v44
	v_lshl_add_u64 v[50:51], v[140:141], 0, s[6:7]
	v_mul_f32_e32 v46, v46, v46
	v_mul_f32_e32 v42, v42, v42
	v_mul_f32_e32 v47, v43, v43
	v_max_f32_e32 v43, 0, v48
	v_mul_f32_e32 v48, v44, v44
	v_max_f32_e32 v44, 0, v49
	s_mov_b32 s6, 0x120000
	v_mul_f32_e32 v43, v43, v43
	v_max_f32_e32 v45, 0, v45
	v_mul_f32_e32 v44, v44, v44
	v_cvt_pk_bf16_f32 v42, v46, v42
	v_add_co_u32_e32 v46, vcc, s6, v140
	v_pk_mul_f32 v[36:37], v[36:37], v[52:53] op_sel_hi:[1,0]
	v_pk_mul_f32 v[34:35], v[34:35], v[52:53] op_sel_hi:[1,0]
	v_mul_f32_e32 v45, v45, v45
	v_cvt_pk_bf16_f32 v43, v43, v44
	v_cvt_pk_bf16_f32 v44, v53, v47
	v_addc_co_u32_e32 v47, vcc, 0, v141, vcc
	v_pk_mul_f32 v[40:41], v[40:41], v[52:53] op_sel_hi:[1,0]
	v_pk_mul_f32 v[38:39], v[38:39], v[52:53] op_sel_hi:[1,0]
	v_max_f32_e32 v34, 0, v34
	v_max_f32_e32 v35, 0, v35
	v_max_f32_e32 v36, 0, v36
	v_cvt_pk_bf16_f32 v45, v48, v45
	v_mov_b32_e32 v188, v42
	v_mov_b32_e32 v189, v43
	v_mov_b32_e32 v190, v44
	v_mov_b32_e32 v191, v45
	v_max_f32_e32 v37, 0, v37
	v_max_f32_e32 v38, 0, v38
	v_mul_f32_e32 v42, v34, v34
	v_max_f32_e32 v34, 0, v39
	v_mul_f32_e32 v39, v35, v35
	v_max_f32_e32 v35, 0, v40
	v_mul_f32_e32 v40, v36, v36
	v_max_f32_e32 v36, 0, v41
	v_mul_f32_e32 v35, v35, v35
	v_mul_f32_e32 v36, v36, v36
	v_mul_f32_e32 v34, v34, v34
	v_mul_f32_e32 v37, v37, v37
	v_cvt_pk_bf16_f32 v35, v35, v36
	v_cvt_pk_bf16_f32 v36, v42, v39
	v_pk_mul_f32 v[30:31], v[30:31], v[142:143] op_sel_hi:[1,0]
	v_pk_mul_f32 v[28:29], v[28:29], v[142:143] op_sel_hi:[1,0]
	v_max_f32_e32 v26, 0, v26
	v_mul_f32_e32 v38, v38, v38
	v_cvt_pk_bf16_f32 v34, v38, v34
	v_cvt_pk_bf16_f32 v37, v40, v37
	v_mov_b32_e32 v192, v34
	v_mov_b32_e32 v193, v35
	v_mov_b32_e32 v194, v36
	v_mov_b32_e32 v195, v37
	s_mov_b64 s[6:7], 0x140000
	v_pk_mul_f32 v[32:33], v[32:33], v[142:143] op_sel_hi:[1,0]
	v_max_f32_e32 v30, 0, v30
	v_mul_f32_e32 v36, v26, v26
	v_max_f32_e32 v26, 0, v31
	v_max_f32_e32 v27, 0, v27
	v_max_f32_e32 v28, 0, v28
	v_lshl_add_u64 v[34:35], v[140:141], 0, s[6:7]
	v_mul_f32_e32 v30, v30, v30
	v_mul_f32_e32 v26, v26, v26
	v_mul_f32_e32 v31, v27, v27
	v_max_f32_e32 v27, 0, v32
	v_mul_f32_e32 v32, v28, v28
	v_max_f32_e32 v28, 0, v33
	s_mov_b32 s6, 0x140000
	v_mul_f32_e32 v27, v27, v27
	v_max_f32_e32 v29, 0, v29
	v_mul_f32_e32 v28, v28, v28
; __device__ __forceinline__ unsigned pk2(float lo, float hi) { unsigned r; asm("v_cvt_pk_bf16_f32 %0, %1, %2" : "=v"(r) : "v"(lo), "v"(hi)); return r; }
; #define PG8_WAIT_V(n) asm volatile("s_waitcnt vmcnt(" #n ")" ::: "memory")
; #define PG8_BAR __builtin_amdgcn_s_barrier()
;     __device__ __forceinline__ void operator()(const f32x4 (&acc)[2][2][4][2], const Unit& u, int ui, int wr, int wc, int fr, int fq) const {
;     ...
;                 const int row = row0 + ai * HALF + m * 16; const float rs = rsv[ai][m];
;                 bf16_t* rowp = O + (size_t)row * ldc + col0;
; #pragma unroll
;                 for (int bj = 0; bj < 2; ++bj) {
;                     f32x4 v0 = acc[ai][bj][m][0] * rs, v1 = acc[ai][bj][m][1] * rs;
;                     if (ACT == 1) {
; #pragma unroll
;                         for (int j = 0; j < 4; ++j) { const float a = fmaxf(v0[j], 0.f), b = fmaxf(v1[j], 0.f); v0[j] = a * a; v1[j] = b * b; }
;                     }
;                     u32x4 w; w.x = pk2(v0[0], v0[1]); w.y = pk2(v0[2], v0[3]); w.z = pk2(v1[0], v1[1]); w.w = pk2(v1[2], v1[3]);
;                     *(u32x4*)(rowp + bj * HALF) = w;
;                 }
; template <class Epi>
; __device__ __forceinline__ void gemm_phase(LAS unsigned char* lds, const Gemm g, const StaticOrder& S, const Epi& E) {
;     ...
;         if (!has_next) break;
; #pragma unroll
;         for (int a = 0; a < 2; ++a)
; #pragma unroll
;             for (int b = 0; b < 2; ++b)
; #pragma unroll
;                 for (int m = 0; m < 4; ++m)
; #pragma unroll
;                     for (int n = 0; n < 2; ++n) acc[a][b][m][n] = (f32x4){0.f, 0.f, 0.f, 0.f};
;         cur = nxt; cA = nA; cB = nB; ++ui;
;     }
;     PG8_WAIT_V(0);
;     if (wr == 0) PG8_BAR;
;     PG8_BAR;
	v_cvt_pk_bf16_f32 v26, v30, v26
	v_add_co_u32_e32 v30, vcc, s6, v140
	v_pk_mul_f32 v[20:21], v[20:21], v[142:143] op_sel_hi:[1,0]
	v_pk_mul_f32 v[18:19], v[18:19], v[142:143] op_sel_hi:[1,0]
	v_mul_f32_e32 v29, v29, v29
	v_cvt_pk_bf16_f32 v27, v27, v28
	v_cvt_pk_bf16_f32 v28, v36, v31
	v_addc_co_u32_e32 v31, vcc, 0, v141, vcc
	v_pk_mul_f32 v[24:25], v[24:25], v[142:143] op_sel_hi:[1,0]
	v_pk_mul_f32 v[22:23], v[22:23], v[142:143] op_sel_hi:[1,0]
	v_max_f32_e32 v18, 0, v18
	v_max_f32_e32 v19, 0, v19
	v_max_f32_e32 v20, 0, v20
	v_cvt_pk_bf16_f32 v29, v32, v29
	v_mov_b32_e32 v196, v26
	v_mov_b32_e32 v197, v27
	v_mov_b32_e32 v198, v28
	v_mov_b32_e32 v199, v29
	v_max_f32_e32 v21, 0, v21
	v_max_f32_e32 v22, 0, v22
	v_mul_f32_e32 v26, v18, v18
	v_max_f32_e32 v18, 0, v23
	v_mul_f32_e32 v23, v19, v19
	v_max_f32_e32 v19, 0, v24
	v_mul_f32_e32 v24, v20, v20
	v_max_f32_e32 v20, 0, v25
	v_mul_f32_e32 v19, v19, v19
	v_mul_f32_e32 v20, v20, v20
	v_mul_f32_e32 v18, v18, v18
	v_mul_f32_e32 v21, v21, v21
	v_cvt_pk_bf16_f32 v19, v19, v20
	v_cvt_pk_bf16_f32 v20, v26, v23
	v_mul_f32_e32 v22, v22, v22
	v_cvt_pk_bf16_f32 v18, v22, v18
	v_cvt_pk_bf16_f32 v21, v24, v21
	v_mov_b32_e32 v200, v18
	v_mov_b32_e32 v201, v19
	v_mov_b32_e32 v202, v20
	v_mov_b32_e32 v203, v21
	s_mov_b64 s[6:7], 0x160000
	s_mov_b32 s87, s8
	v_mov_b32_e32 v20, v143
	v_pk_mul_f32 v[10:11], v[10:11], v[20:21] op_sel_hi:[1,0]
	v_pk_mul_f32 v[14:15], v[14:15], v[20:21] op_sel_hi:[1,0]
	v_pk_mul_f32 v[12:13], v[12:13], v[20:21] op_sel_hi:[1,0]
	v_max_f32_e32 v10, 0, v10
	v_pk_mul_f32 v[16:17], v[16:17], v[20:21] op_sel_hi:[1,0]
	v_max_f32_e32 v14, 0, v14
	v_mul_f32_e32 v21, v10, v10
	v_max_f32_e32 v10, 0, v15
	v_max_f32_e32 v11, 0, v11
	v_max_f32_e32 v12, 0, v12
	v_lshl_add_u64 v[18:19], v[140:141], 0, s[6:7]
	v_mul_f32_e32 v14, v14, v14
	v_mul_f32_e32 v10, v10, v10
	v_mul_f32_e32 v15, v11, v11
	v_max_f32_e32 v11, 0, v16
	v_mul_f32_e32 v16, v12, v12
	v_max_f32_e32 v12, 0, v17
	s_mov_b32 s6, 0x160000
	v_mul_f32_e32 v11, v11, v11
	v_max_f32_e32 v13, 0, v13
	v_mul_f32_e32 v12, v12, v12
	v_cvt_pk_bf16_f32 v10, v14, v10
	v_add_co_u32_e32 v14, vcc, s6, v140
	v_pk_mul_f32 v[4:5], v[4:5], v[20:21] op_sel_hi:[1,0]
	v_pk_mul_f32 v[2:3], v[2:3], v[20:21] op_sel_hi:[1,0]
	v_mul_f32_e32 v13, v13, v13
	v_cvt_pk_bf16_f32 v11, v11, v12
	v_cvt_pk_bf16_f32 v12, v21, v15
	v_addc_co_u32_e32 v15, vcc, 0, v141, vcc
	v_pk_mul_f32 v[8:9], v[8:9], v[20:21] op_sel_hi:[1,0]
	v_pk_mul_f32 v[6:7], v[6:7], v[20:21] op_sel_hi:[1,0]
	v_max_f32_e32 v2, 0, v2
	v_max_f32_e32 v3, 0, v3
	v_max_f32_e32 v4, 0, v4
	v_cvt_pk_bf16_f32 v13, v16, v13
	v_mov_b32_e32 v222, v10
	v_mov_b32_e32 v223, v11
	v_mov_b32_e32 v224, v12
	v_mov_b32_e32 v225, v13
	v_max_f32_e32 v5, 0, v5
	v_max_f32_e32 v6, 0, v6
	v_mul_f32_e32 v10, v2, v2
	v_max_f32_e32 v2, 0, v7
	v_mul_f32_e32 v7, v3, v3
	v_max_f32_e32 v3, 0, v8
	v_mul_f32_e32 v8, v4, v4
	v_max_f32_e32 v4, 0, v9
	v_mul_f32_e32 v2, v2, v2
	v_mul_f32_e32 v3, v3, v3
	v_mul_f32_e32 v4, v4, v4
	v_mul_f32_e32 v5, v5, v5
	s_and_b64 vcc, exec, s[40:41]
	s_mov_b32 s88, s10
	s_mov_b64 s[6:7], s[24:25]
	s_mov_b64 s[36:37], s[12:13]
	s_mov_b32 s89, s86
	v_mul_f32_e32 v6, v6, v6
	v_cvt_pk_bf16_f32 v2, v6, v2
	v_cvt_pk_bf16_f32 v3, v3, v4
	v_cvt_pk_bf16_f32 v4, v10, v7
	v_cvt_pk_bf16_f32 v5, v8, v5
	v_mov_b32_e32 v246, v2
	v_mov_b32_e32 v247, v3
	v_mov_b32_e32 v248, v4
	v_mov_b32_e32 v249, v5
	s_cbranch_vccz .LBB0_163
	global_store_dwordx4 v250, v[158:161], s[4:5]
	global_store_dwordx4 v250, v[164:167], s[4:5] offset:256
	s_nop 1
	v_add_u32_e32 v250, 0x20000, v250
	global_store_dwordx4 v250, v[188:191], s[4:5]
	global_store_dwordx4 v250, v[192:195], s[4:5] offset:256
	s_nop 1
	v_add_u32_e32 v250, 0x20000, v250
	global_store_dwordx4 v250, v[196:199], s[4:5]
	global_store_dwordx4 v250, v[200:203], s[4:5] offset:256
	s_nop 1
	v_add_u32_e32 v250, 0x20000, v250
	global_store_dwordx4 v250, v[222:225], s[4:5]
	global_store_dwordx4 v250, v[246:249], s[4:5] offset:256
	s_nop 1
	v_mov_b64_e32 v[164:165], 0x200
	v_mbcnt_lo_u32_b32 v193, -1, 0
	v_mbcnt_hi_u32_b32 v193, -1, v193
	v_add_u32_e32 v167, s18, v193
	v_mov_b32_e32 v188, 1
	v_mov_b32_e32 v189, 0x358637bd
	v_mov_b32_e32 v190, 0x260
	v_mov_b32_e32 v191, 0x3c0881c4
	v_mov_b32_e32 v192, 0xbab64f3b
	v_mov_b32_e32 v194, 0xf149f2ca
	v_mov_b32_e32 v195, 0xc0
	v_mov_b32_e32 v196, 0x70
	v_mov_b32_e32 v197, 0x71
	v_mov_b32_e32 v198, 5
	v_mov_b32_e32 v199, 2
	v_mov_b32_e32 v200, 3
	v_not_b32_e32 v201, 63
	v_not_b32_e32 v202, 31
	v_mov_b32_e32 v203, 0x7fc00000
	v_mov_b32_e32 v222, 0
	v_mov_b32_e32 v223, 0
	v_mov_b32_e32 v224, 0
	v_mov_b32_e32 v225, 0
	s_waitcnt vmcnt(0)
	v_readlane_b32 s70, v254, 40
	v_readlane_b32 s84, v254, 42
	s_cmpk_gt_u32 s18, 0xff
	v_readlane_b32 s71, v254, 41
	v_readlane_b32 s86, v254, 44
	v_readlane_b32 s87, v254, 45
	v_readlane_b32 s85, v254, 43
	s_cbranch_scc1 .LBB0_174
	s_barrier

; #define PG8_STAGE(bufoff, gbase, voff) do { _Pragma("unroll") for (int _i = 0; _i < 2; ++_i) \
;         __builtin_amdgcn_global_load_lds((const unsigned*)((const char*)(gbase) + (voff)[_i]), (LAS unsigned*)(lds + (bufoff) + ldsw + _i * 8192), 16, 0, 0); } while (0)
; #define PG8_LDA(dst, b, h) do { _Pragma("unroll") for (int m = 0; m < 4; ++m) _Pragma("unroll") for (int k = 0; k < 2; ++k) dst[m][k] = *(const LAS bf16x8*)(lds + PG8_SA(b, h) + aoff + m * 2048 + k * 1024); } while (0)
; #define PG8_LDB(dst, b, h) do { _Pragma("unroll") for (int n = 0; n < 2; ++n) _Pragma("unroll") for (int k = 0; k < 2; ++k) dst[n][k] = *(const LAS bf16x8*)(lds + PG8_SB(b, h) + boff + n * 2048 + k * 1024); } while (0)
; #define PG8_MMA(ai, bj, At, Bt) do { __builtin_amdgcn_s_setprio(1); _Pragma("unroll") for (int m = 0; m < 4; ++m) _Pragma("unroll") for (int n = 0; n < 2; ++n) _Pragma("unroll") for (int k = 0; k < 2; ++k) \
;         acc[ai][bj][m][n] = __builtin_amdgcn_mfma_f32_16x16x32_bf16(Bt[n][k], At[m][k], acc[ai][bj][m][n], 0, 0, 0); __builtin_amdgcn_s_setprio(0); } while (0)
; #define PG8_WAIT_V(n) asm volatile("s_waitcnt vmcnt(" #n ")" ::: "memory")
; #define PG8_WAIT_L(n) asm volatile("s_waitcnt lgkmcnt(" #n ")" ::: "memory")
; #define PG8_BAR __builtin_amdgcn_s_barrier()
; #define PG8_SCHED __builtin_amdgcn_sched_barrier(0)
; template <class Epi>
; __device__ __forceinline__ void gemm_phase(LAS unsigned char* lds, const Gemm g, const StaticOrder& S, const Epi& E) {
;     ...
;             PG8_LDB(B0, 0, 0); PG8_SCHED; PG8_LDA(At, 0, 0); PG8_STAGE(PG8_SA(1, 1), a1 + hstep, voffA);
;             PG8_WAIT_L(8); PG8_BAR; PG8_WAIT_L(0); PG8_MMA(0, 0, At, B0); PG8_BAR; PG8_SCHED;
;             PG8_LDB(B1, 0, 1); PG8_STAGE(PG8_SB(0, 0), b2, voffB);
;             PG8_BAR; PG8_WAIT_L(0); PG8_MMA(0, 1, At, B1); PG8_BAR;
;             PG8_LDA(At, 0, 1); PG8_STAGE(PG8_SA(0, 0), a2, voffA);
;             PG8_BAR; PG8_WAIT_L(0); PG8_MMA(1, 0, At, B0); PG8_BAR; PG8_SCHED;
;             PG8_STAGE(PG8_SB(0, 1), b2 + hstep, voffB);
;             PG8_WAIT_V(6); PG8_BAR; PG8_MMA(1, 1, At, B1); PG8_BAR;
;     ...
;         for (int a = 0; a < 2; ++a)
; #pragma unroll
;             for (int b = 0; b < 2; ++b)
; #pragma unroll
;                 for (int m = 0; m < 4; ++m)
; #pragma unroll
;                     for (int n = 0; n < 2; ++n) acc[a][b][m][n] = (f32x4){0.f, 0.f, 0.f, 0.f};
.LBB0_463:
	s_add_u32 s6, s24, 0xfffc0080
	s_addc_u32 s7, s25, -1
	s_add_i32 s58, 0, 0x10000
	v_add_u32_e32 v153, s58, v149
	ds_read_b128 v[140:143], v153
	ds_read_b128 v[144:147], v153 offset:1024
	ds_read_b128 v[154:157], v153 offset:2048
	ds_read_b128 v[158:161], v153 offset:3072
	s_cmp_eq_u32 s91, 12
	s_cselect_b32 s37, s11, s7
	s_cselect_b32 s36, s71, s6
	s_cselect_b32 s7, s9, s90
	s_cselect_b32 s6, s88, s89
	s_add_i32 m0, s47, 0xc000
	ds_read_b128 v[168:171], v152
	ds_read_b128 v[172:175], v152 offset:1024
	ds_read_b128 v[176:179], v152 offset:2048
	ds_read_b128 v[180:183], v152 offset:3072
	ds_read_b128 v[184:187], v152 offset:4096
	ds_read_b128 v[204:207], v152 offset:5120
	ds_read_b128 v[208:211], v152 offset:6144
	ds_read_b128 v[212:215], v152 offset:7168
	global_load_lds_dwordx4 v136, s[24:25]
	s_add_i32 m0, s47, 0xe000
	s_nop 0
	global_load_lds_dwordx4 v138, s[24:25]
	s_waitcnt lgkmcnt(8)
	s_barrier
	s_waitcnt lgkmcnt(0)
	s_setprio 1
	s_waitcnt lgkmcnt(0)
	v_mfma_f32_16x16x32_bf16 v[126:129], v[140:143], v[168:171], 0
	v_mfma_f32_16x16x32_bf16 v[122:125], v[154:157], v[168:171], 0
	v_mfma_f32_16x16x32_bf16 v[114:117], v[140:143], v[176:179], 0
	v_mfma_f32_16x16x32_bf16 v[106:109], v[154:157], v[176:179], 0
	v_mfma_f32_16x16x32_bf16 v[98:101], v[140:143], v[184:187], 0
	v_mfma_f32_16x16x32_bf16 v[90:93], v[154:157], v[184:187], 0
	v_mfma_f32_16x16x32_bf16 v[82:85], v[140:143], v[208:211], 0
	v_mfma_f32_16x16x32_bf16 v[74:77], v[154:157], v[208:211], 0
	v_mfma_f32_16x16x32_bf16 v[126:129], v[144:147], v[172:175], v[126:129]
	v_mfma_f32_16x16x32_bf16 v[122:125], v[158:161], v[172:175], v[122:125]
	v_mfma_f32_16x16x32_bf16 v[114:117], v[144:147], v[180:183], v[114:117]
	v_mfma_f32_16x16x32_bf16 v[106:109], v[158:161], v[180:183], v[106:109]
	v_mfma_f32_16x16x32_bf16 v[98:101], v[144:147], v[204:207], v[98:101]
	v_mfma_f32_16x16x32_bf16 v[90:93], v[158:161], v[204:207], v[90:93]
	v_mfma_f32_16x16x32_bf16 v[82:85], v[144:147], v[212:215], v[82:85]
	v_mfma_f32_16x16x32_bf16 v[74:77], v[158:161], v[212:215], v[74:77]
	s_setprio 0
	s_barrier
	s_add_i32 s70, 0, 0x14000
	s_add_i32 s58, s58, s44
	v_add_u32_e32 v153, s70, v149
	s_mov_b32 m0, s58
	ds_read_b128 v[216:219], v153
	ds_read_b128 v[226:229], v153 offset:1024
	ds_read_b128 v[230:233], v153 offset:2048
	ds_read_b128 v[234:237], v153 offset:3072
	global_load_lds_dwordx4 v0, s[6:7]
	s_add_i32 m0, s58, 0x2000
	s_nop 0
	global_load_lds_dwordx4 v130, s[6:7]
	s_barrier
	s_waitcnt lgkmcnt(0)
	s_setprio 1
	s_waitcnt lgkmcnt(0)
	v_mfma_f32_16x16x32_bf16 v[118:121], v[216:219], v[168:171], 0
	v_mfma_f32_16x16x32_bf16 v[110:113], v[230:233], v[168:171], 0
	v_mfma_f32_16x16x32_bf16 v[102:105], v[216:219], v[176:179], 0
	v_mfma_f32_16x16x32_bf16 v[94:97], v[230:233], v[176:179], 0
	v_mfma_f32_16x16x32_bf16 v[86:89], v[216:219], v[184:187], 0
	v_mfma_f32_16x16x32_bf16 v[78:81], v[230:233], v[184:187], 0
	v_mfma_f32_16x16x32_bf16 v[70:73], v[216:219], v[208:211], 0
	v_mfma_f32_16x16x32_bf16 v[66:69], v[230:233], v[208:211], 0
	v_mfma_f32_16x16x32_bf16 v[118:121], v[226:229], v[172:175], v[118:121]
	v_mfma_f32_16x16x32_bf16 v[110:113], v[234:237], v[172:175], v[110:113]
	v_mfma_f32_16x16x32_bf16 v[102:105], v[226:229], v[180:183], v[102:105]
	v_mfma_f32_16x16x32_bf16 v[94:97], v[234:237], v[180:183], v[94:97]
	v_mfma_f32_16x16x32_bf16 v[86:89], v[226:229], v[204:207], v[86:89]
	v_mfma_f32_16x16x32_bf16 v[78:81], v[234:237], v[204:207], v[78:81]
	v_mfma_f32_16x16x32_bf16 v[70:73], v[226:229], v[212:215], v[70:73]
	v_mfma_f32_16x16x32_bf16 v[66:69], v[234:237], v[212:215], v[66:69]
	s_setprio 0
	s_mov_b32 m0, s47
	s_add_u32 vcc_lo, s36, 0x80
	s_addc_u32 vcc_hi, s37, 0
	s_barrier
	ds_read_b128 v[168:171], v152 offset:16384
	ds_read_b128 v[172:175], v152 offset:17408
	ds_read_b128 v[176:179], v152 offset:18432
	ds_read_b128 v[180:183], v152 offset:19456
	ds_read_b128 v[184:187], v152 offset:20480
	ds_read_b128 v[204:207], v152 offset:21504
	ds_read_b128 v[208:211], v152 offset:22528
	ds_read_b128 v[212:215], v152 offset:23552
	global_load_lds_dwordx4 v134, s[36:37]
	s_mov_b32 m0, s48
	s_nop 0
	global_load_lds_dwordx4 v132, s[36:37]
	s_barrier
	s_waitcnt lgkmcnt(0)
	s_setprio 1
	s_waitcnt lgkmcnt(0)
	v_mfma_f32_16x16x32_bf16 v[62:65], v[140:143], v[168:171], 0
	v_mfma_f32_16x16x32_bf16 v[58:61], v[154:157], v[168:171], 0
	v_mfma_f32_16x16x32_bf16 v[50:53], v[140:143], v[176:179], 0
	v_mfma_f32_16x16x32_bf16 v[42:45], v[154:157], v[176:179], 0
	v_mfma_f32_16x16x32_bf16 v[34:37], v[140:143], v[184:187], 0
	v_mfma_f32_16x16x32_bf16 v[26:29], v[154:157], v[184:187], 0
	v_mfma_f32_16x16x32_bf16 v[18:21], v[140:143], v[208:211], 0
	v_mfma_f32_16x16x32_bf16 v[10:13], v[154:157], v[208:211], 0
	v_mfma_f32_16x16x32_bf16 v[62:65], v[144:147], v[172:175], v[62:65]
	v_mfma_f32_16x16x32_bf16 v[58:61], v[158:161], v[172:175], v[58:61]
	v_mfma_f32_16x16x32_bf16 v[50:53], v[144:147], v[180:183], v[50:53]
	v_mfma_f32_16x16x32_bf16 v[42:45], v[158:161], v[180:183], v[42:45]
	v_mfma_f32_16x16x32_bf16 v[34:37], v[144:147], v[204:207], v[34:37]
	v_mfma_f32_16x16x32_bf16 v[26:29], v[158:161], v[204:207], v[26:29]
	v_mfma_f32_16x16x32_bf16 v[18:21], v[144:147], v[212:215], v[18:21]
	v_mfma_f32_16x16x32_bf16 v[10:13], v[158:161], v[212:215], v[10:13]
	s_setprio 0
	s_barrier
	s_add_u32 s60, s6, 0x40000
	s_addc_u32 s61, s7, 0
	s_add_i32 s58, s70, s44
	s_mov_b32 m0, s58
	s_nop 0
	global_load_lds_dwordx4 v0, s[60:61]
	s_add_i32 m0, s58, 0x2000
	s_nop 0
	global_load_lds_dwordx4 v130, s[60:61]
	s_waitcnt vmcnt(6)
	s_barrier
; __device__ __forceinline__ unsigned pk2(float lo, float hi) { unsigned r; asm("v_cvt_pk_bf16_f32 %0, %1, %2" : "=v"(r) : "v"(lo), "v"(hi)); return r; }
; #define PG8_STAGE(bufoff, gbase, voff) do { _Pragma("unroll") for (int _i = 0; _i < 2; ++_i) \
;         __builtin_amdgcn_global_load_lds((const unsigned*)((const char*)(gbase) + (voff)[_i]), (LAS unsigned*)(lds + (bufoff) + ldsw + _i * 8192), 16, 0, 0); } while (0)
; #define PG8_LDA(dst, b, h) do { _Pragma("unroll") for (int m = 0; m < 4; ++m) _Pragma("unroll") for (int k = 0; k < 2; ++k) dst[m][k] = *(const LAS bf16x8*)(lds + PG8_SA(b, h) + aoff + m * 2048 + k * 1024); } while (0)
;     __device__ __forceinline__ void operator()(const f32x4 (&acc)[2][2][4][2], const Unit& u, int ui, int wr, int wc, int fr, int fq) const {
;     ...
;                     u32x4 w; w.x = pk2(v0[0], v0[1]); w.y = pk2(v0[2], v0[3]); w.z = pk2(v1[0], v1[1]); w.w = pk2(v1[2], v1[3]);
;                     *(u32x4*)(rowp + bj * HALF) = w;
; template <class Epi>
; __device__ __forceinline__ void gemm_phase(LAS unsigned char* lds, const Gemm g, const StaticOrder& S, const Epi& E) {
;     ...
;             PG8_LDB(B0, 0, 0); PG8_SCHED; PG8_LDA(At, 0, 0); PG8_STAGE(PG8_SA(1, 1), a1 + hstep, voffA);
;             PG8_WAIT_L(8); PG8_BAR; PG8_WAIT_L(0); PG8_MMA(0, 0, At, B0); PG8_BAR; PG8_SCHED;
;             PG8_LDB(B1, 0, 1); PG8_STAGE(PG8_SB(0, 0), b2, voffB);
;             PG8_BAR; PG8_WAIT_L(0); PG8_MMA(0, 1, At, B1); PG8_BAR;
;             PG8_LDA(At, 0, 1); PG8_STAGE(PG8_SA(0, 0), a2, voffA);
;             PG8_BAR; PG8_WAIT_L(0); PG8_MMA(1, 0, At, B0); PG8_BAR; PG8_SCHED;
;             PG8_STAGE(PG8_SB(0, 1), b2 + hstep, voffB);
;             PG8_WAIT_V(6); PG8_BAR; PG8_MMA(1, 1, At, B1); PG8_BAR;
;             PG8_LDB(B0, 1, 0); PG8_SCHED; PG8_LDA(At, 1, 0); PG8_STAGE(PG8_SA(0, 1), a2 + hstep, voffA);
;             PG8_WAIT_L(8); PG8_BAR; PG8_WAIT_L(0); PG8_MMA(0, 0, At, B0); PG8_BAR; PG8_SCHED;
;             PG8_LDB(B1, 1, 1); PG8_STAGE(PG8_SB(1, 0), b3, voffB);
;             PG8_BAR; PG8_WAIT_L(0); PG8_MMA(0, 1, At, B1); PG8_BAR;
;             PG8_LDA(At, 1, 1); PG8_STAGE(PG8_SA(1, 0), a3, voffA);
;             PG8_BAR; PG8_WAIT_L(0); PG8_MMA(1, 0, At, B0); PG8_BAR; PG8_SCHED;
;             PG8_STAGE(PG8_SB(1, 1), b3 + hstep, voffB);
;             PG8_WAIT_V(6); PG8_BAR; PG8_MMA(1, 1, At, B1); PG8_BAR;
	s_setprio 1
	v_mfma_f32_16x16x32_bf16 v[54:57], v[216:219], v[168:171], 0
	v_mfma_f32_16x16x32_bf16 v[46:49], v[230:233], v[168:171], 0
	v_mfma_f32_16x16x32_bf16 v[38:41], v[216:219], v[176:179], 0
	v_mfma_f32_16x16x32_bf16 v[30:33], v[230:233], v[176:179], 0
	v_mfma_f32_16x16x32_bf16 v[22:25], v[216:219], v[184:187], 0
	v_mfma_f32_16x16x32_bf16 v[14:17], v[230:233], v[184:187], 0
	v_mfma_f32_16x16x32_bf16 v[6:9], v[216:219], v[208:211], 0
	v_mfma_f32_16x16x32_bf16 v[2:5], v[230:233], v[208:211], 0
	v_mfma_f32_16x16x32_bf16 v[54:57], v[226:229], v[172:175], v[54:57]
	v_mfma_f32_16x16x32_bf16 v[46:49], v[234:237], v[172:175], v[46:49]
	v_mfma_f32_16x16x32_bf16 v[38:41], v[226:229], v[180:183], v[38:41]
	v_mfma_f32_16x16x32_bf16 v[30:33], v[234:237], v[180:183], v[30:33]
	v_mfma_f32_16x16x32_bf16 v[22:25], v[226:229], v[204:207], v[22:25]
	v_mfma_f32_16x16x32_bf16 v[14:17], v[234:237], v[204:207], v[14:17]
	v_mfma_f32_16x16x32_bf16 v[6:9], v[226:229], v[212:215], v[6:9]
	v_mfma_f32_16x16x32_bf16 v[2:5], v[234:237], v[212:215], v[2:5]
	s_setprio 0
	s_add_i32 s58, 0, 0x18000
	v_add_u32_e32 v153, s58, v149
	s_barrier
	ds_read_b128 v[140:143], v153
	ds_read_b128 v[144:147], v153 offset:1024
	ds_read_b128 v[154:157], v153 offset:2048
	ds_read_b128 v[158:161], v153 offset:3072
	s_add_u32 s36, s36, 0x40000
	s_addc_u32 s37, s37, 0
	s_mov_b32 m0, s49
	ds_read_b128 v[168:171], v152 offset:32768
	ds_read_b128 v[172:175], v152 offset:33792
	ds_read_b128 v[176:179], v152 offset:34816
	ds_read_b128 v[180:183], v152 offset:35840
	ds_read_b128 v[184:187], v152 offset:36864
	ds_read_b128 v[204:207], v152 offset:37888
	ds_read_b128 v[208:211], v152 offset:38912
	ds_read_b128 v[212:215], v152 offset:39936
	global_load_lds_dwordx4 v134, s[36:37]
	s_mov_b32 m0, s54
	s_nop 0
	global_load_lds_dwordx4 v132, s[36:37]
	s_waitcnt lgkmcnt(8)
	s_barrier
	s_waitcnt lgkmcnt(0)
	s_setprio 1
	s_waitcnt lgkmcnt(0)
	v_mfma_f32_16x16x32_bf16 v[126:129], v[140:143], v[168:171], v[126:129]
	v_mfma_f32_16x16x32_bf16 v[122:125], v[154:157], v[168:171], v[122:125]
	s_cmp_eq_u32 s87, 0
	s_cbranch_scc1 .LdsA_skip_0
	global_store_dwordx4 v166, v[162:165], s[4:5]
.LdsA_skip_0:
	v_mfma_f32_16x16x32_bf16 v[114:117], v[140:143], v[176:179], v[114:117]
	v_mfma_f32_16x16x32_bf16 v[106:109], v[154:157], v[176:179], v[106:109]
	v_mfma_f32_16x16x32_bf16 v[98:101], v[140:143], v[184:187], v[98:101]
	v_mfma_f32_16x16x32_bf16 v[90:93], v[154:157], v[184:187], v[90:93]
	v_mfma_f32_16x16x32_bf16 v[82:85], v[140:143], v[208:211], v[82:85]
	v_mfma_f32_16x16x32_bf16 v[74:77], v[154:157], v[208:211], v[74:77]
	v_mfma_f32_16x16x32_bf16 v[126:129], v[144:147], v[172:175], v[126:129]
	v_mfma_f32_16x16x32_bf16 v[122:125], v[158:161], v[172:175], v[122:125]
	v_mfma_f32_16x16x32_bf16 v[114:117], v[144:147], v[180:183], v[114:117]
	v_mfma_f32_16x16x32_bf16 v[106:109], v[158:161], v[180:183], v[106:109]
	v_mfma_f32_16x16x32_bf16 v[98:101], v[144:147], v[204:207], v[98:101]
	v_mfma_f32_16x16x32_bf16 v[90:93], v[158:161], v[204:207], v[90:93]
	v_mfma_f32_16x16x32_bf16 v[82:85], v[144:147], v[212:215], v[82:85]
	v_mfma_f32_16x16x32_bf16 v[74:77], v[158:161], v[212:215], v[74:77]
	s_setprio 0
	s_barrier
	s_add_i32 s36, 0, 0x1c000
	s_add_i32 s37, s58, s44
	v_add_u32_e32 v153, s36, v149
	s_add_u32 s60, s6, 0x80
	s_addc_u32 s61, s7, 0
	s_mov_b32 m0, s37
	ds_read_b128 v[216:219], v153
	ds_read_b128 v[226:229], v153 offset:1024
	ds_read_b128 v[230:233], v153 offset:2048
	ds_read_b128 v[234:237], v153 offset:3072
	global_load_lds_dwordx4 v0, s[60:61]
	s_add_i32 m0, s37, 0x2000
	s_nop 0
	global_load_lds_dwordx4 v130, s[60:61]
	s_barrier
	s_waitcnt lgkmcnt(0)
	s_setprio 1
	s_waitcnt lgkmcnt(0)
	v_mfma_f32_16x16x32_bf16 v[118:121], v[216:219], v[168:171], v[118:121]
	v_mfma_f32_16x16x32_bf16 v[110:113], v[230:233], v[168:171], v[110:113]
	v_mfma_f32_16x16x32_bf16 v[102:105], v[216:219], v[176:179], v[102:105]
	v_mfma_f32_16x16x32_bf16 v[94:97], v[230:233], v[176:179], v[94:97]
	v_mfma_f32_16x16x32_bf16 v[86:89], v[216:219], v[184:187], v[86:89]
	v_mfma_f32_16x16x32_bf16 v[78:81], v[230:233], v[184:187], v[78:81]
	v_mfma_f32_16x16x32_bf16 v[70:73], v[216:219], v[208:211], v[70:73]
	v_mfma_f32_16x16x32_bf16 v[66:69], v[230:233], v[208:211], v[66:69]
	v_mfma_f32_16x16x32_bf16 v[118:121], v[226:229], v[172:175], v[118:121]
	v_mfma_f32_16x16x32_bf16 v[110:113], v[234:237], v[172:175], v[110:113]
	v_mfma_f32_16x16x32_bf16 v[102:105], v[226:229], v[180:183], v[102:105]
	v_mfma_f32_16x16x32_bf16 v[94:97], v[234:237], v[180:183], v[94:97]
	v_mfma_f32_16x16x32_bf16 v[86:89], v[226:229], v[204:207], v[86:89]
	v_mfma_f32_16x16x32_bf16 v[78:81], v[234:237], v[204:207], v[78:81]
	v_mfma_f32_16x16x32_bf16 v[70:73], v[226:229], v[212:215], v[70:73]
	v_mfma_f32_16x16x32_bf16 v[66:69], v[234:237], v[212:215], v[66:69]
	s_setprio 0
	s_mov_b32 m0, s55
	s_barrier
	ds_read_b128 v[168:171], v152 offset:49152
	ds_read_b128 v[172:175], v152 offset:50176
	ds_read_b128 v[176:179], v152 offset:51200
	ds_read_b128 v[180:183], v152 offset:52224
	ds_read_b128 v[184:187], v152 offset:53248
	ds_read_b128 v[204:207], v152 offset:54272
	ds_read_b128 v[208:211], v152 offset:55296
	ds_read_b128 v[212:215], v152 offset:56320
	global_load_lds_dwordx4 v134, vcc
	s_mov_b32 m0, s83
	s_nop 0
	global_load_lds_dwordx4 v132, vcc
	s_barrier
; #define PG8_STAGE(bufoff, gbase, voff) do { _Pragma("unroll") for (int _i = 0; _i < 2; ++_i) \
;         __builtin_amdgcn_global_load_lds((const unsigned*)((const char*)(gbase) + (voff)[_i]), (LAS unsigned*)(lds + (bufoff) + ldsw + _i * 8192), 16, 0, 0); } while (0)
; #define PG8_LDA(dst, b, h) do { _Pragma("unroll") for (int m = 0; m < 4; ++m) _Pragma("unroll") for (int k = 0; k < 2; ++k) dst[m][k] = *(const LAS bf16x8*)(lds + PG8_SA(b, h) + aoff + m * 2048 + k * 1024); } while (0)
; #define PG8_LDB(dst, b, h) do { _Pragma("unroll") for (int n = 0; n < 2; ++n) _Pragma("unroll") for (int k = 0; k < 2; ++k) dst[n][k] = *(const LAS bf16x8*)(lds + PG8_SB(b, h) + boff + n * 2048 + k * 1024); } while (0)
; #define PG8_WAIT_V(n) asm volatile("s_waitcnt vmcnt(" #n ")" ::: "memory")
; #define PG8_WAIT_L(n) asm volatile("s_waitcnt lgkmcnt(" #n ")" ::: "memory")
; #define PG8_BAR __builtin_amdgcn_s_barrier()
; #define PG8_SCHED __builtin_amdgcn_sched_barrier(0)
; template <class Epi>
; __device__ __forceinline__ void gemm_phase(LAS unsigned char* lds, const Gemm g, const StaticOrder& S, const Epi& E) {
;     ...
;             PG8_LDB(B0, 0, 0); PG8_SCHED; PG8_LDA(At, 0, 0); PG8_STAGE(PG8_SA(1, 1), a1 + hstep, voffA);
;             PG8_WAIT_L(8); PG8_BAR; PG8_WAIT_L(0); PG8_MMA(0, 0, At, B0); PG8_BAR; PG8_SCHED;
;             PG8_LDB(B1, 0, 1); PG8_STAGE(PG8_SB(0, 0), b2, voffB);
;             PG8_BAR; PG8_WAIT_L(0); PG8_MMA(0, 1, At, B1); PG8_BAR;
;             PG8_LDA(At, 0, 1); PG8_STAGE(PG8_SA(0, 0), a2, voffA);
;             PG8_BAR; PG8_WAIT_L(0); PG8_MMA(1, 0, At, B0); PG8_BAR; PG8_SCHED;
;             PG8_STAGE(PG8_SB(0, 1), b2 + hstep, voffB);
;             PG8_WAIT_V(6); PG8_BAR; PG8_MMA(1, 1, At, B1); PG8_BAR;
;             PG8_LDB(B0, 1, 0); PG8_SCHED; PG8_LDA(At, 1, 0); PG8_STAGE(PG8_SA(0, 1), a2 + hstep, voffA);
;             PG8_WAIT_L(8); PG8_BAR; PG8_WAIT_L(0); PG8_MMA(0, 0, At, B0); PG8_BAR; PG8_SCHED;
;             PG8_LDB(B1, 1, 1); PG8_STAGE(PG8_SB(1, 0), b3, voffB);
;             PG8_BAR; PG8_WAIT_L(0); PG8_MMA(0, 1, At, B1); PG8_BAR;
;             PG8_LDA(At, 1, 1); PG8_STAGE(PG8_SA(1, 0), a3, voffA);
;             PG8_BAR; PG8_WAIT_L(0); PG8_MMA(1, 0, At, B0); PG8_BAR; PG8_SCHED;
;             PG8_STAGE(PG8_SB(1, 1), b3 + hstep, voffB);
;             PG8_WAIT_V(6); PG8_BAR; PG8_MMA(1, 1, At, B1); PG8_BAR;
	s_waitcnt lgkmcnt(0)
	s_setprio 1
	s_waitcnt lgkmcnt(0)
	v_mfma_f32_16x16x32_bf16 v[62:65], v[140:143], v[168:171], v[62:65]
	v_mfma_f32_16x16x32_bf16 v[58:61], v[154:157], v[168:171], v[58:61]
	v_mfma_f32_16x16x32_bf16 v[50:53], v[140:143], v[176:179], v[50:53]
	v_mfma_f32_16x16x32_bf16 v[42:45], v[154:157], v[176:179], v[42:45]
	v_mfma_f32_16x16x32_bf16 v[34:37], v[140:143], v[184:187], v[34:37]
	v_mfma_f32_16x16x32_bf16 v[26:29], v[154:157], v[184:187], v[26:29]
	v_mfma_f32_16x16x32_bf16 v[18:21], v[140:143], v[208:211], v[18:21]
	v_mfma_f32_16x16x32_bf16 v[10:13], v[154:157], v[208:211], v[10:13]
	v_mfma_f32_16x16x32_bf16 v[62:65], v[144:147], v[172:175], v[62:65]
	v_mfma_f32_16x16x32_bf16 v[58:61], v[158:161], v[172:175], v[58:61]
	v_mfma_f32_16x16x32_bf16 v[50:53], v[144:147], v[180:183], v[50:53]
	v_mfma_f32_16x16x32_bf16 v[42:45], v[158:161], v[180:183], v[42:45]
	v_mfma_f32_16x16x32_bf16 v[34:37], v[144:147], v[204:207], v[34:37]
	v_mfma_f32_16x16x32_bf16 v[26:29], v[158:161], v[204:207], v[26:29]
	v_mfma_f32_16x16x32_bf16 v[18:21], v[144:147], v[212:215], v[18:21]
	v_mfma_f32_16x16x32_bf16 v[10:13], v[158:161], v[212:215], v[10:13]
	s_setprio 0
	s_barrier
	s_add_u32 s6, s6, 0x40080
	s_addc_u32 s7, s7, 0
	s_add_i32 s36, s36, s44
	s_mov_b32 m0, s36
	s_nop 0
	global_load_lds_dwordx4 v0, s[6:7]
	s_add_i32 m0, s36, 0x2000
	s_nop 0
	global_load_lds_dwordx4 v130, s[6:7]
	s_waitcnt vmcnt(6)
	s_barrier
	s_setprio 1
	v_mfma_f32_16x16x32_bf16 v[54:57], v[216:219], v[168:171], v[54:57]
	v_mfma_f32_16x16x32_bf16 v[46:49], v[230:233], v[168:171], v[46:49]
	v_mfma_f32_16x16x32_bf16 v[38:41], v[216:219], v[176:179], v[38:41]
	v_mfma_f32_16x16x32_bf16 v[30:33], v[230:233], v[176:179], v[30:33]
	v_mfma_f32_16x16x32_bf16 v[22:25], v[216:219], v[184:187], v[22:25]
	v_mfma_f32_16x16x32_bf16 v[14:17], v[230:233], v[184:187], v[14:17]
	v_mfma_f32_16x16x32_bf16 v[6:9], v[216:219], v[208:211], v[6:9]
	v_mfma_f32_16x16x32_bf16 v[2:5], v[230:233], v[208:211], v[2:5]
	v_mfma_f32_16x16x32_bf16 v[54:57], v[226:229], v[172:175], v[54:57]
	v_mfma_f32_16x16x32_bf16 v[46:49], v[234:237], v[172:175], v[46:49]
	v_mfma_f32_16x16x32_bf16 v[38:41], v[226:229], v[180:183], v[38:41]
	v_mfma_f32_16x16x32_bf16 v[30:33], v[234:237], v[180:183], v[30:33]
	v_mfma_f32_16x16x32_bf16 v[22:25], v[226:229], v[204:207], v[22:25]
	v_mfma_f32_16x16x32_bf16 v[14:17], v[234:237], v[204:207], v[14:17]
	v_mfma_f32_16x16x32_bf16 v[6:9], v[226:229], v[212:215], v[6:9]
	v_mfma_f32_16x16x32_bf16 v[2:5], v[234:237], v[212:215], v[2:5]
	s_setprio 0
	s_add_i32 s91, s91, 2
	s_add_u32 s24, s24, 0x100
	s_addc_u32 s25, s25, 0
	s_add_u32 s89, s89, 0x100
	s_addc_u32 s90, s90, 0
	s_cmp_gt_u32 s91, 13
	s_barrier
	s_add_u32 s6, s24, 0xfffc0080
	s_addc_u32 s7, s25, -1
	s_add_i32 s58, 0, 0x10000
	v_add_u32_e32 v153, s58, v149
	ds_read_b128 v[140:143], v153
	ds_read_b128 v[144:147], v153 offset:1024
	ds_read_b128 v[154:157], v153 offset:2048
	ds_read_b128 v[158:161], v153 offset:3072
	s_cmp_eq_u32 s91, 12
	s_cselect_b32 s37, s11, s7
	s_cselect_b32 s36, s71, s6
	s_cselect_b32 s7, s9, s90
	s_cselect_b32 s6, s88, s89
	s_add_i32 m0, s47, 0xc000
	ds_read_b128 v[168:171], v152
	ds_read_b128 v[172:175], v152 offset:1024
	ds_read_b128 v[176:179], v152 offset:2048
	ds_read_b128 v[180:183], v152 offset:3072
	ds_read_b128 v[184:187], v152 offset:4096
	ds_read_b128 v[204:207], v152 offset:5120
	ds_read_b128 v[208:211], v152 offset:6144
	ds_read_b128 v[212:215], v152 offset:7168
	global_load_lds_dwordx4 v136, s[24:25]
	s_add_i32 m0, s47, 0xe000
	s_nop 0
	global_load_lds_dwordx4 v138, s[24:25]
	s_waitcnt lgkmcnt(8)
	s_barrier
	s_waitcnt lgkmcnt(0)
	s_setprio 1
	s_waitcnt lgkmcnt(0)
	v_mfma_f32_16x16x32_bf16 v[126:129], v[140:143], v[168:171], v[126:129]
	v_mfma_f32_16x16x32_bf16 v[122:125], v[154:157], v[168:171], v[122:125]
	v_mfma_f32_16x16x32_bf16 v[114:117], v[140:143], v[176:179], v[114:117]
	v_mfma_f32_16x16x32_bf16 v[106:109], v[154:157], v[176:179], v[106:109]
	v_mfma_f32_16x16x32_bf16 v[98:101], v[140:143], v[184:187], v[98:101]
	v_mfma_f32_16x16x32_bf16 v[90:93], v[154:157], v[184:187], v[90:93]
	v_mfma_f32_16x16x32_bf16 v[82:85], v[140:143], v[208:211], v[82:85]
	v_mfma_f32_16x16x32_bf16 v[74:77], v[154:157], v[208:211], v[74:77]
	v_mfma_f32_16x16x32_bf16 v[126:129], v[144:147], v[172:175], v[126:129]
	v_mfma_f32_16x16x32_bf16 v[122:125], v[158:161], v[172:175], v[122:125]
	v_mfma_f32_16x16x32_bf16 v[114:117], v[144:147], v[180:183], v[114:117]
	v_mfma_f32_16x16x32_bf16 v[106:109], v[158:161], v[180:183], v[106:109]
	v_mfma_f32_16x16x32_bf16 v[98:101], v[144:147], v[204:207], v[98:101]
	v_mfma_f32_16x16x32_bf16 v[90:93], v[158:161], v[204:207], v[90:93]
	v_mfma_f32_16x16x32_bf16 v[82:85], v[144:147], v[212:215], v[82:85]
	v_mfma_f32_16x16x32_bf16 v[74:77], v[158:161], v[212:215], v[74:77]
	s_setprio 0
	s_barrier
	s_add_i32 s70, 0, 0x14000
	s_add_i32 s58, s58, s44
	v_add_u32_e32 v153, s70, v149
	s_mov_b32 m0, s58
	ds_read_b128 v[216:219], v153
	ds_read_b128 v[226:229], v153 offset:1024
	ds_read_b128 v[230:233], v153 offset:2048
	ds_read_b128 v[234:237], v153 offset:3072
	global_load_lds_dwordx4 v0, s[6:7]
	s_add_i32 m0, s58, 0x2000
	s_nop 0
	global_load_lds_dwordx4 v130, s[6:7]
	s_barrier
; __device__ __forceinline__ unsigned pk2(float lo, float hi) { unsigned r; asm("v_cvt_pk_bf16_f32 %0, %1, %2" : "=v"(r) : "v"(lo), "v"(hi)); return r; }
; #define PG8_STAGE(bufoff, gbase, voff) do { _Pragma("unroll") for (int _i = 0; _i < 2; ++_i) \
;         __builtin_amdgcn_global_load_lds((const unsigned*)((const char*)(gbase) + (voff)[_i]), (LAS unsigned*)(lds + (bufoff) + ldsw + _i * 8192), 16, 0, 0); } while (0)
; #define PG8_LDA(dst, b, h) do { _Pragma("unroll") for (int m = 0; m < 4; ++m) _Pragma("unroll") for (int k = 0; k < 2; ++k) dst[m][k] = *(const LAS bf16x8*)(lds + PG8_SA(b, h) + aoff + m * 2048 + k * 1024); } while (0)
;     __device__ __forceinline__ void operator()(const f32x4 (&acc)[2][2][4][2], const Unit& u, int ui, int wr, int wc, int fr, int fq) const {
;     ...
;                     u32x4 w; w.x = pk2(v0[0], v0[1]); w.y = pk2(v0[2], v0[3]); w.z = pk2(v1[0], v1[1]); w.w = pk2(v1[2], v1[3]);
;                     *(u32x4*)(rowp + bj * HALF) = w;
; template <class Epi>
; __device__ __forceinline__ void gemm_phase(LAS unsigned char* lds, const Gemm g, const StaticOrder& S, const Epi& E) {
;     ...
;             PG8_LDB(B0, 0, 0); PG8_SCHED; PG8_LDA(At, 0, 0); PG8_STAGE(PG8_SA(1, 1), a1 + hstep, voffA);
;             PG8_WAIT_L(8); PG8_BAR; PG8_WAIT_L(0); PG8_MMA(0, 0, At, B0); PG8_BAR; PG8_SCHED;
;             PG8_LDB(B1, 0, 1); PG8_STAGE(PG8_SB(0, 0), b2, voffB);
;             PG8_BAR; PG8_WAIT_L(0); PG8_MMA(0, 1, At, B1); PG8_BAR;
;             PG8_LDA(At, 0, 1); PG8_STAGE(PG8_SA(0, 0), a2, voffA);
;             PG8_BAR; PG8_WAIT_L(0); PG8_MMA(1, 0, At, B0); PG8_BAR; PG8_SCHED;
;             PG8_STAGE(PG8_SB(0, 1), b2 + hstep, voffB);
;             PG8_WAIT_V(6); PG8_BAR; PG8_MMA(1, 1, At, B1); PG8_BAR;
;             PG8_LDB(B0, 1, 0); PG8_SCHED; PG8_LDA(At, 1, 0); PG8_STAGE(PG8_SA(0, 1), a2 + hstep, voffA);
;             PG8_WAIT_L(8); PG8_BAR; PG8_WAIT_L(0); PG8_MMA(0, 0, At, B0); PG8_BAR; PG8_SCHED;
;             PG8_LDB(B1, 1, 1); PG8_STAGE(PG8_SB(1, 0), b3, voffB);
;             PG8_BAR; PG8_WAIT_L(0); PG8_MMA(0, 1, At, B1); PG8_BAR;
;             PG8_LDA(At, 1, 1); PG8_STAGE(PG8_SA(1, 0), a3, voffA);
;             PG8_BAR; PG8_WAIT_L(0); PG8_MMA(1, 0, At, B0); PG8_BAR; PG8_SCHED;
;             PG8_STAGE(PG8_SB(1, 1), b3 + hstep, voffB);
;             PG8_WAIT_V(6); PG8_BAR; PG8_MMA(1, 1, At, B1); PG8_BAR;
	s_waitcnt lgkmcnt(0)
	s_setprio 1
	s_waitcnt lgkmcnt(0)
	v_mfma_f32_16x16x32_bf16 v[118:121], v[216:219], v[168:171], v[118:121]
	v_mfma_f32_16x16x32_bf16 v[110:113], v[230:233], v[168:171], v[110:113]
	v_mfma_f32_16x16x32_bf16 v[102:105], v[216:219], v[176:179], v[102:105]
	v_mfma_f32_16x16x32_bf16 v[94:97], v[230:233], v[176:179], v[94:97]
	v_mfma_f32_16x16x32_bf16 v[86:89], v[216:219], v[184:187], v[86:89]
	v_mfma_f32_16x16x32_bf16 v[78:81], v[230:233], v[184:187], v[78:81]
	v_mfma_f32_16x16x32_bf16 v[70:73], v[216:219], v[208:211], v[70:73]
	v_mfma_f32_16x16x32_bf16 v[66:69], v[230:233], v[208:211], v[66:69]
	v_mfma_f32_16x16x32_bf16 v[118:121], v[226:229], v[172:175], v[118:121]
	v_mfma_f32_16x16x32_bf16 v[110:113], v[234:237], v[172:175], v[110:113]
	v_mfma_f32_16x16x32_bf16 v[102:105], v[226:229], v[180:183], v[102:105]
	v_mfma_f32_16x16x32_bf16 v[94:97], v[234:237], v[180:183], v[94:97]
	v_mfma_f32_16x16x32_bf16 v[86:89], v[226:229], v[204:207], v[86:89]
	v_mfma_f32_16x16x32_bf16 v[78:81], v[234:237], v[204:207], v[78:81]
	v_mfma_f32_16x16x32_bf16 v[70:73], v[226:229], v[212:215], v[70:73]
	v_mfma_f32_16x16x32_bf16 v[66:69], v[234:237], v[212:215], v[66:69]
	s_setprio 0
	s_mov_b32 m0, s47
	s_add_u32 vcc_lo, s36, 0x80
	s_addc_u32 vcc_hi, s37, 0
	s_barrier
	ds_read_b128 v[168:171], v152 offset:16384
	ds_read_b128 v[172:175], v152 offset:17408
	ds_read_b128 v[176:179], v152 offset:18432
	ds_read_b128 v[180:183], v152 offset:19456
	ds_read_b128 v[184:187], v152 offset:20480
	ds_read_b128 v[204:207], v152 offset:21504
	ds_read_b128 v[208:211], v152 offset:22528
	ds_read_b128 v[212:215], v152 offset:23552
	global_load_lds_dwordx4 v134, s[36:37]
	s_mov_b32 m0, s48
	s_nop 0
	global_load_lds_dwordx4 v132, s[36:37]
	s_barrier
	s_waitcnt lgkmcnt(0)
	s_setprio 1
	s_waitcnt lgkmcnt(0)
	v_mfma_f32_16x16x32_bf16 v[62:65], v[140:143], v[168:171], v[62:65]
	v_mfma_f32_16x16x32_bf16 v[58:61], v[154:157], v[168:171], v[58:61]
	v_mfma_f32_16x16x32_bf16 v[50:53], v[140:143], v[176:179], v[50:53]
	v_mfma_f32_16x16x32_bf16 v[42:45], v[154:157], v[176:179], v[42:45]
	v_mfma_f32_16x16x32_bf16 v[34:37], v[140:143], v[184:187], v[34:37]
	v_mfma_f32_16x16x32_bf16 v[26:29], v[154:157], v[184:187], v[26:29]
	v_mfma_f32_16x16x32_bf16 v[18:21], v[140:143], v[208:211], v[18:21]
	v_mfma_f32_16x16x32_bf16 v[10:13], v[154:157], v[208:211], v[10:13]
	v_mfma_f32_16x16x32_bf16 v[62:65], v[144:147], v[172:175], v[62:65]
	v_mfma_f32_16x16x32_bf16 v[58:61], v[158:161], v[172:175], v[58:61]
	v_mfma_f32_16x16x32_bf16 v[50:53], v[144:147], v[180:183], v[50:53]
	v_mfma_f32_16x16x32_bf16 v[42:45], v[158:161], v[180:183], v[42:45]
	v_mfma_f32_16x16x32_bf16 v[34:37], v[144:147], v[204:207], v[34:37]
	v_mfma_f32_16x16x32_bf16 v[26:29], v[158:161], v[204:207], v[26:29]
	v_mfma_f32_16x16x32_bf16 v[18:21], v[144:147], v[212:215], v[18:21]
	v_mfma_f32_16x16x32_bf16 v[10:13], v[158:161], v[212:215], v[10:13]
	s_setprio 0
	s_barrier
	s_add_u32 s60, s6, 0x40000
	s_addc_u32 s61, s7, 0
	s_add_i32 s58, s70, s44
	s_mov_b32 m0, s58
	s_nop 0
	global_load_lds_dwordx4 v0, s[60:61]
	s_add_i32 m0, s58, 0x2000
	s_nop 0
	global_load_lds_dwordx4 v130, s[60:61]
	s_waitcnt vmcnt(6)
	s_barrier
	s_setprio 1
	v_mfma_f32_16x16x32_bf16 v[54:57], v[216:219], v[168:171], v[54:57]
	v_mfma_f32_16x16x32_bf16 v[46:49], v[230:233], v[168:171], v[46:49]
	v_mfma_f32_16x16x32_bf16 v[38:41], v[216:219], v[176:179], v[38:41]
	v_mfma_f32_16x16x32_bf16 v[30:33], v[230:233], v[176:179], v[30:33]
	v_mfma_f32_16x16x32_bf16 v[22:25], v[216:219], v[184:187], v[22:25]
	v_mfma_f32_16x16x32_bf16 v[14:17], v[230:233], v[184:187], v[14:17]
	v_mfma_f32_16x16x32_bf16 v[6:9], v[216:219], v[208:211], v[6:9]
	v_mfma_f32_16x16x32_bf16 v[2:5], v[230:233], v[208:211], v[2:5]
	v_mfma_f32_16x16x32_bf16 v[54:57], v[226:229], v[172:175], v[54:57]
	v_mfma_f32_16x16x32_bf16 v[46:49], v[234:237], v[172:175], v[46:49]
	v_mfma_f32_16x16x32_bf16 v[38:41], v[226:229], v[180:183], v[38:41]
	v_mfma_f32_16x16x32_bf16 v[30:33], v[234:237], v[180:183], v[30:33]
	v_mfma_f32_16x16x32_bf16 v[22:25], v[226:229], v[204:207], v[22:25]
	v_mfma_f32_16x16x32_bf16 v[14:17], v[234:237], v[204:207], v[14:17]
	v_mfma_f32_16x16x32_bf16 v[6:9], v[226:229], v[212:215], v[6:9]
	v_mfma_f32_16x16x32_bf16 v[2:5], v[234:237], v[212:215], v[2:5]
	s_setprio 0
	s_add_i32 s58, 0, 0x18000
	v_add_u32_e32 v153, s58, v149
	s_barrier
	ds_read_b128 v[140:143], v153
	ds_read_b128 v[144:147], v153 offset:1024
	ds_read_b128 v[154:157], v153 offset:2048
	ds_read_b128 v[158:161], v153 offset:3072
	s_add_u32 s36, s36, 0x40000
	s_addc_u32 s37, s37, 0
	s_mov_b32 m0, s49
	ds_read_b128 v[168:171], v152 offset:32768
	ds_read_b128 v[172:175], v152 offset:33792
	ds_read_b128 v[176:179], v152 offset:34816
	ds_read_b128 v[180:183], v152 offset:35840
	ds_read_b128 v[184:187], v152 offset:36864
	ds_read_b128 v[204:207], v152 offset:37888
	ds_read_b128 v[208:211], v152 offset:38912
	ds_read_b128 v[212:215], v152 offset:39936
	global_load_lds_dwordx4 v134, s[36:37]
	s_mov_b32 m0, s54
	s_nop 0
	global_load_lds_dwordx4 v132, s[36:37]
	s_waitcnt lgkmcnt(8)
	s_barrier
	s_waitcnt lgkmcnt(0)
	s_setprio 1
	s_waitcnt lgkmcnt(0)
	v_mfma_f32_16x16x32_bf16 v[126:129], v[140:143], v[168:171], v[126:129]
	v_mfma_f32_16x16x32_bf16 v[122:125], v[154:157], v[168:171], v[122:125]
	s_cmp_eq_u32 s87, 0
	s_cbranch_scc1 .LdsA_skip_1
	global_store_dwordx4 v166, v[188:191], s[4:5] offset:256
	s_nop 1
	v_add_u32_e32 v166, 0xe000, v166
; #define PG8_STAGE(bufoff, gbase, voff) do { _Pragma("unroll") for (int _i = 0; _i < 2; ++_i) \
;         __builtin_amdgcn_global_load_lds((const unsigned*)((const char*)(gbase) + (voff)[_i]), (LAS unsigned*)(lds + (bufoff) + ldsw + _i * 8192), 16, 0, 0); } while (0)
; #define PG8_LDA(dst, b, h) do { _Pragma("unroll") for (int m = 0; m < 4; ++m) _Pragma("unroll") for (int k = 0; k < 2; ++k) dst[m][k] = *(const LAS bf16x8*)(lds + PG8_SA(b, h) + aoff + m * 2048 + k * 1024); } while (0)
; #define PG8_LDB(dst, b, h) do { _Pragma("unroll") for (int n = 0; n < 2; ++n) _Pragma("unroll") for (int k = 0; k < 2; ++k) dst[n][k] = *(const LAS bf16x8*)(lds + PG8_SB(b, h) + boff + n * 2048 + k * 1024); } while (0)
; #define PG8_WAIT_V(n) asm volatile("s_waitcnt vmcnt(" #n ")" ::: "memory")
; #define PG8_WAIT_L(n) asm volatile("s_waitcnt lgkmcnt(" #n ")" ::: "memory")
; #define PG8_BAR __builtin_amdgcn_s_barrier()
; #define PG8_SCHED __builtin_amdgcn_sched_barrier(0)
; template <class Epi>
; __device__ __forceinline__ void gemm_phase(LAS unsigned char* lds, const Gemm g, const StaticOrder& S, const Epi& E) {
;     ...
;             PG8_LDB(B0, 0, 0); PG8_SCHED; PG8_LDA(At, 0, 0); PG8_STAGE(PG8_SA(1, 1), a1 + hstep, voffA);
;             PG8_WAIT_L(8); PG8_BAR; PG8_WAIT_L(0); PG8_MMA(0, 0, At, B0); PG8_BAR; PG8_SCHED;
;             PG8_LDB(B1, 0, 1); PG8_STAGE(PG8_SB(0, 0), b2, voffB);
;             PG8_BAR; PG8_WAIT_L(0); PG8_MMA(0, 1, At, B1); PG8_BAR;
;             PG8_LDA(At, 0, 1); PG8_STAGE(PG8_SA(0, 0), a2, voffA);
;             PG8_BAR; PG8_WAIT_L(0); PG8_MMA(1, 0, At, B0); PG8_BAR; PG8_SCHED;
;             PG8_STAGE(PG8_SB(0, 1), b2 + hstep, voffB);
;             PG8_WAIT_V(6); PG8_BAR; PG8_MMA(1, 1, At, B1); PG8_BAR;
;             PG8_LDB(B0, 1, 0); PG8_SCHED; PG8_LDA(At, 1, 0); PG8_STAGE(PG8_SA(0, 1), a2 + hstep, voffA);
;             PG8_WAIT_L(8); PG8_BAR; PG8_WAIT_L(0); PG8_MMA(0, 0, At, B0); PG8_BAR; PG8_SCHED;
;             PG8_LDB(B1, 1, 1); PG8_STAGE(PG8_SB(1, 0), b3, voffB);
;             PG8_BAR; PG8_WAIT_L(0); PG8_MMA(0, 1, At, B1); PG8_BAR;
;             PG8_LDA(At, 1, 1); PG8_STAGE(PG8_SA(1, 0), a3, voffA);
;             PG8_BAR; PG8_WAIT_L(0); PG8_MMA(1, 0, At, B0); PG8_BAR; PG8_SCHED;
;             PG8_STAGE(PG8_SB(1, 1), b3 + hstep, voffB);
;             PG8_WAIT_V(6); PG8_BAR; PG8_MMA(1, 1, At, B1); PG8_BAR;
.LdsA_skip_1:
	v_mfma_f32_16x16x32_bf16 v[114:117], v[140:143], v[176:179], v[114:117]
	v_mfma_f32_16x16x32_bf16 v[106:109], v[154:157], v[176:179], v[106:109]
	v_mfma_f32_16x16x32_bf16 v[98:101], v[140:143], v[184:187], v[98:101]
	v_mfma_f32_16x16x32_bf16 v[90:93], v[154:157], v[184:187], v[90:93]
	v_mfma_f32_16x16x32_bf16 v[82:85], v[140:143], v[208:211], v[82:85]
	v_mfma_f32_16x16x32_bf16 v[74:77], v[154:157], v[208:211], v[74:77]
	v_mfma_f32_16x16x32_bf16 v[126:129], v[144:147], v[172:175], v[126:129]
	v_mfma_f32_16x16x32_bf16 v[122:125], v[158:161], v[172:175], v[122:125]
	v_mfma_f32_16x16x32_bf16 v[114:117], v[144:147], v[180:183], v[114:117]
	v_mfma_f32_16x16x32_bf16 v[106:109], v[158:161], v[180:183], v[106:109]
	v_mfma_f32_16x16x32_bf16 v[98:101], v[144:147], v[204:207], v[98:101]
	v_mfma_f32_16x16x32_bf16 v[90:93], v[158:161], v[204:207], v[90:93]
	v_mfma_f32_16x16x32_bf16 v[82:85], v[144:147], v[212:215], v[82:85]
	v_mfma_f32_16x16x32_bf16 v[74:77], v[158:161], v[212:215], v[74:77]
	s_setprio 0
	s_barrier
	s_add_i32 s36, 0, 0x1c000
	s_add_i32 s37, s58, s44
	v_add_u32_e32 v153, s36, v149
	s_add_u32 s60, s6, 0x80
	s_addc_u32 s61, s7, 0
	s_mov_b32 m0, s37
	ds_read_b128 v[216:219], v153
	ds_read_b128 v[226:229], v153 offset:1024
	ds_read_b128 v[230:233], v153 offset:2048
	ds_read_b128 v[234:237], v153 offset:3072
	global_load_lds_dwordx4 v0, s[60:61]
	s_add_i32 m0, s37, 0x2000
	s_nop 0
	global_load_lds_dwordx4 v130, s[60:61]
	s_barrier
	s_waitcnt lgkmcnt(0)
	s_setprio 1
	s_waitcnt lgkmcnt(0)
	v_mfma_f32_16x16x32_bf16 v[118:121], v[216:219], v[168:171], v[118:121]
	v_mfma_f32_16x16x32_bf16 v[110:113], v[230:233], v[168:171], v[110:113]
	v_mfma_f32_16x16x32_bf16 v[102:105], v[216:219], v[176:179], v[102:105]
	v_mfma_f32_16x16x32_bf16 v[94:97], v[230:233], v[176:179], v[94:97]
	v_mfma_f32_16x16x32_bf16 v[86:89], v[216:219], v[184:187], v[86:89]
	v_mfma_f32_16x16x32_bf16 v[78:81], v[230:233], v[184:187], v[78:81]
	v_mfma_f32_16x16x32_bf16 v[70:73], v[216:219], v[208:211], v[70:73]
	v_mfma_f32_16x16x32_bf16 v[66:69], v[230:233], v[208:211], v[66:69]
	v_mfma_f32_16x16x32_bf16 v[118:121], v[226:229], v[172:175], v[118:121]
	v_mfma_f32_16x16x32_bf16 v[110:113], v[234:237], v[172:175], v[110:113]
	v_mfma_f32_16x16x32_bf16 v[102:105], v[226:229], v[180:183], v[102:105]
	v_mfma_f32_16x16x32_bf16 v[94:97], v[234:237], v[180:183], v[94:97]
	v_mfma_f32_16x16x32_bf16 v[86:89], v[226:229], v[204:207], v[86:89]
	v_mfma_f32_16x16x32_bf16 v[78:81], v[234:237], v[204:207], v[78:81]
	v_mfma_f32_16x16x32_bf16 v[70:73], v[226:229], v[212:215], v[70:73]
	v_mfma_f32_16x16x32_bf16 v[66:69], v[234:237], v[212:215], v[66:69]
	s_setprio 0
	s_mov_b32 m0, s55
	s_barrier
	ds_read_b128 v[168:171], v152 offset:49152
	ds_read_b128 v[172:175], v152 offset:50176
	ds_read_b128 v[176:179], v152 offset:51200
	ds_read_b128 v[180:183], v152 offset:52224
	ds_read_b128 v[184:187], v152 offset:53248
	ds_read_b128 v[204:207], v152 offset:54272
	ds_read_b128 v[208:211], v152 offset:55296
	ds_read_b128 v[212:215], v152 offset:56320
	global_load_lds_dwordx4 v134, vcc
	s_mov_b32 m0, s83
	s_nop 0
	global_load_lds_dwordx4 v132, vcc
	s_barrier
	s_waitcnt lgkmcnt(0)
	s_setprio 1
	s_waitcnt lgkmcnt(0)
	v_mfma_f32_16x16x32_bf16 v[62:65], v[140:143], v[168:171], v[62:65]
	v_mfma_f32_16x16x32_bf16 v[58:61], v[154:157], v[168:171], v[58:61]
	v_mfma_f32_16x16x32_bf16 v[50:53], v[140:143], v[176:179], v[50:53]
	v_mfma_f32_16x16x32_bf16 v[42:45], v[154:157], v[176:179], v[42:45]
	v_mfma_f32_16x16x32_bf16 v[34:37], v[140:143], v[184:187], v[34:37]
	v_mfma_f32_16x16x32_bf16 v[26:29], v[154:157], v[184:187], v[26:29]
	v_mfma_f32_16x16x32_bf16 v[18:21], v[140:143], v[208:211], v[18:21]
	v_mfma_f32_16x16x32_bf16 v[10:13], v[154:157], v[208:211], v[10:13]
	v_mfma_f32_16x16x32_bf16 v[62:65], v[144:147], v[172:175], v[62:65]
	v_mfma_f32_16x16x32_bf16 v[58:61], v[158:161], v[172:175], v[58:61]
	v_mfma_f32_16x16x32_bf16 v[50:53], v[144:147], v[180:183], v[50:53]
	v_mfma_f32_16x16x32_bf16 v[42:45], v[158:161], v[180:183], v[42:45]
	v_mfma_f32_16x16x32_bf16 v[34:37], v[144:147], v[204:207], v[34:37]
	v_mfma_f32_16x16x32_bf16 v[26:29], v[158:161], v[204:207], v[26:29]
	v_mfma_f32_16x16x32_bf16 v[18:21], v[144:147], v[212:215], v[18:21]
	v_mfma_f32_16x16x32_bf16 v[10:13], v[158:161], v[212:215], v[10:13]
	s_setprio 0
	s_barrier
	s_add_u32 s6, s6, 0x40080
	s_addc_u32 s7, s7, 0
	s_add_i32 s36, s36, s44
	s_mov_b32 m0, s36
	s_nop 0
	global_load_lds_dwordx4 v0, s[6:7]
	s_add_i32 m0, s36, 0x2000
	s_nop 0
	global_load_lds_dwordx4 v130, s[6:7]
	s_waitcnt vmcnt(6)
	s_barrier
	s_setprio 1
	v_mfma_f32_16x16x32_bf16 v[54:57], v[216:219], v[168:171], v[54:57]
	v_mfma_f32_16x16x32_bf16 v[46:49], v[230:233], v[168:171], v[46:49]
	v_mfma_f32_16x16x32_bf16 v[38:41], v[216:219], v[176:179], v[38:41]
	v_mfma_f32_16x16x32_bf16 v[30:33], v[230:233], v[176:179], v[30:33]
	v_mfma_f32_16x16x32_bf16 v[22:25], v[216:219], v[184:187], v[22:25]
	v_mfma_f32_16x16x32_bf16 v[14:17], v[230:233], v[184:187], v[14:17]
	v_mfma_f32_16x16x32_bf16 v[6:9], v[216:219], v[208:211], v[6:9]
	v_mfma_f32_16x16x32_bf16 v[2:5], v[230:233], v[208:211], v[2:5]
	v_mfma_f32_16x16x32_bf16 v[54:57], v[226:229], v[172:175], v[54:57]
	v_mfma_f32_16x16x32_bf16 v[46:49], v[234:237], v[172:175], v[46:49]
	v_mfma_f32_16x16x32_bf16 v[38:41], v[226:229], v[180:183], v[38:41]
	v_mfma_f32_16x16x32_bf16 v[30:33], v[234:237], v[180:183], v[30:33]
	v_mfma_f32_16x16x32_bf16 v[22:25], v[226:229], v[204:207], v[22:25]
	v_mfma_f32_16x16x32_bf16 v[14:17], v[234:237], v[204:207], v[14:17]
	v_mfma_f32_16x16x32_bf16 v[6:9], v[226:229], v[212:215], v[6:9]
	v_mfma_f32_16x16x32_bf16 v[2:5], v[234:237], v[212:215], v[2:5]
	s_setprio 0
	s_add_i32 s91, s91, 2
	s_add_u32 s24, s24, 0x100
	s_addc_u32 s25, s25, 0
	s_add_u32 s89, s89, 0x100
	s_addc_u32 s90, s90, 0
	s_cmp_gt_u32 s91, 13
	s_barrier
; #define PG8_STAGE(bufoff, gbase, voff) do { _Pragma("unroll") for (int _i = 0; _i < 2; ++_i) \
;         __builtin_amdgcn_global_load_lds((const unsigned*)((const char*)(gbase) + (voff)[_i]), (LAS unsigned*)(lds + (bufoff) + ldsw + _i * 8192), 16, 0, 0); } while (0)
; #define PG8_LDA(dst, b, h) do { _Pragma("unroll") for (int m = 0; m < 4; ++m) _Pragma("unroll") for (int k = 0; k < 2; ++k) dst[m][k] = *(const LAS bf16x8*)(lds + PG8_SA(b, h) + aoff + m * 2048 + k * 1024); } while (0)
; #define PG8_LDB(dst, b, h) do { _Pragma("unroll") for (int n = 0; n < 2; ++n) _Pragma("unroll") for (int k = 0; k < 2; ++k) dst[n][k] = *(const LAS bf16x8*)(lds + PG8_SB(b, h) + boff + n * 2048 + k * 1024); } while (0)
; #define PG8_WAIT_V(n) asm volatile("s_waitcnt vmcnt(" #n ")" ::: "memory")
; #define PG8_WAIT_L(n) asm volatile("s_waitcnt lgkmcnt(" #n ")" ::: "memory")
; #define PG8_BAR __builtin_amdgcn_s_barrier()
; #define PG8_SCHED __builtin_amdgcn_sched_barrier(0)
; template <class Epi>
; __device__ __forceinline__ void gemm_phase(LAS unsigned char* lds, const Gemm g, const StaticOrder& S, const Epi& E) {
;     ...
;             PG8_LDB(B0, 0, 0); PG8_SCHED; PG8_LDA(At, 0, 0); PG8_STAGE(PG8_SA(1, 1), a1 + hstep, voffA);
;             PG8_WAIT_L(8); PG8_BAR; PG8_WAIT_L(0); PG8_MMA(0, 0, At, B0); PG8_BAR; PG8_SCHED;
;             PG8_LDB(B1, 0, 1); PG8_STAGE(PG8_SB(0, 0), b2, voffB);
;             PG8_BAR; PG8_WAIT_L(0); PG8_MMA(0, 1, At, B1); PG8_BAR;
;             PG8_LDA(At, 0, 1); PG8_STAGE(PG8_SA(0, 0), a2, voffA);
;             PG8_BAR; PG8_WAIT_L(0); PG8_MMA(1, 0, At, B0); PG8_BAR; PG8_SCHED;
;             PG8_STAGE(PG8_SB(0, 1), b2 + hstep, voffB);
;             PG8_WAIT_V(6); PG8_BAR; PG8_MMA(1, 1, At, B1); PG8_BAR;
;             PG8_LDB(B0, 1, 0); PG8_SCHED; PG8_LDA(At, 1, 0); PG8_STAGE(PG8_SA(0, 1), a2 + hstep, voffA);
;             PG8_WAIT_L(8); PG8_BAR; PG8_WAIT_L(0); PG8_MMA(0, 0, At, B0); PG8_BAR; PG8_SCHED;
;             PG8_LDB(B1, 1, 1); PG8_STAGE(PG8_SB(1, 0), b3, voffB);
;             PG8_BAR; PG8_WAIT_L(0); PG8_MMA(0, 1, At, B1); PG8_BAR;
;             PG8_LDA(At, 1, 1); PG8_STAGE(PG8_SA(1, 0), a3, voffA);
;             PG8_BAR; PG8_WAIT_L(0); PG8_MMA(1, 0, At, B0); PG8_BAR; PG8_SCHED;
;             PG8_STAGE(PG8_SB(1, 1), b3 + hstep, voffB);
;             PG8_WAIT_V(6); PG8_BAR; PG8_MMA(1, 1, At, B1); PG8_BAR;
	s_add_u32 s6, s24, 0xfffc0080
	s_addc_u32 s7, s25, -1
	s_add_i32 s58, 0, 0x10000
	v_add_u32_e32 v153, s58, v149
	ds_read_b128 v[140:143], v153
	ds_read_b128 v[144:147], v153 offset:1024
	ds_read_b128 v[154:157], v153 offset:2048
	ds_read_b128 v[158:161], v153 offset:3072
	s_cmp_eq_u32 s91, 12
	s_cselect_b32 s37, s11, s7
	s_cselect_b32 s36, s71, s6
	s_cselect_b32 s7, s9, s90
	s_cselect_b32 s6, s88, s89
	s_add_i32 m0, s47, 0xc000
	ds_read_b128 v[168:171], v152
	ds_read_b128 v[172:175], v152 offset:1024
	ds_read_b128 v[176:179], v152 offset:2048
	ds_read_b128 v[180:183], v152 offset:3072
	ds_read_b128 v[184:187], v152 offset:4096
	ds_read_b128 v[204:207], v152 offset:5120
	ds_read_b128 v[208:211], v152 offset:6144
	ds_read_b128 v[212:215], v152 offset:7168
	global_load_lds_dwordx4 v136, s[24:25]
	s_add_i32 m0, s47, 0xe000
	s_nop 0
	global_load_lds_dwordx4 v138, s[24:25]
	s_waitcnt lgkmcnt(8)
	s_barrier
	s_waitcnt lgkmcnt(0)
	s_setprio 1
	s_waitcnt lgkmcnt(0)
	v_mfma_f32_16x16x32_bf16 v[126:129], v[140:143], v[168:171], v[126:129]
	v_mfma_f32_16x16x32_bf16 v[122:125], v[154:157], v[168:171], v[122:125]
	v_mfma_f32_16x16x32_bf16 v[114:117], v[140:143], v[176:179], v[114:117]
	v_mfma_f32_16x16x32_bf16 v[106:109], v[154:157], v[176:179], v[106:109]
	v_mfma_f32_16x16x32_bf16 v[98:101], v[140:143], v[184:187], v[98:101]
	v_mfma_f32_16x16x32_bf16 v[90:93], v[154:157], v[184:187], v[90:93]
	v_mfma_f32_16x16x32_bf16 v[82:85], v[140:143], v[208:211], v[82:85]
	v_mfma_f32_16x16x32_bf16 v[74:77], v[154:157], v[208:211], v[74:77]
	v_mfma_f32_16x16x32_bf16 v[126:129], v[144:147], v[172:175], v[126:129]
	v_mfma_f32_16x16x32_bf16 v[122:125], v[158:161], v[172:175], v[122:125]
	v_mfma_f32_16x16x32_bf16 v[114:117], v[144:147], v[180:183], v[114:117]
	v_mfma_f32_16x16x32_bf16 v[106:109], v[158:161], v[180:183], v[106:109]
	v_mfma_f32_16x16x32_bf16 v[98:101], v[144:147], v[204:207], v[98:101]
	v_mfma_f32_16x16x32_bf16 v[90:93], v[158:161], v[204:207], v[90:93]
	v_mfma_f32_16x16x32_bf16 v[82:85], v[144:147], v[212:215], v[82:85]
	v_mfma_f32_16x16x32_bf16 v[74:77], v[158:161], v[212:215], v[74:77]
	s_setprio 0
	s_barrier
	s_add_i32 s70, 0, 0x14000
	s_add_i32 s58, s58, s44
	v_add_u32_e32 v153, s70, v149
	s_mov_b32 m0, s58
	ds_read_b128 v[216:219], v153
	ds_read_b128 v[226:229], v153 offset:1024
	ds_read_b128 v[230:233], v153 offset:2048
	ds_read_b128 v[234:237], v153 offset:3072
	global_load_lds_dwordx4 v0, s[6:7]
	s_add_i32 m0, s58, 0x2000
	s_nop 0
	global_load_lds_dwordx4 v130, s[6:7]
	s_barrier
	s_waitcnt lgkmcnt(0)
	s_setprio 1
	s_waitcnt lgkmcnt(0)
	v_mfma_f32_16x16x32_bf16 v[118:121], v[216:219], v[168:171], v[118:121]
	v_mfma_f32_16x16x32_bf16 v[110:113], v[230:233], v[168:171], v[110:113]
	v_mfma_f32_16x16x32_bf16 v[102:105], v[216:219], v[176:179], v[102:105]
	v_mfma_f32_16x16x32_bf16 v[94:97], v[230:233], v[176:179], v[94:97]
	v_mfma_f32_16x16x32_bf16 v[86:89], v[216:219], v[184:187], v[86:89]
	v_mfma_f32_16x16x32_bf16 v[78:81], v[230:233], v[184:187], v[78:81]
	v_mfma_f32_16x16x32_bf16 v[70:73], v[216:219], v[208:211], v[70:73]
	v_mfma_f32_16x16x32_bf16 v[66:69], v[230:233], v[208:211], v[66:69]
	v_mfma_f32_16x16x32_bf16 v[118:121], v[226:229], v[172:175], v[118:121]
	v_mfma_f32_16x16x32_bf16 v[110:113], v[234:237], v[172:175], v[110:113]
	v_mfma_f32_16x16x32_bf16 v[102:105], v[226:229], v[180:183], v[102:105]
	v_mfma_f32_16x16x32_bf16 v[94:97], v[234:237], v[180:183], v[94:97]
	v_mfma_f32_16x16x32_bf16 v[86:89], v[226:229], v[204:207], v[86:89]
	v_mfma_f32_16x16x32_bf16 v[78:81], v[234:237], v[204:207], v[78:81]
	v_mfma_f32_16x16x32_bf16 v[70:73], v[226:229], v[212:215], v[70:73]
	v_mfma_f32_16x16x32_bf16 v[66:69], v[234:237], v[212:215], v[66:69]
	s_setprio 0
	s_mov_b32 m0, s47
	s_add_u32 vcc_lo, s36, 0x80
	s_addc_u32 vcc_hi, s37, 0
	s_barrier
	ds_read_b128 v[168:171], v152 offset:16384
	ds_read_b128 v[172:175], v152 offset:17408
	ds_read_b128 v[176:179], v152 offset:18432
	ds_read_b128 v[180:183], v152 offset:19456
	ds_read_b128 v[184:187], v152 offset:20480
	ds_read_b128 v[204:207], v152 offset:21504
	ds_read_b128 v[208:211], v152 offset:22528
	ds_read_b128 v[212:215], v152 offset:23552
	global_load_lds_dwordx4 v134, s[36:37]
	s_mov_b32 m0, s48
	s_nop 0
	global_load_lds_dwordx4 v132, s[36:37]
	s_barrier
	s_waitcnt lgkmcnt(0)
	s_setprio 1
	s_waitcnt lgkmcnt(0)
	v_mfma_f32_16x16x32_bf16 v[62:65], v[140:143], v[168:171], v[62:65]
	v_mfma_f32_16x16x32_bf16 v[58:61], v[154:157], v[168:171], v[58:61]
	v_mfma_f32_16x16x32_bf16 v[50:53], v[140:143], v[176:179], v[50:53]
	v_mfma_f32_16x16x32_bf16 v[42:45], v[154:157], v[176:179], v[42:45]
	v_mfma_f32_16x16x32_bf16 v[34:37], v[140:143], v[184:187], v[34:37]
	v_mfma_f32_16x16x32_bf16 v[26:29], v[154:157], v[184:187], v[26:29]
	v_mfma_f32_16x16x32_bf16 v[18:21], v[140:143], v[208:211], v[18:21]
	v_mfma_f32_16x16x32_bf16 v[10:13], v[154:157], v[208:211], v[10:13]
	v_mfma_f32_16x16x32_bf16 v[62:65], v[144:147], v[172:175], v[62:65]
	v_mfma_f32_16x16x32_bf16 v[58:61], v[158:161], v[172:175], v[58:61]
	v_mfma_f32_16x16x32_bf16 v[50:53], v[144:147], v[180:183], v[50:53]
	v_mfma_f32_16x16x32_bf16 v[42:45], v[158:161], v[180:183], v[42:45]
	v_mfma_f32_16x16x32_bf16 v[34:37], v[144:147], v[204:207], v[34:37]
	v_mfma_f32_16x16x32_bf16 v[26:29], v[158:161], v[204:207], v[26:29]
	v_mfma_f32_16x16x32_bf16 v[18:21], v[144:147], v[212:215], v[18:21]
	v_mfma_f32_16x16x32_bf16 v[10:13], v[158:161], v[212:215], v[10:13]
	s_setprio 0
	s_barrier
	s_add_u32 s60, s6, 0x40000
	s_addc_u32 s61, s7, 0
	s_add_i32 s58, s70, s44
	s_mov_b32 m0, s58
	s_nop 0
	global_load_lds_dwordx4 v0, s[60:61]
	s_add_i32 m0, s58, 0x2000
	s_nop 0
	global_load_lds_dwordx4 v130, s[60:61]
	s_waitcnt vmcnt(6)
	s_barrier
; __device__ __forceinline__ unsigned pk2(float lo, float hi) { unsigned r; asm("v_cvt_pk_bf16_f32 %0, %1, %2" : "=v"(r) : "v"(lo), "v"(hi)); return r; }
; #define PG8_STAGE(bufoff, gbase, voff) do { _Pragma("unroll") for (int _i = 0; _i < 2; ++_i) \
;         __builtin_amdgcn_global_load_lds((const unsigned*)((const char*)(gbase) + (voff)[_i]), (LAS unsigned*)(lds + (bufoff) + ldsw + _i * 8192), 16, 0, 0); } while (0)
; #define PG8_LDA(dst, b, h) do { _Pragma("unroll") for (int m = 0; m < 4; ++m) _Pragma("unroll") for (int k = 0; k < 2; ++k) dst[m][k] = *(const LAS bf16x8*)(lds + PG8_SA(b, h) + aoff + m * 2048 + k * 1024); } while (0)
;     __device__ __forceinline__ void operator()(const f32x4 (&acc)[2][2][4][2], const Unit& u, int ui, int wr, int wc, int fr, int fq) const {
;     ...
;                     u32x4 w; w.x = pk2(v0[0], v0[1]); w.y = pk2(v0[2], v0[3]); w.z = pk2(v1[0], v1[1]); w.w = pk2(v1[2], v1[3]);
;                     *(u32x4*)(rowp + bj * HALF) = w;
; template <class Epi>
; __device__ __forceinline__ void gemm_phase(LAS unsigned char* lds, const Gemm g, const StaticOrder& S, const Epi& E) {
;     ...
;             PG8_LDB(B0, 0, 0); PG8_SCHED; PG8_LDA(At, 0, 0); PG8_STAGE(PG8_SA(1, 1), a1 + hstep, voffA);
;             PG8_WAIT_L(8); PG8_BAR; PG8_WAIT_L(0); PG8_MMA(0, 0, At, B0); PG8_BAR; PG8_SCHED;
;             PG8_LDB(B1, 0, 1); PG8_STAGE(PG8_SB(0, 0), b2, voffB);
;             PG8_BAR; PG8_WAIT_L(0); PG8_MMA(0, 1, At, B1); PG8_BAR;
;             PG8_LDA(At, 0, 1); PG8_STAGE(PG8_SA(0, 0), a2, voffA);
;             PG8_BAR; PG8_WAIT_L(0); PG8_MMA(1, 0, At, B0); PG8_BAR; PG8_SCHED;
;             PG8_STAGE(PG8_SB(0, 1), b2 + hstep, voffB);
;             PG8_WAIT_V(6); PG8_BAR; PG8_MMA(1, 1, At, B1); PG8_BAR;
;             PG8_LDB(B0, 1, 0); PG8_SCHED; PG8_LDA(At, 1, 0); PG8_STAGE(PG8_SA(0, 1), a2 + hstep, voffA);
;             PG8_WAIT_L(8); PG8_BAR; PG8_WAIT_L(0); PG8_MMA(0, 0, At, B0); PG8_BAR; PG8_SCHED;
;             PG8_LDB(B1, 1, 1); PG8_STAGE(PG8_SB(1, 0), b3, voffB);
;             PG8_BAR; PG8_WAIT_L(0); PG8_MMA(0, 1, At, B1); PG8_BAR;
;             PG8_LDA(At, 1, 1); PG8_STAGE(PG8_SA(1, 0), a3, voffA);
;             PG8_BAR; PG8_WAIT_L(0); PG8_MMA(1, 0, At, B0); PG8_BAR; PG8_SCHED;
;             PG8_STAGE(PG8_SB(1, 1), b3 + hstep, voffB);
;             PG8_WAIT_V(6); PG8_BAR; PG8_MMA(1, 1, At, B1); PG8_BAR;
	s_setprio 1
	v_mfma_f32_16x16x32_bf16 v[54:57], v[216:219], v[168:171], v[54:57]
	v_mfma_f32_16x16x32_bf16 v[46:49], v[230:233], v[168:171], v[46:49]
	v_mfma_f32_16x16x32_bf16 v[38:41], v[216:219], v[176:179], v[38:41]
	v_mfma_f32_16x16x32_bf16 v[30:33], v[230:233], v[176:179], v[30:33]
	v_mfma_f32_16x16x32_bf16 v[22:25], v[216:219], v[184:187], v[22:25]
	v_mfma_f32_16x16x32_bf16 v[14:17], v[230:233], v[184:187], v[14:17]
	v_mfma_f32_16x16x32_bf16 v[6:9], v[216:219], v[208:211], v[6:9]
	v_mfma_f32_16x16x32_bf16 v[2:5], v[230:233], v[208:211], v[2:5]
	v_mfma_f32_16x16x32_bf16 v[54:57], v[226:229], v[172:175], v[54:57]
	v_mfma_f32_16x16x32_bf16 v[46:49], v[234:237], v[172:175], v[46:49]
	v_mfma_f32_16x16x32_bf16 v[38:41], v[226:229], v[180:183], v[38:41]
	v_mfma_f32_16x16x32_bf16 v[30:33], v[234:237], v[180:183], v[30:33]
	v_mfma_f32_16x16x32_bf16 v[22:25], v[226:229], v[204:207], v[22:25]
	v_mfma_f32_16x16x32_bf16 v[14:17], v[234:237], v[204:207], v[14:17]
	v_mfma_f32_16x16x32_bf16 v[6:9], v[226:229], v[212:215], v[6:9]
	v_mfma_f32_16x16x32_bf16 v[2:5], v[234:237], v[212:215], v[2:5]
	s_setprio 0
	s_add_i32 s58, 0, 0x18000
	v_add_u32_e32 v153, s58, v149
	s_barrier
	ds_read_b128 v[140:143], v153
	ds_read_b128 v[144:147], v153 offset:1024
	ds_read_b128 v[154:157], v153 offset:2048
	ds_read_b128 v[158:161], v153 offset:3072
	s_add_u32 s36, s36, 0x40000
	s_addc_u32 s37, s37, 0
	s_mov_b32 m0, s49
	ds_read_b128 v[168:171], v152 offset:32768
	ds_read_b128 v[172:175], v152 offset:33792
	ds_read_b128 v[176:179], v152 offset:34816
	ds_read_b128 v[180:183], v152 offset:35840
	ds_read_b128 v[184:187], v152 offset:36864
	ds_read_b128 v[204:207], v152 offset:37888
	ds_read_b128 v[208:211], v152 offset:38912
	ds_read_b128 v[212:215], v152 offset:39936
	global_load_lds_dwordx4 v134, s[36:37]
	s_mov_b32 m0, s54
	s_nop 0
	global_load_lds_dwordx4 v132, s[36:37]
	s_waitcnt lgkmcnt(8)
	s_barrier
	s_waitcnt lgkmcnt(0)
	s_setprio 1
	s_waitcnt lgkmcnt(0)
	v_mfma_f32_16x16x32_bf16 v[126:129], v[140:143], v[168:171], v[126:129]
	v_mfma_f32_16x16x32_bf16 v[122:125], v[154:157], v[168:171], v[122:125]
	s_cmp_eq_u32 s87, 0
	s_cbranch_scc1 .LdsA_skip_2
	global_store_dwordx4 v166, v[192:195], s[4:5]
.LdsA_skip_2:
	v_mfma_f32_16x16x32_bf16 v[114:117], v[140:143], v[176:179], v[114:117]
	v_mfma_f32_16x16x32_bf16 v[106:109], v[154:157], v[176:179], v[106:109]
	v_mfma_f32_16x16x32_bf16 v[98:101], v[140:143], v[184:187], v[98:101]
	v_mfma_f32_16x16x32_bf16 v[90:93], v[154:157], v[184:187], v[90:93]
	v_mfma_f32_16x16x32_bf16 v[82:85], v[140:143], v[208:211], v[82:85]
	v_mfma_f32_16x16x32_bf16 v[74:77], v[154:157], v[208:211], v[74:77]
	v_mfma_f32_16x16x32_bf16 v[126:129], v[144:147], v[172:175], v[126:129]
	v_mfma_f32_16x16x32_bf16 v[122:125], v[158:161], v[172:175], v[122:125]
	v_mfma_f32_16x16x32_bf16 v[114:117], v[144:147], v[180:183], v[114:117]
	v_mfma_f32_16x16x32_bf16 v[106:109], v[158:161], v[180:183], v[106:109]
	v_mfma_f32_16x16x32_bf16 v[98:101], v[144:147], v[204:207], v[98:101]
	v_mfma_f32_16x16x32_bf16 v[90:93], v[158:161], v[204:207], v[90:93]
	v_mfma_f32_16x16x32_bf16 v[82:85], v[144:147], v[212:215], v[82:85]
	v_mfma_f32_16x16x32_bf16 v[74:77], v[158:161], v[212:215], v[74:77]
	s_setprio 0
	s_barrier
	s_add_i32 s36, 0, 0x1c000
	s_add_i32 s37, s58, s44
	v_add_u32_e32 v153, s36, v149
	s_add_u32 s60, s6, 0x80
	s_addc_u32 s61, s7, 0
	s_mov_b32 m0, s37
	ds_read_b128 v[216:219], v153
	ds_read_b128 v[226:229], v153 offset:1024
	ds_read_b128 v[230:233], v153 offset:2048
	ds_read_b128 v[234:237], v153 offset:3072
	global_load_lds_dwordx4 v0, s[60:61]
	s_add_i32 m0, s37, 0x2000
	s_nop 0
	global_load_lds_dwordx4 v130, s[60:61]
	s_barrier
	s_waitcnt lgkmcnt(0)
	s_setprio 1
	s_waitcnt lgkmcnt(0)
	v_mfma_f32_16x16x32_bf16 v[118:121], v[216:219], v[168:171], v[118:121]
	v_mfma_f32_16x16x32_bf16 v[110:113], v[230:233], v[168:171], v[110:113]
	v_mfma_f32_16x16x32_bf16 v[102:105], v[216:219], v[176:179], v[102:105]
	v_mfma_f32_16x16x32_bf16 v[94:97], v[230:233], v[176:179], v[94:97]
	v_mfma_f32_16x16x32_bf16 v[86:89], v[216:219], v[184:187], v[86:89]
	v_mfma_f32_16x16x32_bf16 v[78:81], v[230:233], v[184:187], v[78:81]
	v_mfma_f32_16x16x32_bf16 v[70:73], v[216:219], v[208:211], v[70:73]
	v_mfma_f32_16x16x32_bf16 v[66:69], v[230:233], v[208:211], v[66:69]
	v_mfma_f32_16x16x32_bf16 v[118:121], v[226:229], v[172:175], v[118:121]
	v_mfma_f32_16x16x32_bf16 v[110:113], v[234:237], v[172:175], v[110:113]
	v_mfma_f32_16x16x32_bf16 v[102:105], v[226:229], v[180:183], v[102:105]
	v_mfma_f32_16x16x32_bf16 v[94:97], v[234:237], v[180:183], v[94:97]
	v_mfma_f32_16x16x32_bf16 v[86:89], v[226:229], v[204:207], v[86:89]
	v_mfma_f32_16x16x32_bf16 v[78:81], v[234:237], v[204:207], v[78:81]
	v_mfma_f32_16x16x32_bf16 v[70:73], v[226:229], v[212:215], v[70:73]
	v_mfma_f32_16x16x32_bf16 v[66:69], v[234:237], v[212:215], v[66:69]
	s_setprio 0
	s_mov_b32 m0, s55
	s_barrier
	ds_read_b128 v[168:171], v152 offset:49152
	ds_read_b128 v[172:175], v152 offset:50176
	ds_read_b128 v[176:179], v152 offset:51200
	ds_read_b128 v[180:183], v152 offset:52224
	ds_read_b128 v[184:187], v152 offset:53248
	ds_read_b128 v[204:207], v152 offset:54272
	ds_read_b128 v[208:211], v152 offset:55296
	ds_read_b128 v[212:215], v152 offset:56320
	global_load_lds_dwordx4 v134, vcc
	s_mov_b32 m0, s83
	s_nop 0
	global_load_lds_dwordx4 v132, vcc
	s_barrier
; #define PG8_STAGE(bufoff, gbase, voff) do { _Pragma("unroll") for (int _i = 0; _i < 2; ++_i) \
;         __builtin_amdgcn_global_load_lds((const unsigned*)((const char*)(gbase) + (voff)[_i]), (LAS unsigned*)(lds + (bufoff) + ldsw + _i * 8192), 16, 0, 0); } while (0)
; #define PG8_LDA(dst, b, h) do { _Pragma("unroll") for (int m = 0; m < 4; ++m) _Pragma("unroll") for (int k = 0; k < 2; ++k) dst[m][k] = *(const LAS bf16x8*)(lds + PG8_SA(b, h) + aoff + m * 2048 + k * 1024); } while (0)
; #define PG8_LDB(dst, b, h) do { _Pragma("unroll") for (int n = 0; n < 2; ++n) _Pragma("unroll") for (int k = 0; k < 2; ++k) dst[n][k] = *(const LAS bf16x8*)(lds + PG8_SB(b, h) + boff + n * 2048 + k * 1024); } while (0)
; #define PG8_WAIT_V(n) asm volatile("s_waitcnt vmcnt(" #n ")" ::: "memory")
; #define PG8_WAIT_L(n) asm volatile("s_waitcnt lgkmcnt(" #n ")" ::: "memory")
; #define PG8_BAR __builtin_amdgcn_s_barrier()
; #define PG8_SCHED __builtin_amdgcn_sched_barrier(0)
; template <class Epi>
; __device__ __forceinline__ void gemm_phase(LAS unsigned char* lds, const Gemm g, const StaticOrder& S, const Epi& E) {
;     ...
;             PG8_LDB(B0, 0, 0); PG8_SCHED; PG8_LDA(At, 0, 0); PG8_STAGE(PG8_SA(1, 1), a1 + hstep, voffA);
;             PG8_WAIT_L(8); PG8_BAR; PG8_WAIT_L(0); PG8_MMA(0, 0, At, B0); PG8_BAR; PG8_SCHED;
;             PG8_LDB(B1, 0, 1); PG8_STAGE(PG8_SB(0, 0), b2, voffB);
;             PG8_BAR; PG8_WAIT_L(0); PG8_MMA(0, 1, At, B1); PG8_BAR;
;             PG8_LDA(At, 0, 1); PG8_STAGE(PG8_SA(0, 0), a2, voffA);
;             PG8_BAR; PG8_WAIT_L(0); PG8_MMA(1, 0, At, B0); PG8_BAR; PG8_SCHED;
;             PG8_STAGE(PG8_SB(0, 1), b2 + hstep, voffB);
;             PG8_WAIT_V(6); PG8_BAR; PG8_MMA(1, 1, At, B1); PG8_BAR;
;             PG8_LDB(B0, 1, 0); PG8_SCHED; PG8_LDA(At, 1, 0); PG8_STAGE(PG8_SA(0, 1), a2 + hstep, voffA);
;             PG8_WAIT_L(8); PG8_BAR; PG8_WAIT_L(0); PG8_MMA(0, 0, At, B0); PG8_BAR; PG8_SCHED;
;             PG8_LDB(B1, 1, 1); PG8_STAGE(PG8_SB(1, 0), b3, voffB);
;             PG8_BAR; PG8_WAIT_L(0); PG8_MMA(0, 1, At, B1); PG8_BAR;
;             PG8_LDA(At, 1, 1); PG8_STAGE(PG8_SA(1, 0), a3, voffA);
;             PG8_BAR; PG8_WAIT_L(0); PG8_MMA(1, 0, At, B0); PG8_BAR; PG8_SCHED;
;             PG8_STAGE(PG8_SB(1, 1), b3 + hstep, voffB);
;             PG8_WAIT_V(6); PG8_BAR; PG8_MMA(1, 1, At, B1); PG8_BAR;
	s_waitcnt lgkmcnt(0)
	s_setprio 1
	s_waitcnt lgkmcnt(0)
	v_mfma_f32_16x16x32_bf16 v[62:65], v[140:143], v[168:171], v[62:65]
	v_mfma_f32_16x16x32_bf16 v[58:61], v[154:157], v[168:171], v[58:61]
	v_mfma_f32_16x16x32_bf16 v[50:53], v[140:143], v[176:179], v[50:53]
	v_mfma_f32_16x16x32_bf16 v[42:45], v[154:157], v[176:179], v[42:45]
	v_mfma_f32_16x16x32_bf16 v[34:37], v[140:143], v[184:187], v[34:37]
	v_mfma_f32_16x16x32_bf16 v[26:29], v[154:157], v[184:187], v[26:29]
	v_mfma_f32_16x16x32_bf16 v[18:21], v[140:143], v[208:211], v[18:21]
	v_mfma_f32_16x16x32_bf16 v[10:13], v[154:157], v[208:211], v[10:13]
	v_mfma_f32_16x16x32_bf16 v[62:65], v[144:147], v[172:175], v[62:65]
	v_mfma_f32_16x16x32_bf16 v[58:61], v[158:161], v[172:175], v[58:61]
	v_mfma_f32_16x16x32_bf16 v[50:53], v[144:147], v[180:183], v[50:53]
	v_mfma_f32_16x16x32_bf16 v[42:45], v[158:161], v[180:183], v[42:45]
	v_mfma_f32_16x16x32_bf16 v[34:37], v[144:147], v[204:207], v[34:37]
	v_mfma_f32_16x16x32_bf16 v[26:29], v[158:161], v[204:207], v[26:29]
	v_mfma_f32_16x16x32_bf16 v[18:21], v[144:147], v[212:215], v[18:21]
	v_mfma_f32_16x16x32_bf16 v[10:13], v[158:161], v[212:215], v[10:13]
	s_setprio 0
	s_barrier
	s_add_u32 s6, s6, 0x40080
	s_addc_u32 s7, s7, 0
	s_add_i32 s36, s36, s44
	s_mov_b32 m0, s36
	s_nop 0
	global_load_lds_dwordx4 v0, s[6:7]
	s_add_i32 m0, s36, 0x2000
	s_nop 0
	global_load_lds_dwordx4 v130, s[6:7]
	s_waitcnt vmcnt(6)
	s_barrier
	s_setprio 1
	v_mfma_f32_16x16x32_bf16 v[54:57], v[216:219], v[168:171], v[54:57]
	v_mfma_f32_16x16x32_bf16 v[46:49], v[230:233], v[168:171], v[46:49]
	v_mfma_f32_16x16x32_bf16 v[38:41], v[216:219], v[176:179], v[38:41]
	v_mfma_f32_16x16x32_bf16 v[30:33], v[230:233], v[176:179], v[30:33]
	v_mfma_f32_16x16x32_bf16 v[22:25], v[216:219], v[184:187], v[22:25]
	v_mfma_f32_16x16x32_bf16 v[14:17], v[230:233], v[184:187], v[14:17]
	v_mfma_f32_16x16x32_bf16 v[6:9], v[216:219], v[208:211], v[6:9]
	v_mfma_f32_16x16x32_bf16 v[2:5], v[230:233], v[208:211], v[2:5]
	v_mfma_f32_16x16x32_bf16 v[54:57], v[226:229], v[172:175], v[54:57]
	v_mfma_f32_16x16x32_bf16 v[46:49], v[234:237], v[172:175], v[46:49]
	v_mfma_f32_16x16x32_bf16 v[38:41], v[226:229], v[180:183], v[38:41]
	v_mfma_f32_16x16x32_bf16 v[30:33], v[234:237], v[180:183], v[30:33]
	v_mfma_f32_16x16x32_bf16 v[22:25], v[226:229], v[204:207], v[22:25]
	v_mfma_f32_16x16x32_bf16 v[14:17], v[234:237], v[204:207], v[14:17]
	v_mfma_f32_16x16x32_bf16 v[6:9], v[226:229], v[212:215], v[6:9]
	v_mfma_f32_16x16x32_bf16 v[2:5], v[234:237], v[212:215], v[2:5]
	s_setprio 0
	s_add_i32 s91, s91, 2
	s_add_u32 s24, s24, 0x100
	s_addc_u32 s25, s25, 0
	s_add_u32 s89, s89, 0x100
	s_addc_u32 s90, s90, 0
	s_cmp_gt_u32 s91, 13
	s_barrier
	s_add_u32 s6, s24, 0xfffc0080
	s_addc_u32 s7, s25, -1
	s_add_i32 s58, 0, 0x10000
	v_add_u32_e32 v153, s58, v149
	ds_read_b128 v[140:143], v153
	ds_read_b128 v[144:147], v153 offset:1024
	ds_read_b128 v[154:157], v153 offset:2048
	ds_read_b128 v[158:161], v153 offset:3072
	s_cmp_eq_u32 s91, 12
	s_cselect_b32 s37, s11, s7
	s_cselect_b32 s36, s71, s6
	s_cselect_b32 s7, s9, s90
	s_cselect_b32 s6, s88, s89
	s_add_i32 m0, s47, 0xc000
	ds_read_b128 v[168:171], v152
	ds_read_b128 v[172:175], v152 offset:1024
	ds_read_b128 v[176:179], v152 offset:2048
	ds_read_b128 v[180:183], v152 offset:3072
	ds_read_b128 v[184:187], v152 offset:4096
	ds_read_b128 v[204:207], v152 offset:5120
	ds_read_b128 v[208:211], v152 offset:6144
	ds_read_b128 v[212:215], v152 offset:7168
	global_load_lds_dwordx4 v136, s[24:25]
	s_add_i32 m0, s47, 0xe000
	s_nop 0
	global_load_lds_dwordx4 v138, s[24:25]
	s_waitcnt lgkmcnt(8)
	s_barrier
	s_waitcnt lgkmcnt(0)
	s_setprio 1
	s_waitcnt lgkmcnt(0)
	v_mfma_f32_16x16x32_bf16 v[126:129], v[140:143], v[168:171], v[126:129]
	v_mfma_f32_16x16x32_bf16 v[122:125], v[154:157], v[168:171], v[122:125]
	v_mfma_f32_16x16x32_bf16 v[114:117], v[140:143], v[176:179], v[114:117]
	v_mfma_f32_16x16x32_bf16 v[106:109], v[154:157], v[176:179], v[106:109]
	v_mfma_f32_16x16x32_bf16 v[98:101], v[140:143], v[184:187], v[98:101]
	v_mfma_f32_16x16x32_bf16 v[90:93], v[154:157], v[184:187], v[90:93]
	v_mfma_f32_16x16x32_bf16 v[82:85], v[140:143], v[208:211], v[82:85]
	v_mfma_f32_16x16x32_bf16 v[74:77], v[154:157], v[208:211], v[74:77]
	v_mfma_f32_16x16x32_bf16 v[126:129], v[144:147], v[172:175], v[126:129]
	v_mfma_f32_16x16x32_bf16 v[122:125], v[158:161], v[172:175], v[122:125]
	v_mfma_f32_16x16x32_bf16 v[114:117], v[144:147], v[180:183], v[114:117]
	v_mfma_f32_16x16x32_bf16 v[106:109], v[158:161], v[180:183], v[106:109]
	v_mfma_f32_16x16x32_bf16 v[98:101], v[144:147], v[204:207], v[98:101]
	v_mfma_f32_16x16x32_bf16 v[90:93], v[158:161], v[204:207], v[90:93]
	v_mfma_f32_16x16x32_bf16 v[82:85], v[144:147], v[212:215], v[82:85]
	v_mfma_f32_16x16x32_bf16 v[74:77], v[158:161], v[212:215], v[74:77]
	s_setprio 0
	s_barrier
	s_add_i32 s70, 0, 0x14000
	s_add_i32 s58, s58, s44
	v_add_u32_e32 v153, s70, v149
	s_mov_b32 m0, s58
	ds_read_b128 v[216:219], v153
	ds_read_b128 v[226:229], v153 offset:1024
	ds_read_b128 v[230:233], v153 offset:2048
	ds_read_b128 v[234:237], v153 offset:3072
	global_load_lds_dwordx4 v0, s[6:7]
	s_add_i32 m0, s58, 0x2000
	s_nop 0
	global_load_lds_dwordx4 v130, s[6:7]
	s_barrier
; __device__ __forceinline__ unsigned pk2(float lo, float hi) { unsigned r; asm("v_cvt_pk_bf16_f32 %0, %1, %2" : "=v"(r) : "v"(lo), "v"(hi)); return r; }
; #define PG8_STAGE(bufoff, gbase, voff) do { _Pragma("unroll") for (int _i = 0; _i < 2; ++_i) \
;         __builtin_amdgcn_global_load_lds((const unsigned*)((const char*)(gbase) + (voff)[_i]), (LAS unsigned*)(lds + (bufoff) + ldsw + _i * 8192), 16, 0, 0); } while (0)
; #define PG8_LDA(dst, b, h) do { _Pragma("unroll") for (int m = 0; m < 4; ++m) _Pragma("unroll") for (int k = 0; k < 2; ++k) dst[m][k] = *(const LAS bf16x8*)(lds + PG8_SA(b, h) + aoff + m * 2048 + k * 1024); } while (0)
;     __device__ __forceinline__ void operator()(const f32x4 (&acc)[2][2][4][2], const Unit& u, int ui, int wr, int wc, int fr, int fq) const {
;     ...
;                     u32x4 w; w.x = pk2(v0[0], v0[1]); w.y = pk2(v0[2], v0[3]); w.z = pk2(v1[0], v1[1]); w.w = pk2(v1[2], v1[3]);
;                     *(u32x4*)(rowp + bj * HALF) = w;
; template <class Epi>
; __device__ __forceinline__ void gemm_phase(LAS unsigned char* lds, const Gemm g, const StaticOrder& S, const Epi& E) {
;     ...
;             PG8_LDB(B0, 0, 0); PG8_SCHED; PG8_LDA(At, 0, 0); PG8_STAGE(PG8_SA(1, 1), a1 + hstep, voffA);
;             PG8_WAIT_L(8); PG8_BAR; PG8_WAIT_L(0); PG8_MMA(0, 0, At, B0); PG8_BAR; PG8_SCHED;
;             PG8_LDB(B1, 0, 1); PG8_STAGE(PG8_SB(0, 0), b2, voffB);
;             PG8_BAR; PG8_WAIT_L(0); PG8_MMA(0, 1, At, B1); PG8_BAR;
;             PG8_LDA(At, 0, 1); PG8_STAGE(PG8_SA(0, 0), a2, voffA);
;             PG8_BAR; PG8_WAIT_L(0); PG8_MMA(1, 0, At, B0); PG8_BAR; PG8_SCHED;
;             PG8_STAGE(PG8_SB(0, 1), b2 + hstep, voffB);
;             PG8_WAIT_V(6); PG8_BAR; PG8_MMA(1, 1, At, B1); PG8_BAR;
;             PG8_LDB(B0, 1, 0); PG8_SCHED; PG8_LDA(At, 1, 0); PG8_STAGE(PG8_SA(0, 1), a2 + hstep, voffA);
;             PG8_WAIT_L(8); PG8_BAR; PG8_WAIT_L(0); PG8_MMA(0, 0, At, B0); PG8_BAR; PG8_SCHED;
;             PG8_LDB(B1, 1, 1); PG8_STAGE(PG8_SB(1, 0), b3, voffB);
;             PG8_BAR; PG8_WAIT_L(0); PG8_MMA(0, 1, At, B1); PG8_BAR;
;             PG8_LDA(At, 1, 1); PG8_STAGE(PG8_SA(1, 0), a3, voffA);
;             PG8_BAR; PG8_WAIT_L(0); PG8_MMA(1, 0, At, B0); PG8_BAR; PG8_SCHED;
;             PG8_STAGE(PG8_SB(1, 1), b3 + hstep, voffB);
;             PG8_WAIT_V(6); PG8_BAR; PG8_MMA(1, 1, At, B1); PG8_BAR;
	s_waitcnt lgkmcnt(0)
	s_setprio 1
	s_waitcnt lgkmcnt(0)
	v_mfma_f32_16x16x32_bf16 v[118:121], v[216:219], v[168:171], v[118:121]
	v_mfma_f32_16x16x32_bf16 v[110:113], v[230:233], v[168:171], v[110:113]
	v_mfma_f32_16x16x32_bf16 v[102:105], v[216:219], v[176:179], v[102:105]
	v_mfma_f32_16x16x32_bf16 v[94:97], v[230:233], v[176:179], v[94:97]
	v_mfma_f32_16x16x32_bf16 v[86:89], v[216:219], v[184:187], v[86:89]
	v_mfma_f32_16x16x32_bf16 v[78:81], v[230:233], v[184:187], v[78:81]
	v_mfma_f32_16x16x32_bf16 v[70:73], v[216:219], v[208:211], v[70:73]
	v_mfma_f32_16x16x32_bf16 v[66:69], v[230:233], v[208:211], v[66:69]
	v_mfma_f32_16x16x32_bf16 v[118:121], v[226:229], v[172:175], v[118:121]
	v_mfma_f32_16x16x32_bf16 v[110:113], v[234:237], v[172:175], v[110:113]
	v_mfma_f32_16x16x32_bf16 v[102:105], v[226:229], v[180:183], v[102:105]
	v_mfma_f32_16x16x32_bf16 v[94:97], v[234:237], v[180:183], v[94:97]
	v_mfma_f32_16x16x32_bf16 v[86:89], v[226:229], v[204:207], v[86:89]
	v_mfma_f32_16x16x32_bf16 v[78:81], v[234:237], v[204:207], v[78:81]
	v_mfma_f32_16x16x32_bf16 v[70:73], v[226:229], v[212:215], v[70:73]
	v_mfma_f32_16x16x32_bf16 v[66:69], v[234:237], v[212:215], v[66:69]
	s_setprio 0
	s_mov_b32 m0, s47
	s_add_u32 vcc_lo, s36, 0x80
	s_addc_u32 vcc_hi, s37, 0
	s_barrier
	ds_read_b128 v[168:171], v152 offset:16384
	ds_read_b128 v[172:175], v152 offset:17408
	ds_read_b128 v[176:179], v152 offset:18432
	ds_read_b128 v[180:183], v152 offset:19456
	ds_read_b128 v[184:187], v152 offset:20480
	ds_read_b128 v[204:207], v152 offset:21504
	ds_read_b128 v[208:211], v152 offset:22528
	ds_read_b128 v[212:215], v152 offset:23552
	global_load_lds_dwordx4 v134, s[36:37]
	s_mov_b32 m0, s48
	s_nop 0
	global_load_lds_dwordx4 v132, s[36:37]
	s_barrier
	s_waitcnt lgkmcnt(0)
	s_setprio 1
	s_waitcnt lgkmcnt(0)
	v_mfma_f32_16x16x32_bf16 v[62:65], v[140:143], v[168:171], v[62:65]
	v_mfma_f32_16x16x32_bf16 v[58:61], v[154:157], v[168:171], v[58:61]
	v_mfma_f32_16x16x32_bf16 v[50:53], v[140:143], v[176:179], v[50:53]
	v_mfma_f32_16x16x32_bf16 v[42:45], v[154:157], v[176:179], v[42:45]
	v_mfma_f32_16x16x32_bf16 v[34:37], v[140:143], v[184:187], v[34:37]
	v_mfma_f32_16x16x32_bf16 v[26:29], v[154:157], v[184:187], v[26:29]
	v_mfma_f32_16x16x32_bf16 v[18:21], v[140:143], v[208:211], v[18:21]
	v_mfma_f32_16x16x32_bf16 v[10:13], v[154:157], v[208:211], v[10:13]
	v_mfma_f32_16x16x32_bf16 v[62:65], v[144:147], v[172:175], v[62:65]
	v_mfma_f32_16x16x32_bf16 v[58:61], v[158:161], v[172:175], v[58:61]
	v_mfma_f32_16x16x32_bf16 v[50:53], v[144:147], v[180:183], v[50:53]
	v_mfma_f32_16x16x32_bf16 v[42:45], v[158:161], v[180:183], v[42:45]
	v_mfma_f32_16x16x32_bf16 v[34:37], v[144:147], v[204:207], v[34:37]
	v_mfma_f32_16x16x32_bf16 v[26:29], v[158:161], v[204:207], v[26:29]
	v_mfma_f32_16x16x32_bf16 v[18:21], v[144:147], v[212:215], v[18:21]
	v_mfma_f32_16x16x32_bf16 v[10:13], v[158:161], v[212:215], v[10:13]
	s_setprio 0
	s_barrier
	s_add_u32 s60, s6, 0x40000
	s_addc_u32 s61, s7, 0
	s_add_i32 s58, s70, s44
	s_mov_b32 m0, s58
	s_nop 0
	global_load_lds_dwordx4 v0, s[60:61]
	s_add_i32 m0, s58, 0x2000
	s_nop 0
	global_load_lds_dwordx4 v130, s[60:61]
	s_waitcnt vmcnt(6)
	s_barrier
	s_setprio 1
	v_mfma_f32_16x16x32_bf16 v[54:57], v[216:219], v[168:171], v[54:57]
	v_mfma_f32_16x16x32_bf16 v[46:49], v[230:233], v[168:171], v[46:49]
	v_mfma_f32_16x16x32_bf16 v[38:41], v[216:219], v[176:179], v[38:41]
	v_mfma_f32_16x16x32_bf16 v[30:33], v[230:233], v[176:179], v[30:33]
	v_mfma_f32_16x16x32_bf16 v[22:25], v[216:219], v[184:187], v[22:25]
	v_mfma_f32_16x16x32_bf16 v[14:17], v[230:233], v[184:187], v[14:17]
	v_mfma_f32_16x16x32_bf16 v[6:9], v[216:219], v[208:211], v[6:9]
	v_mfma_f32_16x16x32_bf16 v[2:5], v[230:233], v[208:211], v[2:5]
	v_mfma_f32_16x16x32_bf16 v[54:57], v[226:229], v[172:175], v[54:57]
	v_mfma_f32_16x16x32_bf16 v[46:49], v[234:237], v[172:175], v[46:49]
	v_mfma_f32_16x16x32_bf16 v[38:41], v[226:229], v[180:183], v[38:41]
	v_mfma_f32_16x16x32_bf16 v[30:33], v[234:237], v[180:183], v[30:33]
	v_mfma_f32_16x16x32_bf16 v[22:25], v[226:229], v[204:207], v[22:25]
	v_mfma_f32_16x16x32_bf16 v[14:17], v[234:237], v[204:207], v[14:17]
	v_mfma_f32_16x16x32_bf16 v[6:9], v[226:229], v[212:215], v[6:9]
	v_mfma_f32_16x16x32_bf16 v[2:5], v[234:237], v[212:215], v[2:5]
	s_setprio 0
	s_add_i32 s58, 0, 0x18000
	v_add_u32_e32 v153, s58, v149
	s_barrier
	ds_read_b128 v[140:143], v153
	ds_read_b128 v[144:147], v153 offset:1024
	ds_read_b128 v[154:157], v153 offset:2048
	ds_read_b128 v[158:161], v153 offset:3072
	s_add_u32 s36, s36, 0x40000
	s_addc_u32 s37, s37, 0
	s_mov_b32 m0, s49
	ds_read_b128 v[168:171], v152 offset:32768
	ds_read_b128 v[172:175], v152 offset:33792
	ds_read_b128 v[176:179], v152 offset:34816
	ds_read_b128 v[180:183], v152 offset:35840
	ds_read_b128 v[184:187], v152 offset:36864
	ds_read_b128 v[204:207], v152 offset:37888
	ds_read_b128 v[208:211], v152 offset:38912
	ds_read_b128 v[212:215], v152 offset:39936
	global_load_lds_dwordx4 v134, s[36:37]
	s_mov_b32 m0, s54
	s_nop 0
	global_load_lds_dwordx4 v132, s[36:37]
	s_waitcnt lgkmcnt(8)
	s_barrier
	s_waitcnt lgkmcnt(0)
	s_setprio 1
	s_waitcnt lgkmcnt(0)
	v_mfma_f32_16x16x32_bf16 v[126:129], v[140:143], v[168:171], v[126:129]
	v_mfma_f32_16x16x32_bf16 v[122:125], v[154:157], v[168:171], v[122:125]
	s_cmp_eq_u32 s87, 0
	s_cbranch_scc1 .LdsA_skip_3
	global_store_dwordx4 v166, v[196:199], s[4:5] offset:256
	s_nop 1
	v_add_u32_e32 v166, 0xe000, v166
; #define PG8_STAGE(bufoff, gbase, voff) do { _Pragma("unroll") for (int _i = 0; _i < 2; ++_i) \
;         __builtin_amdgcn_global_load_lds((const unsigned*)((const char*)(gbase) + (voff)[_i]), (LAS unsigned*)(lds + (bufoff) + ldsw + _i * 8192), 16, 0, 0); } while (0)
; #define PG8_LDA(dst, b, h) do { _Pragma("unroll") for (int m = 0; m < 4; ++m) _Pragma("unroll") for (int k = 0; k < 2; ++k) dst[m][k] = *(const LAS bf16x8*)(lds + PG8_SA(b, h) + aoff + m * 2048 + k * 1024); } while (0)
; #define PG8_LDB(dst, b, h) do { _Pragma("unroll") for (int n = 0; n < 2; ++n) _Pragma("unroll") for (int k = 0; k < 2; ++k) dst[n][k] = *(const LAS bf16x8*)(lds + PG8_SB(b, h) + boff + n * 2048 + k * 1024); } while (0)
; #define PG8_WAIT_V(n) asm volatile("s_waitcnt vmcnt(" #n ")" ::: "memory")
; #define PG8_WAIT_L(n) asm volatile("s_waitcnt lgkmcnt(" #n ")" ::: "memory")
; #define PG8_BAR __builtin_amdgcn_s_barrier()
; #define PG8_SCHED __builtin_amdgcn_sched_barrier(0)
; template <class Epi>
; __device__ __forceinline__ void gemm_phase(LAS unsigned char* lds, const Gemm g, const StaticOrder& S, const Epi& E) {
;     ...
;             PG8_LDB(B0, 0, 0); PG8_SCHED; PG8_LDA(At, 0, 0); PG8_STAGE(PG8_SA(1, 1), a1 + hstep, voffA);
;             PG8_WAIT_L(8); PG8_BAR; PG8_WAIT_L(0); PG8_MMA(0, 0, At, B0); PG8_BAR; PG8_SCHED;
;             PG8_LDB(B1, 0, 1); PG8_STAGE(PG8_SB(0, 0), b2, voffB);
;             PG8_BAR; PG8_WAIT_L(0); PG8_MMA(0, 1, At, B1); PG8_BAR;
;             PG8_LDA(At, 0, 1); PG8_STAGE(PG8_SA(0, 0), a2, voffA);
;             PG8_BAR; PG8_WAIT_L(0); PG8_MMA(1, 0, At, B0); PG8_BAR; PG8_SCHED;
;             PG8_STAGE(PG8_SB(0, 1), b2 + hstep, voffB);
;             PG8_WAIT_V(6); PG8_BAR; PG8_MMA(1, 1, At, B1); PG8_BAR;
;             PG8_LDB(B0, 1, 0); PG8_SCHED; PG8_LDA(At, 1, 0); PG8_STAGE(PG8_SA(0, 1), a2 + hstep, voffA);
;             PG8_WAIT_L(8); PG8_BAR; PG8_WAIT_L(0); PG8_MMA(0, 0, At, B0); PG8_BAR; PG8_SCHED;
;             PG8_LDB(B1, 1, 1); PG8_STAGE(PG8_SB(1, 0), b3, voffB);
;             PG8_BAR; PG8_WAIT_L(0); PG8_MMA(0, 1, At, B1); PG8_BAR;
;             PG8_LDA(At, 1, 1); PG8_STAGE(PG8_SA(1, 0), a3, voffA);
;             PG8_BAR; PG8_WAIT_L(0); PG8_MMA(1, 0, At, B0); PG8_BAR; PG8_SCHED;
;             PG8_STAGE(PG8_SB(1, 1), b3 + hstep, voffB);
;             PG8_WAIT_V(6); PG8_BAR; PG8_MMA(1, 1, At, B1); PG8_BAR;
.LdsA_skip_3:
	v_mfma_f32_16x16x32_bf16 v[114:117], v[140:143], v[176:179], v[114:117]
	v_mfma_f32_16x16x32_bf16 v[106:109], v[154:157], v[176:179], v[106:109]
	v_mfma_f32_16x16x32_bf16 v[98:101], v[140:143], v[184:187], v[98:101]
	v_mfma_f32_16x16x32_bf16 v[90:93], v[154:157], v[184:187], v[90:93]
	v_mfma_f32_16x16x32_bf16 v[82:85], v[140:143], v[208:211], v[82:85]
	v_mfma_f32_16x16x32_bf16 v[74:77], v[154:157], v[208:211], v[74:77]
	v_mfma_f32_16x16x32_bf16 v[126:129], v[144:147], v[172:175], v[126:129]
	v_mfma_f32_16x16x32_bf16 v[122:125], v[158:161], v[172:175], v[122:125]
	v_mfma_f32_16x16x32_bf16 v[114:117], v[144:147], v[180:183], v[114:117]
	v_mfma_f32_16x16x32_bf16 v[106:109], v[158:161], v[180:183], v[106:109]
	v_mfma_f32_16x16x32_bf16 v[98:101], v[144:147], v[204:207], v[98:101]
	v_mfma_f32_16x16x32_bf16 v[90:93], v[158:161], v[204:207], v[90:93]
	v_mfma_f32_16x16x32_bf16 v[82:85], v[144:147], v[212:215], v[82:85]
	v_mfma_f32_16x16x32_bf16 v[74:77], v[158:161], v[212:215], v[74:77]
	s_setprio 0
	s_barrier
	s_add_i32 s36, 0, 0x1c000
	s_add_i32 s37, s58, s44
	v_add_u32_e32 v153, s36, v149
	s_add_u32 s60, s6, 0x80
	s_addc_u32 s61, s7, 0
	s_mov_b32 m0, s37
	ds_read_b128 v[216:219], v153
	ds_read_b128 v[226:229], v153 offset:1024
	ds_read_b128 v[230:233], v153 offset:2048
	ds_read_b128 v[234:237], v153 offset:3072
	global_load_lds_dwordx4 v0, s[60:61]
	s_add_i32 m0, s37, 0x2000
	s_nop 0
	global_load_lds_dwordx4 v130, s[60:61]
	s_barrier
	s_waitcnt lgkmcnt(0)
	s_setprio 1
	s_waitcnt lgkmcnt(0)
	v_mfma_f32_16x16x32_bf16 v[118:121], v[216:219], v[168:171], v[118:121]
	v_mfma_f32_16x16x32_bf16 v[110:113], v[230:233], v[168:171], v[110:113]
	v_mfma_f32_16x16x32_bf16 v[102:105], v[216:219], v[176:179], v[102:105]
	v_mfma_f32_16x16x32_bf16 v[94:97], v[230:233], v[176:179], v[94:97]
	v_mfma_f32_16x16x32_bf16 v[86:89], v[216:219], v[184:187], v[86:89]
	v_mfma_f32_16x16x32_bf16 v[78:81], v[230:233], v[184:187], v[78:81]
	v_mfma_f32_16x16x32_bf16 v[70:73], v[216:219], v[208:211], v[70:73]
	v_mfma_f32_16x16x32_bf16 v[66:69], v[230:233], v[208:211], v[66:69]
	v_mfma_f32_16x16x32_bf16 v[118:121], v[226:229], v[172:175], v[118:121]
	v_mfma_f32_16x16x32_bf16 v[110:113], v[234:237], v[172:175], v[110:113]
	v_mfma_f32_16x16x32_bf16 v[102:105], v[226:229], v[180:183], v[102:105]
	v_mfma_f32_16x16x32_bf16 v[94:97], v[234:237], v[180:183], v[94:97]
	v_mfma_f32_16x16x32_bf16 v[86:89], v[226:229], v[204:207], v[86:89]
	v_mfma_f32_16x16x32_bf16 v[78:81], v[234:237], v[204:207], v[78:81]
	v_mfma_f32_16x16x32_bf16 v[70:73], v[226:229], v[212:215], v[70:73]
	v_mfma_f32_16x16x32_bf16 v[66:69], v[234:237], v[212:215], v[66:69]
	s_setprio 0
	s_mov_b32 m0, s55
	s_barrier
	ds_read_b128 v[168:171], v152 offset:49152
	ds_read_b128 v[172:175], v152 offset:50176
	ds_read_b128 v[176:179], v152 offset:51200
	ds_read_b128 v[180:183], v152 offset:52224
	ds_read_b128 v[184:187], v152 offset:53248
	ds_read_b128 v[204:207], v152 offset:54272
	ds_read_b128 v[208:211], v152 offset:55296
	ds_read_b128 v[212:215], v152 offset:56320
	global_load_lds_dwordx4 v134, vcc
	s_mov_b32 m0, s83
	s_nop 0
	global_load_lds_dwordx4 v132, vcc
	s_barrier
	s_waitcnt lgkmcnt(0)
	s_setprio 1
	s_waitcnt lgkmcnt(0)
	v_mfma_f32_16x16x32_bf16 v[62:65], v[140:143], v[168:171], v[62:65]
	v_mfma_f32_16x16x32_bf16 v[58:61], v[154:157], v[168:171], v[58:61]
	v_mfma_f32_16x16x32_bf16 v[50:53], v[140:143], v[176:179], v[50:53]
	v_mfma_f32_16x16x32_bf16 v[42:45], v[154:157], v[176:179], v[42:45]
	v_mfma_f32_16x16x32_bf16 v[34:37], v[140:143], v[184:187], v[34:37]
	v_mfma_f32_16x16x32_bf16 v[26:29], v[154:157], v[184:187], v[26:29]
	v_mfma_f32_16x16x32_bf16 v[18:21], v[140:143], v[208:211], v[18:21]
	v_mfma_f32_16x16x32_bf16 v[10:13], v[154:157], v[208:211], v[10:13]
	v_mfma_f32_16x16x32_bf16 v[62:65], v[144:147], v[172:175], v[62:65]
	v_mfma_f32_16x16x32_bf16 v[58:61], v[158:161], v[172:175], v[58:61]
	v_mfma_f32_16x16x32_bf16 v[50:53], v[144:147], v[180:183], v[50:53]
	v_mfma_f32_16x16x32_bf16 v[42:45], v[158:161], v[180:183], v[42:45]
	v_mfma_f32_16x16x32_bf16 v[34:37], v[144:147], v[204:207], v[34:37]
	v_mfma_f32_16x16x32_bf16 v[26:29], v[158:161], v[204:207], v[26:29]
	v_mfma_f32_16x16x32_bf16 v[18:21], v[144:147], v[212:215], v[18:21]
	v_mfma_f32_16x16x32_bf16 v[10:13], v[158:161], v[212:215], v[10:13]
	s_setprio 0
	s_barrier
	s_add_u32 s6, s6, 0x40080
	s_addc_u32 s7, s7, 0
	s_add_i32 s36, s36, s44
	s_mov_b32 m0, s36
	s_nop 0
	global_load_lds_dwordx4 v0, s[6:7]
	s_add_i32 m0, s36, 0x2000
	s_nop 0
	global_load_lds_dwordx4 v130, s[6:7]
	s_waitcnt vmcnt(6)
	s_barrier
	s_setprio 1
	v_mfma_f32_16x16x32_bf16 v[54:57], v[216:219], v[168:171], v[54:57]
	v_mfma_f32_16x16x32_bf16 v[46:49], v[230:233], v[168:171], v[46:49]
	v_mfma_f32_16x16x32_bf16 v[38:41], v[216:219], v[176:179], v[38:41]
	v_mfma_f32_16x16x32_bf16 v[30:33], v[230:233], v[176:179], v[30:33]
	v_mfma_f32_16x16x32_bf16 v[22:25], v[216:219], v[184:187], v[22:25]
	v_mfma_f32_16x16x32_bf16 v[14:17], v[230:233], v[184:187], v[14:17]
	v_mfma_f32_16x16x32_bf16 v[6:9], v[216:219], v[208:211], v[6:9]
	v_mfma_f32_16x16x32_bf16 v[2:5], v[230:233], v[208:211], v[2:5]
	v_mfma_f32_16x16x32_bf16 v[54:57], v[226:229], v[172:175], v[54:57]
	v_mfma_f32_16x16x32_bf16 v[46:49], v[234:237], v[172:175], v[46:49]
	v_mfma_f32_16x16x32_bf16 v[38:41], v[226:229], v[180:183], v[38:41]
	v_mfma_f32_16x16x32_bf16 v[30:33], v[234:237], v[180:183], v[30:33]
	v_mfma_f32_16x16x32_bf16 v[22:25], v[226:229], v[204:207], v[22:25]
	v_mfma_f32_16x16x32_bf16 v[14:17], v[234:237], v[204:207], v[14:17]
	v_mfma_f32_16x16x32_bf16 v[6:9], v[226:229], v[212:215], v[6:9]
	v_mfma_f32_16x16x32_bf16 v[2:5], v[234:237], v[212:215], v[2:5]
	s_setprio 0
	s_add_i32 s91, s91, 2
	s_add_u32 s24, s24, 0x100
	s_addc_u32 s25, s25, 0
	s_add_u32 s89, s89, 0x100
	s_addc_u32 s90, s90, 0
	s_cmp_gt_u32 s91, 13
	s_barrier
; #define PG8_STAGE(bufoff, gbase, voff) do { _Pragma("unroll") for (int _i = 0; _i < 2; ++_i) \
;         __builtin_amdgcn_global_load_lds((const unsigned*)((const char*)(gbase) + (voff)[_i]), (LAS unsigned*)(lds + (bufoff) + ldsw + _i * 8192), 16, 0, 0); } while (0)
; #define PG8_LDA(dst, b, h) do { _Pragma("unroll") for (int m = 0; m < 4; ++m) _Pragma("unroll") for (int k = 0; k < 2; ++k) dst[m][k] = *(const LAS bf16x8*)(lds + PG8_SA(b, h) + aoff + m * 2048 + k * 1024); } while (0)
; #define PG8_LDB(dst, b, h) do { _Pragma("unroll") for (int n = 0; n < 2; ++n) _Pragma("unroll") for (int k = 0; k < 2; ++k) dst[n][k] = *(const LAS bf16x8*)(lds + PG8_SB(b, h) + boff + n * 2048 + k * 1024); } while (0)
; #define PG8_WAIT_V(n) asm volatile("s_waitcnt vmcnt(" #n ")" ::: "memory")
; #define PG8_WAIT_L(n) asm volatile("s_waitcnt lgkmcnt(" #n ")" ::: "memory")
; #define PG8_BAR __builtin_amdgcn_s_barrier()
; #define PG8_SCHED __builtin_amdgcn_sched_barrier(0)
; template <class Epi>
; __device__ __forceinline__ void gemm_phase(LAS unsigned char* lds, const Gemm g, const StaticOrder& S, const Epi& E) {
;     ...
;             PG8_LDB(B0, 0, 0); PG8_SCHED; PG8_LDA(At, 0, 0); PG8_STAGE(PG8_SA(1, 1), a1 + hstep, voffA);
;             PG8_WAIT_L(8); PG8_BAR; PG8_WAIT_L(0); PG8_MMA(0, 0, At, B0); PG8_BAR; PG8_SCHED;
;             PG8_LDB(B1, 0, 1); PG8_STAGE(PG8_SB(0, 0), b2, voffB);
;             PG8_BAR; PG8_WAIT_L(0); PG8_MMA(0, 1, At, B1); PG8_BAR;
;             PG8_LDA(At, 0, 1); PG8_STAGE(PG8_SA(0, 0), a2, voffA);
;             PG8_BAR; PG8_WAIT_L(0); PG8_MMA(1, 0, At, B0); PG8_BAR; PG8_SCHED;
;             PG8_STAGE(PG8_SB(0, 1), b2 + hstep, voffB);
;             PG8_WAIT_V(6); PG8_BAR; PG8_MMA(1, 1, At, B1); PG8_BAR;
;             PG8_LDB(B0, 1, 0); PG8_SCHED; PG8_LDA(At, 1, 0); PG8_STAGE(PG8_SA(0, 1), a2 + hstep, voffA);
;             PG8_WAIT_L(8); PG8_BAR; PG8_WAIT_L(0); PG8_MMA(0, 0, At, B0); PG8_BAR; PG8_SCHED;
;             PG8_LDB(B1, 1, 1); PG8_STAGE(PG8_SB(1, 0), b3, voffB);
;             PG8_BAR; PG8_WAIT_L(0); PG8_MMA(0, 1, At, B1); PG8_BAR;
;             PG8_LDA(At, 1, 1); PG8_STAGE(PG8_SA(1, 0), a3, voffA);
;             PG8_BAR; PG8_WAIT_L(0); PG8_MMA(1, 0, At, B0); PG8_BAR; PG8_SCHED;
;             PG8_STAGE(PG8_SB(1, 1), b3 + hstep, voffB);
;             PG8_WAIT_V(6); PG8_BAR; PG8_MMA(1, 1, At, B1); PG8_BAR;
	s_add_u32 s6, s24, 0xfffc0080
	s_addc_u32 s7, s25, -1
	s_add_i32 s58, 0, 0x10000
	v_add_u32_e32 v153, s58, v149
	ds_read_b128 v[140:143], v153
	ds_read_b128 v[144:147], v153 offset:1024
	ds_read_b128 v[154:157], v153 offset:2048
	ds_read_b128 v[158:161], v153 offset:3072
	s_cmp_eq_u32 s91, 12
	s_cselect_b32 s37, s11, s7
	s_cselect_b32 s36, s71, s6
	s_cselect_b32 s7, s9, s90
	s_cselect_b32 s6, s88, s89
	s_add_i32 m0, s47, 0xc000
	ds_read_b128 v[168:171], v152
	ds_read_b128 v[172:175], v152 offset:1024
	ds_read_b128 v[176:179], v152 offset:2048
	ds_read_b128 v[180:183], v152 offset:3072
	ds_read_b128 v[184:187], v152 offset:4096
	ds_read_b128 v[204:207], v152 offset:5120
	ds_read_b128 v[208:211], v152 offset:6144
	ds_read_b128 v[212:215], v152 offset:7168
	global_load_lds_dwordx4 v136, s[24:25]
	s_add_i32 m0, s47, 0xe000
	s_nop 0
	global_load_lds_dwordx4 v138, s[24:25]
	s_waitcnt lgkmcnt(8)
	s_barrier
	s_waitcnt lgkmcnt(0)
	s_setprio 1
	s_waitcnt lgkmcnt(0)
	v_mfma_f32_16x16x32_bf16 v[126:129], v[140:143], v[168:171], v[126:129]
	v_mfma_f32_16x16x32_bf16 v[122:125], v[154:157], v[168:171], v[122:125]
	v_mfma_f32_16x16x32_bf16 v[114:117], v[140:143], v[176:179], v[114:117]
	v_mfma_f32_16x16x32_bf16 v[106:109], v[154:157], v[176:179], v[106:109]
	v_mfma_f32_16x16x32_bf16 v[98:101], v[140:143], v[184:187], v[98:101]
	v_mfma_f32_16x16x32_bf16 v[90:93], v[154:157], v[184:187], v[90:93]
	v_mfma_f32_16x16x32_bf16 v[82:85], v[140:143], v[208:211], v[82:85]
	v_mfma_f32_16x16x32_bf16 v[74:77], v[154:157], v[208:211], v[74:77]
	v_mfma_f32_16x16x32_bf16 v[126:129], v[144:147], v[172:175], v[126:129]
	v_mfma_f32_16x16x32_bf16 v[122:125], v[158:161], v[172:175], v[122:125]
	v_mfma_f32_16x16x32_bf16 v[114:117], v[144:147], v[180:183], v[114:117]
	v_mfma_f32_16x16x32_bf16 v[106:109], v[158:161], v[180:183], v[106:109]
	v_mfma_f32_16x16x32_bf16 v[98:101], v[144:147], v[204:207], v[98:101]
	v_mfma_f32_16x16x32_bf16 v[90:93], v[158:161], v[204:207], v[90:93]
	v_mfma_f32_16x16x32_bf16 v[82:85], v[144:147], v[212:215], v[82:85]
	v_mfma_f32_16x16x32_bf16 v[74:77], v[158:161], v[212:215], v[74:77]
	s_setprio 0
	s_barrier
	s_add_i32 s70, 0, 0x14000
	s_add_i32 s58, s58, s44
	v_add_u32_e32 v153, s70, v149
	s_mov_b32 m0, s58
	ds_read_b128 v[216:219], v153
	ds_read_b128 v[226:229], v153 offset:1024
	ds_read_b128 v[230:233], v153 offset:2048
	ds_read_b128 v[234:237], v153 offset:3072
	global_load_lds_dwordx4 v0, s[6:7]
	s_add_i32 m0, s58, 0x2000
	s_nop 0
	global_load_lds_dwordx4 v130, s[6:7]
	s_barrier
	s_waitcnt lgkmcnt(0)
	s_setprio 1
	s_waitcnt lgkmcnt(0)
	v_mfma_f32_16x16x32_bf16 v[118:121], v[216:219], v[168:171], v[118:121]
	v_mfma_f32_16x16x32_bf16 v[110:113], v[230:233], v[168:171], v[110:113]
	v_mfma_f32_16x16x32_bf16 v[102:105], v[216:219], v[176:179], v[102:105]
	v_mfma_f32_16x16x32_bf16 v[94:97], v[230:233], v[176:179], v[94:97]
	v_mfma_f32_16x16x32_bf16 v[86:89], v[216:219], v[184:187], v[86:89]
	v_mfma_f32_16x16x32_bf16 v[78:81], v[230:233], v[184:187], v[78:81]
	v_mfma_f32_16x16x32_bf16 v[70:73], v[216:219], v[208:211], v[70:73]
	v_mfma_f32_16x16x32_bf16 v[66:69], v[230:233], v[208:211], v[66:69]
	v_mfma_f32_16x16x32_bf16 v[118:121], v[226:229], v[172:175], v[118:121]
	v_mfma_f32_16x16x32_bf16 v[110:113], v[234:237], v[172:175], v[110:113]
	v_mfma_f32_16x16x32_bf16 v[102:105], v[226:229], v[180:183], v[102:105]
	v_mfma_f32_16x16x32_bf16 v[94:97], v[234:237], v[180:183], v[94:97]
	v_mfma_f32_16x16x32_bf16 v[86:89], v[226:229], v[204:207], v[86:89]
	v_mfma_f32_16x16x32_bf16 v[78:81], v[234:237], v[204:207], v[78:81]
	v_mfma_f32_16x16x32_bf16 v[70:73], v[226:229], v[212:215], v[70:73]
	v_mfma_f32_16x16x32_bf16 v[66:69], v[234:237], v[212:215], v[66:69]
	s_setprio 0
	s_mov_b32 m0, s47
	s_add_u32 vcc_lo, s36, 0x80
	s_addc_u32 vcc_hi, s37, 0
	s_barrier
	ds_read_b128 v[168:171], v152 offset:16384
	ds_read_b128 v[172:175], v152 offset:17408
	ds_read_b128 v[176:179], v152 offset:18432
	ds_read_b128 v[180:183], v152 offset:19456
	ds_read_b128 v[184:187], v152 offset:20480
	ds_read_b128 v[204:207], v152 offset:21504
	ds_read_b128 v[208:211], v152 offset:22528
	ds_read_b128 v[212:215], v152 offset:23552
	global_load_lds_dwordx4 v134, s[36:37]
	s_mov_b32 m0, s48
	s_nop 0
	global_load_lds_dwordx4 v132, s[36:37]
	s_barrier
	s_waitcnt lgkmcnt(0)
	s_setprio 1
	s_waitcnt lgkmcnt(0)
	v_mfma_f32_16x16x32_bf16 v[62:65], v[140:143], v[168:171], v[62:65]
	v_mfma_f32_16x16x32_bf16 v[58:61], v[154:157], v[168:171], v[58:61]
	v_mfma_f32_16x16x32_bf16 v[50:53], v[140:143], v[176:179], v[50:53]
	v_mfma_f32_16x16x32_bf16 v[42:45], v[154:157], v[176:179], v[42:45]
	v_mfma_f32_16x16x32_bf16 v[34:37], v[140:143], v[184:187], v[34:37]
	v_mfma_f32_16x16x32_bf16 v[26:29], v[154:157], v[184:187], v[26:29]
	v_mfma_f32_16x16x32_bf16 v[18:21], v[140:143], v[208:211], v[18:21]
	v_mfma_f32_16x16x32_bf16 v[10:13], v[154:157], v[208:211], v[10:13]
	v_mfma_f32_16x16x32_bf16 v[62:65], v[144:147], v[172:175], v[62:65]
	v_mfma_f32_16x16x32_bf16 v[58:61], v[158:161], v[172:175], v[58:61]
	v_mfma_f32_16x16x32_bf16 v[50:53], v[144:147], v[180:183], v[50:53]
	v_mfma_f32_16x16x32_bf16 v[42:45], v[158:161], v[180:183], v[42:45]
	v_mfma_f32_16x16x32_bf16 v[34:37], v[144:147], v[204:207], v[34:37]
	v_mfma_f32_16x16x32_bf16 v[26:29], v[158:161], v[204:207], v[26:29]
	v_mfma_f32_16x16x32_bf16 v[18:21], v[144:147], v[212:215], v[18:21]
	v_mfma_f32_16x16x32_bf16 v[10:13], v[158:161], v[212:215], v[10:13]
	s_setprio 0
	s_barrier
	s_add_u32 s60, s6, 0x40000
	s_addc_u32 s61, s7, 0
	s_add_i32 s58, s70, s44
	s_mov_b32 m0, s58
	s_nop 0
	global_load_lds_dwordx4 v0, s[60:61]
	s_add_i32 m0, s58, 0x2000
	s_nop 0
	global_load_lds_dwordx4 v130, s[60:61]
	s_waitcnt vmcnt(6)
	s_barrier
; __device__ __forceinline__ unsigned pk2(float lo, float hi) { unsigned r; asm("v_cvt_pk_bf16_f32 %0, %1, %2" : "=v"(r) : "v"(lo), "v"(hi)); return r; }
; #define PG8_STAGE(bufoff, gbase, voff) do { _Pragma("unroll") for (int _i = 0; _i < 2; ++_i) \
;         __builtin_amdgcn_global_load_lds((const unsigned*)((const char*)(gbase) + (voff)[_i]), (LAS unsigned*)(lds + (bufoff) + ldsw + _i * 8192), 16, 0, 0); } while (0)
; #define PG8_LDA(dst, b, h) do { _Pragma("unroll") for (int m = 0; m < 4; ++m) _Pragma("unroll") for (int k = 0; k < 2; ++k) dst[m][k] = *(const LAS bf16x8*)(lds + PG8_SA(b, h) + aoff + m * 2048 + k * 1024); } while (0)
;     __device__ __forceinline__ void operator()(const f32x4 (&acc)[2][2][4][2], const Unit& u, int ui, int wr, int wc, int fr, int fq) const {
;     ...
;                     u32x4 w; w.x = pk2(v0[0], v0[1]); w.y = pk2(v0[2], v0[3]); w.z = pk2(v1[0], v1[1]); w.w = pk2(v1[2], v1[3]);
;                     *(u32x4*)(rowp + bj * HALF) = w;
; template <class Epi>
; __device__ __forceinline__ void gemm_phase(LAS unsigned char* lds, const Gemm g, const StaticOrder& S, const Epi& E) {
;     ...
;             PG8_LDB(B0, 0, 0); PG8_SCHED; PG8_LDA(At, 0, 0); PG8_STAGE(PG8_SA(1, 1), a1 + hstep, voffA);
;             PG8_WAIT_L(8); PG8_BAR; PG8_WAIT_L(0); PG8_MMA(0, 0, At, B0); PG8_BAR; PG8_SCHED;
;             PG8_LDB(B1, 0, 1); PG8_STAGE(PG8_SB(0, 0), b2, voffB);
;             PG8_BAR; PG8_WAIT_L(0); PG8_MMA(0, 1, At, B1); PG8_BAR;
;             PG8_LDA(At, 0, 1); PG8_STAGE(PG8_SA(0, 0), a2, voffA);
;             PG8_BAR; PG8_WAIT_L(0); PG8_MMA(1, 0, At, B0); PG8_BAR; PG8_SCHED;
;             PG8_STAGE(PG8_SB(0, 1), b2 + hstep, voffB);
;             PG8_WAIT_V(6); PG8_BAR; PG8_MMA(1, 1, At, B1); PG8_BAR;
;             PG8_LDB(B0, 1, 0); PG8_SCHED; PG8_LDA(At, 1, 0); PG8_STAGE(PG8_SA(0, 1), a2 + hstep, voffA);
;             PG8_WAIT_L(8); PG8_BAR; PG8_WAIT_L(0); PG8_MMA(0, 0, At, B0); PG8_BAR; PG8_SCHED;
;             PG8_LDB(B1, 1, 1); PG8_STAGE(PG8_SB(1, 0), b3, voffB);
;             PG8_BAR; PG8_WAIT_L(0); PG8_MMA(0, 1, At, B1); PG8_BAR;
;             PG8_LDA(At, 1, 1); PG8_STAGE(PG8_SA(1, 0), a3, voffA);
;             PG8_BAR; PG8_WAIT_L(0); PG8_MMA(1, 0, At, B0); PG8_BAR; PG8_SCHED;
;             PG8_STAGE(PG8_SB(1, 1), b3 + hstep, voffB);
;             PG8_WAIT_V(6); PG8_BAR; PG8_MMA(1, 1, At, B1); PG8_BAR;
	s_setprio 1
	v_mfma_f32_16x16x32_bf16 v[54:57], v[216:219], v[168:171], v[54:57]
	v_mfma_f32_16x16x32_bf16 v[46:49], v[230:233], v[168:171], v[46:49]
	v_mfma_f32_16x16x32_bf16 v[38:41], v[216:219], v[176:179], v[38:41]
	v_mfma_f32_16x16x32_bf16 v[30:33], v[230:233], v[176:179], v[30:33]
	v_mfma_f32_16x16x32_bf16 v[22:25], v[216:219], v[184:187], v[22:25]
	v_mfma_f32_16x16x32_bf16 v[14:17], v[230:233], v[184:187], v[14:17]
	v_mfma_f32_16x16x32_bf16 v[6:9], v[216:219], v[208:211], v[6:9]
	v_mfma_f32_16x16x32_bf16 v[2:5], v[230:233], v[208:211], v[2:5]
	v_mfma_f32_16x16x32_bf16 v[54:57], v[226:229], v[172:175], v[54:57]
	v_mfma_f32_16x16x32_bf16 v[46:49], v[234:237], v[172:175], v[46:49]
	v_mfma_f32_16x16x32_bf16 v[38:41], v[226:229], v[180:183], v[38:41]
	v_mfma_f32_16x16x32_bf16 v[30:33], v[234:237], v[180:183], v[30:33]
	v_mfma_f32_16x16x32_bf16 v[22:25], v[226:229], v[204:207], v[22:25]
	v_mfma_f32_16x16x32_bf16 v[14:17], v[234:237], v[204:207], v[14:17]
	v_mfma_f32_16x16x32_bf16 v[6:9], v[226:229], v[212:215], v[6:9]
	v_mfma_f32_16x16x32_bf16 v[2:5], v[234:237], v[212:215], v[2:5]
	s_setprio 0
	s_add_i32 s58, 0, 0x18000
	v_add_u32_e32 v153, s58, v149
	s_barrier
	ds_read_b128 v[140:143], v153
	ds_read_b128 v[144:147], v153 offset:1024
	ds_read_b128 v[154:157], v153 offset:2048
	ds_read_b128 v[158:161], v153 offset:3072
	s_add_u32 s36, s36, 0x40000
	s_addc_u32 s37, s37, 0
	s_mov_b32 m0, s49
	ds_read_b128 v[168:171], v152 offset:32768
	ds_read_b128 v[172:175], v152 offset:33792
	ds_read_b128 v[176:179], v152 offset:34816
	ds_read_b128 v[180:183], v152 offset:35840
	ds_read_b128 v[184:187], v152 offset:36864
	ds_read_b128 v[204:207], v152 offset:37888
	ds_read_b128 v[208:211], v152 offset:38912
	ds_read_b128 v[212:215], v152 offset:39936
	global_load_lds_dwordx4 v134, s[36:37]
	s_mov_b32 m0, s54
	s_nop 0
	global_load_lds_dwordx4 v132, s[36:37]
	s_waitcnt lgkmcnt(8)
	s_barrier
	s_waitcnt lgkmcnt(0)
	s_setprio 1
	s_waitcnt lgkmcnt(0)
	v_mfma_f32_16x16x32_bf16 v[126:129], v[140:143], v[168:171], v[126:129]
	v_mfma_f32_16x16x32_bf16 v[122:125], v[154:157], v[168:171], v[122:125]
	s_cmp_eq_u32 s87, 0
	s_cbranch_scc1 .LdsA_skip_4
	global_store_dwordx4 v166, v[200:203], s[4:5]
.LdsA_skip_4:
	v_mfma_f32_16x16x32_bf16 v[114:117], v[140:143], v[176:179], v[114:117]
	v_mfma_f32_16x16x32_bf16 v[106:109], v[154:157], v[176:179], v[106:109]
	v_mfma_f32_16x16x32_bf16 v[98:101], v[140:143], v[184:187], v[98:101]
	v_mfma_f32_16x16x32_bf16 v[90:93], v[154:157], v[184:187], v[90:93]
	v_mfma_f32_16x16x32_bf16 v[82:85], v[140:143], v[208:211], v[82:85]
	v_mfma_f32_16x16x32_bf16 v[74:77], v[154:157], v[208:211], v[74:77]
	v_mfma_f32_16x16x32_bf16 v[126:129], v[144:147], v[172:175], v[126:129]
	v_mfma_f32_16x16x32_bf16 v[122:125], v[158:161], v[172:175], v[122:125]
	v_mfma_f32_16x16x32_bf16 v[114:117], v[144:147], v[180:183], v[114:117]
	v_mfma_f32_16x16x32_bf16 v[106:109], v[158:161], v[180:183], v[106:109]
	v_mfma_f32_16x16x32_bf16 v[98:101], v[144:147], v[204:207], v[98:101]
	v_mfma_f32_16x16x32_bf16 v[90:93], v[158:161], v[204:207], v[90:93]
	v_mfma_f32_16x16x32_bf16 v[82:85], v[144:147], v[212:215], v[82:85]
	v_mfma_f32_16x16x32_bf16 v[74:77], v[158:161], v[212:215], v[74:77]
	s_setprio 0
	s_barrier
	s_add_i32 s36, 0, 0x1c000
	s_add_i32 s37, s58, s44
	v_add_u32_e32 v153, s36, v149
	s_add_u32 s60, s6, 0x80
	s_addc_u32 s61, s7, 0
	s_mov_b32 m0, s37
	ds_read_b128 v[216:219], v153
	ds_read_b128 v[226:229], v153 offset:1024
	ds_read_b128 v[230:233], v153 offset:2048
	ds_read_b128 v[234:237], v153 offset:3072
	global_load_lds_dwordx4 v0, s[60:61]
	s_add_i32 m0, s37, 0x2000
	s_nop 0
	global_load_lds_dwordx4 v130, s[60:61]
	s_barrier
	s_waitcnt lgkmcnt(0)
	s_setprio 1
	s_waitcnt lgkmcnt(0)
	v_mfma_f32_16x16x32_bf16 v[118:121], v[216:219], v[168:171], v[118:121]
	v_mfma_f32_16x16x32_bf16 v[110:113], v[230:233], v[168:171], v[110:113]
	v_mfma_f32_16x16x32_bf16 v[102:105], v[216:219], v[176:179], v[102:105]
	v_mfma_f32_16x16x32_bf16 v[94:97], v[230:233], v[176:179], v[94:97]
	v_mfma_f32_16x16x32_bf16 v[86:89], v[216:219], v[184:187], v[86:89]
	v_mfma_f32_16x16x32_bf16 v[78:81], v[230:233], v[184:187], v[78:81]
	v_mfma_f32_16x16x32_bf16 v[70:73], v[216:219], v[208:211], v[70:73]
	v_mfma_f32_16x16x32_bf16 v[66:69], v[230:233], v[208:211], v[66:69]
	v_mfma_f32_16x16x32_bf16 v[118:121], v[226:229], v[172:175], v[118:121]
	v_mfma_f32_16x16x32_bf16 v[110:113], v[234:237], v[172:175], v[110:113]
	v_mfma_f32_16x16x32_bf16 v[102:105], v[226:229], v[180:183], v[102:105]
	v_mfma_f32_16x16x32_bf16 v[94:97], v[234:237], v[180:183], v[94:97]
	v_mfma_f32_16x16x32_bf16 v[86:89], v[226:229], v[204:207], v[86:89]
	v_mfma_f32_16x16x32_bf16 v[78:81], v[234:237], v[204:207], v[78:81]
	v_mfma_f32_16x16x32_bf16 v[70:73], v[226:229], v[212:215], v[70:73]
	v_mfma_f32_16x16x32_bf16 v[66:69], v[234:237], v[212:215], v[66:69]
	s_setprio 0
	s_mov_b32 m0, s55
	s_barrier
	ds_read_b128 v[168:171], v152 offset:49152
	ds_read_b128 v[172:175], v152 offset:50176
	ds_read_b128 v[176:179], v152 offset:51200
	ds_read_b128 v[180:183], v152 offset:52224
	ds_read_b128 v[184:187], v152 offset:53248
	ds_read_b128 v[204:207], v152 offset:54272
	ds_read_b128 v[208:211], v152 offset:55296
	ds_read_b128 v[212:215], v152 offset:56320
	global_load_lds_dwordx4 v134, vcc
	s_mov_b32 m0, s83
	s_nop 0
	global_load_lds_dwordx4 v132, vcc
	s_barrier
; #define PG8_STAGE(bufoff, gbase, voff) do { _Pragma("unroll") for (int _i = 0; _i < 2; ++_i) \
;         __builtin_amdgcn_global_load_lds((const unsigned*)((const char*)(gbase) + (voff)[_i]), (LAS unsigned*)(lds + (bufoff) + ldsw + _i * 8192), 16, 0, 0); } while (0)
; #define PG8_LDA(dst, b, h) do { _Pragma("unroll") for (int m = 0; m < 4; ++m) _Pragma("unroll") for (int k = 0; k < 2; ++k) dst[m][k] = *(const LAS bf16x8*)(lds + PG8_SA(b, h) + aoff + m * 2048 + k * 1024); } while (0)
; #define PG8_LDB(dst, b, h) do { _Pragma("unroll") for (int n = 0; n < 2; ++n) _Pragma("unroll") for (int k = 0; k < 2; ++k) dst[n][k] = *(const LAS bf16x8*)(lds + PG8_SB(b, h) + boff + n * 2048 + k * 1024); } while (0)
; #define PG8_WAIT_V(n) asm volatile("s_waitcnt vmcnt(" #n ")" ::: "memory")
; #define PG8_WAIT_L(n) asm volatile("s_waitcnt lgkmcnt(" #n ")" ::: "memory")
; #define PG8_BAR __builtin_amdgcn_s_barrier()
; #define PG8_SCHED __builtin_amdgcn_sched_barrier(0)
; template <class Epi>
; __device__ __forceinline__ void gemm_phase(LAS unsigned char* lds, const Gemm g, const StaticOrder& S, const Epi& E) {
;     ...
;             PG8_LDB(B0, 0, 0); PG8_SCHED; PG8_LDA(At, 0, 0); PG8_STAGE(PG8_SA(1, 1), a1 + hstep, voffA);
;             PG8_WAIT_L(8); PG8_BAR; PG8_WAIT_L(0); PG8_MMA(0, 0, At, B0); PG8_BAR; PG8_SCHED;
;             PG8_LDB(B1, 0, 1); PG8_STAGE(PG8_SB(0, 0), b2, voffB);
;             PG8_BAR; PG8_WAIT_L(0); PG8_MMA(0, 1, At, B1); PG8_BAR;
;             PG8_LDA(At, 0, 1); PG8_STAGE(PG8_SA(0, 0), a2, voffA);
;             PG8_BAR; PG8_WAIT_L(0); PG8_MMA(1, 0, At, B0); PG8_BAR; PG8_SCHED;
;             PG8_STAGE(PG8_SB(0, 1), b2 + hstep, voffB);
;             PG8_WAIT_V(6); PG8_BAR; PG8_MMA(1, 1, At, B1); PG8_BAR;
;             PG8_LDB(B0, 1, 0); PG8_SCHED; PG8_LDA(At, 1, 0); PG8_STAGE(PG8_SA(0, 1), a2 + hstep, voffA);
;             PG8_WAIT_L(8); PG8_BAR; PG8_WAIT_L(0); PG8_MMA(0, 0, At, B0); PG8_BAR; PG8_SCHED;
;             PG8_LDB(B1, 1, 1); PG8_STAGE(PG8_SB(1, 0), b3, voffB);
;             PG8_BAR; PG8_WAIT_L(0); PG8_MMA(0, 1, At, B1); PG8_BAR;
;             PG8_LDA(At, 1, 1); PG8_STAGE(PG8_SA(1, 0), a3, voffA);
;             PG8_BAR; PG8_WAIT_L(0); PG8_MMA(1, 0, At, B0); PG8_BAR; PG8_SCHED;
;             PG8_STAGE(PG8_SB(1, 1), b3 + hstep, voffB);
;             PG8_WAIT_V(6); PG8_BAR; PG8_MMA(1, 1, At, B1); PG8_BAR;
	s_waitcnt lgkmcnt(0)
	s_setprio 1
	s_waitcnt lgkmcnt(0)
	v_mfma_f32_16x16x32_bf16 v[62:65], v[140:143], v[168:171], v[62:65]
	v_mfma_f32_16x16x32_bf16 v[58:61], v[154:157], v[168:171], v[58:61]
	v_mfma_f32_16x16x32_bf16 v[50:53], v[140:143], v[176:179], v[50:53]
	v_mfma_f32_16x16x32_bf16 v[42:45], v[154:157], v[176:179], v[42:45]
	v_mfma_f32_16x16x32_bf16 v[34:37], v[140:143], v[184:187], v[34:37]
	v_mfma_f32_16x16x32_bf16 v[26:29], v[154:157], v[184:187], v[26:29]
	v_mfma_f32_16x16x32_bf16 v[18:21], v[140:143], v[208:211], v[18:21]
	v_mfma_f32_16x16x32_bf16 v[10:13], v[154:157], v[208:211], v[10:13]
	v_mfma_f32_16x16x32_bf16 v[62:65], v[144:147], v[172:175], v[62:65]
	v_mfma_f32_16x16x32_bf16 v[58:61], v[158:161], v[172:175], v[58:61]
	v_mfma_f32_16x16x32_bf16 v[50:53], v[144:147], v[180:183], v[50:53]
	v_mfma_f32_16x16x32_bf16 v[42:45], v[158:161], v[180:183], v[42:45]
	v_mfma_f32_16x16x32_bf16 v[34:37], v[144:147], v[204:207], v[34:37]
	v_mfma_f32_16x16x32_bf16 v[26:29], v[158:161], v[204:207], v[26:29]
	v_mfma_f32_16x16x32_bf16 v[18:21], v[144:147], v[212:215], v[18:21]
	v_mfma_f32_16x16x32_bf16 v[10:13], v[158:161], v[212:215], v[10:13]
	s_setprio 0
	s_barrier
	s_add_u32 s6, s6, 0x40080
	s_addc_u32 s7, s7, 0
	s_add_i32 s36, s36, s44
	s_mov_b32 m0, s36
	s_nop 0
	global_load_lds_dwordx4 v0, s[6:7]
	s_add_i32 m0, s36, 0x2000
	s_nop 0
	global_load_lds_dwordx4 v130, s[6:7]
	s_waitcnt vmcnt(6)
	s_barrier
	s_setprio 1
	v_mfma_f32_16x16x32_bf16 v[54:57], v[216:219], v[168:171], v[54:57]
	v_mfma_f32_16x16x32_bf16 v[46:49], v[230:233], v[168:171], v[46:49]
	v_mfma_f32_16x16x32_bf16 v[38:41], v[216:219], v[176:179], v[38:41]
	v_mfma_f32_16x16x32_bf16 v[30:33], v[230:233], v[176:179], v[30:33]
	v_mfma_f32_16x16x32_bf16 v[22:25], v[216:219], v[184:187], v[22:25]
	v_mfma_f32_16x16x32_bf16 v[14:17], v[230:233], v[184:187], v[14:17]
	v_mfma_f32_16x16x32_bf16 v[6:9], v[216:219], v[208:211], v[6:9]
	v_mfma_f32_16x16x32_bf16 v[2:5], v[230:233], v[208:211], v[2:5]
	v_mfma_f32_16x16x32_bf16 v[54:57], v[226:229], v[172:175], v[54:57]
	v_mfma_f32_16x16x32_bf16 v[46:49], v[234:237], v[172:175], v[46:49]
	v_mfma_f32_16x16x32_bf16 v[38:41], v[226:229], v[180:183], v[38:41]
	v_mfma_f32_16x16x32_bf16 v[30:33], v[234:237], v[180:183], v[30:33]
	v_mfma_f32_16x16x32_bf16 v[22:25], v[226:229], v[204:207], v[22:25]
	v_mfma_f32_16x16x32_bf16 v[14:17], v[234:237], v[204:207], v[14:17]
	v_mfma_f32_16x16x32_bf16 v[6:9], v[226:229], v[212:215], v[6:9]
	v_mfma_f32_16x16x32_bf16 v[2:5], v[234:237], v[212:215], v[2:5]
	s_setprio 0
	s_add_i32 s91, s91, 2
	s_add_u32 s24, s24, 0x100
	s_addc_u32 s25, s25, 0
	s_add_u32 s89, s89, 0x100
	s_addc_u32 s90, s90, 0
	s_cmp_gt_u32 s91, 13
	s_barrier
	s_add_u32 s6, s24, 0xfffc0080
	s_addc_u32 s7, s25, -1
	s_add_i32 s58, 0, 0x10000
	v_add_u32_e32 v153, s58, v149
	ds_read_b128 v[140:143], v153
	ds_read_b128 v[144:147], v153 offset:1024
	ds_read_b128 v[154:157], v153 offset:2048
	ds_read_b128 v[158:161], v153 offset:3072
	s_cmp_eq_u32 s91, 12
	s_cselect_b32 s37, s11, s7
	s_cselect_b32 s36, s71, s6
	s_cselect_b32 s7, s9, s90
	s_cselect_b32 s6, s88, s89
	s_add_i32 m0, s47, 0xc000
	ds_read_b128 v[168:171], v152
	ds_read_b128 v[172:175], v152 offset:1024
	ds_read_b128 v[176:179], v152 offset:2048
	ds_read_b128 v[180:183], v152 offset:3072
	ds_read_b128 v[184:187], v152 offset:4096
	ds_read_b128 v[204:207], v152 offset:5120
	ds_read_b128 v[208:211], v152 offset:6144
	ds_read_b128 v[212:215], v152 offset:7168
	global_load_lds_dwordx4 v136, s[24:25]
	s_add_i32 m0, s47, 0xe000
	s_nop 0
	global_load_lds_dwordx4 v138, s[24:25]
	s_waitcnt lgkmcnt(8)
	s_barrier
	s_waitcnt lgkmcnt(0)
	s_setprio 1
	s_waitcnt lgkmcnt(0)
	v_mfma_f32_16x16x32_bf16 v[126:129], v[140:143], v[168:171], v[126:129]
	v_mfma_f32_16x16x32_bf16 v[122:125], v[154:157], v[168:171], v[122:125]
	v_mfma_f32_16x16x32_bf16 v[114:117], v[140:143], v[176:179], v[114:117]
	v_mfma_f32_16x16x32_bf16 v[106:109], v[154:157], v[176:179], v[106:109]
	v_mfma_f32_16x16x32_bf16 v[98:101], v[140:143], v[184:187], v[98:101]
	v_mfma_f32_16x16x32_bf16 v[90:93], v[154:157], v[184:187], v[90:93]
	v_mfma_f32_16x16x32_bf16 v[82:85], v[140:143], v[208:211], v[82:85]
	v_mfma_f32_16x16x32_bf16 v[74:77], v[154:157], v[208:211], v[74:77]
	v_mfma_f32_16x16x32_bf16 v[126:129], v[144:147], v[172:175], v[126:129]
	v_mfma_f32_16x16x32_bf16 v[122:125], v[158:161], v[172:175], v[122:125]
	v_mfma_f32_16x16x32_bf16 v[114:117], v[144:147], v[180:183], v[114:117]
	v_mfma_f32_16x16x32_bf16 v[106:109], v[158:161], v[180:183], v[106:109]
	v_mfma_f32_16x16x32_bf16 v[98:101], v[144:147], v[204:207], v[98:101]
	v_mfma_f32_16x16x32_bf16 v[90:93], v[158:161], v[204:207], v[90:93]
	v_mfma_f32_16x16x32_bf16 v[82:85], v[144:147], v[212:215], v[82:85]
	v_mfma_f32_16x16x32_bf16 v[74:77], v[158:161], v[212:215], v[74:77]
	s_setprio 0
	s_barrier
	s_add_i32 s70, 0, 0x14000
	s_add_i32 s58, s58, s44
	v_add_u32_e32 v153, s70, v149
	s_mov_b32 m0, s58
	ds_read_b128 v[216:219], v153
	ds_read_b128 v[226:229], v153 offset:1024
	ds_read_b128 v[230:233], v153 offset:2048
	ds_read_b128 v[234:237], v153 offset:3072
	global_load_lds_dwordx4 v0, s[6:7]
	s_add_i32 m0, s58, 0x2000
	s_nop 0
	global_load_lds_dwordx4 v130, s[6:7]
	s_barrier
; __device__ __forceinline__ unsigned pk2(float lo, float hi) { unsigned r; asm("v_cvt_pk_bf16_f32 %0, %1, %2" : "=v"(r) : "v"(lo), "v"(hi)); return r; }
; #define PG8_STAGE(bufoff, gbase, voff) do { _Pragma("unroll") for (int _i = 0; _i < 2; ++_i) \
;         __builtin_amdgcn_global_load_lds((const unsigned*)((const char*)(gbase) + (voff)[_i]), (LAS unsigned*)(lds + (bufoff) + ldsw + _i * 8192), 16, 0, 0); } while (0)
; #define PG8_LDA(dst, b, h) do { _Pragma("unroll") for (int m = 0; m < 4; ++m) _Pragma("unroll") for (int k = 0; k < 2; ++k) dst[m][k] = *(const LAS bf16x8*)(lds + PG8_SA(b, h) + aoff + m * 2048 + k * 1024); } while (0)
;     __device__ __forceinline__ void operator()(const f32x4 (&acc)[2][2][4][2], const Unit& u, int ui, int wr, int wc, int fr, int fq) const {
;     ...
;                     u32x4 w; w.x = pk2(v0[0], v0[1]); w.y = pk2(v0[2], v0[3]); w.z = pk2(v1[0], v1[1]); w.w = pk2(v1[2], v1[3]);
;                     *(u32x4*)(rowp + bj * HALF) = w;
; template <class Epi>
; __device__ __forceinline__ void gemm_phase(LAS unsigned char* lds, const Gemm g, const StaticOrder& S, const Epi& E) {
;     ...
;             PG8_LDB(B0, 0, 0); PG8_SCHED; PG8_LDA(At, 0, 0); PG8_STAGE(PG8_SA(1, 1), a1 + hstep, voffA);
;             PG8_WAIT_L(8); PG8_BAR; PG8_WAIT_L(0); PG8_MMA(0, 0, At, B0); PG8_BAR; PG8_SCHED;
;             PG8_LDB(B1, 0, 1); PG8_STAGE(PG8_SB(0, 0), b2, voffB);
;             PG8_BAR; PG8_WAIT_L(0); PG8_MMA(0, 1, At, B1); PG8_BAR;
;             PG8_LDA(At, 0, 1); PG8_STAGE(PG8_SA(0, 0), a2, voffA);
;             PG8_BAR; PG8_WAIT_L(0); PG8_MMA(1, 0, At, B0); PG8_BAR; PG8_SCHED;
;             PG8_STAGE(PG8_SB(0, 1), b2 + hstep, voffB);
;             PG8_WAIT_V(6); PG8_BAR; PG8_MMA(1, 1, At, B1); PG8_BAR;
;             PG8_LDB(B0, 1, 0); PG8_SCHED; PG8_LDA(At, 1, 0); PG8_STAGE(PG8_SA(0, 1), a2 + hstep, voffA);
;             PG8_WAIT_L(8); PG8_BAR; PG8_WAIT_L(0); PG8_MMA(0, 0, At, B0); PG8_BAR; PG8_SCHED;
;             PG8_LDB(B1, 1, 1); PG8_STAGE(PG8_SB(1, 0), b3, voffB);
;             PG8_BAR; PG8_WAIT_L(0); PG8_MMA(0, 1, At, B1); PG8_BAR;
;             PG8_LDA(At, 1, 1); PG8_STAGE(PG8_SA(1, 0), a3, voffA);
;             PG8_BAR; PG8_WAIT_L(0); PG8_MMA(1, 0, At, B0); PG8_BAR; PG8_SCHED;
;             PG8_STAGE(PG8_SB(1, 1), b3 + hstep, voffB);
;             PG8_WAIT_V(6); PG8_BAR; PG8_MMA(1, 1, At, B1); PG8_BAR;
	s_waitcnt lgkmcnt(0)
	s_setprio 1
	s_waitcnt lgkmcnt(0)
	v_mfma_f32_16x16x32_bf16 v[118:121], v[216:219], v[168:171], v[118:121]
	v_mfma_f32_16x16x32_bf16 v[110:113], v[230:233], v[168:171], v[110:113]
	v_mfma_f32_16x16x32_bf16 v[102:105], v[216:219], v[176:179], v[102:105]
	v_mfma_f32_16x16x32_bf16 v[94:97], v[230:233], v[176:179], v[94:97]
	v_mfma_f32_16x16x32_bf16 v[86:89], v[216:219], v[184:187], v[86:89]
	v_mfma_f32_16x16x32_bf16 v[78:81], v[230:233], v[184:187], v[78:81]
	v_mfma_f32_16x16x32_bf16 v[70:73], v[216:219], v[208:211], v[70:73]
	v_mfma_f32_16x16x32_bf16 v[66:69], v[230:233], v[208:211], v[66:69]
	v_mfma_f32_16x16x32_bf16 v[118:121], v[226:229], v[172:175], v[118:121]
	v_mfma_f32_16x16x32_bf16 v[110:113], v[234:237], v[172:175], v[110:113]
	v_mfma_f32_16x16x32_bf16 v[102:105], v[226:229], v[180:183], v[102:105]
	v_mfma_f32_16x16x32_bf16 v[94:97], v[234:237], v[180:183], v[94:97]
	v_mfma_f32_16x16x32_bf16 v[86:89], v[226:229], v[204:207], v[86:89]
	v_mfma_f32_16x16x32_bf16 v[78:81], v[234:237], v[204:207], v[78:81]
	v_mfma_f32_16x16x32_bf16 v[70:73], v[226:229], v[212:215], v[70:73]
	v_mfma_f32_16x16x32_bf16 v[66:69], v[234:237], v[212:215], v[66:69]
	s_setprio 0
	s_mov_b32 m0, s47
	s_add_u32 vcc_lo, s36, 0x80
	s_addc_u32 vcc_hi, s37, 0
	s_barrier
	ds_read_b128 v[168:171], v152 offset:16384
	ds_read_b128 v[172:175], v152 offset:17408
	ds_read_b128 v[176:179], v152 offset:18432
	ds_read_b128 v[180:183], v152 offset:19456
	ds_read_b128 v[184:187], v152 offset:20480
	ds_read_b128 v[204:207], v152 offset:21504
	ds_read_b128 v[208:211], v152 offset:22528
	ds_read_b128 v[212:215], v152 offset:23552
	global_load_lds_dwordx4 v134, s[36:37]
	s_mov_b32 m0, s48
	s_nop 0
	global_load_lds_dwordx4 v132, s[36:37]
	s_barrier
	s_waitcnt lgkmcnt(0)
	s_setprio 1
	s_waitcnt lgkmcnt(0)
	v_mfma_f32_16x16x32_bf16 v[62:65], v[140:143], v[168:171], v[62:65]
	v_mfma_f32_16x16x32_bf16 v[58:61], v[154:157], v[168:171], v[58:61]
	v_mfma_f32_16x16x32_bf16 v[50:53], v[140:143], v[176:179], v[50:53]
	v_mfma_f32_16x16x32_bf16 v[42:45], v[154:157], v[176:179], v[42:45]
	v_mfma_f32_16x16x32_bf16 v[34:37], v[140:143], v[184:187], v[34:37]
	v_mfma_f32_16x16x32_bf16 v[26:29], v[154:157], v[184:187], v[26:29]
	v_mfma_f32_16x16x32_bf16 v[18:21], v[140:143], v[208:211], v[18:21]
	v_mfma_f32_16x16x32_bf16 v[10:13], v[154:157], v[208:211], v[10:13]
	v_mfma_f32_16x16x32_bf16 v[62:65], v[144:147], v[172:175], v[62:65]
	v_mfma_f32_16x16x32_bf16 v[58:61], v[158:161], v[172:175], v[58:61]
	v_mfma_f32_16x16x32_bf16 v[50:53], v[144:147], v[180:183], v[50:53]
	v_mfma_f32_16x16x32_bf16 v[42:45], v[158:161], v[180:183], v[42:45]
	v_mfma_f32_16x16x32_bf16 v[34:37], v[144:147], v[204:207], v[34:37]
	v_mfma_f32_16x16x32_bf16 v[26:29], v[158:161], v[204:207], v[26:29]
	v_mfma_f32_16x16x32_bf16 v[18:21], v[144:147], v[212:215], v[18:21]
	v_mfma_f32_16x16x32_bf16 v[10:13], v[158:161], v[212:215], v[10:13]
	s_setprio 0
	s_barrier
	s_add_u32 s60, s6, 0x40000
	s_addc_u32 s61, s7, 0
	s_add_i32 s58, s70, s44
	s_mov_b32 m0, s58
	s_nop 0
	global_load_lds_dwordx4 v0, s[60:61]
	s_add_i32 m0, s58, 0x2000
	s_nop 0
	global_load_lds_dwordx4 v130, s[60:61]
	s_waitcnt vmcnt(6)
	s_barrier
	s_setprio 1
	v_mfma_f32_16x16x32_bf16 v[54:57], v[216:219], v[168:171], v[54:57]
	v_mfma_f32_16x16x32_bf16 v[46:49], v[230:233], v[168:171], v[46:49]
	v_mfma_f32_16x16x32_bf16 v[38:41], v[216:219], v[176:179], v[38:41]
	v_mfma_f32_16x16x32_bf16 v[30:33], v[230:233], v[176:179], v[30:33]
	v_mfma_f32_16x16x32_bf16 v[22:25], v[216:219], v[184:187], v[22:25]
	v_mfma_f32_16x16x32_bf16 v[14:17], v[230:233], v[184:187], v[14:17]
	v_mfma_f32_16x16x32_bf16 v[6:9], v[216:219], v[208:211], v[6:9]
	v_mfma_f32_16x16x32_bf16 v[2:5], v[230:233], v[208:211], v[2:5]
	v_mfma_f32_16x16x32_bf16 v[54:57], v[226:229], v[172:175], v[54:57]
	v_mfma_f32_16x16x32_bf16 v[46:49], v[234:237], v[172:175], v[46:49]
	v_mfma_f32_16x16x32_bf16 v[38:41], v[226:229], v[180:183], v[38:41]
	v_mfma_f32_16x16x32_bf16 v[30:33], v[234:237], v[180:183], v[30:33]
	v_mfma_f32_16x16x32_bf16 v[22:25], v[226:229], v[204:207], v[22:25]
	v_mfma_f32_16x16x32_bf16 v[14:17], v[234:237], v[204:207], v[14:17]
	v_mfma_f32_16x16x32_bf16 v[6:9], v[226:229], v[212:215], v[6:9]
	v_mfma_f32_16x16x32_bf16 v[2:5], v[234:237], v[212:215], v[2:5]
	s_setprio 0
	s_add_i32 s58, 0, 0x18000
	v_add_u32_e32 v153, s58, v149
	s_barrier
	ds_read_b128 v[140:143], v153
	ds_read_b128 v[144:147], v153 offset:1024
	ds_read_b128 v[154:157], v153 offset:2048
	ds_read_b128 v[158:161], v153 offset:3072
	s_add_u32 s36, s36, 0x40000
	s_addc_u32 s37, s37, 0
	s_mov_b32 m0, s49
	ds_read_b128 v[168:171], v152 offset:32768
	ds_read_b128 v[172:175], v152 offset:33792
	ds_read_b128 v[176:179], v152 offset:34816
	ds_read_b128 v[180:183], v152 offset:35840
	ds_read_b128 v[184:187], v152 offset:36864
	ds_read_b128 v[204:207], v152 offset:37888
	ds_read_b128 v[208:211], v152 offset:38912
	ds_read_b128 v[212:215], v152 offset:39936
	global_load_lds_dwordx4 v134, s[36:37]
	s_mov_b32 m0, s54
	s_nop 0
	global_load_lds_dwordx4 v132, s[36:37]
	s_waitcnt lgkmcnt(8)
	s_barrier
	s_waitcnt lgkmcnt(0)
	s_setprio 1
	s_waitcnt lgkmcnt(0)
	v_mfma_f32_16x16x32_bf16 v[126:129], v[140:143], v[168:171], v[126:129]
	v_mfma_f32_16x16x32_bf16 v[122:125], v[154:157], v[168:171], v[122:125]
	s_cmp_eq_u32 s87, 0
	s_cbranch_scc1 .LdsA_skip_5
	global_store_dwordx4 v166, v[222:225], s[4:5] offset:256
	s_nop 1
	v_add_u32_e32 v166, 0xe000, v166
; #define PG8_STAGE(bufoff, gbase, voff) do { _Pragma("unroll") for (int _i = 0; _i < 2; ++_i) \
;         __builtin_amdgcn_global_load_lds((const unsigned*)((const char*)(gbase) + (voff)[_i]), (LAS unsigned*)(lds + (bufoff) + ldsw + _i * 8192), 16, 0, 0); } while (0)
; #define PG8_LDA(dst, b, h) do { _Pragma("unroll") for (int m = 0; m < 4; ++m) _Pragma("unroll") for (int k = 0; k < 2; ++k) dst[m][k] = *(const LAS bf16x8*)(lds + PG8_SA(b, h) + aoff + m * 2048 + k * 1024); } while (0)
; #define PG8_LDB(dst, b, h) do { _Pragma("unroll") for (int n = 0; n < 2; ++n) _Pragma("unroll") for (int k = 0; k < 2; ++k) dst[n][k] = *(const LAS bf16x8*)(lds + PG8_SB(b, h) + boff + n * 2048 + k * 1024); } while (0)
; #define PG8_WAIT_V(n) asm volatile("s_waitcnt vmcnt(" #n ")" ::: "memory")
; #define PG8_WAIT_L(n) asm volatile("s_waitcnt lgkmcnt(" #n ")" ::: "memory")
; #define PG8_BAR __builtin_amdgcn_s_barrier()
; #define PG8_SCHED __builtin_amdgcn_sched_barrier(0)
; template <class Epi>
; __device__ __forceinline__ void gemm_phase(LAS unsigned char* lds, const Gemm g, const StaticOrder& S, const Epi& E) {
;     ...
;             PG8_LDB(B0, 0, 0); PG8_SCHED; PG8_LDA(At, 0, 0); PG8_STAGE(PG8_SA(1, 1), a1 + hstep, voffA);
;             PG8_WAIT_L(8); PG8_BAR; PG8_WAIT_L(0); PG8_MMA(0, 0, At, B0); PG8_BAR; PG8_SCHED;
;             PG8_LDB(B1, 0, 1); PG8_STAGE(PG8_SB(0, 0), b2, voffB);
;             PG8_BAR; PG8_WAIT_L(0); PG8_MMA(0, 1, At, B1); PG8_BAR;
;             PG8_LDA(At, 0, 1); PG8_STAGE(PG8_SA(0, 0), a2, voffA);
;             PG8_BAR; PG8_WAIT_L(0); PG8_MMA(1, 0, At, B0); PG8_BAR; PG8_SCHED;
;             PG8_STAGE(PG8_SB(0, 1), b2 + hstep, voffB);
;             PG8_WAIT_V(6); PG8_BAR; PG8_MMA(1, 1, At, B1); PG8_BAR;
;             PG8_LDB(B0, 1, 0); PG8_SCHED; PG8_LDA(At, 1, 0); PG8_STAGE(PG8_SA(0, 1), a2 + hstep, voffA);
;             PG8_WAIT_L(8); PG8_BAR; PG8_WAIT_L(0); PG8_MMA(0, 0, At, B0); PG8_BAR; PG8_SCHED;
;             PG8_LDB(B1, 1, 1); PG8_STAGE(PG8_SB(1, 0), b3, voffB);
;             PG8_BAR; PG8_WAIT_L(0); PG8_MMA(0, 1, At, B1); PG8_BAR;
;             PG8_LDA(At, 1, 1); PG8_STAGE(PG8_SA(1, 0), a3, voffA);
;             PG8_BAR; PG8_WAIT_L(0); PG8_MMA(1, 0, At, B0); PG8_BAR; PG8_SCHED;
;             PG8_STAGE(PG8_SB(1, 1), b3 + hstep, voffB);
;             PG8_WAIT_V(6); PG8_BAR; PG8_MMA(1, 1, At, B1); PG8_BAR;
.LdsA_skip_5:
	v_mfma_f32_16x16x32_bf16 v[114:117], v[140:143], v[176:179], v[114:117]
	v_mfma_f32_16x16x32_bf16 v[106:109], v[154:157], v[176:179], v[106:109]
	v_mfma_f32_16x16x32_bf16 v[98:101], v[140:143], v[184:187], v[98:101]
	v_mfma_f32_16x16x32_bf16 v[90:93], v[154:157], v[184:187], v[90:93]
	v_mfma_f32_16x16x32_bf16 v[82:85], v[140:143], v[208:211], v[82:85]
	v_mfma_f32_16x16x32_bf16 v[74:77], v[154:157], v[208:211], v[74:77]
	v_mfma_f32_16x16x32_bf16 v[126:129], v[144:147], v[172:175], v[126:129]
	v_mfma_f32_16x16x32_bf16 v[122:125], v[158:161], v[172:175], v[122:125]
	v_mfma_f32_16x16x32_bf16 v[114:117], v[144:147], v[180:183], v[114:117]
	v_mfma_f32_16x16x32_bf16 v[106:109], v[158:161], v[180:183], v[106:109]
	v_mfma_f32_16x16x32_bf16 v[98:101], v[144:147], v[204:207], v[98:101]
	v_mfma_f32_16x16x32_bf16 v[90:93], v[158:161], v[204:207], v[90:93]
	v_mfma_f32_16x16x32_bf16 v[82:85], v[144:147], v[212:215], v[82:85]
	v_mfma_f32_16x16x32_bf16 v[74:77], v[158:161], v[212:215], v[74:77]
	s_setprio 0
	s_barrier
	s_add_i32 s36, 0, 0x1c000
	s_add_i32 s37, s58, s44
	v_add_u32_e32 v153, s36, v149
	s_add_u32 s60, s6, 0x80
	s_addc_u32 s61, s7, 0
	s_mov_b32 m0, s37
	ds_read_b128 v[216:219], v153
	ds_read_b128 v[226:229], v153 offset:1024
	ds_read_b128 v[230:233], v153 offset:2048
	ds_read_b128 v[234:237], v153 offset:3072
	global_load_lds_dwordx4 v0, s[60:61]
	s_add_i32 m0, s37, 0x2000
	s_nop 0
	global_load_lds_dwordx4 v130, s[60:61]
	s_barrier
	s_waitcnt lgkmcnt(0)
	s_setprio 1
	s_waitcnt lgkmcnt(0)
	v_mfma_f32_16x16x32_bf16 v[118:121], v[216:219], v[168:171], v[118:121]
	v_mfma_f32_16x16x32_bf16 v[110:113], v[230:233], v[168:171], v[110:113]
	v_mfma_f32_16x16x32_bf16 v[102:105], v[216:219], v[176:179], v[102:105]
	v_mfma_f32_16x16x32_bf16 v[94:97], v[230:233], v[176:179], v[94:97]
	v_mfma_f32_16x16x32_bf16 v[86:89], v[216:219], v[184:187], v[86:89]
	v_mfma_f32_16x16x32_bf16 v[78:81], v[230:233], v[184:187], v[78:81]
	v_mfma_f32_16x16x32_bf16 v[70:73], v[216:219], v[208:211], v[70:73]
	v_mfma_f32_16x16x32_bf16 v[66:69], v[230:233], v[208:211], v[66:69]
	v_mfma_f32_16x16x32_bf16 v[118:121], v[226:229], v[172:175], v[118:121]
	v_mfma_f32_16x16x32_bf16 v[110:113], v[234:237], v[172:175], v[110:113]
	v_mfma_f32_16x16x32_bf16 v[102:105], v[226:229], v[180:183], v[102:105]
	v_mfma_f32_16x16x32_bf16 v[94:97], v[234:237], v[180:183], v[94:97]
	v_mfma_f32_16x16x32_bf16 v[86:89], v[226:229], v[204:207], v[86:89]
	v_mfma_f32_16x16x32_bf16 v[78:81], v[234:237], v[204:207], v[78:81]
	v_mfma_f32_16x16x32_bf16 v[70:73], v[226:229], v[212:215], v[70:73]
	v_mfma_f32_16x16x32_bf16 v[66:69], v[234:237], v[212:215], v[66:69]
	s_setprio 0
	s_mov_b32 m0, s55
	s_barrier
	ds_read_b128 v[168:171], v152 offset:49152
	ds_read_b128 v[172:175], v152 offset:50176
	ds_read_b128 v[176:179], v152 offset:51200
	ds_read_b128 v[180:183], v152 offset:52224
	ds_read_b128 v[184:187], v152 offset:53248
	ds_read_b128 v[204:207], v152 offset:54272
	ds_read_b128 v[208:211], v152 offset:55296
	ds_read_b128 v[212:215], v152 offset:56320
	global_load_lds_dwordx4 v134, vcc
	s_mov_b32 m0, s83
	s_nop 0
	global_load_lds_dwordx4 v132, vcc
	s_barrier
	s_waitcnt lgkmcnt(0)
	s_setprio 1
	s_waitcnt lgkmcnt(0)
	v_mfma_f32_16x16x32_bf16 v[62:65], v[140:143], v[168:171], v[62:65]
	v_mfma_f32_16x16x32_bf16 v[58:61], v[154:157], v[168:171], v[58:61]
	v_mfma_f32_16x16x32_bf16 v[50:53], v[140:143], v[176:179], v[50:53]
	v_mfma_f32_16x16x32_bf16 v[42:45], v[154:157], v[176:179], v[42:45]
	v_mfma_f32_16x16x32_bf16 v[34:37], v[140:143], v[184:187], v[34:37]
	v_mfma_f32_16x16x32_bf16 v[26:29], v[154:157], v[184:187], v[26:29]
	v_mfma_f32_16x16x32_bf16 v[18:21], v[140:143], v[208:211], v[18:21]
	v_mfma_f32_16x16x32_bf16 v[10:13], v[154:157], v[208:211], v[10:13]
	v_mfma_f32_16x16x32_bf16 v[62:65], v[144:147], v[172:175], v[62:65]
	v_mfma_f32_16x16x32_bf16 v[58:61], v[158:161], v[172:175], v[58:61]
	v_mfma_f32_16x16x32_bf16 v[50:53], v[144:147], v[180:183], v[50:53]
	v_mfma_f32_16x16x32_bf16 v[42:45], v[158:161], v[180:183], v[42:45]
	v_mfma_f32_16x16x32_bf16 v[34:37], v[144:147], v[204:207], v[34:37]
	v_mfma_f32_16x16x32_bf16 v[26:29], v[158:161], v[204:207], v[26:29]
	v_mfma_f32_16x16x32_bf16 v[18:21], v[144:147], v[212:215], v[18:21]
	v_mfma_f32_16x16x32_bf16 v[10:13], v[158:161], v[212:215], v[10:13]
	s_setprio 0
	s_barrier
	s_add_u32 s6, s6, 0x40080
	s_addc_u32 s7, s7, 0
	s_add_i32 s36, s36, s44
	s_mov_b32 m0, s36
	s_nop 0
	global_load_lds_dwordx4 v0, s[6:7]
	s_add_i32 m0, s36, 0x2000
	s_nop 0
	global_load_lds_dwordx4 v130, s[6:7]
	s_waitcnt vmcnt(6)
	s_barrier
	s_setprio 1
	v_mfma_f32_16x16x32_bf16 v[54:57], v[216:219], v[168:171], v[54:57]
	v_mfma_f32_16x16x32_bf16 v[46:49], v[230:233], v[168:171], v[46:49]
	v_mfma_f32_16x16x32_bf16 v[38:41], v[216:219], v[176:179], v[38:41]
	v_mfma_f32_16x16x32_bf16 v[30:33], v[230:233], v[176:179], v[30:33]
	v_mfma_f32_16x16x32_bf16 v[22:25], v[216:219], v[184:187], v[22:25]
	v_mfma_f32_16x16x32_bf16 v[14:17], v[230:233], v[184:187], v[14:17]
	v_mfma_f32_16x16x32_bf16 v[6:9], v[216:219], v[208:211], v[6:9]
	v_mfma_f32_16x16x32_bf16 v[2:5], v[230:233], v[208:211], v[2:5]
	v_mfma_f32_16x16x32_bf16 v[54:57], v[226:229], v[172:175], v[54:57]
	v_mfma_f32_16x16x32_bf16 v[46:49], v[234:237], v[172:175], v[46:49]
	v_mfma_f32_16x16x32_bf16 v[38:41], v[226:229], v[180:183], v[38:41]
	v_mfma_f32_16x16x32_bf16 v[30:33], v[234:237], v[180:183], v[30:33]
	v_mfma_f32_16x16x32_bf16 v[22:25], v[226:229], v[204:207], v[22:25]
	v_mfma_f32_16x16x32_bf16 v[14:17], v[234:237], v[204:207], v[14:17]
	v_mfma_f32_16x16x32_bf16 v[6:9], v[226:229], v[212:215], v[6:9]
	v_mfma_f32_16x16x32_bf16 v[2:5], v[234:237], v[212:215], v[2:5]
	s_setprio 0
	s_add_i32 s91, s91, 2
	s_add_u32 s24, s24, 0x100
	s_addc_u32 s25, s25, 0
	s_add_u32 s89, s89, 0x100
	s_addc_u32 s90, s90, 0
	s_cmp_gt_u32 s91, 13
	s_barrier
; #define PG8_STAGE(bufoff, gbase, voff) do { _Pragma("unroll") for (int _i = 0; _i < 2; ++_i) \
;         __builtin_amdgcn_global_load_lds((const unsigned*)((const char*)(gbase) + (voff)[_i]), (LAS unsigned*)(lds + (bufoff) + ldsw + _i * 8192), 16, 0, 0); } while (0)
; #define PG8_LDA(dst, b, h) do { _Pragma("unroll") for (int m = 0; m < 4; ++m) _Pragma("unroll") for (int k = 0; k < 2; ++k) dst[m][k] = *(const LAS bf16x8*)(lds + PG8_SA(b, h) + aoff + m * 2048 + k * 1024); } while (0)
; #define PG8_LDB(dst, b, h) do { _Pragma("unroll") for (int n = 0; n < 2; ++n) _Pragma("unroll") for (int k = 0; k < 2; ++k) dst[n][k] = *(const LAS bf16x8*)(lds + PG8_SB(b, h) + boff + n * 2048 + k * 1024); } while (0)
; #define PG8_WAIT_V(n) asm volatile("s_waitcnt vmcnt(" #n ")" ::: "memory")
; #define PG8_WAIT_L(n) asm volatile("s_waitcnt lgkmcnt(" #n ")" ::: "memory")
; #define PG8_BAR __builtin_amdgcn_s_barrier()
; #define PG8_SCHED __builtin_amdgcn_sched_barrier(0)
; template <class Epi>
; __device__ __forceinline__ void gemm_phase(LAS unsigned char* lds, const Gemm g, const StaticOrder& S, const Epi& E) {
;     ...
;             PG8_LDB(B0, 0, 0); PG8_SCHED; PG8_LDA(At, 0, 0); PG8_STAGE(PG8_SA(1, 1), a1 + hstep, voffA);
;             PG8_WAIT_L(8); PG8_BAR; PG8_WAIT_L(0); PG8_MMA(0, 0, At, B0); PG8_BAR; PG8_SCHED;
;             PG8_LDB(B1, 0, 1); PG8_STAGE(PG8_SB(0, 0), b2, voffB);
;             PG8_BAR; PG8_WAIT_L(0); PG8_MMA(0, 1, At, B1); PG8_BAR;
;             PG8_LDA(At, 0, 1); PG8_STAGE(PG8_SA(0, 0), a2, voffA);
;             PG8_BAR; PG8_WAIT_L(0); PG8_MMA(1, 0, At, B0); PG8_BAR; PG8_SCHED;
;             PG8_STAGE(PG8_SB(0, 1), b2 + hstep, voffB);
;             PG8_WAIT_V(6); PG8_BAR; PG8_MMA(1, 1, At, B1); PG8_BAR;
;             PG8_LDB(B0, 1, 0); PG8_SCHED; PG8_LDA(At, 1, 0); PG8_STAGE(PG8_SA(0, 1), a2 + hstep, voffA);
;             PG8_WAIT_L(8); PG8_BAR; PG8_WAIT_L(0); PG8_MMA(0, 0, At, B0); PG8_BAR; PG8_SCHED;
;             PG8_LDB(B1, 1, 1); PG8_STAGE(PG8_SB(1, 0), b3, voffB);
;             PG8_BAR; PG8_WAIT_L(0); PG8_MMA(0, 1, At, B1); PG8_BAR;
;             PG8_LDA(At, 1, 1); PG8_STAGE(PG8_SA(1, 0), a3, voffA);
;             PG8_BAR; PG8_WAIT_L(0); PG8_MMA(1, 0, At, B0); PG8_BAR; PG8_SCHED;
;             PG8_STAGE(PG8_SB(1, 1), b3 + hstep, voffB);
;             PG8_WAIT_V(6); PG8_BAR; PG8_MMA(1, 1, At, B1); PG8_BAR;
	s_add_u32 s6, s24, 0xfffc0080
	s_addc_u32 s7, s25, -1
	s_add_i32 s58, 0, 0x10000
	v_add_u32_e32 v153, s58, v149
	ds_read_b128 v[140:143], v153
	ds_read_b128 v[144:147], v153 offset:1024
	ds_read_b128 v[154:157], v153 offset:2048
	ds_read_b128 v[158:161], v153 offset:3072
	s_cmp_eq_u32 s91, 12
	s_cselect_b32 s37, s11, s7
	s_cselect_b32 s36, s71, s6
	s_cselect_b32 s7, s9, s90
	s_cselect_b32 s6, s88, s89
	s_add_i32 m0, s47, 0xc000
	ds_read_b128 v[168:171], v152
	ds_read_b128 v[172:175], v152 offset:1024
	ds_read_b128 v[176:179], v152 offset:2048
	ds_read_b128 v[180:183], v152 offset:3072
	ds_read_b128 v[184:187], v152 offset:4096
	ds_read_b128 v[204:207], v152 offset:5120
	ds_read_b128 v[208:211], v152 offset:6144
	ds_read_b128 v[212:215], v152 offset:7168
	global_load_lds_dwordx4 v136, s[24:25]
	s_add_i32 m0, s47, 0xe000
	s_nop 0
	global_load_lds_dwordx4 v138, s[24:25]
	s_waitcnt lgkmcnt(8)
	s_barrier
	s_waitcnt lgkmcnt(0)
	s_setprio 1
	s_waitcnt lgkmcnt(0)
	v_mfma_f32_16x16x32_bf16 v[126:129], v[140:143], v[168:171], v[126:129]
	v_mfma_f32_16x16x32_bf16 v[122:125], v[154:157], v[168:171], v[122:125]
	v_mfma_f32_16x16x32_bf16 v[114:117], v[140:143], v[176:179], v[114:117]
	v_mfma_f32_16x16x32_bf16 v[106:109], v[154:157], v[176:179], v[106:109]
	v_mfma_f32_16x16x32_bf16 v[98:101], v[140:143], v[184:187], v[98:101]
	v_mfma_f32_16x16x32_bf16 v[90:93], v[154:157], v[184:187], v[90:93]
	v_mfma_f32_16x16x32_bf16 v[82:85], v[140:143], v[208:211], v[82:85]
	v_mfma_f32_16x16x32_bf16 v[74:77], v[154:157], v[208:211], v[74:77]
	v_mfma_f32_16x16x32_bf16 v[126:129], v[144:147], v[172:175], v[126:129]
	v_mfma_f32_16x16x32_bf16 v[122:125], v[158:161], v[172:175], v[122:125]
	v_mfma_f32_16x16x32_bf16 v[114:117], v[144:147], v[180:183], v[114:117]
	v_mfma_f32_16x16x32_bf16 v[106:109], v[158:161], v[180:183], v[106:109]
	v_mfma_f32_16x16x32_bf16 v[98:101], v[144:147], v[204:207], v[98:101]
	v_mfma_f32_16x16x32_bf16 v[90:93], v[158:161], v[204:207], v[90:93]
	v_mfma_f32_16x16x32_bf16 v[82:85], v[144:147], v[212:215], v[82:85]
	v_mfma_f32_16x16x32_bf16 v[74:77], v[158:161], v[212:215], v[74:77]
	s_setprio 0
	s_barrier
	s_add_i32 s70, 0, 0x14000
	s_add_i32 s58, s58, s44
	v_add_u32_e32 v153, s70, v149
	s_mov_b32 m0, s58
	ds_read_b128 v[216:219], v153
	ds_read_b128 v[226:229], v153 offset:1024
	ds_read_b128 v[230:233], v153 offset:2048
	ds_read_b128 v[234:237], v153 offset:3072
	global_load_lds_dwordx4 v0, s[6:7]
	s_add_i32 m0, s58, 0x2000
	s_nop 0
	global_load_lds_dwordx4 v130, s[6:7]
	s_barrier
	s_waitcnt lgkmcnt(0)
	s_setprio 1
	s_waitcnt lgkmcnt(0)
	v_mfma_f32_16x16x32_bf16 v[118:121], v[216:219], v[168:171], v[118:121]
	v_mfma_f32_16x16x32_bf16 v[110:113], v[230:233], v[168:171], v[110:113]
	v_mfma_f32_16x16x32_bf16 v[102:105], v[216:219], v[176:179], v[102:105]
	v_mfma_f32_16x16x32_bf16 v[94:97], v[230:233], v[176:179], v[94:97]
	v_mfma_f32_16x16x32_bf16 v[86:89], v[216:219], v[184:187], v[86:89]
	v_mfma_f32_16x16x32_bf16 v[78:81], v[230:233], v[184:187], v[78:81]
	v_mfma_f32_16x16x32_bf16 v[70:73], v[216:219], v[208:211], v[70:73]
	v_mfma_f32_16x16x32_bf16 v[66:69], v[230:233], v[208:211], v[66:69]
	v_mfma_f32_16x16x32_bf16 v[118:121], v[226:229], v[172:175], v[118:121]
	v_mfma_f32_16x16x32_bf16 v[110:113], v[234:237], v[172:175], v[110:113]
	v_mfma_f32_16x16x32_bf16 v[102:105], v[226:229], v[180:183], v[102:105]
	v_mfma_f32_16x16x32_bf16 v[94:97], v[234:237], v[180:183], v[94:97]
	v_mfma_f32_16x16x32_bf16 v[86:89], v[226:229], v[204:207], v[86:89]
	v_mfma_f32_16x16x32_bf16 v[78:81], v[234:237], v[204:207], v[78:81]
	v_mfma_f32_16x16x32_bf16 v[70:73], v[226:229], v[212:215], v[70:73]
	v_mfma_f32_16x16x32_bf16 v[66:69], v[234:237], v[212:215], v[66:69]
	s_setprio 0
	s_mov_b32 m0, s47
	s_add_u32 vcc_lo, s36, 0x80
	s_addc_u32 vcc_hi, s37, 0
	s_barrier
	ds_read_b128 v[168:171], v152 offset:16384
	ds_read_b128 v[172:175], v152 offset:17408
	ds_read_b128 v[176:179], v152 offset:18432
	ds_read_b128 v[180:183], v152 offset:19456
	ds_read_b128 v[184:187], v152 offset:20480
	ds_read_b128 v[204:207], v152 offset:21504
	ds_read_b128 v[208:211], v152 offset:22528
	ds_read_b128 v[212:215], v152 offset:23552
	global_load_lds_dwordx4 v134, s[36:37]
	s_mov_b32 m0, s48
	s_nop 0
	global_load_lds_dwordx4 v132, s[36:37]
	s_barrier
	s_waitcnt lgkmcnt(0)
	s_setprio 1
	s_waitcnt lgkmcnt(0)
	v_mfma_f32_16x16x32_bf16 v[62:65], v[140:143], v[168:171], v[62:65]
	v_mfma_f32_16x16x32_bf16 v[58:61], v[154:157], v[168:171], v[58:61]
	v_mfma_f32_16x16x32_bf16 v[50:53], v[140:143], v[176:179], v[50:53]
	v_mfma_f32_16x16x32_bf16 v[42:45], v[154:157], v[176:179], v[42:45]
	v_mfma_f32_16x16x32_bf16 v[34:37], v[140:143], v[184:187], v[34:37]
	v_mfma_f32_16x16x32_bf16 v[26:29], v[154:157], v[184:187], v[26:29]
	v_mfma_f32_16x16x32_bf16 v[18:21], v[140:143], v[208:211], v[18:21]
	v_mfma_f32_16x16x32_bf16 v[10:13], v[154:157], v[208:211], v[10:13]
	v_mfma_f32_16x16x32_bf16 v[62:65], v[144:147], v[172:175], v[62:65]
	v_mfma_f32_16x16x32_bf16 v[58:61], v[158:161], v[172:175], v[58:61]
	v_mfma_f32_16x16x32_bf16 v[50:53], v[144:147], v[180:183], v[50:53]
	v_mfma_f32_16x16x32_bf16 v[42:45], v[158:161], v[180:183], v[42:45]
	v_mfma_f32_16x16x32_bf16 v[34:37], v[144:147], v[204:207], v[34:37]
	v_mfma_f32_16x16x32_bf16 v[26:29], v[158:161], v[204:207], v[26:29]
	v_mfma_f32_16x16x32_bf16 v[18:21], v[144:147], v[212:215], v[18:21]
	v_mfma_f32_16x16x32_bf16 v[10:13], v[158:161], v[212:215], v[10:13]
	s_setprio 0
	s_barrier
	s_add_u32 s60, s6, 0x40000
	s_addc_u32 s61, s7, 0
	s_add_i32 s58, s70, s44
	s_mov_b32 m0, s58
	s_nop 0
	global_load_lds_dwordx4 v0, s[60:61]
	s_add_i32 m0, s58, 0x2000
	s_nop 0
	global_load_lds_dwordx4 v130, s[60:61]
	s_waitcnt vmcnt(6)
	s_barrier
; __device__ __forceinline__ unsigned pk2(float lo, float hi) { unsigned r; asm("v_cvt_pk_bf16_f32 %0, %1, %2" : "=v"(r) : "v"(lo), "v"(hi)); return r; }
; #define PG8_STAGE(bufoff, gbase, voff) do { _Pragma("unroll") for (int _i = 0; _i < 2; ++_i) \
;         __builtin_amdgcn_global_load_lds((const unsigned*)((const char*)(gbase) + (voff)[_i]), (LAS unsigned*)(lds + (bufoff) + ldsw + _i * 8192), 16, 0, 0); } while (0)
; #define PG8_LDA(dst, b, h) do { _Pragma("unroll") for (int m = 0; m < 4; ++m) _Pragma("unroll") for (int k = 0; k < 2; ++k) dst[m][k] = *(const LAS bf16x8*)(lds + PG8_SA(b, h) + aoff + m * 2048 + k * 1024); } while (0)
;     __device__ __forceinline__ void operator()(const f32x4 (&acc)[2][2][4][2], const Unit& u, int ui, int wr, int wc, int fr, int fq) const {
;     ...
;                     u32x4 w; w.x = pk2(v0[0], v0[1]); w.y = pk2(v0[2], v0[3]); w.z = pk2(v1[0], v1[1]); w.w = pk2(v1[2], v1[3]);
;                     *(u32x4*)(rowp + bj * HALF) = w;
; template <class Epi>
; __device__ __forceinline__ void gemm_phase(LAS unsigned char* lds, const Gemm g, const StaticOrder& S, const Epi& E) {
;     ...
;             PG8_LDB(B0, 0, 0); PG8_SCHED; PG8_LDA(At, 0, 0); PG8_STAGE(PG8_SA(1, 1), a1 + hstep, voffA);
;             PG8_WAIT_L(8); PG8_BAR; PG8_WAIT_L(0); PG8_MMA(0, 0, At, B0); PG8_BAR; PG8_SCHED;
;             PG8_LDB(B1, 0, 1); PG8_STAGE(PG8_SB(0, 0), b2, voffB);
;             PG8_BAR; PG8_WAIT_L(0); PG8_MMA(0, 1, At, B1); PG8_BAR;
;             PG8_LDA(At, 0, 1); PG8_STAGE(PG8_SA(0, 0), a2, voffA);
;             PG8_BAR; PG8_WAIT_L(0); PG8_MMA(1, 0, At, B0); PG8_BAR; PG8_SCHED;
;             PG8_STAGE(PG8_SB(0, 1), b2 + hstep, voffB);
;             PG8_WAIT_V(6); PG8_BAR; PG8_MMA(1, 1, At, B1); PG8_BAR;
;             PG8_LDB(B0, 1, 0); PG8_SCHED; PG8_LDA(At, 1, 0); PG8_STAGE(PG8_SA(0, 1), a2 + hstep, voffA);
;             PG8_WAIT_L(8); PG8_BAR; PG8_WAIT_L(0); PG8_MMA(0, 0, At, B0); PG8_BAR; PG8_SCHED;
;             PG8_LDB(B1, 1, 1); PG8_STAGE(PG8_SB(1, 0), b3, voffB);
;             PG8_BAR; PG8_WAIT_L(0); PG8_MMA(0, 1, At, B1); PG8_BAR;
;             PG8_LDA(At, 1, 1); PG8_STAGE(PG8_SA(1, 0), a3, voffA);
;             PG8_BAR; PG8_WAIT_L(0); PG8_MMA(1, 0, At, B0); PG8_BAR; PG8_SCHED;
;             PG8_STAGE(PG8_SB(1, 1), b3 + hstep, voffB);
;             PG8_WAIT_V(6); PG8_BAR; PG8_MMA(1, 1, At, B1); PG8_BAR;
	s_setprio 1
	v_mfma_f32_16x16x32_bf16 v[54:57], v[216:219], v[168:171], v[54:57]
	v_mfma_f32_16x16x32_bf16 v[46:49], v[230:233], v[168:171], v[46:49]
	v_mfma_f32_16x16x32_bf16 v[38:41], v[216:219], v[176:179], v[38:41]
	v_mfma_f32_16x16x32_bf16 v[30:33], v[230:233], v[176:179], v[30:33]
	v_mfma_f32_16x16x32_bf16 v[22:25], v[216:219], v[184:187], v[22:25]
	v_mfma_f32_16x16x32_bf16 v[14:17], v[230:233], v[184:187], v[14:17]
	v_mfma_f32_16x16x32_bf16 v[6:9], v[216:219], v[208:211], v[6:9]
	v_mfma_f32_16x16x32_bf16 v[2:5], v[230:233], v[208:211], v[2:5]
	v_mfma_f32_16x16x32_bf16 v[54:57], v[226:229], v[172:175], v[54:57]
	v_mfma_f32_16x16x32_bf16 v[46:49], v[234:237], v[172:175], v[46:49]
	v_mfma_f32_16x16x32_bf16 v[38:41], v[226:229], v[180:183], v[38:41]
	v_mfma_f32_16x16x32_bf16 v[30:33], v[234:237], v[180:183], v[30:33]
	v_mfma_f32_16x16x32_bf16 v[22:25], v[226:229], v[204:207], v[22:25]
	v_mfma_f32_16x16x32_bf16 v[14:17], v[234:237], v[204:207], v[14:17]
	v_mfma_f32_16x16x32_bf16 v[6:9], v[226:229], v[212:215], v[6:9]
	v_mfma_f32_16x16x32_bf16 v[2:5], v[234:237], v[212:215], v[2:5]
	s_setprio 0
	s_add_i32 s58, 0, 0x18000
	v_add_u32_e32 v153, s58, v149
	s_barrier
	ds_read_b128 v[140:143], v153
	ds_read_b128 v[144:147], v153 offset:1024
	ds_read_b128 v[154:157], v153 offset:2048
	ds_read_b128 v[158:161], v153 offset:3072
	s_add_u32 s36, s36, 0x40000
	s_addc_u32 s37, s37, 0
	s_mov_b32 m0, s49
	ds_read_b128 v[168:171], v152 offset:32768
	ds_read_b128 v[172:175], v152 offset:33792
	ds_read_b128 v[176:179], v152 offset:34816
	ds_read_b128 v[180:183], v152 offset:35840
	ds_read_b128 v[184:187], v152 offset:36864
	ds_read_b128 v[204:207], v152 offset:37888
	ds_read_b128 v[208:211], v152 offset:38912
	ds_read_b128 v[212:215], v152 offset:39936
	global_load_lds_dwordx4 v134, s[36:37]
	s_mov_b32 m0, s54
	s_nop 0
	global_load_lds_dwordx4 v132, s[36:37]
	s_waitcnt lgkmcnt(8)
	s_barrier
	s_waitcnt lgkmcnt(0)
	s_setprio 1
	s_waitcnt lgkmcnt(0)
	v_mfma_f32_16x16x32_bf16 v[126:129], v[140:143], v[168:171], v[126:129]
	v_mfma_f32_16x16x32_bf16 v[122:125], v[154:157], v[168:171], v[122:125]
	s_cmp_eq_u32 s87, 0
	s_cbranch_scc1 .LdsA_skip_6
	global_store_dwordx4 v166, v[244:247], s[4:5]
.LdsA_skip_6:
	v_mfma_f32_16x16x32_bf16 v[114:117], v[140:143], v[176:179], v[114:117]
	v_mfma_f32_16x16x32_bf16 v[106:109], v[154:157], v[176:179], v[106:109]
	v_mfma_f32_16x16x32_bf16 v[98:101], v[140:143], v[184:187], v[98:101]
	v_mfma_f32_16x16x32_bf16 v[90:93], v[154:157], v[184:187], v[90:93]
	v_mfma_f32_16x16x32_bf16 v[82:85], v[140:143], v[208:211], v[82:85]
	v_mfma_f32_16x16x32_bf16 v[74:77], v[154:157], v[208:211], v[74:77]
	v_mfma_f32_16x16x32_bf16 v[126:129], v[144:147], v[172:175], v[126:129]
	v_mfma_f32_16x16x32_bf16 v[122:125], v[158:161], v[172:175], v[122:125]
	v_mfma_f32_16x16x32_bf16 v[114:117], v[144:147], v[180:183], v[114:117]
	v_mfma_f32_16x16x32_bf16 v[106:109], v[158:161], v[180:183], v[106:109]
	v_mfma_f32_16x16x32_bf16 v[98:101], v[144:147], v[204:207], v[98:101]
	v_mfma_f32_16x16x32_bf16 v[90:93], v[158:161], v[204:207], v[90:93]
	v_mfma_f32_16x16x32_bf16 v[82:85], v[144:147], v[212:215], v[82:85]
	v_mfma_f32_16x16x32_bf16 v[74:77], v[158:161], v[212:215], v[74:77]
	s_setprio 0
	s_barrier
	s_add_i32 s36, 0, 0x1c000
	s_add_i32 s37, s58, s44
	v_add_u32_e32 v153, s36, v149
	s_add_u32 s60, s6, 0x80
	s_addc_u32 s61, s7, 0
	s_mov_b32 m0, s37
	ds_read_b128 v[216:219], v153
	ds_read_b128 v[226:229], v153 offset:1024
	ds_read_b128 v[230:233], v153 offset:2048
	ds_read_b128 v[234:237], v153 offset:3072
	global_load_lds_dwordx4 v0, s[60:61]
	s_add_i32 m0, s37, 0x2000
	s_nop 0
	global_load_lds_dwordx4 v130, s[60:61]
	s_barrier
	s_waitcnt lgkmcnt(0)
	s_setprio 1
	s_waitcnt lgkmcnt(0)
	v_mfma_f32_16x16x32_bf16 v[118:121], v[216:219], v[168:171], v[118:121]
	v_mfma_f32_16x16x32_bf16 v[110:113], v[230:233], v[168:171], v[110:113]
	v_mfma_f32_16x16x32_bf16 v[102:105], v[216:219], v[176:179], v[102:105]
	v_mfma_f32_16x16x32_bf16 v[94:97], v[230:233], v[176:179], v[94:97]
	v_mfma_f32_16x16x32_bf16 v[86:89], v[216:219], v[184:187], v[86:89]
	v_mfma_f32_16x16x32_bf16 v[78:81], v[230:233], v[184:187], v[78:81]
	v_mfma_f32_16x16x32_bf16 v[70:73], v[216:219], v[208:211], v[70:73]
	v_mfma_f32_16x16x32_bf16 v[66:69], v[230:233], v[208:211], v[66:69]
	v_mfma_f32_16x16x32_bf16 v[118:121], v[226:229], v[172:175], v[118:121]
	v_mfma_f32_16x16x32_bf16 v[110:113], v[234:237], v[172:175], v[110:113]
	v_mfma_f32_16x16x32_bf16 v[102:105], v[226:229], v[180:183], v[102:105]
	v_mfma_f32_16x16x32_bf16 v[94:97], v[234:237], v[180:183], v[94:97]
	v_mfma_f32_16x16x32_bf16 v[86:89], v[226:229], v[204:207], v[86:89]
	v_mfma_f32_16x16x32_bf16 v[78:81], v[234:237], v[204:207], v[78:81]
	v_mfma_f32_16x16x32_bf16 v[70:73], v[226:229], v[212:215], v[70:73]
	v_mfma_f32_16x16x32_bf16 v[66:69], v[234:237], v[212:215], v[66:69]
	s_setprio 0
	s_mov_b32 m0, s55
	s_barrier
	ds_read_b128 v[168:171], v152 offset:49152
	ds_read_b128 v[172:175], v152 offset:50176
	ds_read_b128 v[176:179], v152 offset:51200
	ds_read_b128 v[180:183], v152 offset:52224
	ds_read_b128 v[184:187], v152 offset:53248
	ds_read_b128 v[204:207], v152 offset:54272
	ds_read_b128 v[208:211], v152 offset:55296
	ds_read_b128 v[212:215], v152 offset:56320
	global_load_lds_dwordx4 v134, vcc
	s_mov_b32 m0, s83
	s_nop 0
	global_load_lds_dwordx4 v132, vcc
	s_barrier
; #define PG8_STAGE(bufoff, gbase, voff) do { _Pragma("unroll") for (int _i = 0; _i < 2; ++_i) \
;         __builtin_amdgcn_global_load_lds((const unsigned*)((const char*)(gbase) + (voff)[_i]), (LAS unsigned*)(lds + (bufoff) + ldsw + _i * 8192), 16, 0, 0); } while (0)
; #define PG8_LDA(dst, b, h) do { _Pragma("unroll") for (int m = 0; m < 4; ++m) _Pragma("unroll") for (int k = 0; k < 2; ++k) dst[m][k] = *(const LAS bf16x8*)(lds + PG8_SA(b, h) + aoff + m * 2048 + k * 1024); } while (0)
; #define PG8_LDB(dst, b, h) do { _Pragma("unroll") for (int n = 0; n < 2; ++n) _Pragma("unroll") for (int k = 0; k < 2; ++k) dst[n][k] = *(const LAS bf16x8*)(lds + PG8_SB(b, h) + boff + n * 2048 + k * 1024); } while (0)
; #define PG8_WAIT_V(n) asm volatile("s_waitcnt vmcnt(" #n ")" ::: "memory")
; #define PG8_WAIT_L(n) asm volatile("s_waitcnt lgkmcnt(" #n ")" ::: "memory")
; #define PG8_BAR __builtin_amdgcn_s_barrier()
; #define PG8_SCHED __builtin_amdgcn_sched_barrier(0)
; template <class Epi>
; __device__ __forceinline__ void gemm_phase(LAS unsigned char* lds, const Gemm g, const StaticOrder& S, const Epi& E) {
;     ...
;             PG8_LDB(B0, 0, 0); PG8_SCHED; PG8_LDA(At, 0, 0); PG8_STAGE(PG8_SA(1, 1), a1 + hstep, voffA);
;             PG8_WAIT_L(8); PG8_BAR; PG8_WAIT_L(0); PG8_MMA(0, 0, At, B0); PG8_BAR; PG8_SCHED;
;             PG8_LDB(B1, 0, 1); PG8_STAGE(PG8_SB(0, 0), b2, voffB);
;             PG8_BAR; PG8_WAIT_L(0); PG8_MMA(0, 1, At, B1); PG8_BAR;
;             PG8_LDA(At, 0, 1); PG8_STAGE(PG8_SA(0, 0), a2, voffA);
;             PG8_BAR; PG8_WAIT_L(0); PG8_MMA(1, 0, At, B0); PG8_BAR; PG8_SCHED;
;             PG8_STAGE(PG8_SB(0, 1), b2 + hstep, voffB);
;             PG8_WAIT_V(6); PG8_BAR; PG8_MMA(1, 1, At, B1); PG8_BAR;
;             PG8_LDB(B0, 1, 0); PG8_SCHED; PG8_LDA(At, 1, 0); PG8_STAGE(PG8_SA(0, 1), a2 + hstep, voffA);
;             PG8_WAIT_L(8); PG8_BAR; PG8_WAIT_L(0); PG8_MMA(0, 0, At, B0); PG8_BAR; PG8_SCHED;
;             PG8_LDB(B1, 1, 1); PG8_STAGE(PG8_SB(1, 0), b3, voffB);
;             PG8_BAR; PG8_WAIT_L(0); PG8_MMA(0, 1, At, B1); PG8_BAR;
;             PG8_LDA(At, 1, 1); PG8_STAGE(PG8_SA(1, 0), a3, voffA);
;             PG8_BAR; PG8_WAIT_L(0); PG8_MMA(1, 0, At, B0); PG8_BAR; PG8_SCHED;
;             PG8_STAGE(PG8_SB(1, 1), b3 + hstep, voffB);
;             PG8_WAIT_V(6); PG8_BAR; PG8_MMA(1, 1, At, B1); PG8_BAR;
	s_waitcnt lgkmcnt(0)
	s_setprio 1
	s_waitcnt lgkmcnt(0)
	v_mfma_f32_16x16x32_bf16 v[62:65], v[140:143], v[168:171], v[62:65]
	v_mfma_f32_16x16x32_bf16 v[58:61], v[154:157], v[168:171], v[58:61]
	v_mfma_f32_16x16x32_bf16 v[50:53], v[140:143], v[176:179], v[50:53]
	v_mfma_f32_16x16x32_bf16 v[42:45], v[154:157], v[176:179], v[42:45]
	v_mfma_f32_16x16x32_bf16 v[34:37], v[140:143], v[184:187], v[34:37]
	v_mfma_f32_16x16x32_bf16 v[26:29], v[154:157], v[184:187], v[26:29]
	v_mfma_f32_16x16x32_bf16 v[18:21], v[140:143], v[208:211], v[18:21]
	v_mfma_f32_16x16x32_bf16 v[10:13], v[154:157], v[208:211], v[10:13]
	v_mfma_f32_16x16x32_bf16 v[62:65], v[144:147], v[172:175], v[62:65]
	v_mfma_f32_16x16x32_bf16 v[58:61], v[158:161], v[172:175], v[58:61]
	v_mfma_f32_16x16x32_bf16 v[50:53], v[144:147], v[180:183], v[50:53]
	v_mfma_f32_16x16x32_bf16 v[42:45], v[158:161], v[180:183], v[42:45]
	v_mfma_f32_16x16x32_bf16 v[34:37], v[144:147], v[204:207], v[34:37]
	v_mfma_f32_16x16x32_bf16 v[26:29], v[158:161], v[204:207], v[26:29]
	v_mfma_f32_16x16x32_bf16 v[18:21], v[144:147], v[212:215], v[18:21]
	v_mfma_f32_16x16x32_bf16 v[10:13], v[158:161], v[212:215], v[10:13]
	s_setprio 0
	s_barrier
	s_add_u32 s6, s6, 0x40080
	s_addc_u32 s7, s7, 0
	s_add_i32 s36, s36, s44
	s_mov_b32 m0, s36
	s_nop 0
	global_load_lds_dwordx4 v0, s[6:7]
	s_add_i32 m0, s36, 0x2000
	s_nop 0
	global_load_lds_dwordx4 v130, s[6:7]
	s_waitcnt vmcnt(6)
	s_barrier
	s_setprio 1
	v_mfma_f32_16x16x32_bf16 v[54:57], v[216:219], v[168:171], v[54:57]
	v_mfma_f32_16x16x32_bf16 v[46:49], v[230:233], v[168:171], v[46:49]
	v_mfma_f32_16x16x32_bf16 v[38:41], v[216:219], v[176:179], v[38:41]
	v_mfma_f32_16x16x32_bf16 v[30:33], v[230:233], v[176:179], v[30:33]
	v_mfma_f32_16x16x32_bf16 v[22:25], v[216:219], v[184:187], v[22:25]
	v_mfma_f32_16x16x32_bf16 v[14:17], v[230:233], v[184:187], v[14:17]
	v_mfma_f32_16x16x32_bf16 v[6:9], v[216:219], v[208:211], v[6:9]
	v_mfma_f32_16x16x32_bf16 v[2:5], v[230:233], v[208:211], v[2:5]
	v_mfma_f32_16x16x32_bf16 v[54:57], v[226:229], v[172:175], v[54:57]
	v_mfma_f32_16x16x32_bf16 v[46:49], v[234:237], v[172:175], v[46:49]
	v_mfma_f32_16x16x32_bf16 v[38:41], v[226:229], v[180:183], v[38:41]
	v_mfma_f32_16x16x32_bf16 v[30:33], v[234:237], v[180:183], v[30:33]
	v_mfma_f32_16x16x32_bf16 v[22:25], v[226:229], v[204:207], v[22:25]
	v_mfma_f32_16x16x32_bf16 v[14:17], v[234:237], v[204:207], v[14:17]
	v_mfma_f32_16x16x32_bf16 v[6:9], v[226:229], v[212:215], v[6:9]
	v_mfma_f32_16x16x32_bf16 v[2:5], v[234:237], v[212:215], v[2:5]
	s_setprio 0
	s_add_i32 s91, s91, 2
	s_add_u32 s24, s24, 0x100
	s_addc_u32 s25, s25, 0
	s_add_u32 s89, s89, 0x100
	s_addc_u32 s90, s90, 0
	s_cmp_gt_u32 s91, 13
	s_barrier
	s_add_u32 s6, s24, 0xfffc0080
	s_addc_u32 s7, s25, -1
	s_add_i32 s58, 0, 0x10000
	v_add_u32_e32 v153, s58, v149
	ds_read_b128 v[140:143], v153
	ds_read_b128 v[144:147], v153 offset:1024
	ds_read_b128 v[154:157], v153 offset:2048
	ds_read_b128 v[158:161], v153 offset:3072
	s_cmp_eq_u32 s91, 12
	s_cselect_b32 s37, s11, s7
	s_cselect_b32 s36, s71, s6
	s_cselect_b32 s7, s9, s90
	s_cselect_b32 s6, s88, s89
	s_add_i32 m0, s47, 0xc000
	ds_read_b128 v[168:171], v152
	ds_read_b128 v[172:175], v152 offset:1024
	ds_read_b128 v[176:179], v152 offset:2048
	ds_read_b128 v[180:183], v152 offset:3072
	ds_read_b128 v[184:187], v152 offset:4096
	ds_read_b128 v[204:207], v152 offset:5120
	ds_read_b128 v[208:211], v152 offset:6144
	ds_read_b128 v[212:215], v152 offset:7168
	global_load_lds_dwordx4 v136, s[24:25]
	s_add_i32 m0, s47, 0xe000
	s_nop 0
	global_load_lds_dwordx4 v138, s[24:25]
	s_waitcnt lgkmcnt(8)
	s_barrier
	s_waitcnt lgkmcnt(0)
	s_setprio 1
	s_waitcnt lgkmcnt(0)
	v_mfma_f32_16x16x32_bf16 v[126:129], v[140:143], v[168:171], v[126:129]
	v_mfma_f32_16x16x32_bf16 v[122:125], v[154:157], v[168:171], v[122:125]
	v_mfma_f32_16x16x32_bf16 v[114:117], v[140:143], v[176:179], v[114:117]
	v_mfma_f32_16x16x32_bf16 v[106:109], v[154:157], v[176:179], v[106:109]
	v_mfma_f32_16x16x32_bf16 v[98:101], v[140:143], v[184:187], v[98:101]
	v_mfma_f32_16x16x32_bf16 v[90:93], v[154:157], v[184:187], v[90:93]
	v_mfma_f32_16x16x32_bf16 v[82:85], v[140:143], v[208:211], v[82:85]
	v_mfma_f32_16x16x32_bf16 v[74:77], v[154:157], v[208:211], v[74:77]
	v_mfma_f32_16x16x32_bf16 v[126:129], v[144:147], v[172:175], v[126:129]
	v_mfma_f32_16x16x32_bf16 v[122:125], v[158:161], v[172:175], v[122:125]
	v_mfma_f32_16x16x32_bf16 v[114:117], v[144:147], v[180:183], v[114:117]
	v_mfma_f32_16x16x32_bf16 v[106:109], v[158:161], v[180:183], v[106:109]
	v_mfma_f32_16x16x32_bf16 v[98:101], v[144:147], v[204:207], v[98:101]
	v_mfma_f32_16x16x32_bf16 v[90:93], v[158:161], v[204:207], v[90:93]
	v_mfma_f32_16x16x32_bf16 v[82:85], v[144:147], v[212:215], v[82:85]
	v_mfma_f32_16x16x32_bf16 v[74:77], v[158:161], v[212:215], v[74:77]
	s_setprio 0
	s_barrier
	s_add_i32 s70, 0, 0x14000
	s_add_i32 s58, s58, s44
	v_add_u32_e32 v153, s70, v149
	s_mov_b32 m0, s58
	ds_read_b128 v[216:219], v153
	ds_read_b128 v[226:229], v153 offset:1024
	ds_read_b128 v[230:233], v153 offset:2048
	ds_read_b128 v[234:237], v153 offset:3072
	global_load_lds_dwordx4 v0, s[6:7]
	s_add_i32 m0, s58, 0x2000
	s_nop 0
	global_load_lds_dwordx4 v130, s[6:7]
	s_barrier
; __device__ __forceinline__ unsigned pk2(float lo, float hi) { unsigned r; asm("v_cvt_pk_bf16_f32 %0, %1, %2" : "=v"(r) : "v"(lo), "v"(hi)); return r; }
; #define PG8_STAGE(bufoff, gbase, voff) do { _Pragma("unroll") for (int _i = 0; _i < 2; ++_i) \
;         __builtin_amdgcn_global_load_lds((const unsigned*)((const char*)(gbase) + (voff)[_i]), (LAS unsigned*)(lds + (bufoff) + ldsw + _i * 8192), 16, 0, 0); } while (0)
; #define PG8_LDA(dst, b, h) do { _Pragma("unroll") for (int m = 0; m < 4; ++m) _Pragma("unroll") for (int k = 0; k < 2; ++k) dst[m][k] = *(const LAS bf16x8*)(lds + PG8_SA(b, h) + aoff + m * 2048 + k * 1024); } while (0)
;     __device__ __forceinline__ void operator()(const f32x4 (&acc)[2][2][4][2], const Unit& u, int ui, int wr, int wc, int fr, int fq) const {
;     ...
;                     u32x4 w; w.x = pk2(v0[0], v0[1]); w.y = pk2(v0[2], v0[3]); w.z = pk2(v1[0], v1[1]); w.w = pk2(v1[2], v1[3]);
;                     *(u32x4*)(rowp + bj * HALF) = w;
; template <class Epi>
; __device__ __forceinline__ void gemm_phase(LAS unsigned char* lds, const Gemm g, const StaticOrder& S, const Epi& E) {
;     ...
;             PG8_LDB(B0, 0, 0); PG8_SCHED; PG8_LDA(At, 0, 0); PG8_STAGE(PG8_SA(1, 1), a1 + hstep, voffA);
;             PG8_WAIT_L(8); PG8_BAR; PG8_WAIT_L(0); PG8_MMA(0, 0, At, B0); PG8_BAR; PG8_SCHED;
;             PG8_LDB(B1, 0, 1); PG8_STAGE(PG8_SB(0, 0), b2, voffB);
;             PG8_BAR; PG8_WAIT_L(0); PG8_MMA(0, 1, At, B1); PG8_BAR;
;             PG8_LDA(At, 0, 1); PG8_STAGE(PG8_SA(0, 0), a2, voffA);
;             PG8_BAR; PG8_WAIT_L(0); PG8_MMA(1, 0, At, B0); PG8_BAR; PG8_SCHED;
;             PG8_STAGE(PG8_SB(0, 1), b2 + hstep, voffB);
;             PG8_WAIT_V(6); PG8_BAR; PG8_MMA(1, 1, At, B1); PG8_BAR;
;             PG8_LDB(B0, 1, 0); PG8_SCHED; PG8_LDA(At, 1, 0); PG8_STAGE(PG8_SA(0, 1), a2 + hstep, voffA);
;             PG8_WAIT_L(8); PG8_BAR; PG8_WAIT_L(0); PG8_MMA(0, 0, At, B0); PG8_BAR; PG8_SCHED;
;             PG8_LDB(B1, 1, 1); PG8_STAGE(PG8_SB(1, 0), b3, voffB);
;             PG8_BAR; PG8_WAIT_L(0); PG8_MMA(0, 1, At, B1); PG8_BAR;
;             PG8_LDA(At, 1, 1); PG8_STAGE(PG8_SA(1, 0), a3, voffA);
;             PG8_BAR; PG8_WAIT_L(0); PG8_MMA(1, 0, At, B0); PG8_BAR; PG8_SCHED;
;             PG8_STAGE(PG8_SB(1, 1), b3 + hstep, voffB);
;             PG8_WAIT_V(6); PG8_BAR; PG8_MMA(1, 1, At, B1); PG8_BAR;
	s_waitcnt lgkmcnt(0)
	s_setprio 1
	s_waitcnt lgkmcnt(0)
	v_mfma_f32_16x16x32_bf16 v[118:121], v[216:219], v[168:171], v[118:121]
	v_mfma_f32_16x16x32_bf16 v[110:113], v[230:233], v[168:171], v[110:113]
	v_mfma_f32_16x16x32_bf16 v[102:105], v[216:219], v[176:179], v[102:105]
	v_mfma_f32_16x16x32_bf16 v[94:97], v[230:233], v[176:179], v[94:97]
	v_mfma_f32_16x16x32_bf16 v[86:89], v[216:219], v[184:187], v[86:89]
	v_mfma_f32_16x16x32_bf16 v[78:81], v[230:233], v[184:187], v[78:81]
	v_mfma_f32_16x16x32_bf16 v[70:73], v[216:219], v[208:211], v[70:73]
	v_mfma_f32_16x16x32_bf16 v[66:69], v[230:233], v[208:211], v[66:69]
	v_mfma_f32_16x16x32_bf16 v[118:121], v[226:229], v[172:175], v[118:121]
	v_mfma_f32_16x16x32_bf16 v[110:113], v[234:237], v[172:175], v[110:113]
	v_mfma_f32_16x16x32_bf16 v[102:105], v[226:229], v[180:183], v[102:105]
	v_mfma_f32_16x16x32_bf16 v[94:97], v[234:237], v[180:183], v[94:97]
	v_mfma_f32_16x16x32_bf16 v[86:89], v[226:229], v[204:207], v[86:89]
	v_mfma_f32_16x16x32_bf16 v[78:81], v[234:237], v[204:207], v[78:81]
	v_mfma_f32_16x16x32_bf16 v[70:73], v[226:229], v[212:215], v[70:73]
	v_mfma_f32_16x16x32_bf16 v[66:69], v[234:237], v[212:215], v[66:69]
	s_setprio 0
	s_mov_b32 m0, s47
	s_add_u32 vcc_lo, s36, 0x80
	s_addc_u32 vcc_hi, s37, 0
	s_barrier
	ds_read_b128 v[168:171], v152 offset:16384
	ds_read_b128 v[172:175], v152 offset:17408
	ds_read_b128 v[176:179], v152 offset:18432
	ds_read_b128 v[180:183], v152 offset:19456
	ds_read_b128 v[184:187], v152 offset:20480
	ds_read_b128 v[204:207], v152 offset:21504
	ds_read_b128 v[208:211], v152 offset:22528
	ds_read_b128 v[212:215], v152 offset:23552
	global_load_lds_dwordx4 v134, s[36:37]
	s_mov_b32 m0, s48
	s_nop 0
	global_load_lds_dwordx4 v132, s[36:37]
	s_barrier
	s_waitcnt lgkmcnt(0)
	s_setprio 1
	s_waitcnt lgkmcnt(0)
	v_mfma_f32_16x16x32_bf16 v[62:65], v[140:143], v[168:171], v[62:65]
	v_mfma_f32_16x16x32_bf16 v[58:61], v[154:157], v[168:171], v[58:61]
	v_mfma_f32_16x16x32_bf16 v[50:53], v[140:143], v[176:179], v[50:53]
	v_mfma_f32_16x16x32_bf16 v[42:45], v[154:157], v[176:179], v[42:45]
	v_mfma_f32_16x16x32_bf16 v[34:37], v[140:143], v[184:187], v[34:37]
	v_mfma_f32_16x16x32_bf16 v[26:29], v[154:157], v[184:187], v[26:29]
	v_mfma_f32_16x16x32_bf16 v[18:21], v[140:143], v[208:211], v[18:21]
	v_mfma_f32_16x16x32_bf16 v[10:13], v[154:157], v[208:211], v[10:13]
	v_mfma_f32_16x16x32_bf16 v[62:65], v[144:147], v[172:175], v[62:65]
	v_mfma_f32_16x16x32_bf16 v[58:61], v[158:161], v[172:175], v[58:61]
	v_mfma_f32_16x16x32_bf16 v[50:53], v[144:147], v[180:183], v[50:53]
	v_mfma_f32_16x16x32_bf16 v[42:45], v[158:161], v[180:183], v[42:45]
	v_mfma_f32_16x16x32_bf16 v[34:37], v[144:147], v[204:207], v[34:37]
	v_mfma_f32_16x16x32_bf16 v[26:29], v[158:161], v[204:207], v[26:29]
	v_mfma_f32_16x16x32_bf16 v[18:21], v[144:147], v[212:215], v[18:21]
	v_mfma_f32_16x16x32_bf16 v[10:13], v[158:161], v[212:215], v[10:13]
	s_setprio 0
	s_barrier
	s_add_u32 s60, s6, 0x40000
	s_addc_u32 s61, s7, 0
	s_add_i32 s58, s70, s44
	s_mov_b32 m0, s58
	s_nop 0
	global_load_lds_dwordx4 v0, s[60:61]
	s_add_i32 m0, s58, 0x2000
	s_nop 0
	global_load_lds_dwordx4 v130, s[60:61]
	s_waitcnt vmcnt(6)
	s_barrier
	s_setprio 1
	v_mfma_f32_16x16x32_bf16 v[54:57], v[216:219], v[168:171], v[54:57]
	v_mfma_f32_16x16x32_bf16 v[46:49], v[230:233], v[168:171], v[46:49]
	v_mfma_f32_16x16x32_bf16 v[38:41], v[216:219], v[176:179], v[38:41]
	v_mfma_f32_16x16x32_bf16 v[30:33], v[230:233], v[176:179], v[30:33]
	v_mfma_f32_16x16x32_bf16 v[22:25], v[216:219], v[184:187], v[22:25]
	v_mfma_f32_16x16x32_bf16 v[14:17], v[230:233], v[184:187], v[14:17]
	v_mfma_f32_16x16x32_bf16 v[6:9], v[216:219], v[208:211], v[6:9]
	v_mfma_f32_16x16x32_bf16 v[2:5], v[230:233], v[208:211], v[2:5]
	v_mfma_f32_16x16x32_bf16 v[54:57], v[226:229], v[172:175], v[54:57]
	v_mfma_f32_16x16x32_bf16 v[46:49], v[234:237], v[172:175], v[46:49]
	v_mfma_f32_16x16x32_bf16 v[38:41], v[226:229], v[180:183], v[38:41]
	v_mfma_f32_16x16x32_bf16 v[30:33], v[234:237], v[180:183], v[30:33]
	v_mfma_f32_16x16x32_bf16 v[22:25], v[226:229], v[204:207], v[22:25]
	v_mfma_f32_16x16x32_bf16 v[14:17], v[234:237], v[204:207], v[14:17]
	v_mfma_f32_16x16x32_bf16 v[6:9], v[226:229], v[212:215], v[6:9]
	v_mfma_f32_16x16x32_bf16 v[2:5], v[234:237], v[212:215], v[2:5]
	s_setprio 0
	s_add_i32 s58, 0, 0x18000
	v_add_u32_e32 v153, s58, v149
	s_barrier
	ds_read_b128 v[140:143], v153
	ds_read_b128 v[144:147], v153 offset:1024
	ds_read_b128 v[154:157], v153 offset:2048
	ds_read_b128 v[158:161], v153 offset:3072
	s_add_u32 s36, s36, 0x40000
	s_addc_u32 s37, s37, 0
	s_mov_b32 m0, s49
	ds_read_b128 v[168:171], v152 offset:32768
	ds_read_b128 v[172:175], v152 offset:33792
	ds_read_b128 v[176:179], v152 offset:34816
	ds_read_b128 v[180:183], v152 offset:35840
	ds_read_b128 v[184:187], v152 offset:36864
	ds_read_b128 v[204:207], v152 offset:37888
	ds_read_b128 v[208:211], v152 offset:38912
	ds_read_b128 v[212:215], v152 offset:39936
	global_load_lds_dwordx4 v134, s[36:37]
	s_mov_b32 m0, s54
	s_nop 0
	global_load_lds_dwordx4 v132, s[36:37]
	s_waitcnt lgkmcnt(8)
	s_barrier
	s_waitcnt lgkmcnt(0)
	s_setprio 1
	s_waitcnt lgkmcnt(0)
	v_mfma_f32_16x16x32_bf16 v[126:129], v[140:143], v[168:171], v[126:129]
	v_mfma_f32_16x16x32_bf16 v[122:125], v[154:157], v[168:171], v[122:125]
	s_cmp_eq_u32 s87, 0
	s_cbranch_scc1 .LdsA_skip_7
	global_store_dwordx4 v166, v[248:251], s[4:5] offset:256
; #define PG8_STAGE(bufoff, gbase, voff) do { _Pragma("unroll") for (int _i = 0; _i < 2; ++_i) \
;         __builtin_amdgcn_global_load_lds((const unsigned*)((const char*)(gbase) + (voff)[_i]), (LAS unsigned*)(lds + (bufoff) + ldsw + _i * 8192), 16, 0, 0); } while (0)
; #define PG8_LDA(dst, b, h) do { _Pragma("unroll") for (int m = 0; m < 4; ++m) _Pragma("unroll") for (int k = 0; k < 2; ++k) dst[m][k] = *(const LAS bf16x8*)(lds + PG8_SA(b, h) + aoff + m * 2048 + k * 1024); } while (0)
; #define PG8_LDB(dst, b, h) do { _Pragma("unroll") for (int n = 0; n < 2; ++n) _Pragma("unroll") for (int k = 0; k < 2; ++k) dst[n][k] = *(const LAS bf16x8*)(lds + PG8_SB(b, h) + boff + n * 2048 + k * 1024); } while (0)
; #define PG8_WAIT_V(n) asm volatile("s_waitcnt vmcnt(" #n ")" ::: "memory")
; #define PG8_WAIT_L(n) asm volatile("s_waitcnt lgkmcnt(" #n ")" ::: "memory")
; #define PG8_BAR __builtin_amdgcn_s_barrier()
; #define PG8_SCHED __builtin_amdgcn_sched_barrier(0)
; template <class Epi>
; __device__ __forceinline__ void gemm_phase(LAS unsigned char* lds, const Gemm g, const StaticOrder& S, const Epi& E) {
;     ...
;             PG8_LDB(B0, 0, 0); PG8_SCHED; PG8_LDA(At, 0, 0); PG8_STAGE(PG8_SA(1, 1), a1 + hstep, voffA);
;             PG8_WAIT_L(8); PG8_BAR; PG8_WAIT_L(0); PG8_MMA(0, 0, At, B0); PG8_BAR; PG8_SCHED;
;             PG8_LDB(B1, 0, 1); PG8_STAGE(PG8_SB(0, 0), b2, voffB);
;             PG8_BAR; PG8_WAIT_L(0); PG8_MMA(0, 1, At, B1); PG8_BAR;
;             PG8_LDA(At, 0, 1); PG8_STAGE(PG8_SA(0, 0), a2, voffA);
;             PG8_BAR; PG8_WAIT_L(0); PG8_MMA(1, 0, At, B0); PG8_BAR; PG8_SCHED;
;             PG8_STAGE(PG8_SB(0, 1), b2 + hstep, voffB);
;             PG8_WAIT_V(6); PG8_BAR; PG8_MMA(1, 1, At, B1); PG8_BAR;
;             PG8_LDB(B0, 1, 0); PG8_SCHED; PG8_LDA(At, 1, 0); PG8_STAGE(PG8_SA(0, 1), a2 + hstep, voffA);
;             PG8_WAIT_L(8); PG8_BAR; PG8_WAIT_L(0); PG8_MMA(0, 0, At, B0); PG8_BAR; PG8_SCHED;
;             PG8_LDB(B1, 1, 1); PG8_STAGE(PG8_SB(1, 0), b3, voffB);
;             PG8_BAR; PG8_WAIT_L(0); PG8_MMA(0, 1, At, B1); PG8_BAR;
;             PG8_LDA(At, 1, 1); PG8_STAGE(PG8_SA(1, 0), a3, voffA);
;             PG8_BAR; PG8_WAIT_L(0); PG8_MMA(1, 0, At, B0); PG8_BAR; PG8_SCHED;
;             PG8_STAGE(PG8_SB(1, 1), b3 + hstep, voffB);
;             PG8_WAIT_V(6); PG8_BAR; PG8_MMA(1, 1, At, B1); PG8_BAR;
.LdsA_skip_7:
	v_mfma_f32_16x16x32_bf16 v[114:117], v[140:143], v[176:179], v[114:117]
	v_mfma_f32_16x16x32_bf16 v[106:109], v[154:157], v[176:179], v[106:109]
	v_mfma_f32_16x16x32_bf16 v[98:101], v[140:143], v[184:187], v[98:101]
	v_mfma_f32_16x16x32_bf16 v[90:93], v[154:157], v[184:187], v[90:93]
	v_mfma_f32_16x16x32_bf16 v[82:85], v[140:143], v[208:211], v[82:85]
	v_mfma_f32_16x16x32_bf16 v[74:77], v[154:157], v[208:211], v[74:77]
	v_mfma_f32_16x16x32_bf16 v[126:129], v[144:147], v[172:175], v[126:129]
	v_mfma_f32_16x16x32_bf16 v[122:125], v[158:161], v[172:175], v[122:125]
	v_mfma_f32_16x16x32_bf16 v[114:117], v[144:147], v[180:183], v[114:117]
	v_mfma_f32_16x16x32_bf16 v[106:109], v[158:161], v[180:183], v[106:109]
	v_mfma_f32_16x16x32_bf16 v[98:101], v[144:147], v[204:207], v[98:101]
	v_mfma_f32_16x16x32_bf16 v[90:93], v[158:161], v[204:207], v[90:93]
	v_mfma_f32_16x16x32_bf16 v[82:85], v[144:147], v[212:215], v[82:85]
	v_mfma_f32_16x16x32_bf16 v[74:77], v[158:161], v[212:215], v[74:77]
	s_setprio 0
	s_barrier
	s_add_i32 s36, 0, 0x1c000
	s_add_i32 s37, s58, s44
	v_add_u32_e32 v153, s36, v149
	s_add_u32 s60, s6, 0x80
	s_addc_u32 s61, s7, 0
	s_mov_b32 m0, s37
	ds_read_b128 v[216:219], v153
	ds_read_b128 v[226:229], v153 offset:1024
	ds_read_b128 v[230:233], v153 offset:2048
	ds_read_b128 v[234:237], v153 offset:3072
	global_load_lds_dwordx4 v0, s[60:61]
	s_add_i32 m0, s37, 0x2000
	s_nop 0
	global_load_lds_dwordx4 v130, s[60:61]
	s_barrier
	s_waitcnt lgkmcnt(0)
	s_setprio 1
	s_waitcnt lgkmcnt(0)
	v_mfma_f32_16x16x32_bf16 v[118:121], v[216:219], v[168:171], v[118:121]
	v_mfma_f32_16x16x32_bf16 v[110:113], v[230:233], v[168:171], v[110:113]
	v_mfma_f32_16x16x32_bf16 v[102:105], v[216:219], v[176:179], v[102:105]
	v_mfma_f32_16x16x32_bf16 v[94:97], v[230:233], v[176:179], v[94:97]
	v_mfma_f32_16x16x32_bf16 v[86:89], v[216:219], v[184:187], v[86:89]
	v_mfma_f32_16x16x32_bf16 v[78:81], v[230:233], v[184:187], v[78:81]
	v_mfma_f32_16x16x32_bf16 v[70:73], v[216:219], v[208:211], v[70:73]
	v_mfma_f32_16x16x32_bf16 v[66:69], v[230:233], v[208:211], v[66:69]
	v_mfma_f32_16x16x32_bf16 v[118:121], v[226:229], v[172:175], v[118:121]
	v_mfma_f32_16x16x32_bf16 v[110:113], v[234:237], v[172:175], v[110:113]
	v_mfma_f32_16x16x32_bf16 v[102:105], v[226:229], v[180:183], v[102:105]
	v_mfma_f32_16x16x32_bf16 v[94:97], v[234:237], v[180:183], v[94:97]
	v_mfma_f32_16x16x32_bf16 v[86:89], v[226:229], v[204:207], v[86:89]
	v_mfma_f32_16x16x32_bf16 v[78:81], v[234:237], v[204:207], v[78:81]
	v_mfma_f32_16x16x32_bf16 v[70:73], v[226:229], v[212:215], v[70:73]
	v_mfma_f32_16x16x32_bf16 v[66:69], v[234:237], v[212:215], v[66:69]
	s_setprio 0
	s_mov_b32 m0, s55
	s_barrier
	ds_read_b128 v[168:171], v152 offset:49152
	ds_read_b128 v[172:175], v152 offset:50176
	ds_read_b128 v[176:179], v152 offset:51200
	ds_read_b128 v[180:183], v152 offset:52224
	ds_read_b128 v[184:187], v152 offset:53248
	ds_read_b128 v[204:207], v152 offset:54272
	ds_read_b128 v[208:211], v152 offset:55296
	ds_read_b128 v[212:215], v152 offset:56320
	global_load_lds_dwordx4 v134, vcc
	s_mov_b32 m0, s83
	s_nop 0
	global_load_lds_dwordx4 v132, vcc
	s_barrier
	s_waitcnt lgkmcnt(0)
	s_setprio 1
	s_waitcnt lgkmcnt(0)
	v_mfma_f32_16x16x32_bf16 v[62:65], v[140:143], v[168:171], v[62:65]
	v_mfma_f32_16x16x32_bf16 v[58:61], v[154:157], v[168:171], v[58:61]
	v_mfma_f32_16x16x32_bf16 v[50:53], v[140:143], v[176:179], v[50:53]
	v_mfma_f32_16x16x32_bf16 v[42:45], v[154:157], v[176:179], v[42:45]
	v_mfma_f32_16x16x32_bf16 v[34:37], v[140:143], v[184:187], v[34:37]
	v_mfma_f32_16x16x32_bf16 v[26:29], v[154:157], v[184:187], v[26:29]
	v_mfma_f32_16x16x32_bf16 v[18:21], v[140:143], v[208:211], v[18:21]
	v_mfma_f32_16x16x32_bf16 v[10:13], v[154:157], v[208:211], v[10:13]
	v_mfma_f32_16x16x32_bf16 v[62:65], v[144:147], v[172:175], v[62:65]
	v_mfma_f32_16x16x32_bf16 v[58:61], v[158:161], v[172:175], v[58:61]
	v_mfma_f32_16x16x32_bf16 v[50:53], v[144:147], v[180:183], v[50:53]
	v_mfma_f32_16x16x32_bf16 v[42:45], v[158:161], v[180:183], v[42:45]
	v_mfma_f32_16x16x32_bf16 v[34:37], v[144:147], v[204:207], v[34:37]
	v_mfma_f32_16x16x32_bf16 v[26:29], v[158:161], v[204:207], v[26:29]
	v_mfma_f32_16x16x32_bf16 v[18:21], v[144:147], v[212:215], v[18:21]
	v_mfma_f32_16x16x32_bf16 v[10:13], v[158:161], v[212:215], v[10:13]
	s_setprio 0
	s_barrier
	s_add_u32 s6, s6, 0x40080
	s_addc_u32 s7, s7, 0
	s_add_i32 s36, s36, s44
	s_mov_b32 m0, s36
	s_nop 0
	global_load_lds_dwordx4 v0, s[6:7]
	s_add_i32 m0, s36, 0x2000
	s_nop 0
	global_load_lds_dwordx4 v130, s[6:7]
	s_waitcnt vmcnt(6)
	s_barrier
	s_setprio 1
	v_mfma_f32_16x16x32_bf16 v[54:57], v[216:219], v[168:171], v[54:57]
	v_mfma_f32_16x16x32_bf16 v[46:49], v[230:233], v[168:171], v[46:49]
	v_mfma_f32_16x16x32_bf16 v[38:41], v[216:219], v[176:179], v[38:41]
	v_mfma_f32_16x16x32_bf16 v[30:33], v[230:233], v[176:179], v[30:33]
	v_mfma_f32_16x16x32_bf16 v[22:25], v[216:219], v[184:187], v[22:25]
	v_mfma_f32_16x16x32_bf16 v[14:17], v[230:233], v[184:187], v[14:17]
	v_mfma_f32_16x16x32_bf16 v[6:9], v[216:219], v[208:211], v[6:9]
	v_mfma_f32_16x16x32_bf16 v[2:5], v[230:233], v[208:211], v[2:5]
	v_mfma_f32_16x16x32_bf16 v[54:57], v[226:229], v[172:175], v[54:57]
	v_mfma_f32_16x16x32_bf16 v[46:49], v[234:237], v[172:175], v[46:49]
	v_mfma_f32_16x16x32_bf16 v[38:41], v[226:229], v[180:183], v[38:41]
	v_mfma_f32_16x16x32_bf16 v[30:33], v[234:237], v[180:183], v[30:33]
	v_mfma_f32_16x16x32_bf16 v[22:25], v[226:229], v[204:207], v[22:25]
	v_mfma_f32_16x16x32_bf16 v[14:17], v[234:237], v[204:207], v[14:17]
	v_mfma_f32_16x16x32_bf16 v[6:9], v[226:229], v[212:215], v[6:9]
	v_mfma_f32_16x16x32_bf16 v[2:5], v[234:237], v[212:215], v[2:5]
	s_setprio 0
	s_add_i32 s91, s91, 2
	s_add_u32 s24, s24, 0x100
	s_addc_u32 s25, s25, 0
	s_add_u32 s89, s89, 0x100
	s_addc_u32 s90, s90, 0
	s_cmp_gt_u32 s91, 13
	s_barrier
; __device__ __forceinline__ unsigned pk2(float lo, float hi) { unsigned r; asm("v_cvt_pk_bf16_f32 %0, %1, %2" : "=v"(r) : "v"(lo), "v"(hi)); return r; }
;     __device__ __forceinline__ void operator()(const f32x4 (&acc)[2][2][4][2], const Unit& u, int ui, int wr, int wc, int fr, int fq) const {
;         const int lrow0 = wr * 64 + fr, row0 = u.pm * BM + lrow0, col0 = u.pn * BM + wc * 32 + 8 * fq;
;         float rsv[2][4];
; #pragma unroll
;         for (int ai = 0; ai < 2; ++ai)
; #pragma unroll
;             for (int m = 0; m < 4; ++m) rsv[ai][m] = rstab[ui * 256 + lrow0 + ai * HALF + m * 16];
; #pragma unroll
;         for (int ai = 0; ai < 2; ++ai)
; #pragma unroll
;             for (int m = 0; m < 4; ++m) {
;                 const int row = row0 + ai * HALF + m * 16; const float rs = rsv[ai][m];
;                 bf16_t* rowp = O + (size_t)row * ldc + col0;
; #pragma unroll
;                 for (int bj = 0; bj < 2; ++bj) {
;                     f32x4 v0 = acc[ai][bj][m][0] * rs, v1 = acc[ai][bj][m][1] * rs;
;                     if (ACT == 1) {
; #pragma unroll
;                         for (int j = 0; j < 4; ++j) { const float a = fmaxf(v0[j], 0.f), b = fmaxf(v1[j], 0.f); v0[j] = a * a; v1[j] = b * b; }
;                     }
;                     u32x4 w; w.x = pk2(v0[0], v0[1]); w.y = pk2(v0[2], v0[3]); w.z = pk2(v1[0], v1[1]); w.w = pk2(v1[2], v1[3]);
;                     *(u32x4*)(rowp + bj * HALF) = w;
	v_lshl_add_u32 v140, s87, 10, v150
	v_lshl_or_b32 v144, s85, 8, v151
	v_lshl_add_u32 v153, s86, 8, v148
	v_mul_u32_u24_e32 v166, 0xe00, v153
	v_lshl_add_u32 v166, v144, 1, v166
	v_add_u32_e32 v166, 0x70000, v166
	ds_read2_b32 v[154:155], v140 offset1:16
	ds_read2_b32 v[156:157], v140 offset0:32 offset1:48
	ds_read2_b32 v[146:147], v140 offset0:128 offset1:144
	ds_read2_b32 v[140:141], v140 offset0:160 offset1:176
	v_ashrrev_i32_e32 v145, 31, v144
	v_mov_b64_e32 v[142:143], s[4:5]
	v_mad_i64_i32 v[158:159], s[6:7], v153, s65, v[142:143]
	v_lshlrev_b64 v[144:145], 1, v[144:145]
	v_lshl_add_u64 v[158:159], v[158:159], 0, v[144:145]
	s_waitcnt lgkmcnt(0)
	v_pk_mul_f32 v[128:129], v[128:129], v[154:155] op_sel_hi:[1,0]
	v_pk_mul_f32 v[126:127], v[126:127], v[154:155] op_sel_hi:[1,0]
	v_pk_mul_f32 v[160:161], v[124:125], v[154:155] op_sel_hi:[1,0]
	v_pk_mul_f32 v[124:125], v[122:123], v[154:155] op_sel_hi:[1,0]
	v_cvt_pk_bf16_f32 v122, v126, v127
	v_cvt_pk_bf16_f32 v123, v128, v129
	v_pk_mul_f32 v[118:119], v[118:119], v[154:155] op_sel_hi:[1,0]
	v_cvt_pk_bf16_f32 v124, v124, v125
	v_cvt_pk_bf16_f32 v125, v160, v161
	global_store_dwordx4 v[158:159], v[122:125], off
	v_pk_mul_f32 v[120:121], v[120:121], v[154:155] op_sel_hi:[1,0]
	v_pk_mul_f32 v[98:99], v[98:99], v[156:157] op_sel_hi:[1,0]
	v_pk_mul_f32 v[122:123], v[112:113], v[154:155] op_sel_hi:[1,0]
	v_pk_mul_f32 v[112:113], v[110:111], v[154:155] op_sel_hi:[1,0]
	v_cvt_pk_bf16_f32 v110, v118, v119
	v_cvt_pk_bf16_f32 v111, v120, v121
	v_pk_mul_f32 v[86:87], v[86:87], v[156:157] op_sel_hi:[1,0]
	v_cvt_pk_bf16_f32 v112, v112, v113
	v_cvt_pk_bf16_f32 v113, v122, v123
	global_store_dwordx4 v[158:159], v[110:113], off offset:256
	v_pk_mul_f32 v[88:89], v[88:89], v[156:157] op_sel_hi:[1,0]
	v_pk_mul_f32 v[64:65], v[64:65], v[146:147] op_sel_hi:[1,0]
	v_or_b32_e32 v110, 16, v153
	v_mad_i64_i32 v[110:111], s[6:7], v110, s65, v[142:143]
	v_mov_b32_e32 v112, v155
	v_lshl_add_u64 v[110:111], v[110:111], 0, v[144:145]
	v_pk_mul_f32 v[116:117], v[116:117], v[112:113] op_sel_hi:[1,0]
	v_pk_mul_f32 v[114:115], v[114:115], v[112:113] op_sel_hi:[1,0]
	v_pk_mul_f32 v[118:119], v[108:109], v[112:113] op_sel_hi:[1,0]
	v_pk_mul_f32 v[108:109], v[106:107], v[112:113] op_sel_hi:[1,0]
	v_cvt_pk_bf16_f32 v106, v114, v115
	v_cvt_pk_bf16_f32 v107, v116, v117
	v_pk_mul_f32 v[102:103], v[102:103], v[112:113] op_sel_hi:[1,0]
	v_cvt_pk_bf16_f32 v108, v108, v109
	v_cvt_pk_bf16_f32 v109, v118, v119
	global_store_dwordx4 v[110:111], v[106:109], off
	v_pk_mul_f32 v[104:105], v[104:105], v[112:113] op_sel_hi:[1,0]
	v_pk_mul_f32 v[62:63], v[62:63], v[146:147] op_sel_hi:[1,0]
	v_pk_mul_f32 v[106:107], v[96:97], v[112:113] op_sel_hi:[1,0]
	v_pk_mul_f32 v[96:97], v[94:95], v[112:113] op_sel_hi:[1,0]
	v_cvt_pk_bf16_f32 v94, v102, v103
	v_cvt_pk_bf16_f32 v95, v104, v105
	v_pk_mul_f32 v[54:55], v[54:55], v[146:147] op_sel_hi:[1,0]
	v_cvt_pk_bf16_f32 v96, v96, v97
	v_cvt_pk_bf16_f32 v97, v106, v107
	global_store_dwordx4 v[110:111], v[94:97], off offset:256
	v_pk_mul_f32 v[56:57], v[56:57], v[146:147] op_sel_hi:[1,0]
	v_pk_mul_f32 v[34:35], v[34:35], v[140:141] op_sel_hi:[1,0]
	v_or_b32_e32 v94, 32, v153
	v_mad_i64_i32 v[94:95], s[6:7], v94, s65, v[142:143]
	v_lshl_add_u64 v[94:95], v[94:95], 0, v[144:145]
	v_pk_mul_f32 v[96:97], v[100:101], v[156:157] op_sel_hi:[1,0]
	v_pk_mul_f32 v[100:101], v[92:93], v[156:157] op_sel_hi:[1,0]
	v_pk_mul_f32 v[92:93], v[90:91], v[156:157] op_sel_hi:[1,0]
	v_cvt_pk_bf16_f32 v90, v98, v99
	v_cvt_pk_bf16_f32 v91, v96, v97
	v_pk_mul_f32 v[22:23], v[22:23], v[140:141] op_sel_hi:[1,0]
	v_cvt_pk_bf16_f32 v92, v92, v93
	v_cvt_pk_bf16_f32 v93, v100, v101
	global_store_dwordx4 v[94:95], v[90:93], off
	v_pk_mul_f32 v[24:25], v[24:25], v[140:141] op_sel_hi:[1,0]
	s_and_b64 vcc, exec, s[40:41]
	v_pk_mul_f32 v[90:91], v[80:81], v[156:157] op_sel_hi:[1,0]
	v_pk_mul_f32 v[80:81], v[78:79], v[156:157] op_sel_hi:[1,0]
	v_cvt_pk_bf16_f32 v78, v86, v87
	v_cvt_pk_bf16_f32 v79, v88, v89
	s_mov_b32 s85, s8
	v_cvt_pk_bf16_f32 v80, v80, v81
	v_cvt_pk_bf16_f32 v81, v90, v91
	global_store_dwordx4 v[94:95], v[78:81], off offset:256
	s_mov_b32 s86, s10
	s_mov_b64 s[24:25], s[12:13]
	v_or_b32_e32 v78, 48, v153
	v_mad_i64_i32 v[78:79], s[6:7], v78, s65, v[142:143]
	v_mov_b32_e32 v80, v157
	v_lshl_add_u64 v[78:79], v[78:79], 0, v[144:145]
	v_pk_mul_f32 v[84:85], v[84:85], v[80:81] op_sel_hi:[1,0]
	v_pk_mul_f32 v[82:83], v[82:83], v[80:81] op_sel_hi:[1,0]
	v_pk_mul_f32 v[86:87], v[76:77], v[80:81] op_sel_hi:[1,0]
	v_pk_mul_f32 v[76:77], v[74:75], v[80:81] op_sel_hi:[1,0]
	v_cvt_pk_bf16_f32 v74, v82, v83
	v_cvt_pk_bf16_f32 v75, v84, v85
	v_pk_mul_f32 v[70:71], v[70:71], v[80:81] op_sel_hi:[1,0]
	v_cvt_pk_bf16_f32 v76, v76, v77
	v_cvt_pk_bf16_f32 v77, v86, v87
	global_store_dwordx4 v[78:79], v[74:77], off
	v_pk_mul_f32 v[72:73], v[72:73], v[80:81] op_sel_hi:[1,0]
	s_mov_b32 s87, s84
	v_pk_mul_f32 v[74:75], v[68:69], v[80:81] op_sel_hi:[1,0]
	v_pk_mul_f32 v[68:69], v[66:67], v[80:81] op_sel_hi:[1,0]
	v_cvt_pk_bf16_f32 v66, v70, v71
	v_cvt_pk_bf16_f32 v67, v72, v73
	s_nop 0
	v_cvt_pk_bf16_f32 v68, v68, v69
	v_cvt_pk_bf16_f32 v69, v74, v75
	global_store_dwordx4 v[78:79], v[66:69], off offset:256
	s_nop 1
	v_add_u32_e32 v66, 0x80, v153
	v_mad_i64_i32 v[66:67], s[6:7], v66, s65, v[142:143]
	v_lshl_add_u64 v[66:67], v[66:67], 0, v[144:145]
; __device__ __forceinline__ unsigned pk2(float lo, float hi) { unsigned r; asm("v_cvt_pk_bf16_f32 %0, %1, %2" : "=v"(r) : "v"(lo), "v"(hi)); return r; }
; #define PG8_WAIT_V(n) asm volatile("s_waitcnt vmcnt(" #n ")" ::: "memory")
; #define PG8_BAR __builtin_amdgcn_s_barrier()
;     __device__ __forceinline__ void operator()(const f32x4 (&acc)[2][2][4][2], const Unit& u, int ui, int wr, int wc, int fr, int fq) const {
;     ...
;         for (int ai = 0; ai < 2; ++ai)
; #pragma unroll
;             for (int m = 0; m < 4; ++m) {
;                 const int row = row0 + ai * HALF + m * 16; const float rs = rsv[ai][m];
;                 bf16_t* rowp = O + (size_t)row * ldc + col0;
; #pragma unroll
;                 for (int bj = 0; bj < 2; ++bj) {
;                     f32x4 v0 = acc[ai][bj][m][0] * rs, v1 = acc[ai][bj][m][1] * rs;
;                     if (ACT == 1) {
; #pragma unroll
;                         for (int j = 0; j < 4; ++j) { const float a = fmaxf(v0[j], 0.f), b = fmaxf(v1[j], 0.f); v0[j] = a * a; v1[j] = b * b; }
;                     }
;                     u32x4 w; w.x = pk2(v0[0], v0[1]); w.y = pk2(v0[2], v0[3]); w.z = pk2(v1[0], v1[1]); w.w = pk2(v1[2], v1[3]);
;                     *(u32x4*)(rowp + bj * HALF) = w;
; template <class Epi>
; __device__ __forceinline__ void gemm_phase(LAS unsigned char* lds, const Gemm g, const StaticOrder& S, const Epi& E) {
;     ...
;         E(acc, cur, ui, wr, wc, fr, fq);
;         if (!has_next) break;
; #pragma unroll
;         for (int a = 0; a < 2; ++a)
; #pragma unroll
;             for (int b = 0; b < 2; ++b)
; #pragma unroll
;                 for (int m = 0; m < 4; ++m)
; #pragma unroll
;                     for (int n = 0; n < 2; ++n) acc[a][b][m][n] = (f32x4){0.f, 0.f, 0.f, 0.f};
;         cur = nxt; cA = nA; cB = nB; ++ui;
;     }
;     PG8_WAIT_V(0);
;     if (wr == 0) PG8_BAR;
;     PG8_BAR;
	v_pk_mul_f32 v[68:69], v[60:61], v[146:147] op_sel_hi:[1,0]
	v_pk_mul_f32 v[60:61], v[58:59], v[146:147] op_sel_hi:[1,0]
	v_cvt_pk_bf16_f32 v58, v62, v63
	v_cvt_pk_bf16_f32 v59, v64, v65
	s_nop 0
	v_cvt_pk_bf16_f32 v60, v60, v61
	v_cvt_pk_bf16_f32 v61, v68, v69
	v_mov_b32_e32 v162, v58
	v_mov_b32_e32 v163, v59
	v_mov_b32_e32 v164, v60
	v_mov_b32_e32 v165, v61
	s_nop 1
	v_pk_mul_f32 v[58:59], v[48:49], v[146:147] op_sel_hi:[1,0]
	v_pk_mul_f32 v[48:49], v[46:47], v[146:147] op_sel_hi:[1,0]
	v_cvt_pk_bf16_f32 v46, v54, v55
	v_cvt_pk_bf16_f32 v47, v56, v57
	s_nop 0
	v_cvt_pk_bf16_f32 v48, v48, v49
	v_cvt_pk_bf16_f32 v49, v58, v59
	v_mov_b32_e32 v188, v46
	v_mov_b32_e32 v189, v47
	v_mov_b32_e32 v190, v48
	v_mov_b32_e32 v191, v49
	s_nop 1
	v_add_u32_e32 v46, 0x90, v153
	v_mad_i64_i32 v[46:47], s[6:7], v46, s65, v[142:143]
	v_mov_b32_e32 v48, v147
	v_lshl_add_u64 v[46:47], v[46:47], 0, v[144:145]
	v_pk_mul_f32 v[52:53], v[52:53], v[48:49] op_sel_hi:[1,0]
	v_pk_mul_f32 v[50:51], v[50:51], v[48:49] op_sel_hi:[1,0]
	v_pk_mul_f32 v[54:55], v[44:45], v[48:49] op_sel_hi:[1,0]
	v_pk_mul_f32 v[44:45], v[42:43], v[48:49] op_sel_hi:[1,0]
	v_cvt_pk_bf16_f32 v42, v50, v51
	v_cvt_pk_bf16_f32 v43, v52, v53
	v_pk_mul_f32 v[38:39], v[38:39], v[48:49] op_sel_hi:[1,0]
	v_cvt_pk_bf16_f32 v44, v44, v45
	v_cvt_pk_bf16_f32 v45, v54, v55
	v_mov_b32_e32 v192, v42
	v_mov_b32_e32 v193, v43
	v_mov_b32_e32 v194, v44
	v_mov_b32_e32 v195, v45
	v_pk_mul_f32 v[40:41], v[40:41], v[48:49] op_sel_hi:[1,0]
	s_nop 0
	v_pk_mul_f32 v[42:43], v[32:33], v[48:49] op_sel_hi:[1,0]
	v_pk_mul_f32 v[32:33], v[30:31], v[48:49] op_sel_hi:[1,0]
	v_cvt_pk_bf16_f32 v30, v38, v39
	v_cvt_pk_bf16_f32 v31, v40, v41
	s_nop 0
	v_cvt_pk_bf16_f32 v32, v32, v33
	v_cvt_pk_bf16_f32 v33, v42, v43
	v_mov_b32_e32 v196, v30
	v_mov_b32_e32 v197, v31
	v_mov_b32_e32 v198, v32
	v_mov_b32_e32 v199, v33
	s_nop 1
	v_add_u32_e32 v30, 0xa0, v153
	v_mad_i64_i32 v[30:31], s[6:7], v30, s65, v[142:143]
	v_lshl_add_u64 v[30:31], v[30:31], 0, v[144:145]
	v_pk_mul_f32 v[32:33], v[36:37], v[140:141] op_sel_hi:[1,0]
	v_pk_mul_f32 v[36:37], v[28:29], v[140:141] op_sel_hi:[1,0]
	v_pk_mul_f32 v[28:29], v[26:27], v[140:141] op_sel_hi:[1,0]
	v_cvt_pk_bf16_f32 v26, v34, v35
	v_cvt_pk_bf16_f32 v27, v32, v33
	s_nop 0
	v_cvt_pk_bf16_f32 v28, v28, v29
	v_cvt_pk_bf16_f32 v29, v36, v37
	v_mov_b32_e32 v200, v26
	v_mov_b32_e32 v201, v27
	v_mov_b32_e32 v202, v28
	v_mov_b32_e32 v203, v29
	s_nop 1
	v_pk_mul_f32 v[26:27], v[16:17], v[140:141] op_sel_hi:[1,0]
	v_pk_mul_f32 v[16:17], v[14:15], v[140:141] op_sel_hi:[1,0]
	v_cvt_pk_bf16_f32 v14, v22, v23
	v_cvt_pk_bf16_f32 v15, v24, v25
	s_nop 0
	v_cvt_pk_bf16_f32 v16, v16, v17
	v_cvt_pk_bf16_f32 v17, v26, v27
	v_mov_b32_e32 v222, v14
	v_mov_b32_e32 v223, v15
	v_mov_b32_e32 v224, v16
	v_mov_b32_e32 v225, v17
	s_nop 1
	v_add_u32_e32 v14, 0xb0, v153
	v_mad_i64_i32 v[14:15], s[6:7], v14, s65, v[142:143]
	v_mov_b32_e32 v16, v141
	v_lshl_add_u64 v[14:15], v[14:15], 0, v[144:145]
	v_pk_mul_f32 v[20:21], v[20:21], v[16:17] op_sel_hi:[1,0]
	v_pk_mul_f32 v[18:19], v[18:19], v[16:17] op_sel_hi:[1,0]
	v_pk_mul_f32 v[22:23], v[12:13], v[16:17] op_sel_hi:[1,0]
	v_pk_mul_f32 v[12:13], v[10:11], v[16:17] op_sel_hi:[1,0]
	v_cvt_pk_bf16_f32 v10, v18, v19
	v_cvt_pk_bf16_f32 v11, v20, v21
	s_mov_b64 s[6:7], s[22:23]
	v_cvt_pk_bf16_f32 v12, v12, v13
	v_cvt_pk_bf16_f32 v13, v22, v23
	v_mov_b32_e32 v244, v10
	v_mov_b32_e32 v245, v11
	v_mov_b32_e32 v246, v12
	v_mov_b32_e32 v247, v13
	v_pk_mul_f32 v[8:9], v[8:9], v[16:17] op_sel_hi:[1,0]
	v_pk_mul_f32 v[6:7], v[6:7], v[16:17] op_sel_hi:[1,0]
	v_pk_mul_f32 v[10:11], v[4:5], v[16:17] op_sel_hi:[1,0]
	v_pk_mul_f32 v[4:5], v[2:3], v[16:17] op_sel_hi:[1,0]
	v_cvt_pk_bf16_f32 v2, v6, v7
	v_cvt_pk_bf16_f32 v3, v8, v9
	s_nop 0
	v_cvt_pk_bf16_f32 v4, v4, v5
	v_cvt_pk_bf16_f32 v5, v10, v11
	v_mov_b32_e32 v248, v2
	v_mov_b32_e32 v249, v3
	v_mov_b32_e32 v250, v4
	v_mov_b32_e32 v251, v5
	s_cbranch_vccz .LBB0_460
	global_store_dwordx4 v166, v[162:165], s[4:5]
	global_store_dwordx4 v166, v[188:191], s[4:5] offset:256
	s_nop 1
	v_add_u32_e32 v166, 0xe000, v166
	global_store_dwordx4 v166, v[192:195], s[4:5]
	global_store_dwordx4 v166, v[196:199], s[4:5] offset:256
	s_nop 1
	v_add_u32_e32 v166, 0xe000, v166
	global_store_dwordx4 v166, v[200:203], s[4:5]
	global_store_dwordx4 v166, v[222:225], s[4:5] offset:256
	s_nop 1
	v_add_u32_e32 v166, 0xe000, v166
	global_store_dwordx4 v166, v[244:247], s[4:5]
	global_store_dwordx4 v166, v[248:251], s[4:5] offset:256
	s_nop 1
	v_mov_b64_e32 v[164:165], 0x200
	v_mbcnt_lo_u32_b32 v193, -1, 0
	v_mbcnt_hi_u32_b32 v193, -1, v193
	v_mov_b32_e32 v188, 1
	v_mov_b32_e32 v189, 0x358637bd
	v_mov_b32_e32 v190, 0x260
	v_mov_b32_e32 v191, 0x3c0881c4
	v_mov_b32_e32 v192, 0xbab64f3b
	v_mov_b32_e32 v194, 0xf149f2ca
	v_mov_b32_e32 v195, 0xc0
	v_mov_b32_e32 v196, 0x70
	v_mov_b32_e32 v197, 0x71
	v_mov_b32_e32 v198, 5
	v_mov_b32_e32 v199, 2
	v_mov_b32_e32 v200, 3
	v_not_b32_e32 v201, 63
	v_not_b32_e32 v202, 31
	v_mov_b32_e32 v203, 0x7fc00000
	v_mov_b32_e32 v222, 0
	v_mov_b32_e32 v223, 0
	v_mov_b32_e32 v224, 0
	v_mov_b32_e32 v225, 0
	s_waitcnt vmcnt(0)
	v_readlane_b32 s70, v254, 40
	v_readlane_b32 s84, v254, 42
	s_cmpk_gt_u32 s18, 0xff
	v_readlane_b32 s71, v254, 41
	v_readlane_b32 s86, v254, 44
	v_readlane_b32 s87, v254, 45
	v_readlane_b32 s85, v254, 43
	s_cbranch_scc1 .LBB0_467
	s_barrier
